# MLA loop v2 (DMA issue spread under MFMAs, uniform vmcnt) + branch-free NA softmax body + drop redundant vmcnt(0) before acc zeroing in GEMM tile prologues
# speedup vs baseline: 1.0079x; 1.0079x over previous
; DI int tid_opaque() { int t = threadIdx.x; asm volatile("" : "+v"(t)); return t; }
; #define LDS_PTR(p) ((__attribute__((address_space(3))) unsigned*)(p))
; template <int PIPE>
; DI void gemm_loop_g(const u16* __restrict__ Xp, long ldx_l, long ldx_i, long kxs,
;                     const u16* __restrict__ Yp, long ldy_l, long ldy_i, long kys, int K,
;                     f32x4 (&acc)[4][8], unsigned char* smem) {
;   const int t = tid_opaque(), l = t & 63, w = __builtin_amdgcn_readfirstlane(t >> 6), wx = w >> 1, wy = w & 1;
;   const int lrow = t >> 3, gch = (t & 7) ^ ((t >> 4) & 7);
;   const u16* xs = Xp + (long)lrow * ldx_l + gch * 8;
;   const u16* ys = Yp + (long)lrow * ldy_l + gch * 8;
;   const int fsw = (l >> 1) & 7, lg = l >> 4;
;   const unsigned fr0 = (l & 15) * 128 + ((lg ^ fsw) << 4);
;   const unsigned fr1 = (l & 15) * 128 + (((lg + 4) ^ fsw) << 4);
;   const unsigned ub = wx * 8192, vb = 32768 + wy * 16384;
;   const int nk = K >> 6;
;   const int rot = (int)((blockIdx.x >> 3) + (blockIdx.x & 7) * 5) % nk;
;   auto issue = [&](int kt0, int stage) {
;     int kt = kt0 + rot; if (kt >= nk) kt -= nk;
;     unsigned char* sb = smem + stage * 65536 + t * 16;
; #pragma unroll
;     for (int i = 0; i < 4; ++i)
;       __builtin_amdgcn_global_load_lds((const unsigned*)(xs + i * ldx_i + kt * kxs), LDS_PTR(sb + i * 8192), 16, 0, 0);
; #pragma unroll
;     for (int i = 0; i < 4; ++i)
;       __builtin_amdgcn_global_load_lds((const unsigned*)(ys + i * ldy_i + kt * kys), LDS_PTR(sb + 32768 + i * 8192), 16, 0, 0);
;   };
;   __syncthreads();
;   issue(0, 0);
;   asm volatile("s_waitcnt vmcnt(0)" ::: "memory");
;   __syncthreads();
; DI void zero_acc(f32x4 (&acc)[4][8]) {
; #pragma unroll
;   for (int i = 0; i < 4; ++i)
; #pragma unroll
;     for (int j = 0; j < 8; ++j) acc[i][j] = f32x4{0.f, 0.f, 0.f, 0.f};
; }
.LBB0_80:
	s_mul_hi_u32 s6, s65, 0xaaaaaaab
	s_lshr_b32 s63, s6, 3
	s_mul_i32 s62, s63, -12
	s_and_b32 s6, s6, -8
	s_add_i32 s62, s62, s65
	s_or_b32 s66, s6, s53
	s_lshl_b32 s8, s66, 8
	s_lshl_b32 s6, s62, 8
	s_cmp_gt_i32 s62, 7
	s_cselect_b64 s[10:11], -1, 0
	s_mov_b64 s[60:61], -1
	s_and_b64 vcc, exec, s[10:11]
	s_cbranch_vccz .LBB0_86
	s_mov_b32 s7, s19
	s_lshl_b64 s[48:49], s[6:7], 11
	s_add_u32 s48, s22, s48
	s_mov_b32 s9, s19
	v_mov_b32_e32 v4, v182
	s_addc_u32 s49, s23, s49
	s_lshl_b64 s[60:61], s[8:9], 11
	s_waitcnt lgkmcnt(0)
	s_add_u32 s60, s12, s60
	v_ashrrev_i32_e32 v0, 3, v4
	v_lshrrev_b32_e32 v5, 4, v4
	v_xor_b32_e32 v6, v5, v4
	v_ashrrev_i32_e32 v1, 31, v0
	s_addc_u32 s61, s13, s61
	v_lshlrev_b64 v[0:1], 11, v[0:1]
	v_lshlrev_b32_e32 v6, 4, v6
	v_lshl_add_u64 v[2:3], s[48:49], 0, v[0:1]
	v_and_b32_e32 v128, 0x70, v6
	v_lshl_add_u64 v[0:1], s[60:61], 0, v[0:1]
	v_lshl_add_u64 v[132:133], v[2:3], 0, v[128:129]
	v_lshl_add_u64 v[134:135], v[0:1], 0, v[128:129]
	v_lshlrev_b32_e32 v128, 4, v4
	s_mov_b32 s59, s19
	v_readfirstlane_b32 s7, v128
	v_add_u32_e32 v2, 0x2000, v128
	v_lshl_add_u64 v[0:1], v[132:133], 0, s[58:59]
	s_mov_b32 m0, s7
	v_lshl_add_u64 v[136:137], v[132:133], 0, s[24:25]
	v_readfirstlane_b32 s7, v2
	v_add_u32_e32 v2, 0x4000, v128
	s_barrier
	global_load_lds_dwordx4 v[0:1], off
	v_lshl_add_u64 v[0:1], v[136:137], 0, s[58:59]
	s_mov_b32 m0, s7
	v_lshl_add_u64 v[138:139], v[132:133], 0, s[26:27]
	v_readfirstlane_b32 s7, v2
	v_add_u32_e32 v2, 0x6000, v128
	global_load_lds_dwordx4 v[0:1], off
	v_lshl_add_u64 v[0:1], v[138:139], 0, s[58:59]
	s_mov_b32 m0, s7
	v_lshl_add_u64 v[140:141], v[132:133], 0, s[28:29]
	v_readfirstlane_b32 s7, v2
	v_add_u32_e32 v2, 0x8000, v128
	global_load_lds_dwordx4 v[0:1], off
	v_lshl_add_u64 v[0:1], v[140:141], 0, s[58:59]
	s_mov_b32 m0, s7
	v_readfirstlane_b32 s7, v2
	v_add_u32_e32 v2, 0xa000, v128
	global_load_lds_dwordx4 v[0:1], off
	v_lshl_add_u64 v[0:1], v[134:135], 0, s[58:59]
	s_mov_b32 m0, s7
	v_lshl_add_u64 v[142:143], v[134:135], 0, s[24:25]
	v_readfirstlane_b32 s7, v2
	v_add_u32_e32 v2, 0xc000, v128
	global_load_lds_dwordx4 v[0:1], off
	v_lshl_add_u64 v[0:1], v[142:143], 0, s[58:59]
	s_mov_b32 m0, s7
	v_lshl_add_u64 v[144:145], v[134:135], 0, s[26:27]
	v_readfirstlane_b32 s7, v2
	v_add_u32_e32 v2, 0xe000, v128
	global_load_lds_dwordx4 v[0:1], off
	v_lshl_add_u64 v[0:1], v[144:145], 0, s[58:59]
	s_mov_b32 m0, s7
	v_lshl_add_u64 v[146:147], v[134:135], 0, s[28:29]
	v_readfirstlane_b32 s7, v2
	global_load_lds_dwordx4 v[0:1], off
	v_lshl_add_u64 v[0:1], v[146:147], 0, s[58:59]
	s_mov_b32 m0, s7
	v_lshlrev_b32_e32 v2, 7, v4
	global_load_lds_dwordx4 v[0:1], off
	v_bfe_u32 v0, v4, 4, 2
	v_bfe_u32 v1, v4, 1, 3
	v_readfirstlane_b32 s9, v4
	s_nop 0
	v_bitop3_b32 v0, v0, v1, 4 bitop3:0x36
	v_and_b32_e32 v2, 0x780, v2
	s_lshl_b32 s7, s9, 8
	s_lshl_b32 s9, s9, 6
	v_lshl_or_b32 v131, v0, 4, v2
	v_bitop3_b32 v0, v5, v1, 3 bitop3:0x6c
	v_mov_b32_e32 v8, 0
	s_and_b32 s7, s7, 0x4000
	s_and_b32 s9, s9, 0xffffe000
	v_lshl_or_b32 v156, v0, 4, v2
	s_mov_b32 s18, 0
	s_mov_b32 s33, 0x10000
	v_mov_b32_e32 v9, v8
	v_mov_b32_e32 v10, v8
	v_mov_b32_e32 v11, v8
	v_mov_b32_e32 v12, v8
	v_mov_b32_e32 v13, v8
	v_mov_b32_e32 v14, v8
	v_mov_b32_e32 v15, v8
	v_mov_b32_e32 v28, v8
	v_mov_b32_e32 v29, v8
	v_mov_b32_e32 v30, v8
	v_mov_b32_e32 v31, v8
	v_mov_b32_e32 v44, v8
	v_mov_b32_e32 v45, v8
	v_mov_b32_e32 v46, v8
	v_mov_b32_e32 v47, v8
	v_mov_b32_e32 v60, v8
	v_mov_b32_e32 v61, v8
	v_mov_b32_e32 v62, v8
	v_mov_b32_e32 v63, v8
	v_mov_b32_e32 v76, v8
	v_mov_b32_e32 v77, v8
	v_mov_b32_e32 v78, v8
	v_mov_b32_e32 v79, v8
	v_mov_b32_e32 v92, v8
	v_mov_b32_e32 v93, v8
	v_mov_b32_e32 v94, v8
	v_mov_b32_e32 v95, v8
	v_mov_b32_e32 v108, v8
	v_mov_b32_e32 v109, v8
	v_mov_b32_e32 v110, v8
	v_mov_b32_e32 v111, v8
	v_mov_b32_e32 v0, v8
	v_mov_b32_e32 v1, v8
	v_mov_b32_e32 v2, v8
	v_mov_b32_e32 v3, v8
	v_mov_b32_e32 v20, v8
	v_mov_b32_e32 v21, v8
	v_mov_b32_e32 v22, v8
	v_mov_b32_e32 v23, v8
	v_mov_b32_e32 v36, v8
	v_mov_b32_e32 v37, v8
	v_mov_b32_e32 v38, v8
	v_mov_b32_e32 v39, v8
	v_mov_b32_e32 v52, v8
	v_mov_b32_e32 v53, v8
	v_mov_b32_e32 v54, v8
	v_mov_b32_e32 v55, v8
	v_mov_b32_e32 v68, v8
	v_mov_b32_e32 v69, v8
	v_mov_b32_e32 v70, v8
	v_mov_b32_e32 v71, v8
	v_mov_b32_e32 v84, v8
	v_mov_b32_e32 v85, v8
	v_mov_b32_e32 v86, v8
	v_mov_b32_e32 v87, v8
	v_mov_b32_e32 v100, v8
	v_mov_b32_e32 v101, v8
	v_mov_b32_e32 v102, v8
	v_mov_b32_e32 v103, v8
	v_mov_b32_e32 v116, v8
	v_mov_b32_e32 v117, v8
	v_mov_b32_e32 v118, v8
	v_mov_b32_e32 v119, v8
	v_mov_b32_e32 v4, v8
	v_mov_b32_e32 v5, v8
	v_mov_b32_e32 v6, v8
	v_mov_b32_e32 v7, v8
	v_mov_b32_e32 v24, v8
	v_mov_b32_e32 v25, v8
	v_mov_b32_e32 v26, v8
	v_mov_b32_e32 v27, v8
	v_mov_b32_e32 v40, v8
	v_mov_b32_e32 v41, v8
	v_mov_b32_e32 v42, v8
	v_mov_b32_e32 v43, v8
	v_mov_b32_e32 v56, v8
	v_mov_b32_e32 v57, v8
	v_mov_b32_e32 v58, v8
	v_mov_b32_e32 v59, v8
	v_mov_b32_e32 v72, v8
	v_mov_b32_e32 v73, v8
	v_mov_b32_e32 v74, v8
	v_mov_b32_e32 v75, v8
	v_mov_b32_e32 v88, v8
	v_mov_b32_e32 v89, v8
	v_mov_b32_e32 v90, v8
	v_mov_b32_e32 v91, v8
	v_mov_b32_e32 v104, v8
	v_mov_b32_e32 v105, v8
	v_mov_b32_e32 v106, v8
	v_mov_b32_e32 v107, v8
	v_mov_b32_e32 v120, v8
	v_mov_b32_e32 v121, v8
	v_mov_b32_e32 v122, v8
	v_mov_b32_e32 v123, v8
	v_mov_b32_e32 v16, v8
	v_mov_b32_e32 v17, v8
	v_mov_b32_e32 v18, v8
	v_mov_b32_e32 v19, v8
	v_mov_b32_e32 v32, v8
	v_mov_b32_e32 v33, v8
	v_mov_b32_e32 v34, v8
	v_mov_b32_e32 v35, v8
	v_mov_b32_e32 v48, v8
	v_mov_b32_e32 v49, v8
	v_mov_b32_e32 v50, v8
	v_mov_b32_e32 v51, v8
	v_mov_b32_e32 v64, v8
	v_mov_b32_e32 v65, v8
	v_mov_b32_e32 v66, v8
	v_mov_b32_e32 v67, v8
	v_mov_b32_e32 v80, v8
	v_mov_b32_e32 v81, v8
	v_mov_b32_e32 v82, v8
	v_mov_b32_e32 v83, v8
	v_mov_b32_e32 v96, v8
	v_mov_b32_e32 v97, v8
	v_mov_b32_e32 v98, v8
	v_mov_b32_e32 v99, v8
	v_mov_b32_e32 v112, v8
	v_mov_b32_e32 v113, v8
	v_mov_b32_e32 v114, v8
	v_mov_b32_e32 v115, v8
	v_mov_b32_e32 v124, v8
	v_mov_b32_e32 v125, v8
	v_mov_b32_e32 v126, v8
	v_mov_b32_e32 v127, v8
	s_waitcnt vmcnt(0) lgkmcnt(0)
	s_barrier
	s_branch .LBB0_83

; DI int tid_opaque() { int t = threadIdx.x; asm volatile("" : "+v"(t)); return t; }
; #define LDS_PTR(p) ((__attribute__((address_space(3))) unsigned*)(p))
; template <int PIPE>
; DI void gemm_loop_g(const u16* __restrict__ Xp, long ldx_l, long ldx_i, long kxs,
;                     const u16* __restrict__ Yp, long ldy_l, long ldy_i, long kys, int K,
;                     f32x4 (&acc)[4][8], unsigned char* smem) {
;   const int t = tid_opaque(), l = t & 63, w = __builtin_amdgcn_readfirstlane(t >> 6), wx = w >> 1, wy = w & 1;
;   const int lrow = t >> 3, gch = (t & 7) ^ ((t >> 4) & 7);
;   const u16* xs = Xp + (long)lrow * ldx_l + gch * 8;
;   const u16* ys = Yp + (long)lrow * ldy_l + gch * 8;
;   const int fsw = (l >> 1) & 7, lg = l >> 4;
;   const unsigned fr0 = (l & 15) * 128 + ((lg ^ fsw) << 4);
;   const unsigned fr1 = (l & 15) * 128 + (((lg + 4) ^ fsw) << 4);
;   const unsigned ub = wx * 8192, vb = 32768 + wy * 16384;
;   const int nk = K >> 6;
;   const int rot = (int)((blockIdx.x >> 3) + (blockIdx.x & 7) * 5) % nk;
;   auto issue = [&](int kt0, int stage) {
;     int kt = kt0 + rot; if (kt >= nk) kt -= nk;
;     unsigned char* sb = smem + stage * 65536 + t * 16;
; #pragma unroll
;     for (int i = 0; i < 4; ++i)
;       __builtin_amdgcn_global_load_lds((const unsigned*)(xs + i * ldx_i + kt * kxs), LDS_PTR(sb + i * 8192), 16, 0, 0);
; #pragma unroll
;     for (int i = 0; i < 4; ++i)
;       __builtin_amdgcn_global_load_lds((const unsigned*)(ys + i * ldy_i + kt * kys), LDS_PTR(sb + 32768 + i * 8192), 16, 0, 0);
;   };
;   __syncthreads();
;   issue(0, 0);
;   asm volatile("s_waitcnt vmcnt(0)" ::: "memory");
;   __syncthreads();
; DI void zero_acc(f32x4 (&acc)[4][8]) {
; #pragma unroll
;   for (int i = 0; i < 4; ++i)
; #pragma unroll
;     for (int j = 0; j < 8; ++j) acc[i][j] = f32x4{0.f, 0.f, 0.f, 0.f};
; }
.LBB0_86:
	s_and_b64 vcc, exec, s[60:61]
	s_cbranch_vccz .LBB0_91
	s_lshr_b32 s18, s63, 1
	s_lshl_b64 s[48:49], s[18:19], 23
	s_waitcnt lgkmcnt(0)
	s_add_u32 s7, s12, s48
	s_addc_u32 s9, s13, s49
	s_lshl_b32 s18, s66, 13
	s_and_b32 s18, s18, 0x1e000
	s_add_u32 s48, s7, s18
	s_addc_u32 s49, s9, 0
	s_ashr_i32 s7, s6, 31
	v_mov_b32_e32 v4, v182
	s_lshl_b64 s[60:61], s[6:7], 11
	s_add_u32 s60, s22, s60
	v_ashrrev_i32_e32 v0, 3, v4
	v_lshrrev_b32_e32 v5, 4, v4
	v_xor_b32_e32 v6, v5, v4
	v_ashrrev_i32_e32 v1, 31, v0
	s_addc_u32 s61, s23, s61
	v_lshlrev_b64 v[2:3], 17, v[0:1]
	v_lshlrev_b32_e32 v6, 4, v6
	v_lshlrev_b64 v[0:1], 11, v[0:1]
	v_lshl_add_u64 v[2:3], s[48:49], 0, v[2:3]
	v_and_b32_e32 v128, 0x70, v6
	v_lshl_add_u64 v[0:1], s[60:61], 0, v[0:1]
	v_lshl_add_u64 v[132:133], v[2:3], 0, v[128:129]
	v_lshl_add_u64 v[134:135], v[0:1], 0, v[128:129]
	v_lshlrev_b32_e32 v128, 4, v4
	s_mov_b32 s59, s19
	v_readfirstlane_b32 s7, v128
	v_add_u32_e32 v2, 0x2000, v128
	v_lshl_add_u64 v[0:1], v[132:133], 0, s[58:59]
	s_mov_b32 m0, s7
	v_readfirstlane_b32 s7, v2
	v_add_u32_e32 v2, 0x4000, v128
	s_barrier
	global_load_lds_dwordx4 v[0:1], off
	v_lshl_add_u64 v[0:1], v[0:1], 0, s[30:31]
	s_mov_b32 m0, s7
	v_lshl_add_u64 v[136:137], v[132:133], 0, s[36:37]
	v_readfirstlane_b32 s7, v2
	v_add_u32_e32 v2, 0x6000, v128
	global_load_lds_dwordx4 v[0:1], off
	v_lshl_add_u64 v[0:1], v[136:137], 0, s[58:59]
	s_mov_b32 m0, s7
	v_lshl_add_u64 v[138:139], v[132:133], 0, s[38:39]
	v_readfirstlane_b32 s7, v2
	v_add_u32_e32 v2, 0x8000, v128
	global_load_lds_dwordx4 v[0:1], off
	v_lshl_add_u64 v[0:1], v[138:139], 0, s[58:59]
	s_mov_b32 m0, s7
	v_readfirstlane_b32 s7, v2
	v_add_u32_e32 v2, 0xa000, v128
	global_load_lds_dwordx4 v[0:1], off
	v_lshl_add_u64 v[0:1], v[134:135], 0, s[58:59]
	s_mov_b32 m0, s7
	v_lshl_add_u64 v[140:141], v[134:135], 0, s[24:25]
	v_readfirstlane_b32 s7, v2
	v_add_u32_e32 v2, 0xc000, v128
	global_load_lds_dwordx4 v[0:1], off
	v_lshl_add_u64 v[0:1], v[140:141], 0, s[58:59]
	s_mov_b32 m0, s7
	v_lshl_add_u64 v[142:143], v[134:135], 0, s[26:27]
	v_readfirstlane_b32 s7, v2
	v_add_u32_e32 v2, 0xe000, v128
	global_load_lds_dwordx4 v[0:1], off
	v_lshl_add_u64 v[0:1], v[142:143], 0, s[58:59]
	s_mov_b32 m0, s7
	v_lshl_add_u64 v[144:145], v[134:135], 0, s[28:29]
	v_readfirstlane_b32 s7, v2
	global_load_lds_dwordx4 v[0:1], off
	v_lshl_add_u64 v[0:1], v[144:145], 0, s[58:59]
	s_mov_b32 m0, s7
	v_lshlrev_b32_e32 v2, 7, v4
	global_load_lds_dwordx4 v[0:1], off
	v_bfe_u32 v0, v4, 4, 2
	v_bfe_u32 v1, v4, 1, 3
	v_readfirstlane_b32 s9, v4
	s_nop 0
	v_bitop3_b32 v0, v0, v1, 4 bitop3:0x36
	v_and_b32_e32 v2, 0x780, v2
	s_lshl_b32 s7, s9, 8
	s_lshl_b32 s9, s9, 6
	v_lshl_or_b32 v131, v0, 4, v2
	v_bitop3_b32 v0, v5, v1, 3 bitop3:0x6c
	v_mov_b32_e32 v8, 0
	s_and_b32 s7, s7, 0x4000
	s_and_b32 s9, s9, 0xffffe000
	v_lshl_or_b32 v146, v0, 4, v2
	s_mov_b32 s18, 0
	s_mov_b32 s33, 0x10000
	v_mov_b32_e32 v9, v8
	v_mov_b32_e32 v10, v8
	v_mov_b32_e32 v11, v8
	v_mov_b32_e32 v12, v8
	v_mov_b32_e32 v13, v8
	v_mov_b32_e32 v14, v8
	v_mov_b32_e32 v15, v8
	v_mov_b32_e32 v28, v8
	v_mov_b32_e32 v29, v8
	v_mov_b32_e32 v30, v8
	v_mov_b32_e32 v31, v8
	v_mov_b32_e32 v44, v8
	v_mov_b32_e32 v45, v8
	v_mov_b32_e32 v46, v8
	v_mov_b32_e32 v47, v8
	v_mov_b32_e32 v60, v8
	v_mov_b32_e32 v61, v8
	v_mov_b32_e32 v62, v8
	v_mov_b32_e32 v63, v8
	v_mov_b32_e32 v76, v8
	v_mov_b32_e32 v77, v8
	v_mov_b32_e32 v78, v8
	v_mov_b32_e32 v79, v8
	v_mov_b32_e32 v92, v8
	v_mov_b32_e32 v93, v8
	v_mov_b32_e32 v94, v8
	v_mov_b32_e32 v95, v8
	v_mov_b32_e32 v108, v8
	v_mov_b32_e32 v109, v8
	v_mov_b32_e32 v110, v8
	v_mov_b32_e32 v111, v8
	v_mov_b32_e32 v0, v8
	v_mov_b32_e32 v1, v8
	v_mov_b32_e32 v2, v8
	v_mov_b32_e32 v3, v8
	v_mov_b32_e32 v20, v8
	v_mov_b32_e32 v21, v8
	v_mov_b32_e32 v22, v8
	v_mov_b32_e32 v23, v8
	v_mov_b32_e32 v36, v8
	v_mov_b32_e32 v37, v8
	v_mov_b32_e32 v38, v8
	v_mov_b32_e32 v39, v8
	v_mov_b32_e32 v52, v8
	v_mov_b32_e32 v53, v8
	v_mov_b32_e32 v54, v8
	v_mov_b32_e32 v55, v8
	v_mov_b32_e32 v68, v8
	v_mov_b32_e32 v69, v8
	v_mov_b32_e32 v70, v8
	v_mov_b32_e32 v71, v8
	v_mov_b32_e32 v84, v8
	v_mov_b32_e32 v85, v8
	v_mov_b32_e32 v86, v8
	v_mov_b32_e32 v87, v8
	v_mov_b32_e32 v100, v8
	v_mov_b32_e32 v101, v8
	v_mov_b32_e32 v102, v8
	v_mov_b32_e32 v103, v8
	v_mov_b32_e32 v116, v8
	v_mov_b32_e32 v117, v8
	v_mov_b32_e32 v118, v8
	v_mov_b32_e32 v119, v8
	v_mov_b32_e32 v4, v8
	v_mov_b32_e32 v5, v8
	v_mov_b32_e32 v6, v8
	v_mov_b32_e32 v7, v8
	v_mov_b32_e32 v24, v8
	v_mov_b32_e32 v25, v8
	v_mov_b32_e32 v26, v8
	v_mov_b32_e32 v27, v8
	v_mov_b32_e32 v40, v8
	v_mov_b32_e32 v41, v8
	v_mov_b32_e32 v42, v8
	v_mov_b32_e32 v43, v8
	v_mov_b32_e32 v56, v8
	v_mov_b32_e32 v57, v8
	v_mov_b32_e32 v58, v8
	v_mov_b32_e32 v59, v8
	v_mov_b32_e32 v72, v8
	v_mov_b32_e32 v73, v8
	v_mov_b32_e32 v74, v8
	v_mov_b32_e32 v75, v8
	v_mov_b32_e32 v88, v8
	v_mov_b32_e32 v89, v8
	v_mov_b32_e32 v90, v8
	v_mov_b32_e32 v91, v8
	v_mov_b32_e32 v104, v8
	v_mov_b32_e32 v105, v8
	v_mov_b32_e32 v106, v8
	v_mov_b32_e32 v107, v8
	v_mov_b32_e32 v120, v8
	v_mov_b32_e32 v121, v8
	v_mov_b32_e32 v122, v8
	v_mov_b32_e32 v123, v8
	v_mov_b32_e32 v16, v8
	v_mov_b32_e32 v17, v8
	v_mov_b32_e32 v18, v8
	v_mov_b32_e32 v19, v8
	v_mov_b32_e32 v32, v8
	v_mov_b32_e32 v33, v8
	v_mov_b32_e32 v34, v8
	v_mov_b32_e32 v35, v8
	v_mov_b32_e32 v48, v8
	v_mov_b32_e32 v49, v8
	v_mov_b32_e32 v50, v8
	v_mov_b32_e32 v51, v8
	v_mov_b32_e32 v64, v8
	v_mov_b32_e32 v65, v8
	v_mov_b32_e32 v66, v8
	v_mov_b32_e32 v67, v8
	v_mov_b32_e32 v80, v8
	v_mov_b32_e32 v81, v8
	v_mov_b32_e32 v82, v8
	v_mov_b32_e32 v83, v8
	v_mov_b32_e32 v96, v8
	v_mov_b32_e32 v97, v8
	v_mov_b32_e32 v98, v8
	v_mov_b32_e32 v99, v8
	v_mov_b32_e32 v112, v8
	v_mov_b32_e32 v113, v8
	v_mov_b32_e32 v114, v8
	v_mov_b32_e32 v115, v8
	v_mov_b32_e32 v124, v8
	v_mov_b32_e32 v125, v8
	v_mov_b32_e32 v126, v8
	v_mov_b32_e32 v127, v8
	s_waitcnt vmcnt(0) lgkmcnt(0)
	s_barrier
	s_branch .LBB0_89

; DI int tid_opaque() { int t = threadIdx.x; asm volatile("" : "+v"(t)); return t; }
; #define LDS_PTR(p) ((__attribute__((address_space(3))) unsigned*)(p))
; template <int PIPE>
; DI void gemm_loop_g(const u16* __restrict__ Xp, long ldx_l, long ldx_i, long kxs,
;                     const u16* __restrict__ Yp, long ldy_l, long ldy_i, long kys, int K,
;                     f32x4 (&acc)[4][8], unsigned char* smem) {
;   const int t = tid_opaque(), l = t & 63, w = __builtin_amdgcn_readfirstlane(t >> 6), wx = w >> 1, wy = w & 1;
;   const int lrow = t >> 3, gch = (t & 7) ^ ((t >> 4) & 7);
;   const u16* xs = Xp + (long)lrow * ldx_l + gch * 8;
;   const u16* ys = Yp + (long)lrow * ldy_l + gch * 8;
;   const int fsw = (l >> 1) & 7, lg = l >> 4;
;   const unsigned fr0 = (l & 15) * 128 + ((lg ^ fsw) << 4);
;   const unsigned fr1 = (l & 15) * 128 + (((lg + 4) ^ fsw) << 4);
;   const unsigned ub = wx * 8192, vb = 32768 + wy * 16384;
;   const int nk = K >> 6;
;   const int rot = (int)((blockIdx.x >> 3) + (blockIdx.x & 7) * 5) % nk;
;   auto issue = [&](int kt0, int stage) {
;     int kt = kt0 + rot; if (kt >= nk) kt -= nk;
;     unsigned char* sb = smem + stage * 65536 + t * 16;
; #pragma unroll
;     for (int i = 0; i < 4; ++i)
;       __builtin_amdgcn_global_load_lds((const unsigned*)(xs + i * ldx_i + kt * kxs), LDS_PTR(sb + i * 8192), 16, 0, 0);
; #pragma unroll
;     for (int i = 0; i < 4; ++i)
;       __builtin_amdgcn_global_load_lds((const unsigned*)(ys + i * ldy_i + kt * kys), LDS_PTR(sb + 32768 + i * 8192), 16, 0, 0);
;   };
;   __syncthreads();
;   issue(0, 0);
;   asm volatile("s_waitcnt vmcnt(0)" ::: "memory");
;   __syncthreads();
; template <int MODE>
; DI void gemm_phase(const Params& p, const GP& g, unsigned char* smem) {
;     ...
;     if (MODE == M_FFT1) {
;       const int bt = mt >> 8, cg = mt & 255;
;       gemm_loop_g<0>(Ab + ((long)(bt * 1024 + cg * 4)) * 8192, 64, 8192, 4096, Wb, 128, 64 * 128, 64, 128, acc, smem);
.LBB0_108:
	s_lshl_b32 s10, s54, 3
	s_and_b32 s10, s10, 0xf8
	s_lshr_b32 s33, s54, 5
	s_or_b32 s10, s10, s53
	s_lshl_b32 s36, s33, 10
	s_lshl_b32 s48, s10, 2
	s_or_b32 s10, s48, s36
	v_mov_b32_e32 v4, v182
	s_lshl_b64 s[36:37], s[10:11], 14
	s_add_u32 s36, s20, s36
	v_ashrrev_i32_e32 v0, 3, v4
	v_lshrrev_b32_e32 v18, 4, v4
	v_xor_b32_e32 v5, v18, v4
	v_ashrrev_i32_e32 v1, 31, v0
	s_addc_u32 s37, s21, s37
	v_readfirstlane_b32 s38, v4
	v_lshlrev_b64 v[2:3], 7, v[0:1]
	v_lshlrev_b32_e32 v5, 4, v5
	v_lshl_add_u64 v[2:3], s[36:37], 0, v[2:3]
	v_and_b32_e32 v128, 0x70, v5
	s_lshl_b32 s36, s38, 8
	v_lshlrev_b32_e32 v22, 4, v4
	v_lshl_add_u64 v[2:3], v[2:3], 0, v[128:129]
	v_lshlrev_b32_e32 v5, 7, v4
	s_and_b32 s49, s36, 0x4000
	v_readfirstlane_b32 s36, v22
	v_bfe_u32 v19, v4, 1, 3
	v_bfe_u32 v20, v4, 4, 2
	v_and_b32_e32 v21, 0x780, v5
	v_lshl_add_u64 v[4:5], v[2:3], 0, s[14:15]
	s_mov_b32 m0, s36
	v_add_u32_e32 v8, 0x2000, v22
	s_waitcnt lgkmcnt(0)
	s_barrier
	global_load_lds_dwordx4 v[4:5], off
	v_lshl_add_u64 v[4:5], v[2:3], 0, s[16:17]
	v_readfirstlane_b32 s36, v8
	v_lshl_add_u64 v[6:7], v[4:5], 0, s[14:15]
	s_mov_b32 m0, s36
	v_add_u32_e32 v10, 0x4000, v22
	global_load_lds_dwordx4 v[6:7], off
	v_lshl_add_u64 v[6:7], v[2:3], 0, s[18:19]
	v_readfirstlane_b32 s36, v10
	v_lshlrev_b64 v[0:1], 8, v[0:1]
	v_lshl_add_u64 v[8:9], v[6:7], 0, s[14:15]
	s_mov_b32 m0, s36
	v_add_u32_e32 v12, 0x6000, v22
	v_lshl_add_u64 v[0:1], s[22:23], 0, v[0:1]
	global_load_lds_dwordx4 v[8:9], off
	v_lshl_add_u64 v[8:9], v[2:3], 0, s[24:25]
	v_readfirstlane_b32 s36, v12
	v_add_u32_e32 v12, 0x8000, v22
	v_lshl_add_u64 v[0:1], v[0:1], 0, v[128:129]
	v_lshl_add_u64 v[10:11], v[8:9], 0, s[14:15]
	s_mov_b32 m0, s36
	v_readfirstlane_b32 s36, v12
	global_load_lds_dwordx4 v[10:11], off
	v_lshl_add_u64 v[10:11], v[0:1], 0, s[26:27]
	s_mov_b32 m0, s36
	v_add_u32_e32 v14, 0xa000, v22
	global_load_lds_dwordx4 v[10:11], off
	v_lshl_add_u64 v[10:11], v[0:1], 0, s[16:17]
	v_readfirstlane_b32 s36, v14
	v_lshl_add_u64 v[12:13], v[10:11], 0, s[26:27]
	s_mov_b32 m0, s36
	v_add_u32_e32 v16, 0xc000, v22
	global_load_lds_dwordx4 v[12:13], off
	v_lshl_add_u64 v[12:13], v[0:1], 0, s[18:19]
	v_readfirstlane_b32 s36, v16
	v_lshl_add_u64 v[14:15], v[12:13], 0, s[26:27]
	s_mov_b32 m0, s36
	v_add_u32_e32 v23, 0xe000, v22
	global_load_lds_dwordx4 v[14:15], off
	v_lshl_add_u64 v[14:15], v[0:1], 0, s[24:25]
	v_readfirstlane_b32 s36, v23
	v_lshl_add_u64 v[16:17], v[14:15], 0, s[26:27]
	s_mov_b32 m0, s36
	v_lshl_add_u64 v[172:173], v[0:1], 0, s[30:31]
	global_load_lds_dwordx4 v[16:17], off
	s_nop 0
	v_bitop3_b32 v0, v18, v19, 3 bitop3:0x6c
	s_lshl_b32 s10, s38, 6
	v_lshl_or_b32 v128, v0, 4, v21
	v_bitop3_b32 v0, v20, v19, 4 bitop3:0x36
	s_and_b32 s10, s10, 0xffffe000
	v_lshl_add_u64 v[164:165], v[2:3], 0, s[28:29]
	v_lshl_add_u64 v[166:167], v[4:5], 0, s[28:29]
	v_lshl_add_u64 v[168:169], v[6:7], 0, s[28:29]
	v_lshl_add_u64 v[170:171], v[8:9], 0, s[28:29]
	v_lshl_add_u64 v[174:175], v[10:11], 0, s[30:31]
	v_lshl_add_u64 v[176:177], v[12:13], 0, s[30:31]
	v_lshl_add_u64 v[178:179], v[14:15], 0, s[30:31]
	v_lshl_or_b32 v163, v0, 4, v21
	v_add_u32_e32 v188, 0x10000, v22
	v_add_u32_e32 v189, 0x12000, v22
	v_add_u32_e32 v190, 0x14000, v22
	v_add_u32_e32 v191, 0x16000, v22
	v_add_u32_e32 v192, 0x18000, v22
	v_add_u32_e32 v193, 0x1a000, v22
	v_add_u32_e32 v194, 0x1c000, v22
	v_add_u32_e32 v195, 0x1e000, v22
	s_mov_b64 s[38:39], -1
	s_mov_b32 s55, 0
	v_mov_b32_e32 v12, 0
	v_mov_b32_e32 v13, v129
	v_mov_b32_e32 v14, v129
	v_mov_b32_e32 v15, v129
	v_mov_b32_e32 v44, 0
	v_mov_b32_e32 v45, v129
	v_mov_b32_e32 v46, v129
	v_mov_b32_e32 v47, v129
	v_mov_b32_e32 v56, 0
	v_mov_b32_e32 v57, v129
	v_mov_b32_e32 v58, v129
	v_mov_b32_e32 v59, v129
	v_mov_b32_e32 v88, 0
	v_mov_b32_e32 v89, v129
	v_mov_b32_e32 v90, v129
	v_mov_b32_e32 v91, v129
	v_mov_b32_e32 v0, 0
	v_mov_b32_e32 v1, v129
	v_mov_b32_e32 v2, v129
	v_mov_b32_e32 v3, v129
	v_mov_b32_e32 v24, 0
	v_mov_b32_e32 v25, v129
	v_mov_b32_e32 v26, v129
	v_mov_b32_e32 v27, v129
	v_mov_b32_e32 v60, 0
	v_mov_b32_e32 v61, v129
	v_mov_b32_e32 v62, v129
	v_mov_b32_e32 v63, v129
	v_mov_b32_e32 v92, 0
	v_mov_b32_e32 v93, v129
	v_mov_b32_e32 v94, v129
	v_mov_b32_e32 v95, v129
	v_mov_b32_e32 v4, 0
	v_mov_b32_e32 v5, v129
	v_mov_b32_e32 v6, v129
	v_mov_b32_e32 v7, v129
	v_mov_b32_e32 v36, 0
	v_mov_b32_e32 v37, v129
	v_mov_b32_e32 v38, v129
	v_mov_b32_e32 v39, v129
	v_mov_b32_e32 v72, 0
	v_mov_b32_e32 v73, v129
	v_mov_b32_e32 v74, v129
	v_mov_b32_e32 v75, v129
	v_mov_b32_e32 v104, 0
	v_mov_b32_e32 v105, v129
	v_mov_b32_e32 v106, v129
	v_mov_b32_e32 v107, v129
	v_mov_b32_e32 v8, 0
	v_mov_b32_e32 v9, v129
	v_mov_b32_e32 v10, v129
	v_mov_b32_e32 v11, v129
	v_mov_b32_e32 v40, 0
	v_mov_b32_e32 v41, v129
	v_mov_b32_e32 v42, v129
	v_mov_b32_e32 v43, v129
	v_mov_b32_e32 v76, 0
	v_mov_b32_e32 v77, v129
	v_mov_b32_e32 v78, v129
	v_mov_b32_e32 v79, v129
	v_mov_b32_e32 v108, 0
	v_mov_b32_e32 v109, v129
	v_mov_b32_e32 v110, v129
	v_mov_b32_e32 v111, v129
	v_mov_b32_e32 v16, 0
	v_mov_b32_e32 v17, v129
	v_mov_b32_e32 v18, v129
	v_mov_b32_e32 v19, v129
	v_mov_b32_e32 v48, 0
	v_mov_b32_e32 v49, v129
	v_mov_b32_e32 v50, v129
	v_mov_b32_e32 v51, v129
	v_mov_b32_e32 v80, 0
	v_mov_b32_e32 v81, v129
	v_mov_b32_e32 v82, v129
	v_mov_b32_e32 v83, v129
	v_mov_b32_e32 v112, 0
	v_mov_b32_e32 v113, v129
	v_mov_b32_e32 v114, v129
	v_mov_b32_e32 v115, v129
	v_mov_b32_e32 v20, 0
	v_mov_b32_e32 v21, v129
	v_mov_b32_e32 v22, v129
	v_mov_b32_e32 v23, v129
	v_mov_b32_e32 v52, 0
	v_mov_b32_e32 v53, v129
	v_mov_b32_e32 v54, v129
	v_mov_b32_e32 v55, v129
	v_mov_b32_e32 v84, 0
	v_mov_b32_e32 v85, v129
	v_mov_b32_e32 v86, v129
	v_mov_b32_e32 v87, v129
	v_mov_b32_e32 v116, 0
	v_mov_b32_e32 v117, v129
	v_mov_b32_e32 v118, v129
	v_mov_b32_e32 v119, v129
	v_mov_b32_e32 v28, 0
	v_mov_b32_e32 v29, v129
	v_mov_b32_e32 v30, v129
	v_mov_b32_e32 v31, v129
	v_mov_b32_e32 v64, 0
	v_mov_b32_e32 v65, v129
	v_mov_b32_e32 v66, v129
	v_mov_b32_e32 v67, v129
	v_mov_b32_e32 v96, 0
	v_mov_b32_e32 v97, v129
	v_mov_b32_e32 v98, v129
	v_mov_b32_e32 v99, v129
	v_mov_b32_e32 v120, 0
	v_mov_b32_e32 v121, v129
	v_mov_b32_e32 v122, v129
	v_mov_b32_e32 v123, v129
	v_mov_b32_e32 v32, 0
	v_mov_b32_e32 v33, v129
	v_mov_b32_e32 v34, v129
	v_mov_b32_e32 v35, v129
	v_mov_b32_e32 v68, 0
	v_mov_b32_e32 v69, v129
	v_mov_b32_e32 v70, v129
	v_mov_b32_e32 v71, v129
	v_mov_b32_e32 v100, 0
	v_mov_b32_e32 v101, v129
	v_mov_b32_e32 v102, v129
	v_mov_b32_e32 v103, v129
	v_mov_b32_e32 v124, 0
	v_mov_b32_e32 v125, v129
	v_mov_b32_e32 v126, v129
	v_mov_b32_e32 v127, v129
	s_waitcnt vmcnt(0) lgkmcnt(0)
	s_barrier
	s_branch .LBB0_110

; DI int tid_opaque() { int t = threadIdx.x; asm volatile("" : "+v"(t)); return t; }
; #define LDS_PTR(p) ((__attribute__((address_space(3))) unsigned*)(p))
; template <int PIPE>
; DI void gemm_loop_g(const u16* __restrict__ Xp, long ldx_l, long ldx_i, long kxs,
;                     const u16* __restrict__ Yp, long ldy_l, long ldy_i, long kys, int K,
;                     f32x4 (&acc)[4][8], unsigned char* smem) {
;   const int t = tid_opaque(), l = t & 63, w = __builtin_amdgcn_readfirstlane(t >> 6), wx = w >> 1, wy = w & 1;
;   const int lrow = t >> 3, gch = (t & 7) ^ ((t >> 4) & 7);
;   const u16* xs = Xp + (long)lrow * ldx_l + gch * 8;
;   const u16* ys = Yp + (long)lrow * ldy_l + gch * 8;
;   const int fsw = (l >> 1) & 7, lg = l >> 4;
;   const unsigned fr0 = (l & 15) * 128 + ((lg ^ fsw) << 4);
;   const unsigned fr1 = (l & 15) * 128 + (((lg + 4) ^ fsw) << 4);
;   const unsigned ub = wx * 8192, vb = 32768 + wy * 16384;
;   const int nk = K >> 6;
;   const int rot = (int)((blockIdx.x >> 3) + (blockIdx.x & 7) * 5) % nk;
;   auto issue = [&](int kt0, int stage) {
;     int kt = kt0 + rot; if (kt >= nk) kt -= nk;
;     unsigned char* sb = smem + stage * 65536 + t * 16;
; #pragma unroll
;     for (int i = 0; i < 4; ++i)
;       __builtin_amdgcn_global_load_lds((const unsigned*)(xs + i * ldx_i + kt * kxs), LDS_PTR(sb + i * 8192), 16, 0, 0);
; #pragma unroll
;     for (int i = 0; i < 4; ++i)
;       __builtin_amdgcn_global_load_lds((const unsigned*)(ys + i * ldy_i + kt * kys), LDS_PTR(sb + 32768 + i * 8192), 16, 0, 0);
;   };
;   __syncthreads();
;   issue(0, 0);
;   asm volatile("s_waitcnt vmcnt(0)" ::: "memory");
;   __syncthreads();
; template <int MODE>
; DI void gemm_phase(const Params& p, const GP& g, unsigned char* smem) {
;     ...
;     } else if (MODE == M_FFT3) {
;       const int bt = mt >> 8, v = (mt >> 2) & 63, cq = mt & 3;
;       gemm_loop(Ab + (((long)(bt * 64 + v)) * 1024 + cq * 256) * 128, 128, Wb, 128, 128, acc, smem);
.LBB0_127:
	s_lshl_b32 s8, s55, 3
	s_or_b32 s8, s8, s38
	s_lshr_b32 s28, s55, 5
	s_bfe_u32 s10, s8, 0x60002
	s_lshl_b32 s8, s28, 6
	s_or_b32 s8, s10, s8
	v_mov_b32_e32 v18, v182
	s_lshl_b64 s[30:31], s[8:9], 18
	s_add_u32 s30, s39, s30
	v_ashrrev_i32_e32 v0, 3, v18
	v_lshrrev_b32_e32 v19, 4, v18
	v_xor_b32_e32 v4, v19, v18
	v_ashrrev_i32_e32 v1, 31, v0
	s_addc_u32 s31, s54, s31
	v_lshlrev_b64 v[0:1], 8, v[0:1]
	v_lshlrev_b32_e32 v4, 4, v4
	v_lshl_add_u64 v[2:3], s[30:31], 0, v[0:1]
	v_and_b32_e32 v68, 0x70, v4
	v_lshlrev_b32_e32 v20, 4, v18
	v_lshl_add_u64 v[2:3], v[2:3], 0, v[68:69]
	v_readfirstlane_b32 s8, v20
	v_lshl_add_u64 v[4:5], v[2:3], 0, s[14:15]
	s_mov_b32 m0, s8
	v_add_u32_e32 v8, 0x2000, v20
	s_barrier
	global_load_lds_dwordx4 v[4:5], off
	v_lshl_add_u64 v[4:5], v[2:3], 0, s[16:17]
	v_readfirstlane_b32 s8, v8
	v_lshl_add_u64 v[6:7], v[4:5], 0, s[14:15]
	s_mov_b32 m0, s8
	v_add_u32_e32 v10, 0x4000, v20
	global_load_lds_dwordx4 v[6:7], off
	v_lshl_add_u64 v[6:7], v[2:3], 0, s[18:19]
	v_readfirstlane_b32 s8, v10
	v_lshl_add_u64 v[8:9], v[6:7], 0, s[14:15]
	s_mov_b32 m0, s8
	v_add_u32_e32 v12, 0x6000, v20
	v_lshl_add_u64 v[0:1], s[6:7], 0, v[0:1]
	global_load_lds_dwordx4 v[8:9], off
	v_lshl_add_u64 v[8:9], v[2:3], 0, s[24:25]
	v_readfirstlane_b32 s8, v12
	v_add_u32_e32 v12, 0x8000, v20
	v_lshl_add_u64 v[0:1], v[0:1], 0, v[68:69]
	v_lshl_add_u64 v[10:11], v[8:9], 0, s[14:15]
	s_mov_b32 m0, s8
	v_readfirstlane_b32 s8, v12
	global_load_lds_dwordx4 v[10:11], off
	v_lshl_add_u64 v[10:11], v[0:1], 0, s[14:15]
	s_mov_b32 m0, s8
	v_add_u32_e32 v14, 0xa000, v20
	global_load_lds_dwordx4 v[10:11], off
	v_lshl_add_u64 v[10:11], v[0:1], 0, s[16:17]
	v_readfirstlane_b32 s8, v14
	v_lshl_add_u64 v[12:13], v[10:11], 0, s[14:15]
	s_mov_b32 m0, s8
	v_add_u32_e32 v16, 0xc000, v20
	global_load_lds_dwordx4 v[12:13], off
	v_lshl_add_u64 v[12:13], v[0:1], 0, s[18:19]
	v_readfirstlane_b32 s8, v16
	v_lshl_add_u64 v[14:15], v[12:13], 0, s[14:15]
	s_mov_b32 m0, s8
	v_add_u32_e32 v21, 0xe000, v20
	global_load_lds_dwordx4 v[14:15], off
	v_lshl_add_u64 v[14:15], v[0:1], 0, s[24:25]
	v_readfirstlane_b32 s8, v21
	v_lshl_add_u64 v[16:17], v[14:15], 0, s[14:15]
	s_mov_b32 m0, s8
	v_readfirstlane_b32 s11, v18
	global_load_lds_dwordx4 v[16:17], off
	v_bfe_u32 v16, v18, 4, 2
	v_bfe_u32 v17, v18, 1, 3
	v_lshlrev_b32_e32 v18, 7, v18
	s_nop 0
	v_bitop3_b32 v16, v16, v17, 4 bitop3:0x36
	v_and_b32_e32 v18, 0x780, v18
	s_lshl_b32 s8, s11, 8
	s_lshl_b32 s11, s11, 6
	v_lshl_or_b32 v67, v16, 4, v18
	v_bitop3_b32 v16, v19, v17, 3 bitop3:0x6c
	s_and_b32 s8, s8, 0x4000
	s_and_b32 s11, s11, 0xffffe000
	v_lshl_or_b32 v68, v16, 4, v18
	v_add_u32_e32 v77, 0x10000, v20
	v_lshl_add_u64 v[82:83], v[2:3], 0, s[26:27]
	v_lshl_add_u64 v[84:85], v[4:5], 0, s[26:27]
	v_add_u32_e32 v79, 0x12000, v20
	v_lshl_add_u64 v[86:87], v[6:7], 0, s[26:27]
	v_add_u32_e32 v81, 0x14000, v20
	v_lshl_add_u64 v[88:89], v[8:9], 0, s[26:27]
	v_add_u32_e32 v98, 0x16000, v20
	v_add_u32_e32 v99, 0x18000, v20
	v_lshl_add_u64 v[90:91], v[0:1], 0, s[26:27]
	v_lshl_add_u64 v[92:93], v[10:11], 0, s[26:27]
	v_add_u32_e32 v100, 0x1a000, v20
	v_lshl_add_u64 v[94:95], v[12:13], 0, s[26:27]
	v_add_u32_e32 v101, 0x1c000, v20
	v_lshl_add_u64 v[96:97], v[14:15], 0, s[26:27]
	v_add_u32_e32 v102, 0x1e000, v20
	s_mov_b64 s[30:31], 0
	s_mov_b64 s[36:37], -1
	s_mov_b32 s29, 0
	v_mov_b32_e32 v0, 0
	v_mov_b32_e32 v1, v69
	v_mov_b32_e32 v2, v69
	v_mov_b32_e32 v3, v69
	v_mov_b32_e32 v16, 0
	v_mov_b32_e32 v17, v69
	v_mov_b32_e32 v18, v69
	v_mov_b32_e32 v19, v69
	v_mov_b32_e32 v32, 0
	v_mov_b32_e32 v33, v69
	v_mov_b32_e32 v34, v69
	v_mov_b32_e32 v35, v69
	v_mov_b32_e32 v48, 0
	v_mov_b32_e32 v49, v69
	v_mov_b32_e32 v50, v69
	v_mov_b32_e32 v51, v69
	v_mov_b32_e32 v4, 0
	v_mov_b32_e32 v5, v69
	v_mov_b32_e32 v6, v69
	v_mov_b32_e32 v7, v69
	v_mov_b32_e32 v20, 0
	v_mov_b32_e32 v21, v69
	v_mov_b32_e32 v22, v69
	v_mov_b32_e32 v23, v69
	v_mov_b32_e32 v36, 0
	v_mov_b32_e32 v37, v69
	v_mov_b32_e32 v38, v69
	v_mov_b32_e32 v39, v69
	v_mov_b32_e32 v52, 0
	v_mov_b32_e32 v53, v69
	v_mov_b32_e32 v54, v69
	v_mov_b32_e32 v55, v69
	v_mov_b32_e32 v8, 0
	v_mov_b32_e32 v9, v69
	v_mov_b32_e32 v10, v69
	v_mov_b32_e32 v11, v69
	v_mov_b32_e32 v24, 0
	v_mov_b32_e32 v25, v69
	v_mov_b32_e32 v26, v69
	v_mov_b32_e32 v27, v69
	v_mov_b32_e32 v40, 0
	v_mov_b32_e32 v41, v69
	v_mov_b32_e32 v42, v69
	v_mov_b32_e32 v43, v69
	v_mov_b32_e32 v56, 0
	v_mov_b32_e32 v57, v69
	v_mov_b32_e32 v58, v69
	v_mov_b32_e32 v59, v69
	v_mov_b32_e32 v12, 0
	v_mov_b32_e32 v13, v69
	v_mov_b32_e32 v14, v69
	v_mov_b32_e32 v15, v69
	v_mov_b32_e32 v28, 0
	v_mov_b32_e32 v29, v69
	v_mov_b32_e32 v30, v69
	v_mov_b32_e32 v31, v69
	v_mov_b32_e32 v44, 0
	v_mov_b32_e32 v45, v69
	v_mov_b32_e32 v46, v69
	v_mov_b32_e32 v47, v69
	v_mov_b32_e32 v60, 0
	v_mov_b32_e32 v61, v69
	v_mov_b32_e32 v62, v69
	v_mov_b32_e32 v63, v69
	s_waitcnt vmcnt(0) lgkmcnt(0)
	s_barrier
	s_branch .LBB0_129

; DI int tid_opaque() { int t = threadIdx.x; asm volatile("" : "+v"(t)); return t; }
; #define LDS_PTR(p) ((__attribute__((address_space(3))) unsigned*)(p))
; template <int PIPE>
; DI void gemm_loop_g(const u16* __restrict__ Xp, long ldx_l, long ldx_i, long kxs,
;                     const u16* __restrict__ Yp, long ldy_l, long ldy_i, long kys, int K,
;                     f32x4 (&acc)[4][8], unsigned char* smem) {
;   const int t = tid_opaque(), l = t & 63, w = __builtin_amdgcn_readfirstlane(t >> 6), wx = w >> 1, wy = w & 1;
;   const int lrow = t >> 3, gch = (t & 7) ^ ((t >> 4) & 7);
;   const u16* xs = Xp + (long)lrow * ldx_l + gch * 8;
;   const u16* ys = Yp + (long)lrow * ldy_l + gch * 8;
;   const int fsw = (l >> 1) & 7, lg = l >> 4;
;   const unsigned fr0 = (l & 15) * 128 + ((lg ^ fsw) << 4);
;   const unsigned fr1 = (l & 15) * 128 + (((lg + 4) ^ fsw) << 4);
;   const unsigned ub = wx * 8192, vb = 32768 + wy * 16384;
;   const int nk = K >> 6;
;   const int rot = (int)((blockIdx.x >> 3) + (blockIdx.x & 7) * 5) % nk;
;   auto issue = [&](int kt0, int stage) {
;     int kt = kt0 + rot; if (kt >= nk) kt -= nk;
;     unsigned char* sb = smem + stage * 65536 + t * 16;
; #pragma unroll
;     for (int i = 0; i < 4; ++i)
;       __builtin_amdgcn_global_load_lds((const unsigned*)(xs + i * ldx_i + kt * kxs), LDS_PTR(sb + i * 8192), 16, 0, 0);
; #pragma unroll
;     for (int i = 0; i < 4; ++i)
;       __builtin_amdgcn_global_load_lds((const unsigned*)(ys + i * ldy_i + kt * kys), LDS_PTR(sb + 32768 + i * 8192), 16, 0, 0);
;   };
;   __syncthreads();
;   issue(0, 0);
;   asm volatile("s_waitcnt vmcnt(0)" ::: "memory");
;   __syncthreads();
; DI void zero_acc(f32x4 (&acc)[4][8]) {
; #pragma unroll
;   for (int i = 0; i < 4; ++i)
; #pragma unroll
;     for (int j = 0; j < 8; ++j) acc[i][j] = f32x4{0.f, 0.f, 0.f, 0.f};
; }
.LBB0_146:
	s_lshl_b32 s10, s58, 9
	s_and_b32 s10, s10, 0xfffff800
	s_or_b32 s28, s10, s54
	s_lshl_b32 s10, s58, 8
	s_and_b32 s10, s10, 0x300
	s_lshl_b32 s11, s10, 11
	s_add_u32 s30, s6, s11
	s_addc_u32 s31, s7, 0
	s_ashr_i32 s29, s28, 31
	v_mov_b32_e32 v4, v182
	s_lshl_b64 s[48:49], s[28:29], 11
	s_add_u32 s48, s52, s48
	v_ashrrev_i32_e32 v0, 3, v4
	v_lshrrev_b32_e32 v5, 4, v4
	v_xor_b32_e32 v6, v5, v4
	v_ashrrev_i32_e32 v1, 31, v0
	s_addc_u32 s49, s53, s49
	v_lshlrev_b64 v[0:1], 11, v[0:1]
	v_lshlrev_b32_e32 v6, 4, v6
	v_lshl_add_u64 v[2:3], s[30:31], 0, v[0:1]
	v_and_b32_e32 v128, 0x70, v6
	v_lshl_add_u64 v[0:1], s[48:49], 0, v[0:1]
	v_lshl_add_u64 v[130:131], v[2:3], 0, v[128:129]
	v_lshl_add_u64 v[132:133], v[0:1], 0, v[128:129]
	v_lshlrev_b32_e32 v128, 4, v4
	v_add_u32_e32 v2, 0x2000, v128
	v_readfirstlane_b32 s11, v128
	v_lshl_add_u64 v[0:1], v[130:131], 0, s[8:9]
	s_mov_b32 m0, s11
	v_lshl_add_u64 v[134:135], v[130:131], 0, s[14:15]
	v_readfirstlane_b32 s11, v2
	v_add_u32_e32 v2, 0x4000, v128
	s_barrier
	global_load_lds_dwordx4 v[0:1], off
	v_lshl_add_u64 v[0:1], v[134:135], 0, s[8:9]
	s_mov_b32 m0, s11
	v_lshl_add_u64 v[136:137], v[130:131], 0, s[24:25]
	v_readfirstlane_b32 s11, v2
	v_add_u32_e32 v2, 0x6000, v128
	global_load_lds_dwordx4 v[0:1], off
	v_lshl_add_u64 v[0:1], v[136:137], 0, s[8:9]
	s_mov_b32 m0, s11
	v_lshl_add_u64 v[138:139], v[130:131], 0, s[26:27]
	v_readfirstlane_b32 s11, v2
	v_add_u32_e32 v2, 0x8000, v128
	global_load_lds_dwordx4 v[0:1], off
	v_lshl_add_u64 v[0:1], v[138:139], 0, s[8:9]
	s_mov_b32 m0, s11
	v_readfirstlane_b32 s11, v2
	v_add_u32_e32 v2, 0xa000, v128
	global_load_lds_dwordx4 v[0:1], off
	v_lshl_add_u64 v[0:1], v[132:133], 0, s[8:9]
	s_mov_b32 m0, s11
	v_lshl_add_u64 v[140:141], v[132:133], 0, s[14:15]
	v_readfirstlane_b32 s11, v2
	v_add_u32_e32 v2, 0xc000, v128
	global_load_lds_dwordx4 v[0:1], off
	v_lshl_add_u64 v[0:1], v[140:141], 0, s[8:9]
	s_mov_b32 m0, s11
	v_lshl_add_u64 v[142:143], v[132:133], 0, s[24:25]
	v_readfirstlane_b32 s11, v2
	v_add_u32_e32 v2, 0xe000, v128
	global_load_lds_dwordx4 v[0:1], off
	v_lshl_add_u64 v[0:1], v[142:143], 0, s[8:9]
	s_mov_b32 m0, s11
	v_lshl_add_u64 v[144:145], v[132:133], 0, s[26:27]
	v_readfirstlane_b32 s11, v2
	global_load_lds_dwordx4 v[0:1], off
	v_lshl_add_u64 v[0:1], v[144:145], 0, s[8:9]
	s_mov_b32 m0, s11
	v_lshlrev_b32_e32 v2, 7, v4
	global_load_lds_dwordx4 v[0:1], off
	v_bfe_u32 v0, v4, 4, 2
	v_bfe_u32 v1, v4, 1, 3
	v_readfirstlane_b32 s29, v4
	s_nop 0
	v_bitop3_b32 v0, v0, v1, 4 bitop3:0x36
	v_and_b32_e32 v2, 0x780, v2
	s_lshl_b32 s11, s29, 8
	s_lshl_b32 s29, s29, 6
	v_lshl_or_b32 v148, v0, 4, v2
	v_bitop3_b32 v0, v5, v1, 3 bitop3:0x6c
	s_and_b32 s11, s11, 0x4000
	s_and_b32 s29, s29, 0xffffe000
	v_lshl_or_b32 v149, v0, 4, v2
	s_mov_b32 s30, 0x10000
	s_mov_b32 s31, 0
	v_mov_b32_e32 v12, 0
	v_mov_b32_e32 v13, v129
	v_mov_b32_e32 v14, v129
	v_mov_b32_e32 v15, v129
	v_mov_b32_e32 v4, 0
	v_mov_b32_e32 v5, v129
	v_mov_b32_e32 v6, v129
	v_mov_b32_e32 v7, v129
	v_mov_b32_e32 v24, 0
	v_mov_b32_e32 v25, v129
	v_mov_b32_e32 v26, v129
	v_mov_b32_e32 v27, v129
	v_mov_b32_e32 v40, 0
	v_mov_b32_e32 v41, v129
	v_mov_b32_e32 v42, v129
	v_mov_b32_e32 v43, v129
	v_mov_b32_e32 v56, 0
	v_mov_b32_e32 v57, v129
	v_mov_b32_e32 v58, v129
	v_mov_b32_e32 v59, v129
	v_mov_b32_e32 v72, 0
	v_mov_b32_e32 v73, v129
	v_mov_b32_e32 v74, v129
	v_mov_b32_e32 v75, v129
	v_mov_b32_e32 v88, 0
	v_mov_b32_e32 v89, v129
	v_mov_b32_e32 v90, v129
	v_mov_b32_e32 v91, v129
	v_mov_b32_e32 v104, 0
	v_mov_b32_e32 v105, v129
	v_mov_b32_e32 v106, v129
	v_mov_b32_e32 v107, v129
	v_mov_b32_e32 v0, 0
	v_mov_b32_e32 v1, v129
	v_mov_b32_e32 v2, v129
	v_mov_b32_e32 v3, v129
	v_mov_b32_e32 v20, 0
	v_mov_b32_e32 v21, v129
	v_mov_b32_e32 v22, v129
	v_mov_b32_e32 v23, v129
	v_mov_b32_e32 v36, 0
	v_mov_b32_e32 v37, v129
	v_mov_b32_e32 v38, v129
	v_mov_b32_e32 v39, v129
	v_mov_b32_e32 v52, 0
	v_mov_b32_e32 v53, v129
	v_mov_b32_e32 v54, v129
	v_mov_b32_e32 v55, v129
	v_mov_b32_e32 v68, 0
	v_mov_b32_e32 v69, v129
	v_mov_b32_e32 v70, v129
	v_mov_b32_e32 v71, v129
	v_mov_b32_e32 v84, 0
	v_mov_b32_e32 v85, v129
	v_mov_b32_e32 v86, v129
	v_mov_b32_e32 v87, v129
	v_mov_b32_e32 v100, 0
	v_mov_b32_e32 v101, v129
	v_mov_b32_e32 v102, v129
	v_mov_b32_e32 v103, v129
	v_mov_b32_e32 v116, 0
	v_mov_b32_e32 v117, v129
	v_mov_b32_e32 v118, v129
	v_mov_b32_e32 v119, v129
	v_mov_b32_e32 v8, 0
	v_mov_b32_e32 v9, v129
	v_mov_b32_e32 v10, v129
	v_mov_b32_e32 v11, v129
	v_mov_b32_e32 v28, 0
	v_mov_b32_e32 v29, v129
	v_mov_b32_e32 v30, v129
	v_mov_b32_e32 v31, v129
	v_mov_b32_e32 v44, 0
	v_mov_b32_e32 v45, v129
	v_mov_b32_e32 v46, v129
	v_mov_b32_e32 v47, v129
	v_mov_b32_e32 v60, 0
	v_mov_b32_e32 v61, v129
	v_mov_b32_e32 v62, v129
	v_mov_b32_e32 v63, v129
	v_mov_b32_e32 v76, 0
	v_mov_b32_e32 v77, v129
	v_mov_b32_e32 v78, v129
	v_mov_b32_e32 v79, v129
	v_mov_b32_e32 v92, 0
	v_mov_b32_e32 v93, v129
	v_mov_b32_e32 v94, v129
	v_mov_b32_e32 v95, v129
	v_mov_b32_e32 v108, 0
	v_mov_b32_e32 v109, v129
	v_mov_b32_e32 v110, v129
	v_mov_b32_e32 v111, v129
	v_mov_b32_e32 v120, 0
	v_mov_b32_e32 v121, v129
	v_mov_b32_e32 v122, v129
	v_mov_b32_e32 v123, v129
	v_mov_b32_e32 v16, 0
	v_mov_b32_e32 v17, v129
	v_mov_b32_e32 v18, v129
	v_mov_b32_e32 v19, v129
	v_mov_b32_e32 v32, 0
	v_mov_b32_e32 v33, v129
	v_mov_b32_e32 v34, v129
	v_mov_b32_e32 v35, v129
	v_mov_b32_e32 v48, 0
	v_mov_b32_e32 v49, v129
	v_mov_b32_e32 v50, v129
	v_mov_b32_e32 v51, v129
	v_mov_b32_e32 v64, 0
	v_mov_b32_e32 v65, v129
	v_mov_b32_e32 v66, v129
	v_mov_b32_e32 v67, v129
	v_mov_b32_e32 v80, 0
	v_mov_b32_e32 v81, v129
	v_mov_b32_e32 v82, v129
	v_mov_b32_e32 v83, v129
	v_mov_b32_e32 v96, 0
	v_mov_b32_e32 v97, v129
	v_mov_b32_e32 v98, v129
	v_mov_b32_e32 v99, v129
	v_mov_b32_e32 v112, 0
	v_mov_b32_e32 v113, v129
	v_mov_b32_e32 v114, v129
	v_mov_b32_e32 v115, v129
	v_mov_b32_e32 v124, 0
	v_mov_b32_e32 v125, v129
	v_mov_b32_e32 v126, v129
	v_mov_b32_e32 v127, v129
	s_waitcnt vmcnt(0) lgkmcnt(0)
	s_barrier
	s_branch .LBB0_148

; DI int tid_opaque() { int t = threadIdx.x; asm volatile("" : "+v"(t)); return t; }
; #define LDS_PTR(p) ((__attribute__((address_space(3))) unsigned*)(p))
; template <int PIPE>
; DI void gemm_loop_g(const u16* __restrict__ Xp, long ldx_l, long ldx_i, long kxs,
;                     const u16* __restrict__ Yp, long ldy_l, long ldy_i, long kys, int K,
;                     f32x4 (&acc)[4][8], unsigned char* smem) {
;   const int t = tid_opaque(), l = t & 63, w = __builtin_amdgcn_readfirstlane(t >> 6), wx = w >> 1, wy = w & 1;
;   const int lrow = t >> 3, gch = (t & 7) ^ ((t >> 4) & 7);
;   const u16* xs = Xp + (long)lrow * ldx_l + gch * 8;
;   const u16* ys = Yp + (long)lrow * ldy_l + gch * 8;
;   const int fsw = (l >> 1) & 7, lg = l >> 4;
;   const unsigned fr0 = (l & 15) * 128 + ((lg ^ fsw) << 4);
;   const unsigned fr1 = (l & 15) * 128 + (((lg + 4) ^ fsw) << 4);
;   const unsigned ub = wx * 8192, vb = 32768 + wy * 16384;
;   const int nk = K >> 6;
;   const int rot = (int)((blockIdx.x >> 3) + (blockIdx.x & 7) * 5) % nk;
;   auto issue = [&](int kt0, int stage) {
;     int kt = kt0 + rot; if (kt >= nk) kt -= nk;
;     unsigned char* sb = smem + stage * 65536 + t * 16;
; #pragma unroll
;     for (int i = 0; i < 4; ++i)
;       __builtin_amdgcn_global_load_lds((const unsigned*)(xs + i * ldx_i + kt * kxs), LDS_PTR(sb + i * 8192), 16, 0, 0);
; #pragma unroll
;     for (int i = 0; i < 4; ++i)
;       __builtin_amdgcn_global_load_lds((const unsigned*)(ys + i * ldy_i + kt * kys), LDS_PTR(sb + 32768 + i * 8192), 16, 0, 0);
;   };
;   __syncthreads();
;   issue(0, 0);
;   asm volatile("s_waitcnt vmcnt(0)" ::: "memory");
;   __syncthreads();
; template <int MODE>
; DI void gemm_phase(const Params& p, const GP& g, unsigned char* smem) {
;     ...
;     if (MODE == M_PLE) {
;       const u16* pb = (const u16*)g.d1;
;       gemm_loop(g.W2 + (long)n0 * 256, 256, pb + (long)m0 * 256, 256, 256, acc, smem);
.LBB0_166:
	s_lshl_b32 s6, s69, 9
	s_and_b32 s6, s6, 0xfffff800
	s_or_b32 s12, s6, s66
	s_lshl_b32 s6, s69, 8
	s_and_b32 s6, s6, 0x300
	s_lshl_b32 s7, s6, 9
	s_add_u32 s8, s16, s7
	v_mov_b32_e32 v6, v182
	s_addc_u32 s9, s17, 0
	s_ashr_i32 s13, s12, 31
	s_lshl_b64 s[10:11], s[12:13], 9
	v_ashrrev_i32_e32 v2, 3, v6
	v_lshrrev_b32_e32 v7, 4, v6
	v_xor_b32_e32 v8, v7, v6
	v_ashrrev_i32_e32 v3, 31, v2
	s_waitcnt lgkmcnt(0)
	v_lshl_add_u64 v[0:1], v[128:129], 0, s[10:11]
	v_lshlrev_b64 v[2:3], 9, v[2:3]
	v_lshlrev_b32_e32 v8, 4, v8
	v_lshl_add_u64 v[4:5], s[8:9], 0, v[2:3]
	v_and_b32_e32 v130, 0x70, v8
	v_lshl_add_u64 v[0:1], v[0:1], 0, v[2:3]
	v_lshl_add_u64 v[132:133], v[4:5], 0, v[130:131]
	v_lshl_add_u64 v[134:135], v[0:1], 0, v[130:131]
	v_lshlrev_b32_e32 v130, 4, v6
	v_add_u32_e32 v2, 0x2000, v130
	v_readfirstlane_b32 s7, v130
	v_lshl_add_u64 v[0:1], v[132:133], 0, s[24:25]
	s_mov_b32 m0, s7
	v_lshl_add_u64 v[136:137], v[132:133], 0, s[28:29]
	v_readfirstlane_b32 s7, v2
	v_add_u32_e32 v2, 0x4000, v130
	s_barrier
	global_load_lds_dwordx4 v[0:1], off
	v_lshl_add_u64 v[0:1], v[136:137], 0, s[24:25]
	s_mov_b32 m0, s7
	v_lshl_add_u64 v[138:139], v[132:133], 0, s[30:31]
	v_readfirstlane_b32 s7, v2
	v_add_u32_e32 v2, 0x6000, v130
	global_load_lds_dwordx4 v[0:1], off
	v_lshl_add_u64 v[0:1], v[138:139], 0, s[24:25]
	s_mov_b32 m0, s7
	v_lshl_add_u64 v[140:141], v[132:133], 0, s[54:55]
	v_readfirstlane_b32 s7, v2
	v_add_u32_e32 v2, 0x8000, v130
	global_load_lds_dwordx4 v[0:1], off
	v_lshl_add_u64 v[0:1], v[140:141], 0, s[24:25]
	s_mov_b32 m0, s7
	v_readfirstlane_b32 s7, v2
	v_add_u32_e32 v2, 0xa000, v130
	global_load_lds_dwordx4 v[0:1], off
	v_lshl_add_u64 v[0:1], v[134:135], 0, s[24:25]
	s_mov_b32 m0, s7
	v_lshl_add_u64 v[142:143], v[134:135], 0, s[28:29]
	v_readfirstlane_b32 s7, v2
	v_add_u32_e32 v2, 0xc000, v130
	global_load_lds_dwordx4 v[0:1], off
	v_lshl_add_u64 v[0:1], v[142:143], 0, s[24:25]
	s_mov_b32 m0, s7
	v_lshl_add_u64 v[144:145], v[134:135], 0, s[30:31]
	v_readfirstlane_b32 s7, v2
	v_add_u32_e32 v2, 0xe000, v130
	global_load_lds_dwordx4 v[0:1], off
	v_lshl_add_u64 v[0:1], v[144:145], 0, s[24:25]
	s_mov_b32 m0, s7
	v_lshl_add_u64 v[146:147], v[134:135], 0, s[54:55]
	v_readfirstlane_b32 s7, v2
	global_load_lds_dwordx4 v[0:1], off
	v_lshl_add_u64 v[0:1], v[146:147], 0, s[24:25]
	s_mov_b32 m0, s7
	v_lshlrev_b32_e32 v2, 7, v6
	global_load_lds_dwordx4 v[0:1], off
	v_bfe_u32 v0, v6, 4, 2
	v_bfe_u32 v1, v6, 1, 3
	v_readfirstlane_b32 s10, v6
	s_nop 0
	v_bitop3_b32 v0, v0, v1, 4 bitop3:0x36
	v_and_b32_e32 v2, 0x780, v2
	s_lshl_b32 s7, s10, 8
	s_lshl_b32 s8, s10, 6
	v_lshl_or_b32 v148, v0, 4, v2
	v_bitop3_b32 v0, v7, v1, 3 bitop3:0x6c
	s_and_b32 s7, s7, 0x4000
	s_and_b32 s10, s8, 0xffffe000
	v_lshl_or_b32 v149, v0, 4, v2
	s_mov_b32 s11, 0x10000
	s_mov_b32 s33, 0
	v_mov_b32_e32 v40, 0
	v_mov_b32_e32 v41, v131
	v_mov_b32_e32 v42, v131
	v_mov_b32_e32 v43, v131
	v_mov_b32_e32 v0, 0
	v_mov_b32_e32 v1, v131
	v_mov_b32_e32 v2, v131
	v_mov_b32_e32 v3, v131
	v_mov_b32_e32 v8, 0
	v_mov_b32_e32 v9, v131
	v_mov_b32_e32 v10, v131
	v_mov_b32_e32 v11, v131
	v_mov_b32_e32 v20, 0
	v_mov_b32_e32 v21, v131
	v_mov_b32_e32 v22, v131
	v_mov_b32_e32 v23, v131
	v_mov_b32_e32 v36, 0
	v_mov_b32_e32 v37, v131
	v_mov_b32_e32 v38, v131
	v_mov_b32_e32 v39, v131
	v_mov_b32_e32 v56, 0
	v_mov_b32_e32 v57, v131
	v_mov_b32_e32 v58, v131
	v_mov_b32_e32 v59, v131
	v_mov_b32_e32 v72, 0
	v_mov_b32_e32 v73, v131
	v_mov_b32_e32 v74, v131
	v_mov_b32_e32 v75, v131
	v_mov_b32_e32 v96, 0
	v_mov_b32_e32 v97, v131
	v_mov_b32_e32 v98, v131
	v_mov_b32_e32 v99, v131
	v_mov_b32_e32 v4, 0
	v_mov_b32_e32 v5, v131
	v_mov_b32_e32 v6, v131
	v_mov_b32_e32 v7, v131
	v_mov_b32_e32 v12, 0
	v_mov_b32_e32 v13, v131
	v_mov_b32_e32 v14, v131
	v_mov_b32_e32 v15, v131
	v_mov_b32_e32 v24, 0
	v_mov_b32_e32 v25, v131
	v_mov_b32_e32 v26, v131
	v_mov_b32_e32 v27, v131
	v_mov_b32_e32 v44, 0
	v_mov_b32_e32 v45, v131
	v_mov_b32_e32 v46, v131
	v_mov_b32_e32 v47, v131
	v_mov_b32_e32 v64, 0
	v_mov_b32_e32 v65, v131
	v_mov_b32_e32 v66, v131
	v_mov_b32_e32 v67, v131
	v_mov_b32_e32 v76, 0
	v_mov_b32_e32 v77, v131
	v_mov_b32_e32 v78, v131
	v_mov_b32_e32 v79, v131
	v_mov_b32_e32 v88, 0
	v_mov_b32_e32 v89, v131
	v_mov_b32_e32 v90, v131
	v_mov_b32_e32 v91, v131
	v_mov_b32_e32 v112, 0
	v_mov_b32_e32 v113, v131
	v_mov_b32_e32 v114, v131
	v_mov_b32_e32 v115, v131
	v_mov_b32_e32 v16, 0
	v_mov_b32_e32 v17, v131
	v_mov_b32_e32 v18, v131
	v_mov_b32_e32 v19, v131
	v_mov_b32_e32 v28, 0
	v_mov_b32_e32 v29, v131
	v_mov_b32_e32 v30, v131
	v_mov_b32_e32 v31, v131
	v_mov_b32_e32 v48, 0
	v_mov_b32_e32 v49, v131
	v_mov_b32_e32 v50, v131
	v_mov_b32_e32 v51, v131
	v_mov_b32_e32 v60, 0
	v_mov_b32_e32 v61, v131
	v_mov_b32_e32 v62, v131
	v_mov_b32_e32 v63, v131
	v_mov_b32_e32 v80, 0
	v_mov_b32_e32 v81, v131
	v_mov_b32_e32 v82, v131
	v_mov_b32_e32 v83, v131
	v_mov_b32_e32 v92, 0
	v_mov_b32_e32 v93, v131
	v_mov_b32_e32 v94, v131
	v_mov_b32_e32 v95, v131
	v_mov_b32_e32 v108, 0
	v_mov_b32_e32 v109, v131
	v_mov_b32_e32 v110, v131
	v_mov_b32_e32 v111, v131
	v_mov_b32_e32 v116, 0
	v_mov_b32_e32 v117, v131
	v_mov_b32_e32 v118, v131
	v_mov_b32_e32 v119, v131
	v_mov_b32_e32 v32, 0
	v_mov_b32_e32 v33, v131
	v_mov_b32_e32 v34, v131
	v_mov_b32_e32 v35, v131
	v_mov_b32_e32 v52, 0
	v_mov_b32_e32 v53, v131
	v_mov_b32_e32 v54, v131
	v_mov_b32_e32 v55, v131
	v_mov_b32_e32 v68, 0
	v_mov_b32_e32 v69, v131
	v_mov_b32_e32 v70, v131
	v_mov_b32_e32 v71, v131
	v_mov_b32_e32 v84, 0
	v_mov_b32_e32 v85, v131
	v_mov_b32_e32 v86, v131
	v_mov_b32_e32 v87, v131
	v_mov_b32_e32 v100, 0
	v_mov_b32_e32 v101, v131
	v_mov_b32_e32 v102, v131
	v_mov_b32_e32 v103, v131
	v_mov_b32_e32 v104, 0
	v_mov_b32_e32 v105, v131
	v_mov_b32_e32 v106, v131
	v_mov_b32_e32 v107, v131
	v_mov_b32_e32 v120, 0
	v_mov_b32_e32 v121, v131
	v_mov_b32_e32 v122, v131
	v_mov_b32_e32 v123, v131
	v_mov_b32_e32 v124, 0
	v_mov_b32_e32 v125, v131
	v_mov_b32_e32 v126, v131
	v_mov_b32_e32 v127, v131
	s_waitcnt vmcnt(0) lgkmcnt(0)
	s_barrier
	s_branch .LBB0_168

; DI int tid_opaque() { int t = threadIdx.x; asm volatile("" : "+v"(t)); return t; }
; DI u32x2 pack4(float a, float b, float c, float d) { u32x2 r; r.x = pack2(a, b); r.y = pack2(c, d); return r; }
; #define LDS_PTR(p) ((__attribute__((address_space(3))) unsigned*)(p))
; #define EPI_END if (i == 3 && (j & 3) == 3) __builtin_amdgcn_sched_barrier(0); }
; template <int PIPE>
; DI void gemm_loop_g(const u16* __restrict__ Xp, long ldx_l, long ldx_i, long kxs,
;                     const u16* __restrict__ Yp, long ldy_l, long ldy_i, long kys, int K,
;                     f32x4 (&acc)[4][8], unsigned char* smem) {
;   const int t = tid_opaque(), l = t & 63, w = __builtin_amdgcn_readfirstlane(t >> 6), wx = w >> 1, wy = w & 1;
;   const int lrow = t >> 3, gch = (t & 7) ^ ((t >> 4) & 7);
;   const u16* xs = Xp + (long)lrow * ldx_l + gch * 8;
;   const u16* ys = Yp + (long)lrow * ldy_l + gch * 8;
;   const int fsw = (l >> 1) & 7, lg = l >> 4;
;   const unsigned fr0 = (l & 15) * 128 + ((lg ^ fsw) << 4);
;   const unsigned fr1 = (l & 15) * 128 + (((lg + 4) ^ fsw) << 4);
;   const unsigned ub = wx * 8192, vb = 32768 + wy * 16384;
;   const int nk = K >> 6;
;   const int rot = (int)((blockIdx.x >> 3) + (blockIdx.x & 7) * 5) % nk;
;   auto issue = [&](int kt0, int stage) {
;     int kt = kt0 + rot; if (kt >= nk) kt -= nk;
;     unsigned char* sb = smem + stage * 65536 + t * 16;
; #pragma unroll
;     for (int i = 0; i < 4; ++i)
;       __builtin_amdgcn_global_load_lds((const unsigned*)(xs + i * ldx_i + kt * kxs), LDS_PTR(sb + i * 8192), 16, 0, 0);
; #pragma unroll
;     for (int i = 0; i < 4; ++i)
;       __builtin_amdgcn_global_load_lds((const unsigned*)(ys + i * ldy_i + kt * kys), LDS_PTR(sb + 32768 + i * 8192), 16, 0, 0);
;   };
;   __syncthreads();
;   issue(0, 0);
; template <int MODE>
; DI void gemm_phase(const Params& p, const GP& g, unsigned char* smem) {
;     ...
;       u16* xb = (u16*)g.d0;
;       EPI_STD_BEGIN
;         *(u32x2*)(xb + (long)m * 1024 + n4) = pack4(v[0], v[1], v[2], v[3]);
;       EPI_END
;       zero_acc(acc);
.LBB0_170:
	v_or_b32_e32 v160, s12, v185
	v_add_u32_e32 v134, s6, v184
	v_ashrrev_i32_e32 v161, 31, v160
	v_lshlrev_b64 v[164:165], 11, v[160:161]
	v_ashrrev_i32_e32 v135, 31, v134
	v_or_b32_e32 v156, 16, v160
	v_lshl_add_u64 v[132:133], s[38:39], 0, v[164:165]
	v_cvt_pk_bf16_f32 v124, v124, v125
	v_cvt_pk_bf16_f32 v125, v126, v127
	v_lshlrev_b64 v[126:127], 1, v[134:135]
	v_ashrrev_i32_e32 v157, 31, v156
	v_lshl_add_u64 v[132:133], v[132:133], 0, v[126:127]
	v_cvt_pk_bf16_f32 v96, v96, v97
	v_cvt_pk_bf16_f32 v97, v98, v99
	v_lshlrev_b64 v[162:163], 11, v[156:157]
	v_or_b32_e32 v152, 32, v160
	global_store_dwordx2 v[132:133], v[96:97], off offset:96
	v_lshl_add_u64 v[96:97], s[38:39], 0, v[162:163]
	v_ashrrev_i32_e32 v153, 31, v152
	v_lshl_add_u64 v[96:97], v[96:97], 0, v[126:127]
	v_cvt_pk_bf16_f32 v72, v72, v73
	v_cvt_pk_bf16_f32 v73, v74, v75
	v_lshlrev_b64 v[158:159], 11, v[152:153]
	v_or_b32_e32 v148, 48, v160
	global_store_dwordx2 v[96:97], v[72:73], off offset:96
	v_lshl_add_u64 v[72:73], s[38:39], 0, v[158:159]
	v_ashrrev_i32_e32 v149, 31, v148
	v_lshl_add_u64 v[72:73], v[72:73], 0, v[126:127]
	v_cvt_pk_bf16_f32 v56, v56, v57
	v_cvt_pk_bf16_f32 v57, v58, v59
	v_lshlrev_b64 v[154:155], 11, v[148:149]
	global_store_dwordx2 v[72:73], v[56:57], off offset:96
	v_lshl_add_u64 v[56:57], s[38:39], 0, v[154:155]
	v_cvt_pk_bf16_f32 v74, v104, v105
	v_cvt_pk_bf16_f32 v75, v106, v107
	v_cvt_pk_bf16_f32 v58, v100, v101
	v_cvt_pk_bf16_f32 v59, v102, v103
	v_lshl_add_u64 v[56:57], v[56:57], 0, v[126:127]
	v_cvt_pk_bf16_f32 v98, v120, v121
	v_cvt_pk_bf16_f32 v99, v122, v123
	global_store_dwordx2 v[72:73], v[74:75], off
	v_cvt_pk_bf16_f32 v74, v92, v93
	v_cvt_pk_bf16_f32 v75, v94, v95
	global_store_dwordx2 v[56:57], v[58:59], off
	v_cvt_pk_bf16_f32 v58, v80, v81
	v_cvt_pk_bf16_f32 v59, v82, v83
	v_cvt_pk_bf16_f32 v116, v116, v117
	v_cvt_pk_bf16_f32 v117, v118, v119
	v_cvt_pk_bf16_f32 v112, v112, v113
	v_cvt_pk_bf16_f32 v113, v114, v115
	global_store_dwordx2 v[96:97], v[98:99], off
	v_cvt_pk_bf16_f32 v98, v108, v109
	v_cvt_pk_bf16_f32 v99, v110, v111
	v_cvt_pk_bf16_f32 v88, v88, v89
	v_cvt_pk_bf16_f32 v89, v90, v91
	global_store_dwordx2 v[72:73], v[74:75], off offset:32
	v_cvt_pk_bf16_f32 v74, v76, v77
	v_cvt_pk_bf16_f32 v75, v78, v79
	global_store_dwordx2 v[56:57], v[58:59], off offset:32
	v_cvt_pk_bf16_f32 v58, v64, v65
	v_cvt_pk_bf16_f32 v59, v66, v67
	v_cvt_pk_bf16_f32 v36, v36, v37
	v_cvt_pk_bf16_f32 v37, v38, v39
	global_store_dwordx2 v[132:133], v[124:125], off
	global_store_dwordx2 v[132:133], v[116:117], off offset:32
	global_store_dwordx2 v[132:133], v[112:113], off offset:64
	global_store_dwordx2 v[96:97], v[98:99], off offset:32
	global_store_dwordx2 v[96:97], v[88:89], off offset:64
	global_store_dwordx2 v[72:73], v[74:75], off offset:64
	global_store_dwordx2 v[56:57], v[58:59], off offset:64
	global_store_dwordx2 v[56:57], v[36:37], off offset:96
	v_or_b32_e32 v144, 64, v160
	v_ashrrev_i32_e32 v145, 31, v144
	v_lshlrev_b64 v[150:151], 11, v[144:145]
	v_or_b32_e32 v140, 0x50, v160
	v_lshl_add_u64 v[36:37], s[38:39], 0, v[150:151]
	v_ashrrev_i32_e32 v141, 31, v140
	v_lshl_add_u64 v[36:37], v[36:37], 0, v[126:127]
	v_cvt_pk_bf16_f32 v20, v20, v21
	v_cvt_pk_bf16_f32 v21, v22, v23
	v_lshlrev_b64 v[146:147], 11, v[140:141]
	v_or_b32_e32 v136, 0x60, v160
	global_store_dwordx2 v[36:37], v[20:21], off offset:96
	v_lshl_add_u64 v[20:21], s[38:39], 0, v[146:147]
	v_ashrrev_i32_e32 v137, 31, v136
	v_lshl_add_u64 v[20:21], v[20:21], 0, v[126:127]
	v_cvt_pk_bf16_f32 v8, v8, v9
	v_cvt_pk_bf16_f32 v9, v10, v11
	v_lshlrev_b64 v[142:143], 11, v[136:137]
	v_or_b32_e32 v132, 0x70, v160
	global_store_dwordx2 v[20:21], v[8:9], off offset:96
	v_lshl_add_u64 v[8:9], s[38:39], 0, v[142:143]
	v_ashrrev_i32_e32 v133, 31, v132
	v_lshl_add_u64 v[8:9], v[8:9], 0, v[126:127]
	v_cvt_pk_bf16_f32 v0, v0, v1
	v_cvt_pk_bf16_f32 v1, v2, v3
	v_lshlrev_b64 v[138:139], 11, v[132:133]
	global_store_dwordx2 v[8:9], v[0:1], off offset:96
	v_lshl_add_u64 v[0:1], s[38:39], 0, v[138:139]
	v_cvt_pk_bf16_f32 v2, v32, v33
	v_cvt_pk_bf16_f32 v3, v34, v35
	v_lshl_add_u64 v[0:1], v[0:1], 0, v[126:127]
	v_cvt_pk_bf16_f32 v38, v84, v85
	v_cvt_pk_bf16_f32 v39, v86, v87
	v_cvt_pk_bf16_f32 v22, v68, v69
	v_cvt_pk_bf16_f32 v23, v70, v71
	v_cvt_pk_bf16_f32 v10, v52, v53
	v_cvt_pk_bf16_f32 v11, v54, v55
	global_store_dwordx2 v[0:1], v[2:3], off
	v_cvt_pk_bf16_f32 v2, v16, v17
	v_cvt_pk_bf16_f32 v3, v18, v19
	global_store_dwordx2 v[36:37], v[38:39], off
	v_cvt_pk_bf16_f32 v38, v60, v61
	v_cvt_pk_bf16_f32 v39, v62, v63
	global_store_dwordx2 v[20:21], v[22:23], off
	v_cvt_pk_bf16_f32 v22, v48, v49
	v_cvt_pk_bf16_f32 v23, v50, v51
	global_store_dwordx2 v[8:9], v[10:11], off
	v_cvt_pk_bf16_f32 v10, v28, v29
	v_cvt_pk_bf16_f32 v11, v30, v31
	global_store_dwordx2 v[0:1], v[2:3], off offset:32
	v_cvt_pk_bf16_f32 v2, v4, v5
	v_cvt_pk_bf16_f32 v3, v6, v7
	global_store_dwordx2 v[36:37], v[38:39], off offset:32
	v_cvt_pk_bf16_f32 v38, v44, v45
	v_cvt_pk_bf16_f32 v39, v46, v47
	global_store_dwordx2 v[20:21], v[22:23], off offset:32
	v_cvt_pk_bf16_f32 v22, v24, v25
	v_cvt_pk_bf16_f32 v23, v26, v27
	global_store_dwordx2 v[8:9], v[10:11], off offset:32
	v_cvt_pk_bf16_f32 v10, v12, v13
	v_cvt_pk_bf16_f32 v11, v14, v15
	global_store_dwordx2 v[0:1], v[2:3], off offset:64
	v_cvt_pk_bf16_f32 v2, v40, v41
	v_cvt_pk_bf16_f32 v3, v42, v43
	global_store_dwordx2 v[36:37], v[38:39], off offset:64
	global_store_dwordx2 v[20:21], v[22:23], off offset:64
	global_store_dwordx2 v[8:9], v[10:11], off offset:64
	global_store_dwordx2 v[0:1], v[2:3], off offset:96
	s_lshl_b32 s6, s6, 11
	s_add_u32 s6, s18, s6
	v_mov_b32_e32 v4, v182
	s_addc_u32 s7, s19, 0
	s_lshl_b64 s[8:9], s[12:13], 11
	s_add_u32 s8, s36, s8
	v_ashrrev_i32_e32 v0, 3, v4
	v_lshrrev_b32_e32 v5, 4, v4
	v_xor_b32_e32 v6, v5, v4
	v_ashrrev_i32_e32 v1, 31, v0
	s_addc_u32 s9, s37, s9
	v_lshlrev_b64 v[0:1], 11, v[0:1]
	v_lshlrev_b32_e32 v6, 4, v6
	v_lshl_add_u64 v[2:3], s[6:7], 0, v[0:1]
	v_and_b32_e32 v130, 0x70, v6
	v_lshl_add_u64 v[0:1], s[8:9], 0, v[0:1]
	v_lshl_add_u64 v[166:167], v[2:3], 0, v[130:131]
	v_lshl_add_u64 v[168:169], v[0:1], 0, v[130:131]
	v_lshlrev_b32_e32 v130, 4, v4
	v_add_u32_e32 v2, 0x2000, v130
	v_readfirstlane_b32 s6, v130
	v_lshl_add_u64 v[0:1], v[166:167], 0, s[56:57]
	s_mov_b32 m0, s6
	v_lshl_add_u64 v[170:171], v[166:167], 0, s[58:59]
	v_readfirstlane_b32 s6, v2
	v_add_u32_e32 v2, 0x4000, v130
	s_barrier
; #define LDS_PTR(p) ((__attribute__((address_space(3))) unsigned*)(p))
; template <int PIPE>
; DI void gemm_loop_g(const u16* __restrict__ Xp, long ldx_l, long ldx_i, long kxs,
;                     const u16* __restrict__ Yp, long ldy_l, long ldy_i, long kys, int K,
;                     f32x4 (&acc)[4][8], unsigned char* smem) {
;     ...
;   auto issue = [&](int kt0, int stage) {
;     int kt = kt0 + rot; if (kt >= nk) kt -= nk;
;     unsigned char* sb = smem + stage * 65536 + t * 16;
; #pragma unroll
;     for (int i = 0; i < 4; ++i)
;       __builtin_amdgcn_global_load_lds((const unsigned*)(xs + i * ldx_i + kt * kxs), LDS_PTR(sb + i * 8192), 16, 0, 0);
; #pragma unroll
;     for (int i = 0; i < 4; ++i)
;       __builtin_amdgcn_global_load_lds((const unsigned*)(ys + i * ldy_i + kt * kys), LDS_PTR(sb + 32768 + i * 8192), 16, 0, 0);
;   };
;   __syncthreads();
;   issue(0, 0);
;   asm volatile("s_waitcnt vmcnt(0)" ::: "memory");
;   __syncthreads();
; DI void zero_acc(f32x4 (&acc)[4][8]) {
; #pragma unroll
;   for (int i = 0; i < 4; ++i)
; #pragma unroll
;     for (int j = 0; j < 8; ++j) acc[i][j] = f32x4{0.f, 0.f, 0.f, 0.f};
; }
	global_load_lds_dwordx4 v[0:1], off
	v_lshl_add_u64 v[0:1], v[170:171], 0, s[56:57]
	s_mov_b32 m0, s6
	v_lshl_add_u64 v[172:173], v[166:167], 0, s[60:61]
	v_readfirstlane_b32 s6, v2
	v_add_u32_e32 v2, 0x6000, v130
	global_load_lds_dwordx4 v[0:1], off
	v_lshl_add_u64 v[0:1], v[172:173], 0, s[56:57]
	s_mov_b32 m0, s6
	v_lshl_add_u64 v[174:175], v[166:167], 0, s[62:63]
	v_readfirstlane_b32 s6, v2
	v_add_u32_e32 v2, 0x8000, v130
	global_load_lds_dwordx4 v[0:1], off
	v_lshl_add_u64 v[0:1], v[174:175], 0, s[56:57]
	s_mov_b32 m0, s6
	v_readfirstlane_b32 s6, v2
	v_add_u32_e32 v2, 0xa000, v130
	global_load_lds_dwordx4 v[0:1], off
	v_lshl_add_u64 v[0:1], v[168:169], 0, s[56:57]
	s_mov_b32 m0, s6
	v_lshl_add_u64 v[176:177], v[168:169], 0, s[58:59]
	v_readfirstlane_b32 s6, v2
	v_add_u32_e32 v2, 0xc000, v130
	global_load_lds_dwordx4 v[0:1], off
	v_lshl_add_u64 v[0:1], v[176:177], 0, s[56:57]
	s_mov_b32 m0, s6
	v_lshl_add_u64 v[178:179], v[168:169], 0, s[60:61]
	v_readfirstlane_b32 s6, v2
	v_add_u32_e32 v2, 0xe000, v130
	global_load_lds_dwordx4 v[0:1], off
	v_lshl_add_u64 v[0:1], v[178:179], 0, s[56:57]
	s_mov_b32 m0, s6
	v_lshl_add_u64 v[180:181], v[168:169], 0, s[62:63]
	v_readfirstlane_b32 s6, v2
	global_load_lds_dwordx4 v[0:1], off
	v_lshl_add_u64 v[0:1], v[180:181], 0, s[56:57]
	s_mov_b32 m0, s6
	v_lshlrev_b32_e32 v2, 7, v4
	global_load_lds_dwordx4 v[0:1], off
	v_bfe_u32 v0, v4, 4, 2
	v_bfe_u32 v1, v4, 1, 3
	v_readfirstlane_b32 s10, v4
	s_nop 0
	v_bitop3_b32 v0, v0, v1, 4 bitop3:0x36
	v_and_b32_e32 v2, 0x780, v2
	s_lshl_b32 s6, s10, 8
	s_lshl_b32 s7, s10, 6
	v_lshl_or_b32 v187, v0, 4, v2
	v_bitop3_b32 v0, v5, v1, 3 bitop3:0x6c
	v_mov_b32_e32 v4, 0
	s_and_b32 s6, s6, 0x4000
	s_and_b32 s7, s7, 0xffffe000
	v_lshl_or_b32 v188, v0, 4, v2
	s_mov_b32 s10, 0
	s_mov_b32 s11, 0x10000
	v_mov_b32_e32 v5, v4
	v_mov_b32_e32 v6, v4
	v_mov_b32_e32 v7, v4
	v_mov_b32_e32 v16, v4
	v_mov_b32_e32 v17, v4
	v_mov_b32_e32 v18, v4
	v_mov_b32_e32 v19, v4
	v_mov_b32_e32 v32, v4
	v_mov_b32_e32 v33, v4
	v_mov_b32_e32 v34, v4
	v_mov_b32_e32 v35, v4
	v_mov_b32_e32 v48, v4
	v_mov_b32_e32 v49, v4
	v_mov_b32_e32 v50, v4
	v_mov_b32_e32 v51, v4
	v_mov_b32_e32 v64, v4
	v_mov_b32_e32 v65, v4
	v_mov_b32_e32 v66, v4
	v_mov_b32_e32 v67, v4
	v_mov_b32_e32 v80, v4
	v_mov_b32_e32 v81, v4
	v_mov_b32_e32 v82, v4
	v_mov_b32_e32 v83, v4
	v_mov_b32_e32 v96, v4
	v_mov_b32_e32 v97, v4
	v_mov_b32_e32 v98, v4
	v_mov_b32_e32 v99, v4
	v_mov_b32_e32 v112, v4
	v_mov_b32_e32 v113, v4
	v_mov_b32_e32 v114, v4
	v_mov_b32_e32 v115, v4
	v_mov_b32_e32 v0, v4
	v_mov_b32_e32 v1, v4
	v_mov_b32_e32 v2, v4
	v_mov_b32_e32 v3, v4
	v_mov_b32_e32 v20, v4
	v_mov_b32_e32 v21, v4
	v_mov_b32_e32 v22, v4
	v_mov_b32_e32 v23, v4
	v_mov_b32_e32 v36, v4
	v_mov_b32_e32 v37, v4
	v_mov_b32_e32 v38, v4
	v_mov_b32_e32 v39, v4
	v_mov_b32_e32 v52, v4
	v_mov_b32_e32 v53, v4
	v_mov_b32_e32 v54, v4
	v_mov_b32_e32 v55, v4
	v_mov_b32_e32 v68, v4
	v_mov_b32_e32 v69, v4
	v_mov_b32_e32 v70, v4
	v_mov_b32_e32 v71, v4
	v_mov_b32_e32 v84, v4
	v_mov_b32_e32 v85, v4
	v_mov_b32_e32 v86, v4
	v_mov_b32_e32 v87, v4
	v_mov_b32_e32 v100, v4
	v_mov_b32_e32 v101, v4
	v_mov_b32_e32 v102, v4
	v_mov_b32_e32 v103, v4
	v_mov_b32_e32 v116, v4
	v_mov_b32_e32 v117, v4
	v_mov_b32_e32 v118, v4
	v_mov_b32_e32 v119, v4
	v_mov_b32_e32 v8, v4
	v_mov_b32_e32 v9, v4
	v_mov_b32_e32 v10, v4
	v_mov_b32_e32 v11, v4
	v_mov_b32_e32 v24, v4
	v_mov_b32_e32 v25, v4
	v_mov_b32_e32 v26, v4
	v_mov_b32_e32 v27, v4
	v_mov_b32_e32 v40, v4
	v_mov_b32_e32 v41, v4
	v_mov_b32_e32 v42, v4
	v_mov_b32_e32 v43, v4
	v_mov_b32_e32 v56, v4
	v_mov_b32_e32 v57, v4
	v_mov_b32_e32 v58, v4
	v_mov_b32_e32 v59, v4
	v_mov_b32_e32 v72, v4
	v_mov_b32_e32 v73, v4
	v_mov_b32_e32 v74, v4
	v_mov_b32_e32 v75, v4
	v_mov_b32_e32 v88, v4
	v_mov_b32_e32 v89, v4
	v_mov_b32_e32 v90, v4
	v_mov_b32_e32 v91, v4
	v_mov_b32_e32 v104, v4
	v_mov_b32_e32 v105, v4
	v_mov_b32_e32 v106, v4
	v_mov_b32_e32 v107, v4
	v_mov_b32_e32 v120, v4
	v_mov_b32_e32 v121, v4
	v_mov_b32_e32 v122, v4
	v_mov_b32_e32 v123, v4
	v_mov_b32_e32 v12, v4
	v_mov_b32_e32 v13, v4
	v_mov_b32_e32 v14, v4
	v_mov_b32_e32 v15, v4
	v_mov_b32_e32 v28, v4
	v_mov_b32_e32 v29, v4
	v_mov_b32_e32 v30, v4
	v_mov_b32_e32 v31, v4
	v_mov_b32_e32 v44, v4
	v_mov_b32_e32 v45, v4
	v_mov_b32_e32 v46, v4
	v_mov_b32_e32 v47, v4
	v_mov_b32_e32 v60, v4
	v_mov_b32_e32 v61, v4
	v_mov_b32_e32 v62, v4
	v_mov_b32_e32 v63, v4
	v_mov_b32_e32 v76, v4
	v_mov_b32_e32 v77, v4
	v_mov_b32_e32 v78, v4
	v_mov_b32_e32 v79, v4
	v_mov_b32_e32 v92, v4
	v_mov_b32_e32 v93, v4
	v_mov_b32_e32 v94, v4
	v_mov_b32_e32 v95, v4
	v_mov_b32_e32 v108, v4
	v_mov_b32_e32 v109, v4
	v_mov_b32_e32 v110, v4
	v_mov_b32_e32 v111, v4
	v_mov_b32_e32 v124, v4
	v_mov_b32_e32 v125, v4
	v_mov_b32_e32 v126, v4
	v_mov_b32_e32 v127, v4
	s_waitcnt vmcnt(0) lgkmcnt(0)
	s_barrier
	s_branch .LBB0_172

; DI int tid_opaque() { int t = threadIdx.x; asm volatile("" : "+v"(t)); return t; }
; #define LDS_PTR(p) ((__attribute__((address_space(3))) unsigned*)(p))
; template <int PIPE>
; DI void gemm_loop_g(const u16* __restrict__ Xp, long ldx_l, long ldx_i, long kxs,
;                     const u16* __restrict__ Yp, long ldy_l, long ldy_i, long kys, int K,
;                     f32x4 (&acc)[4][8], unsigned char* smem) {
;   const int t = tid_opaque(), l = t & 63, w = __builtin_amdgcn_readfirstlane(t >> 6), wx = w >> 1, wy = w & 1;
;   const int lrow = t >> 3, gch = (t & 7) ^ ((t >> 4) & 7);
;   const u16* xs = Xp + (long)lrow * ldx_l + gch * 8;
;   const u16* ys = Yp + (long)lrow * ldy_l + gch * 8;
;   const int fsw = (l >> 1) & 7, lg = l >> 4;
;   const unsigned fr0 = (l & 15) * 128 + ((lg ^ fsw) << 4);
;   const unsigned fr1 = (l & 15) * 128 + (((lg + 4) ^ fsw) << 4);
;   const unsigned ub = wx * 8192, vb = 32768 + wy * 16384;
;   const int nk = K >> 6;
;   const int rot = (int)((blockIdx.x >> 3) + (blockIdx.x & 7) * 5) % nk;
;   auto issue = [&](int kt0, int stage) {
;     int kt = kt0 + rot; if (kt >= nk) kt -= nk;
;     unsigned char* sb = smem + stage * 65536 + t * 16;
; #pragma unroll
;     for (int i = 0; i < 4; ++i)
;       __builtin_amdgcn_global_load_lds((const unsigned*)(xs + i * ldx_i + kt * kxs), LDS_PTR(sb + i * 8192), 16, 0, 0);
; #pragma unroll
;     for (int i = 0; i < 4; ++i)
;       __builtin_amdgcn_global_load_lds((const unsigned*)(ys + i * ldy_i + kt * kys), LDS_PTR(sb + 32768 + i * 8192), 16, 0, 0);
;   };
;   __syncthreads();
;   issue(0, 0);
;   asm volatile("s_waitcnt vmcnt(0)" ::: "memory");
;   __syncthreads();
; DI void zero_acc(f32x4 (&acc)[4][8]) {
; #pragma unroll
;   for (int i = 0; i < 4; ++i)
; #pragma unroll
;     for (int j = 0; j < 8; ++j) acc[i][j] = f32x4{0.f, 0.f, 0.f, 0.f};
; }
.LBB0_203:
	s_lshl_b32 s6, s90, 7
	s_and_b32 s6, s6, 0xfffff800
	s_and_b32 s91, s90, 15
	s_or_b32 s12, s6, s59
	s_and_b32 s6, s90, 12
	s_cmp_lg_u32 s6, 8
	s_cselect_b64 s[14:15], -1, 0
	s_ashr_i32 s13, s12, 31
	s_lshl_b64 s[6:7], s[12:13], 11
	s_add_u32 s80, s18, s6
	s_addc_u32 s81, s19, s7
	s_lshl_b32 s6, s91, 19
	s_add_u32 s16, s24, s6
	s_addc_u32 s17, s25, 0
	s_mov_b64 s[82:83], -1
	s_and_b64 vcc, exec, s[14:15]
	s_cbranch_vccz .LBB0_209
	v_mov_b32_e32 v4, v182
	s_nop 0
	v_ashrrev_i32_e32 v0, 3, v4
	v_lshrrev_b32_e32 v5, 4, v4
	v_xor_b32_e32 v6, v5, v4
	v_ashrrev_i32_e32 v1, 31, v0
	v_lshlrev_b64 v[0:1], 11, v[0:1]
	v_lshlrev_b32_e32 v6, 4, v6
	v_lshl_add_u64 v[2:3], s[16:17], 0, v[0:1]
	v_and_b32_e32 v128, 0x70, v6
	v_lshl_add_u64 v[0:1], s[80:81], 0, v[0:1]
	v_lshl_add_u64 v[130:131], v[2:3], 0, v[128:129]
	v_lshl_add_u64 v[132:133], v[0:1], 0, v[128:129]
	v_lshlrev_b32_e32 v128, 4, v4
	v_add_u32_e32 v2, 0x2000, v128
	v_readfirstlane_b32 s6, v128
	v_lshl_add_u64 v[0:1], v[130:131], 0, s[28:29]
	s_mov_b32 m0, s6
	v_lshl_add_u64 v[134:135], v[130:131], 0, s[30:31]
	v_readfirstlane_b32 s6, v2
	v_add_u32_e32 v2, 0x4000, v128
	s_barrier
	global_load_lds_dwordx4 v[0:1], off
	v_lshl_add_u64 v[0:1], v[134:135], 0, s[28:29]
	s_mov_b32 m0, s6
	v_lshl_add_u64 v[136:137], v[130:131], 0, s[54:55]
	v_readfirstlane_b32 s6, v2
	v_add_u32_e32 v2, 0x6000, v128
	global_load_lds_dwordx4 v[0:1], off
	v_lshl_add_u64 v[0:1], v[136:137], 0, s[28:29]
	s_mov_b32 m0, s6
	v_lshl_add_u64 v[138:139], v[130:131], 0, s[56:57]
	v_readfirstlane_b32 s6, v2
	v_add_u32_e32 v2, 0x8000, v128
	global_load_lds_dwordx4 v[0:1], off
	v_lshl_add_u64 v[0:1], v[138:139], 0, s[28:29]
	s_mov_b32 m0, s6
	v_readfirstlane_b32 s6, v2
	v_add_u32_e32 v2, 0xa000, v128
	global_load_lds_dwordx4 v[0:1], off
	v_lshl_add_u64 v[0:1], v[132:133], 0, s[28:29]
	s_mov_b32 m0, s6
	v_lshl_add_u64 v[140:141], v[132:133], 0, s[30:31]
	v_readfirstlane_b32 s6, v2
	v_add_u32_e32 v2, 0xc000, v128
	global_load_lds_dwordx4 v[0:1], off
	v_lshl_add_u64 v[0:1], v[140:141], 0, s[28:29]
	s_mov_b32 m0, s6
	v_lshl_add_u64 v[142:143], v[132:133], 0, s[54:55]
	v_readfirstlane_b32 s6, v2
	v_add_u32_e32 v2, 0xe000, v128
	global_load_lds_dwordx4 v[0:1], off
	v_lshl_add_u64 v[0:1], v[142:143], 0, s[28:29]
	s_mov_b32 m0, s6
	v_lshl_add_u64 v[144:145], v[132:133], 0, s[56:57]
	v_readfirstlane_b32 s6, v2
	global_load_lds_dwordx4 v[0:1], off
	v_lshl_add_u64 v[0:1], v[144:145], 0, s[28:29]
	s_mov_b32 m0, s6
	v_lshlrev_b32_e32 v2, 7, v4
	global_load_lds_dwordx4 v[0:1], off
	v_bfe_u32 v0, v4, 4, 2
	v_bfe_u32 v1, v4, 1, 3
	v_readfirstlane_b32 s7, v4
	s_nop 0
	v_bitop3_b32 v0, v0, v1, 4 bitop3:0x36
	v_and_b32_e32 v2, 0x780, v2
	s_lshl_b32 s6, s7, 8
	s_lshl_b32 s7, s7, 6
	v_lshl_or_b32 v151, v0, 4, v2
	v_bitop3_b32 v0, v5, v1, 3 bitop3:0x6c
	v_mov_b32_e32 v8, 0
	s_and_b32 s6, s6, 0x4000
	s_and_b32 s7, s7, 0xffffe000
	v_lshl_or_b32 v152, v0, 4, v2
	s_mov_b32 s10, 0
	s_mov_b32 s11, 0x10000
	v_mov_b32_e32 v9, v8
	v_mov_b32_e32 v10, v8
	v_mov_b32_e32 v11, v8
	v_mov_b32_e32 v12, v8
	v_mov_b32_e32 v13, v8
	v_mov_b32_e32 v14, v8
	v_mov_b32_e32 v15, v8
	v_mov_b32_e32 v28, v8
	v_mov_b32_e32 v29, v8
	v_mov_b32_e32 v30, v8
	v_mov_b32_e32 v31, v8
	v_mov_b32_e32 v44, v8
	v_mov_b32_e32 v45, v8
	v_mov_b32_e32 v46, v8
	v_mov_b32_e32 v47, v8
	v_mov_b32_e32 v60, v8
	v_mov_b32_e32 v61, v8
	v_mov_b32_e32 v62, v8
	v_mov_b32_e32 v63, v8
	v_mov_b32_e32 v76, v8
	v_mov_b32_e32 v77, v8
	v_mov_b32_e32 v78, v8
	v_mov_b32_e32 v79, v8
	v_mov_b32_e32 v92, v8
	v_mov_b32_e32 v93, v8
	v_mov_b32_e32 v94, v8
	v_mov_b32_e32 v95, v8
	v_mov_b32_e32 v108, v8
	v_mov_b32_e32 v109, v8
	v_mov_b32_e32 v110, v8
	v_mov_b32_e32 v111, v8
	v_mov_b32_e32 v0, v8
	v_mov_b32_e32 v1, v8
	v_mov_b32_e32 v2, v8
	v_mov_b32_e32 v3, v8
	v_mov_b32_e32 v20, v8
	v_mov_b32_e32 v21, v8
	v_mov_b32_e32 v22, v8
	v_mov_b32_e32 v23, v8
	v_mov_b32_e32 v36, v8
	v_mov_b32_e32 v37, v8
	v_mov_b32_e32 v38, v8
	v_mov_b32_e32 v39, v8
	v_mov_b32_e32 v52, v8
	v_mov_b32_e32 v53, v8
	v_mov_b32_e32 v54, v8
	v_mov_b32_e32 v55, v8
	v_mov_b32_e32 v68, v8
	v_mov_b32_e32 v69, v8
	v_mov_b32_e32 v70, v8
	v_mov_b32_e32 v71, v8
	v_mov_b32_e32 v84, v8
	v_mov_b32_e32 v85, v8
	v_mov_b32_e32 v86, v8
	v_mov_b32_e32 v87, v8
	v_mov_b32_e32 v100, v8
	v_mov_b32_e32 v101, v8
	v_mov_b32_e32 v102, v8
	v_mov_b32_e32 v103, v8
	v_mov_b32_e32 v116, v8
	v_mov_b32_e32 v117, v8
	v_mov_b32_e32 v118, v8
	v_mov_b32_e32 v119, v8
	v_mov_b32_e32 v4, v8
	v_mov_b32_e32 v5, v8
	v_mov_b32_e32 v6, v8
	v_mov_b32_e32 v7, v8
	v_mov_b32_e32 v24, v8
	v_mov_b32_e32 v25, v8
	v_mov_b32_e32 v26, v8
	v_mov_b32_e32 v27, v8
	v_mov_b32_e32 v40, v8
	v_mov_b32_e32 v41, v8
	v_mov_b32_e32 v42, v8
	v_mov_b32_e32 v43, v8
	v_mov_b32_e32 v56, v8
	v_mov_b32_e32 v57, v8
	v_mov_b32_e32 v58, v8
	v_mov_b32_e32 v59, v8
	v_mov_b32_e32 v72, v8
	v_mov_b32_e32 v73, v8
	v_mov_b32_e32 v74, v8
	v_mov_b32_e32 v75, v8
	v_mov_b32_e32 v88, v8
	v_mov_b32_e32 v89, v8
	v_mov_b32_e32 v90, v8
	v_mov_b32_e32 v91, v8
	v_mov_b32_e32 v104, v8
	v_mov_b32_e32 v105, v8
	v_mov_b32_e32 v106, v8
	v_mov_b32_e32 v107, v8
	v_mov_b32_e32 v120, v8
	v_mov_b32_e32 v121, v8
	v_mov_b32_e32 v122, v8
	v_mov_b32_e32 v123, v8
	v_mov_b32_e32 v16, v8
	v_mov_b32_e32 v17, v8
	v_mov_b32_e32 v18, v8
	v_mov_b32_e32 v19, v8
	v_mov_b32_e32 v32, v8
	v_mov_b32_e32 v33, v8
	v_mov_b32_e32 v34, v8
	v_mov_b32_e32 v35, v8
	v_mov_b32_e32 v48, v8
	v_mov_b32_e32 v49, v8
	v_mov_b32_e32 v50, v8
	v_mov_b32_e32 v51, v8
	v_mov_b32_e32 v64, v8
	v_mov_b32_e32 v65, v8
	v_mov_b32_e32 v66, v8
	v_mov_b32_e32 v67, v8
	v_mov_b32_e32 v80, v8
	v_mov_b32_e32 v81, v8
	v_mov_b32_e32 v82, v8
	v_mov_b32_e32 v83, v8
	v_mov_b32_e32 v96, v8
	v_mov_b32_e32 v97, v8
	v_mov_b32_e32 v98, v8
	v_mov_b32_e32 v99, v8
	v_mov_b32_e32 v112, v8
	v_mov_b32_e32 v113, v8
	v_mov_b32_e32 v114, v8
	v_mov_b32_e32 v115, v8
	v_mov_b32_e32 v124, v8
	v_mov_b32_e32 v125, v8
	v_mov_b32_e32 v126, v8
	v_mov_b32_e32 v127, v8
	s_waitcnt vmcnt(0) lgkmcnt(0)
	s_barrier
	s_branch .LBB0_206

; DI int tid_opaque() { int t = threadIdx.x; asm volatile("" : "+v"(t)); return t; }
; #define LDS_PTR(p) ((__attribute__((address_space(3))) unsigned*)(p))
; template <int PIPE>
; DI void gemm_loop_g(const u16* __restrict__ Xp, long ldx_l, long ldx_i, long kxs,
;                     const u16* __restrict__ Yp, long ldy_l, long ldy_i, long kys, int K,
;                     f32x4 (&acc)[4][8], unsigned char* smem) {
;   const int t = tid_opaque(), l = t & 63, w = __builtin_amdgcn_readfirstlane(t >> 6), wx = w >> 1, wy = w & 1;
;   const int lrow = t >> 3, gch = (t & 7) ^ ((t >> 4) & 7);
;   const u16* xs = Xp + (long)lrow * ldx_l + gch * 8;
;   const u16* ys = Yp + (long)lrow * ldy_l + gch * 8;
;   const int fsw = (l >> 1) & 7, lg = l >> 4;
;   const unsigned fr0 = (l & 15) * 128 + ((lg ^ fsw) << 4);
;   const unsigned fr1 = (l & 15) * 128 + (((lg + 4) ^ fsw) << 4);
;   const unsigned ub = wx * 8192, vb = 32768 + wy * 16384;
;   const int nk = K >> 6;
;   const int rot = (int)((blockIdx.x >> 3) + (blockIdx.x & 7) * 5) % nk;
;   auto issue = [&](int kt0, int stage) {
;     int kt = kt0 + rot; if (kt >= nk) kt -= nk;
;     unsigned char* sb = smem + stage * 65536 + t * 16;
; #pragma unroll
;     for (int i = 0; i < 4; ++i)
;       __builtin_amdgcn_global_load_lds((const unsigned*)(xs + i * ldx_i + kt * kxs), LDS_PTR(sb + i * 8192), 16, 0, 0);
; #pragma unroll
;     for (int i = 0; i < 4; ++i)
;       __builtin_amdgcn_global_load_lds((const unsigned*)(ys + i * ldy_i + kt * kys), LDS_PTR(sb + 32768 + i * 8192), 16, 0, 0);
;   };
;   __syncthreads();
;   issue(0, 0);
;   asm volatile("s_waitcnt vmcnt(0)" ::: "memory");
;   __syncthreads();
; DI void zero_acc(f32x4 (&acc)[4][8]) {
; #pragma unroll
;   for (int i = 0; i < 4; ++i)
; #pragma unroll
;     for (int j = 0; j < 8; ++j) acc[i][j] = f32x4{0.f, 0.f, 0.f, 0.f};
; }
.LBB0_209:
	s_and_b64 vcc, exec, s[82:83]
	s_cbranch_vccz .LBB0_214
	s_nop 1
	v_mov_b32_e32 v4, v182
	s_nop 0
	v_ashrrev_i32_e32 v0, 3, v4
	v_lshrrev_b32_e32 v5, 4, v4
	v_xor_b32_e32 v6, v5, v4
	v_ashrrev_i32_e32 v1, 31, v0
	v_lshlrev_b64 v[0:1], 11, v[0:1]
	v_lshlrev_b32_e32 v6, 4, v6
	v_lshl_add_u64 v[2:3], s[80:81], 0, v[0:1]
	v_and_b32_e32 v128, 0x70, v6
	v_lshl_add_u64 v[0:1], s[16:17], 0, v[0:1]
	v_lshl_add_u64 v[130:131], v[2:3], 0, v[128:129]
	v_lshl_add_u64 v[132:133], v[0:1], 0, v[128:129]
	v_lshlrev_b32_e32 v128, 4, v4
	v_add_u32_e32 v2, 0x2000, v128
	v_readfirstlane_b32 s6, v128
	v_lshl_add_u64 v[0:1], v[130:131], 0, s[28:29]
	s_mov_b32 m0, s6
	v_lshl_add_u64 v[134:135], v[130:131], 0, s[30:31]
	v_readfirstlane_b32 s6, v2
	v_add_u32_e32 v2, 0x4000, v128
	s_barrier
	global_load_lds_dwordx4 v[0:1], off
	v_lshl_add_u64 v[0:1], v[134:135], 0, s[28:29]
	s_mov_b32 m0, s6
	v_lshl_add_u64 v[136:137], v[130:131], 0, s[54:55]
	v_readfirstlane_b32 s6, v2
	v_add_u32_e32 v2, 0x6000, v128
	global_load_lds_dwordx4 v[0:1], off
	v_lshl_add_u64 v[0:1], v[136:137], 0, s[28:29]
	s_mov_b32 m0, s6
	v_lshl_add_u64 v[138:139], v[130:131], 0, s[56:57]
	v_readfirstlane_b32 s6, v2
	v_add_u32_e32 v2, 0x8000, v128
	global_load_lds_dwordx4 v[0:1], off
	v_lshl_add_u64 v[0:1], v[138:139], 0, s[28:29]
	s_mov_b32 m0, s6
	v_readfirstlane_b32 s6, v2
	v_add_u32_e32 v2, 0xa000, v128
	global_load_lds_dwordx4 v[0:1], off
	v_lshl_add_u64 v[0:1], v[132:133], 0, s[28:29]
	s_mov_b32 m0, s6
	v_lshl_add_u64 v[140:141], v[132:133], 0, s[30:31]
	v_readfirstlane_b32 s6, v2
	v_add_u32_e32 v2, 0xc000, v128
	global_load_lds_dwordx4 v[0:1], off
	v_lshl_add_u64 v[0:1], v[140:141], 0, s[28:29]
	s_mov_b32 m0, s6
	v_lshl_add_u64 v[142:143], v[132:133], 0, s[54:55]
	v_readfirstlane_b32 s6, v2
	v_add_u32_e32 v2, 0xe000, v128
	global_load_lds_dwordx4 v[0:1], off
	v_lshl_add_u64 v[0:1], v[142:143], 0, s[28:29]
	s_mov_b32 m0, s6
	v_lshl_add_u64 v[144:145], v[132:133], 0, s[56:57]
	v_readfirstlane_b32 s6, v2
	global_load_lds_dwordx4 v[0:1], off
	v_lshl_add_u64 v[0:1], v[144:145], 0, s[28:29]
	s_mov_b32 m0, s6
	v_lshlrev_b32_e32 v2, 7, v4
	global_load_lds_dwordx4 v[0:1], off
	v_bfe_u32 v0, v4, 4, 2
	v_bfe_u32 v1, v4, 1, 3
	v_readfirstlane_b32 s7, v4
	s_nop 0
	v_bitop3_b32 v0, v0, v1, 4 bitop3:0x36
	v_and_b32_e32 v2, 0x780, v2
	s_lshl_b32 s6, s7, 8
	s_lshl_b32 s7, s7, 6
	v_lshl_or_b32 v151, v0, 4, v2
	v_bitop3_b32 v0, v5, v1, 3 bitop3:0x6c
	v_mov_b32_e32 v8, 0
	s_and_b32 s6, s6, 0x4000
	s_and_b32 s7, s7, 0xffffe000
	v_lshl_or_b32 v152, v0, 4, v2
	s_mov_b32 s10, 0
	s_mov_b32 s11, 0x10000
	v_mov_b32_e32 v9, v8
	v_mov_b32_e32 v10, v8
	v_mov_b32_e32 v11, v8
	v_mov_b32_e32 v12, v8
	v_mov_b32_e32 v13, v8
	v_mov_b32_e32 v14, v8
	v_mov_b32_e32 v15, v8
	v_mov_b32_e32 v28, v8
	v_mov_b32_e32 v29, v8
	v_mov_b32_e32 v30, v8
	v_mov_b32_e32 v31, v8
	v_mov_b32_e32 v44, v8
	v_mov_b32_e32 v45, v8
	v_mov_b32_e32 v46, v8
	v_mov_b32_e32 v47, v8
	v_mov_b32_e32 v60, v8
	v_mov_b32_e32 v61, v8
	v_mov_b32_e32 v62, v8
	v_mov_b32_e32 v63, v8
	v_mov_b32_e32 v76, v8
	v_mov_b32_e32 v77, v8
	v_mov_b32_e32 v78, v8
	v_mov_b32_e32 v79, v8
	v_mov_b32_e32 v92, v8
	v_mov_b32_e32 v93, v8
	v_mov_b32_e32 v94, v8
	v_mov_b32_e32 v95, v8
	v_mov_b32_e32 v108, v8
	v_mov_b32_e32 v109, v8
	v_mov_b32_e32 v110, v8
	v_mov_b32_e32 v111, v8
	v_mov_b32_e32 v0, v8
	v_mov_b32_e32 v1, v8
	v_mov_b32_e32 v2, v8
	v_mov_b32_e32 v3, v8
	v_mov_b32_e32 v20, v8
	v_mov_b32_e32 v21, v8
	v_mov_b32_e32 v22, v8
	v_mov_b32_e32 v23, v8
	v_mov_b32_e32 v36, v8
	v_mov_b32_e32 v37, v8
	v_mov_b32_e32 v38, v8
	v_mov_b32_e32 v39, v8
	v_mov_b32_e32 v52, v8
	v_mov_b32_e32 v53, v8
	v_mov_b32_e32 v54, v8
	v_mov_b32_e32 v55, v8
	v_mov_b32_e32 v68, v8
	v_mov_b32_e32 v69, v8
	v_mov_b32_e32 v70, v8
	v_mov_b32_e32 v71, v8
	v_mov_b32_e32 v84, v8
	v_mov_b32_e32 v85, v8
	v_mov_b32_e32 v86, v8
	v_mov_b32_e32 v87, v8
	v_mov_b32_e32 v100, v8
	v_mov_b32_e32 v101, v8
	v_mov_b32_e32 v102, v8
	v_mov_b32_e32 v103, v8
	v_mov_b32_e32 v116, v8
	v_mov_b32_e32 v117, v8
	v_mov_b32_e32 v118, v8
	v_mov_b32_e32 v119, v8
	v_mov_b32_e32 v4, v8
	v_mov_b32_e32 v5, v8
	v_mov_b32_e32 v6, v8
	v_mov_b32_e32 v7, v8
	v_mov_b32_e32 v24, v8
	v_mov_b32_e32 v25, v8
	v_mov_b32_e32 v26, v8
	v_mov_b32_e32 v27, v8
	v_mov_b32_e32 v40, v8
	v_mov_b32_e32 v41, v8
	v_mov_b32_e32 v42, v8
	v_mov_b32_e32 v43, v8
	v_mov_b32_e32 v56, v8
	v_mov_b32_e32 v57, v8
	v_mov_b32_e32 v58, v8
	v_mov_b32_e32 v59, v8
	v_mov_b32_e32 v72, v8
	v_mov_b32_e32 v73, v8
	v_mov_b32_e32 v74, v8
	v_mov_b32_e32 v75, v8
	v_mov_b32_e32 v88, v8
	v_mov_b32_e32 v89, v8
	v_mov_b32_e32 v90, v8
	v_mov_b32_e32 v91, v8
	v_mov_b32_e32 v104, v8
	v_mov_b32_e32 v105, v8
	v_mov_b32_e32 v106, v8
	v_mov_b32_e32 v107, v8
	v_mov_b32_e32 v120, v8
	v_mov_b32_e32 v121, v8
	v_mov_b32_e32 v122, v8
	v_mov_b32_e32 v123, v8
	v_mov_b32_e32 v16, v8
	v_mov_b32_e32 v17, v8
	v_mov_b32_e32 v18, v8
	v_mov_b32_e32 v19, v8
	v_mov_b32_e32 v32, v8
	v_mov_b32_e32 v33, v8
	v_mov_b32_e32 v34, v8
	v_mov_b32_e32 v35, v8
	v_mov_b32_e32 v48, v8
	v_mov_b32_e32 v49, v8
	v_mov_b32_e32 v50, v8
	v_mov_b32_e32 v51, v8
	v_mov_b32_e32 v64, v8
	v_mov_b32_e32 v65, v8
	v_mov_b32_e32 v66, v8
	v_mov_b32_e32 v67, v8
	v_mov_b32_e32 v80, v8
	v_mov_b32_e32 v81, v8
	v_mov_b32_e32 v82, v8
	v_mov_b32_e32 v83, v8
	v_mov_b32_e32 v96, v8
	v_mov_b32_e32 v97, v8
	v_mov_b32_e32 v98, v8
	v_mov_b32_e32 v99, v8
	v_mov_b32_e32 v112, v8
	v_mov_b32_e32 v113, v8
	v_mov_b32_e32 v114, v8
	v_mov_b32_e32 v115, v8
	v_mov_b32_e32 v124, v8
	v_mov_b32_e32 v125, v8
	v_mov_b32_e32 v126, v8
	v_mov_b32_e32 v127, v8
	s_waitcnt vmcnt(0) lgkmcnt(0)
	s_barrier
	s_branch .LBB0_212

; DI int tid_opaque() { int t = threadIdx.x; asm volatile("" : "+v"(t)); return t; }
; #define LDS_PTR(p) ((__attribute__((address_space(3))) unsigned*)(p))
; DI void na_phase(const Params& p, const u16* q, const u16* k, const u16* vt, const u16* z, u16* og, unsigned char* smem) {
;     ...
;     const int hg = item & 7, r = (item >> 3) & 63, b = item >> 9;
;     const int h = hg * 4 + hh;
;     const int rs = min(max(r - 4, 0), 56);
;     __syncthreads();
;     if (hg != cur_hg) {
;       if (!(w & 1)) for (int i = l; i < 465; i += 64) rp[i] = p.na_rpb[h * 465 + i];
;       cur_hg = hg;
;     }
;     auto issue = [&](int ri) {
;       const int t2 = tid_opaque();
;       unsigned char* sb = smem + (ri & 3) * NSTG + t2 * 16;
;       const long tok0 = (long)b * 4096 + (rs + ri) * 64;
; #pragma unroll
;       for (int i = 0; i < 2; ++i) {
;         const int cid = t2 + 512 * i, row = cid >> 4, c = (cid & 15) ^ (row & 15);
;         __builtin_amdgcn_global_load_lds((const unsigned*)(k + (tok0 + row) * 1024 + hg * 128 + c * 8), LDS_PTR(sb + i * 8192), 16, 0, 0);
;       }
; #pragma unroll
;       for (int i = 0; i < 2; ++i) {
;         const int cid = t2 + 512 * i, row = cid >> 3, c = (cid & 7) ^ ((row >> 1) & 7);
;         __builtin_amdgcn_global_load_lds((const unsigned*)(vt + ((long)(b * 1024 + hg * 128 + row)) * 4096 + (rs + ri) * 64 + c * 8),
;                                          LDS_PTR(sb + 16384 + i * 8192), 16, 0, 0);
;       }
;     };
;     bf16x8 qf[2];
; #pragma unroll
;     for (int jj = 0; jj < 2; ++jj)
;       qf[jj] = *(const bf16x8*)(q + ((long)b * 4096 + r * 64 + (jb + jj) * 16 + lq) * 1024 + h * 32 + lg * 8);
;     issue(0); issue(1); issue(2);
.LBB0_236:
	s_and_b32 s7, s49, 7
	s_lshl_b32 s7, s7, 7
	s_lshl_b64 s[84:85], s[82:83], 7
	s_add_u32 s84, s11, s84
	s_addc_u32 s85, s48, s85
	s_ashr_i32 s88, s95, 9
	s_ashr_i32 s89, s88, 31
	s_lshl_b64 s[90:91], s[82:83], 6
	s_lshl_b64 s[82:83], s[88:89], 12
	v_lshl_or_b32 v70, s8, 6, v38
	v_or_b32_e32 v8, s82, v70
	v_mov_b32_e32 v1, s83
	s_lshl_b32 s86, s18, 5
	v_or_b32_e32 v0, s97, v8
	s_ashr_i32 s87, s86, 31
	v_lshlrev_b64 v[4:5], 11, v[0:1]
	v_or_b32_e32 v0, s33, v8
	s_mul_i32 s40, s9, 0x7c
	s_mul_i32 s41, s8, 0x7c
	v_lshl_add_u64 v[2:3], s[86:87], 1, v[34:35]
	v_lshlrev_b64 v[0:1], 11, v[0:1]
	s_sub_i32 s40, s40, s41
	v_lshl_add_u64 v[4:5], v[2:3], 0, v[4:5]
	v_lshl_add_u64 v[0:1], v[2:3], 0, v[0:1]
	v_mov_b32_e32 v2, v182
	v_add_u32_e32 v71, s40, v50
	v_add_u32_e32 v72, s40, v51
	v_add_u32_e32 v73, s40, v52
	v_add_u32_e32 v74, s40, v53
	v_add_u32_e32 v75, s40, v54
	v_add_u32_e32 v76, s40, v55
	v_add_u32_e32 v77, s40, v56
	v_add_u32_e32 v78, s40, v57
	v_add_u32_e32 v79, s40, v58
	v_add_u32_e32 v80, s40, v59
	v_add_u32_e32 v81, s40, v60
	v_add_u32_e32 v82, s40, v61
	v_add_u32_e32 v83, s40, v62
	v_add_u32_e32 v84, s40, v63
	v_add_u32_e32 v85, s40, v64
	v_add_u32_e32 v86, s40, v65
	global_load_dwordx4 v[4:7], v[4:5], off
	s_lshl_b32 s40, s9, 6
	global_load_dwordx4 v[8:11], v[0:1], off
	s_or_b32 s92, s82, s40
	v_ashrrev_i32_e32 v0, 4, v2
	s_mov_b32 s93, s83
	v_ashrrev_i32_e32 v1, 31, v0
	v_xor_b32_e32 v12, v0, v2
	v_lshl_add_u64 v[0:1], s[92:93], 0, v[0:1]
	v_lshlrev_b64 v[0:1], 11, v[0:1]
	v_lshlrev_b32_e32 v3, 4, v2
	v_lshl_add_u64 v[0:1], s[52:53], 0, v[0:1]
	s_lshl_b32 s18, s6, 8
	v_lshlrev_b32_e32 v12, 4, v12
	v_lshl_add_u64 v[0:1], v[0:1], 0, s[18:19]
	v_and_b32_e32 v32, 0xf0, v12
	v_readfirstlane_b32 s8, v3
	v_lshl_add_u64 v[0:1], v[0:1], 0, v[32:33]
	s_mov_b32 m0, s8
	v_add_u32_e32 v12, 0x200, v2
	global_load_lds_dwordx4 v[0:1], off
	v_ashrrev_i32_e32 v0, 4, v12
	v_ashrrev_i32_e32 v1, 31, v0
	v_xor_b32_e32 v13, v0, v2
	v_lshl_add_u64 v[0:1], s[92:93], 0, v[0:1]
	v_lshlrev_b64 v[0:1], 11, v[0:1]
	v_lshlrev_b32_e32 v13, 4, v13
	v_lshl_add_u64 v[0:1], s[52:53], 0, v[0:1]
	v_and_b32_e32 v32, 0xf0, v13
	v_add_u32_e32 v13, 0x2000, v3
	v_lshl_add_u64 v[0:1], v[0:1], 0, s[18:19]
	v_readfirstlane_b32 s8, v13
	v_lshl_add_u64 v[0:1], v[0:1], 0, v[32:33]
	s_mov_b32 m0, s8
	s_lshl_b32 s41, s6, 7
	global_load_lds_dwordx4 v[0:1], off
	v_lshrrev_b32_e32 v0, 4, v2
	s_lshl_b32 s8, s88, 10
	v_xor_b32_e32 v13, v0, v2
	v_ashrrev_i32_e32 v0, 3, v2
	s_or_b32 s41, s41, s8
	v_add_u32_e32 v0, s41, v0
	v_ashrrev_i32_e32 v1, 31, v0
	v_lshlrev_b64 v[0:1], 13, v[0:1]
	v_add_u32_e32 v14, 0x4000, v3
	v_lshl_add_u64 v[0:1], s[50:51], 0, v[0:1]
	s_lshl_b32 s88, s9, 7
	s_mov_b32 s89, s19
	v_lshlrev_b32_e32 v2, 4, v13
	v_lshl_add_u64 v[0:1], v[0:1], 0, s[88:89]
	v_and_b32_e32 v32, 0x70, v2
	v_readfirstlane_b32 s9, v14
	v_lshl_add_u64 v[0:1], v[0:1], 0, v[32:33]
	s_mov_b32 m0, s9
	v_add_u32_e32 v2, 0x6000, v3
	global_load_lds_dwordx4 v[0:1], off
	v_ashrrev_i32_e32 v0, 3, v12
	v_add_u32_e32 v0, s41, v0
	v_ashrrev_i32_e32 v1, 31, v0
	v_lshlrev_b64 v[0:1], 13, v[0:1]
	v_lshl_add_u64 v[0:1], s[50:51], 0, v[0:1]
	v_lshl_add_u64 v[0:1], v[0:1], 0, s[88:89]
	v_readfirstlane_b32 s9, v2
	v_lshl_add_u64 v[0:1], v[0:1], 0, v[32:33]
	s_mov_b32 m0, s9
	v_mov_b32_e32 v2, v182
	s_add_i32 s9, s40, 64
	global_load_lds_dwordx4 v[0:1], off
	s_add_u32 s92, s82, s9
	v_ashrrev_i32_e32 v0, 4, v2
	s_addc_u32 s93, s83, 0
	v_ashrrev_i32_e32 v1, 31, v0
	v_xor_b32_e32 v13, v0, v2
	v_lshl_add_u64 v[0:1], s[92:93], 0, v[0:1]
	v_lshlrev_b32_e32 v3, 4, v2
	v_lshlrev_b64 v[0:1], 11, v[0:1]
	v_add_u32_e32 v12, 0x8000, v3
	v_lshl_add_u64 v[0:1], s[52:53], 0, v[0:1]
	v_lshlrev_b32_e32 v13, 4, v13
	v_lshl_add_u64 v[0:1], v[0:1], 0, s[18:19]
	v_and_b32_e32 v32, 0xf0, v13
	v_readfirstlane_b32 s9, v12
	v_lshl_add_u64 v[0:1], v[0:1], 0, v[32:33]
	s_mov_b32 m0, s9
	v_add_u32_e32 v12, 0x200, v2
	global_load_lds_dwordx4 v[0:1], off
	v_ashrrev_i32_e32 v0, 4, v12
	v_ashrrev_i32_e32 v1, 31, v0
	v_xor_b32_e32 v13, v0, v2
	v_lshl_add_u64 v[0:1], s[92:93], 0, v[0:1]
	v_lshlrev_b64 v[0:1], 11, v[0:1]
	v_lshlrev_b32_e32 v13, 4, v13
; DI int tid_opaque() { int t = threadIdx.x; asm volatile("" : "+v"(t)); return t; }
; #define LDS_PTR(p) ((__attribute__((address_space(3))) unsigned*)(p))
; DI void na_phase(const Params& p, const u16* q, const u16* k, const u16* vt, const u16* z, u16* og, unsigned char* smem) {
;     ...
;     auto issue = [&](int ri) {
;       const int t2 = tid_opaque();
;       unsigned char* sb = smem + (ri & 3) * NSTG + t2 * 16;
;       const long tok0 = (long)b * 4096 + (rs + ri) * 64;
; #pragma unroll
;       for (int i = 0; i < 2; ++i) {
;         const int cid = t2 + 512 * i, row = cid >> 4, c = (cid & 15) ^ (row & 15);
;         __builtin_amdgcn_global_load_lds((const unsigned*)(k + (tok0 + row) * 1024 + hg * 128 + c * 8), LDS_PTR(sb + i * 8192), 16, 0, 0);
;       }
; #pragma unroll
;       for (int i = 0; i < 2; ++i) {
;         const int cid = t2 + 512 * i, row = cid >> 3, c = (cid & 7) ^ ((row >> 1) & 7);
;         __builtin_amdgcn_global_load_lds((const unsigned*)(vt + ((long)(b * 1024 + hg * 128 + row)) * 4096 + (rs + ri) * 64 + c * 8),
;                                          LDS_PTR(sb + 16384 + i * 8192), 16, 0, 0);
;       }
;     };
;     bf16x8 qf[2];
; #pragma unroll
;     for (int jj = 0; jj < 2; ++jj)
;       qf[jj] = *(const bf16x8*)(q + ((long)b * 4096 + r * 64 + (jb + jj) * 16 + lq) * 1024 + h * 32 + lg * 8);
;     issue(0); issue(1); issue(2);
;     f32x4 o[2][2];
;     float lrun[2];
; #pragma unroll
;     for (int jj = 0; jj < 2; ++jj) { o[jj][0] = f32x4{0.f, 0.f, 0.f, 0.f}; o[jj][1] = f32x4{0.f, 0.f, 0.f, 0.f}; lrun[jj] = 0.f; }
; #pragma unroll 1
;     for (int ri = 0; ri < 8; ++ri) {
;       if (ri <= 5) asm volatile("s_waitcnt vmcnt(8)" ::: "memory");
;       else if (ri == 6) asm volatile("s_waitcnt vmcnt(4)" ::: "memory");
;       else asm volatile("s_waitcnt vmcnt(0)" ::: "memory");
;       asm volatile("s_waitcnt lgkmcnt(0)" ::: "memory");
;       __builtin_amdgcn_s_barrier();
;       if (ri + 3 < 8) issue(ri + 3);
	v_lshl_add_u64 v[0:1], s[52:53], 0, v[0:1]
	v_and_b32_e32 v32, 0xf0, v13
	v_add_u32_e32 v13, 0xa000, v3
	v_lshl_add_u64 v[0:1], v[0:1], 0, s[18:19]
	v_readfirstlane_b32 s9, v13
	v_lshl_add_u64 v[0:1], v[0:1], 0, v[32:33]
	s_mov_b32 m0, s9
	v_add_u32_e32 v14, 0xc000, v3
	global_load_lds_dwordx4 v[0:1], off
	v_lshrrev_b32_e32 v0, 4, v2
	v_xor_b32_e32 v13, v0, v2
	v_ashrrev_i32_e32 v0, 3, v2
	v_add_u32_e32 v0, s41, v0
	v_ashrrev_i32_e32 v1, 31, v0
	v_lshlrev_b64 v[0:1], 13, v[0:1]
	v_lshl_add_u64 v[0:1], s[50:51], 0, v[0:1]
	v_lshlrev_b32_e32 v2, 4, v13
	v_lshl_add_u64 v[0:1], v[0:1], 0, s[88:89]
	v_and_b32_e32 v32, 0x70, v2
	v_lshl_add_u64 v[0:1], v[0:1], 0, v[32:33]
	v_readfirstlane_b32 s9, v14
	v_lshl_add_u64 v[0:1], v[0:1], 0, s[78:79]
	s_mov_b32 m0, s9
	v_add_u32_e32 v2, 0xe000, v3
	global_load_lds_dwordx4 v[0:1], off
	v_ashrrev_i32_e32 v0, 3, v12
	v_add_u32_e32 v0, s41, v0
	v_ashrrev_i32_e32 v1, 31, v0
	v_lshlrev_b64 v[0:1], 13, v[0:1]
	v_lshl_add_u64 v[0:1], s[50:51], 0, v[0:1]
	v_lshl_add_u64 v[0:1], v[0:1], 0, s[88:89]
	v_lshl_add_u64 v[0:1], v[0:1], 0, v[32:33]
	v_readfirstlane_b32 s9, v2
	v_lshl_add_u64 v[0:1], v[0:1], 0, s[78:79]
	s_mov_b32 m0, s9
	v_mov_b32_e32 v2, v182
	s_addk_i32 s40, 0x80
	global_load_lds_dwordx4 v[0:1], off
	s_add_u32 s92, s82, s40
	v_ashrrev_i32_e32 v0, 4, v2
	s_addc_u32 s93, s83, 0
	v_ashrrev_i32_e32 v1, 31, v0
	v_xor_b32_e32 v13, v0, v2
	v_lshl_add_u64 v[0:1], s[92:93], 0, v[0:1]
	v_lshlrev_b32_e32 v3, 4, v2
	v_lshlrev_b64 v[0:1], 11, v[0:1]
	v_add_u32_e32 v12, 0x10000, v3
	v_lshl_add_u64 v[0:1], s[52:53], 0, v[0:1]
	v_lshlrev_b32_e32 v13, 4, v13
	v_lshl_add_u64 v[0:1], v[0:1], 0, s[18:19]
	v_and_b32_e32 v32, 0xf0, v13
	v_readfirstlane_b32 s9, v12
	v_lshl_add_u64 v[0:1], v[0:1], 0, v[32:33]
	s_mov_b32 m0, s9
	v_add_u32_e32 v12, 0x200, v2
	global_load_lds_dwordx4 v[0:1], off
	v_ashrrev_i32_e32 v0, 4, v12
	v_ashrrev_i32_e32 v1, 31, v0
	v_xor_b32_e32 v13, v0, v2
	v_lshl_add_u64 v[0:1], s[92:93], 0, v[0:1]
	v_lshlrev_b64 v[0:1], 11, v[0:1]
	v_lshlrev_b32_e32 v13, 4, v13
	v_lshl_add_u64 v[0:1], s[52:53], 0, v[0:1]
	v_and_b32_e32 v32, 0xf0, v13
	v_add_u32_e32 v13, 0x12000, v3
	v_lshl_add_u64 v[0:1], v[0:1], 0, s[18:19]
	v_readfirstlane_b32 s9, v13
	v_lshl_add_u64 v[0:1], v[0:1], 0, v[32:33]
	s_mov_b32 m0, s9
	v_add_u32_e32 v14, 0x14000, v3
	global_load_lds_dwordx4 v[0:1], off
	v_lshrrev_b32_e32 v0, 4, v2
	v_xor_b32_e32 v13, v0, v2
	v_ashrrev_i32_e32 v0, 3, v2
	v_add_u32_e32 v0, s41, v0
	v_ashrrev_i32_e32 v1, 31, v0
	v_lshlrev_b64 v[0:1], 13, v[0:1]
	v_lshl_add_u64 v[0:1], s[50:51], 0, v[0:1]
	v_lshlrev_b32_e32 v2, 4, v13
	v_lshl_add_u64 v[0:1], v[0:1], 0, s[88:89]
	v_and_b32_e32 v32, 0x70, v2
	v_lshl_add_u64 v[0:1], v[0:1], 0, v[32:33]
	v_readfirstlane_b32 s9, v14
	v_lshl_add_u64 v[0:1], v[0:1], 0, s[80:81]
	s_mov_b32 m0, s9
	v_add_u32_e32 v2, 0x16000, v3
	global_load_lds_dwordx4 v[0:1], off
	v_ashrrev_i32_e32 v0, 3, v12
	v_add_u32_e32 v0, s41, v0
	v_ashrrev_i32_e32 v1, 31, v0
	v_lshlrev_b64 v[0:1], 13, v[0:1]
	v_lshl_add_u64 v[0:1], s[50:51], 0, v[0:1]
	v_lshl_add_u64 v[0:1], v[0:1], 0, s[88:89]
	v_lshl_add_u64 v[0:1], v[0:1], 0, v[32:33]
	v_readfirstlane_b32 s9, v2
	v_lshl_add_u64 v[0:1], v[0:1], 0, s[80:81]
	s_mov_b32 m0, s9
	s_add_u32 s88, s52, s18
	global_load_lds_dwordx4 v[0:1], off
	s_addc_u32 s89, s53, 0
	s_or_b32 s7, s8, s7
	s_add_u32 s8, s82, s90
	s_addc_u32 s9, s83, s91
	s_add_u32 s90, s8, 0xc0
	v_mov_b32_e32 v0, 0
	s_addc_u32 s91, s9, 0
	s_mov_b32 s18, 0x18000
	s_mov_b32 s8, 0
	s_mov_b32 s9, 0
	v_mov_b32_e32 v1, v0
	v_mov_b32_e32 v2, v0
	v_mov_b32_e32 v3, v0
	v_mov_b32_e32 v12, v0
	v_mov_b32_e32 v13, v0
	v_mov_b32_e32 v14, v0
	v_mov_b32_e32 v15, v0
	v_mov_b32_e32 v16, v0
	v_mov_b32_e32 v17, v0
	v_mov_b32_e32 v18, v0
	v_mov_b32_e32 v19, v0
	v_mov_b32_e32 v20, v0
	v_mov_b32_e32 v21, v0
	v_mov_b32_e32 v22, v0
	v_mov_b32_e32 v23, v0
	v_mov_b32_e32 v88, v0
	v_mov_b32_e32 v87, v0
	s_waitcnt vmcnt(0)
	s_branch .LBB0_238
.LBB0_238:
	s_cmp_gt_u32 s9, 5
	s_mov_b64 s[92:93], -1
	s_cbranch_scc0 .LBB0_244
	s_cmpk_lg_i32 s8, 0x2e8
	s_cbranch_scc0 .LBB0_241
	s_waitcnt vmcnt(0)
	s_mov_b64 s[92:93], 0

; #define MFMA16(a, b, c) __builtin_amdgcn_mfma_f32_16x16x32_bf16((a), (b), (c), 0, 0, 0)
; DI bf16x8 cat8(s16x4 lo, s16x4 hi) { return __builtin_shufflevector(lo, hi, 0, 1, 2, 3, 4, 5, 6, 7); }
; DI void na_phase(const Params& p, const u16* q, const u16* k, const u16* vt, const u16* z, u16* og, unsigned char* smem) {
;     ...
;       const unsigned char* Ks = smem + (ri & 3) * NSTG;
;       const unsigned char* Vs = Ks + 16384;
;       const int ro = rs + ri - r + 7;
; #pragma unroll
;       for (int jj = 0; jj < 2; ++jj) {
;         const int j = jb + jj;
;         const int kcs = min(max(j * 16 - 8, 0), 32);
;         f32x4 sc[2];
; #pragma unroll
;         for (int c2 = 0; c2 < 2; ++c2) {
;           const int row = kcs + c2 * 16 + lq;
;           const bf16x8 kf = *(const bf16x8*)(Ks + row * 256 + (((hh * 4 + lg) ^ (row & 15)) << 4));
;           sc[c2] = MFMA16(kf, qf[jj], (f32x4{0.f, 0.f, 0.f, 0.f}));
;         }
;         const int qcol = j * 16 + lq, win = min(max(qcol - 8, 0), 48);
;         float ps = 0.f;
; #pragma unroll
;         for (int c2 = 0; c2 < 2; ++c2)
; #pragma unroll
;           for (int rr = 0; rr < 4; ++rr) {
;             const int kcol = kcs + c2 * 16 + lg * 4 + rr;
;             const bool valid = (kcol >= win) && (kcol < win + 16);
;             const int co = min(max(kcol - qcol + 15, 0), 30);
;             const float e = valid ? __expf(fminf(sc[c2][rr] + rp[ro * 31 + co], 80.f)) : 0.f;
;             sc[c2][rr] = e;
;             ps += e;
;           }
;         lrun[jj] += ps;
;         const bf16x8 pf = pack8(sc[0], sc[1]);
; #pragma unroll
;         for (int dt = 0; dt < 2; ++dt) {
;           const int vrow = hh * 32 + dt * 16 + lq, vsw = (vrow >> 1) & 7, ch = (kcs >> 3) + (lg >> 1);
;           const unsigned char* vr = Vs + vrow * 128 + (lg & 1) * 8;
;           const s16x4 lo = *(const s16x4*)(vr + ((ch ^ vsw) << 4));
;           const s16x4 hi = *(const s16x4*)(vr + (((ch + 2) ^ vsw) << 4));
;           o[jj][dt] = MFMA16(cat8(lo, hi), pf, o[jj][dt]);
;         }
;       }
.LBB0_248:
	s_add_i32 s40, s18, 0xfffe8000
	s_and_b32 vcc_lo, s40, 0x18000
	v_or_b32_e32 v176, vcc_lo, v41
	v_add3_u32 v177, vcc_lo, v45, v46
	v_add_u32_e32 v176, v176, v42
	ds_read_b128 v[108:111], v176
	ds_read_b128 v[112:115], v176 offset:4096
	ds_read_b128 v[116:119], v177
	ds_read_b128 v[120:123], v177 offset:4096
	v_add_u32_e32 v140, s8, v86
	v_add_u32_e32 v141, s8, v85
	v_add_u32_e32 v142, s8, v84
	v_add_u32_e32 v143, s8, v83
	v_add_u32_e32 v144, s8, v82
	v_add_u32_e32 v145, s8, v81
	v_add_u32_e32 v146, s8, v80
	v_add_u32_e32 v147, s8, v79
	ds_read_b32 v140, v140
	ds_read_b32 v141, v141
	ds_read_b32 v142, v142
	ds_read_b32 v143, v143
	ds_read_b32 v144, v144
	ds_read_b32 v145, v145
	ds_read_b32 v146, v146
	ds_read_b32 v147, v147
	s_waitcnt lgkmcnt(11)
	v_mfma_f32_16x16x32_bf16 v[124:127], v[108:111], v[4:7], 0
	s_waitcnt lgkmcnt(10)
	v_mfma_f32_16x16x32_bf16 v[128:131], v[112:115], v[4:7], 0
	s_waitcnt lgkmcnt(9)
	v_mfma_f32_16x16x32_bf16 v[132:135], v[116:119], v[8:11], 0
	s_waitcnt lgkmcnt(8)
	v_mfma_f32_16x16x32_bf16 v[136:139], v[120:123], v[8:11], 0
	v_add_u32_e32 v148, s8, v78
	v_add_u32_e32 v149, s8, v77
	v_add_u32_e32 v150, s8, v76
	v_add_u32_e32 v151, s8, v75
	v_add_u32_e32 v152, s8, v74
	v_add_u32_e32 v153, s8, v73
	v_add_u32_e32 v154, s8, v72
	v_add_u32_e32 v155, s8, v71
	s_waitcnt lgkmcnt(7)
	ds_read_b32 v148, v148
	ds_read_b32 v149, v149
	ds_read_b32 v150, v150
	ds_read_b32 v151, v151
	ds_read_b32 v152, v152
	ds_read_b32 v153, v153
	ds_read_b32 v154, v154
	ds_read_b32 v155, v155
	s_add_i32 s40, s10, vcc_lo
	v_add3_u32 v172, s40, v39, v40
	v_add_u32_e32 v173, v172, v44
	v_add_u32_e32 v174, v172, v47
	v_add_u32_e32 v175, v172, v48
	v_add_u32_e32 v172, v172, v43
	s_waitcnt lgkmcnt(15)
	s_waitcnt lgkmcnt(8)
	v_add_f32_e32 v124, v124, v140
	v_add_f32_e32 v125, v125, v141
	v_add_f32_e32 v126, v126, v142
	v_add_f32_e32 v127, v127, v143
	v_add_f32_e32 v128, v128, v144
	v_add_f32_e32 v129, v129, v145
	v_add_f32_e32 v130, v130, v146
	v_add_f32_e32 v131, v131, v147
	v_min_f32_e32 v124, 0x42a00000, v124
	v_min_f32_e32 v125, 0x42a00000, v125
	v_min_f32_e32 v126, 0x42a00000, v126
	v_min_f32_e32 v127, 0x42a00000, v127
	v_min_f32_e32 v128, 0x42a00000, v128
	v_min_f32_e32 v129, 0x42a00000, v129
	v_min_f32_e32 v130, 0x42a00000, v130
	v_min_f32_e32 v131, 0x42a00000, v131
	v_mul_f32_e32 v124, 0x3fb8aa3b, v124
	v_mul_f32_e32 v125, 0x3fb8aa3b, v125
	v_mul_f32_e32 v126, 0x3fb8aa3b, v126
	v_mul_f32_e32 v127, 0x3fb8aa3b, v127
	v_mul_f32_e32 v128, 0x3fb8aa3b, v128
	v_mul_f32_e32 v129, 0x3fb8aa3b, v129
	v_mul_f32_e32 v130, 0x3fb8aa3b, v130
	v_mul_f32_e32 v131, 0x3fb8aa3b, v131
	v_exp_f32_e32 v124, v124
	v_exp_f32_e32 v125, v125
	v_exp_f32_e32 v126, v126
	v_exp_f32_e32 v127, v127
	v_exp_f32_e32 v128, v128
	v_exp_f32_e32 v129, v129
	v_exp_f32_e32 v130, v130
	v_exp_f32_e32 v131, v131
	v_cndmask_b32_e64 v124, 0, v124, s[24:25]
	v_cndmask_b32_e64 v125, 0, v125, s[26:27]
	v_cndmask_b32_e64 v126, 0, v126, s[28:29]
	v_cndmask_b32_e64 v127, 0, v127, s[30:31]
	v_cndmask_b32_e64 v128, 0, v128, s[54:55]
	v_cndmask_b32_e64 v129, 0, v129, s[56:57]
	v_cndmask_b32_e64 v130, 0, v130, s[58:59]
	v_cndmask_b32_e64 v131, 0, v131, s[60:61]
	ds_read_b64 v[156:157], v172 offset:16384
	ds_read_b64 v[158:159], v173 offset:16384
	ds_read_b64 v[160:161], v172 offset:18432
	ds_read_b64 v[162:163], v173 offset:18432
	v_add_f32_e32 v192, v124, v125
	v_add_f32_e32 v193, v126, v127
	v_add_f32_e32 v194, v128, v129
	v_add_f32_e32 v195, v130, v131
	v_cvt_pk_bf16_f32 v184, v124, v125
	v_cvt_pk_bf16_f32 v185, v126, v127
	v_cvt_pk_bf16_f32 v186, v128, v129
	v_cvt_pk_bf16_f32 v187, v130, v131
	v_add_f32_e32 v192, v192, v193
	v_add_f32_e32 v194, v194, v195
	v_add_f32_e32 v192, v192, v194
	v_add_f32_e32 v88, v88, v192
	s_waitcnt lgkmcnt(2)
	v_mfma_f32_16x16x32_bf16 v[20:23], v[156:159], v[184:187], v[20:23]
	s_waitcnt lgkmcnt(0)
	v_mfma_f32_16x16x32_bf16 v[16:19], v[160:163], v[184:187], v[16:19]
	ds_read_b64 v[164:165], v174 offset:16384
	ds_read_b64 v[166:167], v175 offset:16384
	ds_read_b64 v[168:169], v174 offset:18432
	ds_read_b64 v[170:171], v175 offset:18432
	v_add_f32_e32 v132, v132, v148
	v_add_f32_e32 v133, v133, v149
	v_add_f32_e32 v134, v134, v150
	v_add_f32_e32 v135, v135, v151
	v_add_f32_e32 v136, v136, v152
	v_add_f32_e32 v137, v137, v153
	v_add_f32_e32 v138, v138, v154
	v_add_f32_e32 v139, v139, v155
	v_min_f32_e32 v132, 0x42a00000, v132
	v_min_f32_e32 v133, 0x42a00000, v133
	v_min_f32_e32 v134, 0x42a00000, v134
	v_min_f32_e32 v135, 0x42a00000, v135
	v_min_f32_e32 v136, 0x42a00000, v136
	v_min_f32_e32 v137, 0x42a00000, v137
	v_min_f32_e32 v138, 0x42a00000, v138
	v_min_f32_e32 v139, 0x42a00000, v139
	v_mul_f32_e32 v132, 0x3fb8aa3b, v132
	v_mul_f32_e32 v133, 0x3fb8aa3b, v133
	v_mul_f32_e32 v134, 0x3fb8aa3b, v134
	v_mul_f32_e32 v135, 0x3fb8aa3b, v135
	v_mul_f32_e32 v136, 0x3fb8aa3b, v136
	v_mul_f32_e32 v137, 0x3fb8aa3b, v137
	v_mul_f32_e32 v138, 0x3fb8aa3b, v138
	v_mul_f32_e32 v139, 0x3fb8aa3b, v139
	v_exp_f32_e32 v132, v132
	v_exp_f32_e32 v133, v133
	v_exp_f32_e32 v134, v134
	v_exp_f32_e32 v135, v135
	v_exp_f32_e32 v136, v136
	v_exp_f32_e32 v137, v137
	v_exp_f32_e32 v138, v138
	v_exp_f32_e32 v139, v139
	v_cndmask_b32_e64 v132, 0, v132, s[62:63]
	v_cndmask_b32_e64 v133, 0, v133, s[64:65]
	v_cndmask_b32_e64 v134, 0, v134, s[66:67]
	v_cndmask_b32_e64 v135, 0, v135, s[68:69]
	v_cndmask_b32_e64 v136, 0, v136, s[70:71]
	v_cndmask_b32_e64 v137, 0, v137, s[72:73]
	v_cndmask_b32_e64 v138, 0, v138, s[74:75]
	v_cndmask_b32_e64 v139, 0, v139, s[76:77]
	v_add_f32_e32 v192, v132, v133
	v_add_f32_e32 v193, v134, v135
	v_add_f32_e32 v194, v136, v137
	v_add_f32_e32 v195, v138, v139
	v_cvt_pk_bf16_f32 v188, v132, v133
	v_cvt_pk_bf16_f32 v189, v134, v135
	v_cvt_pk_bf16_f32 v190, v136, v137
	v_cvt_pk_bf16_f32 v191, v138, v139
	v_add_f32_e32 v192, v192, v193
	v_add_f32_e32 v194, v194, v195
	v_add_f32_e32 v192, v192, v194
	v_add_f32_e32 v87, v87, v192
	s_waitcnt lgkmcnt(2)
	v_mfma_f32_16x16x32_bf16 v[12:15], v[164:167], v[188:191], v[12:15]
	s_waitcnt lgkmcnt(0)
	v_mfma_f32_16x16x32_bf16 v[0:3], v[168:171], v[188:191], v[0:3]
	s_add_i32 s9, s9, 1
	s_add_u32 s84, s84, 0x80
	s_addc_u32 s85, s85, 0
	s_add_u32 s90, s90, 64
	s_addc_u32 s91, s91, 0
	s_add_i32 s18, s18, 0x8000
	s_addk_i32 s8, 0x7c
	s_cmpk_eq_i32 s8, 0x3e0
	s_cbranch_scc1 .LBB0_231
	s_branch .LBB0_238

; DI int tid_opaque() { int t = threadIdx.x; asm volatile("" : "+v"(t)); return t; }
; #define LDS_PTR(p) ((__attribute__((address_space(3))) unsigned*)(p))
; template <int PIPE>
; DI void gemm_loop_g(const u16* __restrict__ Xp, long ldx_l, long ldx_i, long kxs,
;                     const u16* __restrict__ Yp, long ldy_l, long ldy_i, long kys, int K,
;                     f32x4 (&acc)[4][8], unsigned char* smem) {
;   const int t = tid_opaque(), l = t & 63, w = __builtin_amdgcn_readfirstlane(t >> 6), wx = w >> 1, wy = w & 1;
;   const int lrow = t >> 3, gch = (t & 7) ^ ((t >> 4) & 7);
;   const u16* xs = Xp + (long)lrow * ldx_l + gch * 8;
;   const u16* ys = Yp + (long)lrow * ldy_l + gch * 8;
;   const int fsw = (l >> 1) & 7, lg = l >> 4;
;   const unsigned fr0 = (l & 15) * 128 + ((lg ^ fsw) << 4);
;   const unsigned fr1 = (l & 15) * 128 + (((lg + 4) ^ fsw) << 4);
;   const unsigned ub = wx * 8192, vb = 32768 + wy * 16384;
;   const int nk = K >> 6;
;   const int rot = (int)((blockIdx.x >> 3) + (blockIdx.x & 7) * 5) % nk;
;   auto issue = [&](int kt0, int stage) {
;     int kt = kt0 + rot; if (kt >= nk) kt -= nk;
;     unsigned char* sb = smem + stage * 65536 + t * 16;
; #pragma unroll
;     for (int i = 0; i < 4; ++i)
;       __builtin_amdgcn_global_load_lds((const unsigned*)(xs + i * ldx_i + kt * kxs), LDS_PTR(sb + i * 8192), 16, 0, 0);
; #pragma unroll
;     for (int i = 0; i < 4; ++i)
;       __builtin_amdgcn_global_load_lds((const unsigned*)(ys + i * ldy_i + kt * kys), LDS_PTR(sb + 32768 + i * 8192), 16, 0, 0);
;   };
;   __syncthreads();
;   issue(0, 0);
;   asm volatile("s_waitcnt vmcnt(0)" ::: "memory");
;   __syncthreads();
; DI void zero_acc(f32x4 (&acc)[4][8]) {
; #pragma unroll
;   for (int i = 0; i < 4; ++i)
; #pragma unroll
;     for (int j = 0; j < 8; ++j) acc[i][j] = f32x4{0.f, 0.f, 0.f, 0.f};
; }
.LBB0_294:
	s_lshl_b32 s6, s11, 9
	s_and_b32 s6, s6, 0xfffff800
	s_or_b32 s28, s6, s30
	s_lshl_b32 s6, s11, 8
	s_and_b32 s6, s6, 0x300
	s_lshl_b32 s7, s6, 11
	s_waitcnt lgkmcnt(0)
	s_add_u32 s8, s14, s7
	s_addc_u32 s9, s15, 0
	s_ashr_i32 s29, s28, 31
	v_mov_b32_e32 v4, v182
	s_lshl_b64 s[40:41], s[28:29], 11
	s_add_u32 s40, s36, s40
	v_ashrrev_i32_e32 v0, 3, v4
	v_lshrrev_b32_e32 v5, 4, v4
	v_xor_b32_e32 v6, v5, v4
	v_ashrrev_i32_e32 v1, 31, v0
	s_addc_u32 s41, s37, s41
	v_lshlrev_b64 v[0:1], 11, v[0:1]
	v_lshlrev_b32_e32 v6, 4, v6
	v_lshl_add_u64 v[2:3], s[8:9], 0, v[0:1]
	v_and_b32_e32 v128, 0x70, v6
	v_lshl_add_u64 v[0:1], s[40:41], 0, v[0:1]
	v_lshl_add_u64 v[130:131], v[2:3], 0, v[128:129]
	v_lshl_add_u64 v[132:133], v[0:1], 0, v[128:129]
	v_lshlrev_b32_e32 v128, 4, v4
	v_add_u32_e32 v2, 0x2000, v128
	v_readfirstlane_b32 s7, v128
	v_lshl_add_u64 v[0:1], v[130:131], 0, s[16:17]
	s_mov_b32 m0, s7
	v_lshl_add_u64 v[134:135], v[130:131], 0, s[18:19]
	v_readfirstlane_b32 s7, v2
	v_add_u32_e32 v2, 0x4000, v128
	s_barrier
	global_load_lds_dwordx4 v[0:1], off
	v_lshl_add_u64 v[0:1], v[134:135], 0, s[16:17]
	s_mov_b32 m0, s7
	v_lshl_add_u64 v[136:137], v[130:131], 0, s[24:25]
	v_readfirstlane_b32 s7, v2
	v_add_u32_e32 v2, 0x6000, v128
	global_load_lds_dwordx4 v[0:1], off
	v_lshl_add_u64 v[0:1], v[136:137], 0, s[16:17]
	s_mov_b32 m0, s7
	v_lshl_add_u64 v[138:139], v[130:131], 0, s[26:27]
	v_readfirstlane_b32 s7, v2
	v_add_u32_e32 v2, 0x8000, v128
	global_load_lds_dwordx4 v[0:1], off
	v_lshl_add_u64 v[0:1], v[138:139], 0, s[16:17]
	s_mov_b32 m0, s7
	v_readfirstlane_b32 s7, v2
	v_add_u32_e32 v2, 0xa000, v128
	global_load_lds_dwordx4 v[0:1], off
	v_lshl_add_u64 v[0:1], v[132:133], 0, s[16:17]
	s_mov_b32 m0, s7
	v_lshl_add_u64 v[140:141], v[132:133], 0, s[18:19]
	v_readfirstlane_b32 s7, v2
	v_add_u32_e32 v2, 0xc000, v128
	global_load_lds_dwordx4 v[0:1], off
	v_lshl_add_u64 v[0:1], v[140:141], 0, s[16:17]
	s_mov_b32 m0, s7
	v_lshl_add_u64 v[142:143], v[132:133], 0, s[24:25]
	v_readfirstlane_b32 s7, v2
	v_add_u32_e32 v2, 0xe000, v128
	global_load_lds_dwordx4 v[0:1], off
	v_lshl_add_u64 v[0:1], v[142:143], 0, s[16:17]
	s_mov_b32 m0, s7
	v_lshl_add_u64 v[144:145], v[132:133], 0, s[26:27]
	v_readfirstlane_b32 s7, v2
	global_load_lds_dwordx4 v[0:1], off
	v_lshl_add_u64 v[0:1], v[144:145], 0, s[16:17]
	s_mov_b32 m0, s7
	v_lshlrev_b32_e32 v2, 7, v4
	global_load_lds_dwordx4 v[0:1], off
	v_bfe_u32 v0, v4, 4, 2
	v_bfe_u32 v1, v4, 1, 3
	v_readfirstlane_b32 s29, v4
	s_nop 0
	v_bitop3_b32 v0, v0, v1, 4 bitop3:0x36
	v_and_b32_e32 v2, 0x780, v2
	s_lshl_b32 s7, s29, 8
	s_lshl_b32 s8, s29, 6
	v_lshl_or_b32 v148, v0, 4, v2
	v_bitop3_b32 v0, v5, v1, 3 bitop3:0x6c
	s_and_b32 s7, s7, 0x4000
	s_and_b32 s29, s8, 0xffffe000
	v_lshl_or_b32 v149, v0, 4, v2
	s_mov_b32 s31, 0x10000
	s_mov_b32 s33, 0
	v_mov_b32_e32 v12, 0
	v_mov_b32_e32 v13, v129
	v_mov_b32_e32 v14, v129
	v_mov_b32_e32 v15, v129
	v_mov_b32_e32 v4, 0
	v_mov_b32_e32 v5, v129
	v_mov_b32_e32 v6, v129
	v_mov_b32_e32 v7, v129
	v_mov_b32_e32 v24, 0
	v_mov_b32_e32 v25, v129
	v_mov_b32_e32 v26, v129
	v_mov_b32_e32 v27, v129
	v_mov_b32_e32 v40, 0
	v_mov_b32_e32 v41, v129
	v_mov_b32_e32 v42, v129
	v_mov_b32_e32 v43, v129
	v_mov_b32_e32 v56, 0
	v_mov_b32_e32 v57, v129
	v_mov_b32_e32 v58, v129
	v_mov_b32_e32 v59, v129
	v_mov_b32_e32 v72, 0
	v_mov_b32_e32 v73, v129
	v_mov_b32_e32 v74, v129
	v_mov_b32_e32 v75, v129
	v_mov_b32_e32 v88, 0
	v_mov_b32_e32 v89, v129
	v_mov_b32_e32 v90, v129
	v_mov_b32_e32 v91, v129
	v_mov_b32_e32 v104, 0
	v_mov_b32_e32 v105, v129
	v_mov_b32_e32 v106, v129
	v_mov_b32_e32 v107, v129
	v_mov_b32_e32 v0, 0
	v_mov_b32_e32 v1, v129
	v_mov_b32_e32 v2, v129
	v_mov_b32_e32 v3, v129
	v_mov_b32_e32 v20, 0
	v_mov_b32_e32 v21, v129
	v_mov_b32_e32 v22, v129
	v_mov_b32_e32 v23, v129
	v_mov_b32_e32 v36, 0
	v_mov_b32_e32 v37, v129
	v_mov_b32_e32 v38, v129
	v_mov_b32_e32 v39, v129
	v_mov_b32_e32 v52, 0
	v_mov_b32_e32 v53, v129
	v_mov_b32_e32 v54, v129
	v_mov_b32_e32 v55, v129
	v_mov_b32_e32 v68, 0
	v_mov_b32_e32 v69, v129
	v_mov_b32_e32 v70, v129
	v_mov_b32_e32 v71, v129
	v_mov_b32_e32 v84, 0
	v_mov_b32_e32 v85, v129
	v_mov_b32_e32 v86, v129
	v_mov_b32_e32 v87, v129
	v_mov_b32_e32 v100, 0
	v_mov_b32_e32 v101, v129
	v_mov_b32_e32 v102, v129
	v_mov_b32_e32 v103, v129
	v_mov_b32_e32 v116, 0
	v_mov_b32_e32 v117, v129
	v_mov_b32_e32 v118, v129
	v_mov_b32_e32 v119, v129
	v_mov_b32_e32 v8, 0
	v_mov_b32_e32 v9, v129
	v_mov_b32_e32 v10, v129
	v_mov_b32_e32 v11, v129
	v_mov_b32_e32 v28, 0
	v_mov_b32_e32 v29, v129
	v_mov_b32_e32 v30, v129
	v_mov_b32_e32 v31, v129
	v_mov_b32_e32 v44, 0
	v_mov_b32_e32 v45, v129
	v_mov_b32_e32 v46, v129
	v_mov_b32_e32 v47, v129
	v_mov_b32_e32 v60, 0
	v_mov_b32_e32 v61, v129
	v_mov_b32_e32 v62, v129
	v_mov_b32_e32 v63, v129
	v_mov_b32_e32 v76, 0
	v_mov_b32_e32 v77, v129
	v_mov_b32_e32 v78, v129
	v_mov_b32_e32 v79, v129
	v_mov_b32_e32 v92, 0
	v_mov_b32_e32 v93, v129
	v_mov_b32_e32 v94, v129
	v_mov_b32_e32 v95, v129
	v_mov_b32_e32 v108, 0
	v_mov_b32_e32 v109, v129
	v_mov_b32_e32 v110, v129
	v_mov_b32_e32 v111, v129
	v_mov_b32_e32 v120, 0
	v_mov_b32_e32 v121, v129
	v_mov_b32_e32 v122, v129
	v_mov_b32_e32 v123, v129
	v_mov_b32_e32 v16, 0
	v_mov_b32_e32 v17, v129
	v_mov_b32_e32 v18, v129
	v_mov_b32_e32 v19, v129
	v_mov_b32_e32 v32, 0
	v_mov_b32_e32 v33, v129
	v_mov_b32_e32 v34, v129
	v_mov_b32_e32 v35, v129
	v_mov_b32_e32 v48, 0
	v_mov_b32_e32 v49, v129
	v_mov_b32_e32 v50, v129
	v_mov_b32_e32 v51, v129
	v_mov_b32_e32 v64, 0
	v_mov_b32_e32 v65, v129
	v_mov_b32_e32 v66, v129
	v_mov_b32_e32 v67, v129
	v_mov_b32_e32 v80, 0
	v_mov_b32_e32 v81, v129
	v_mov_b32_e32 v82, v129
	v_mov_b32_e32 v83, v129
	v_mov_b32_e32 v96, 0
	v_mov_b32_e32 v97, v129
	v_mov_b32_e32 v98, v129
	v_mov_b32_e32 v99, v129
	v_mov_b32_e32 v112, 0
	v_mov_b32_e32 v113, v129
	v_mov_b32_e32 v114, v129
	v_mov_b32_e32 v115, v129
	v_mov_b32_e32 v124, 0
	v_mov_b32_e32 v125, v129
	v_mov_b32_e32 v126, v129
	v_mov_b32_e32 v127, v129
	s_waitcnt vmcnt(0) lgkmcnt(0)
	s_barrier
	s_branch .LBB0_296

; DI int tid_opaque() { int t = threadIdx.x; asm volatile("" : "+v"(t)); return t; }
; #define LDS_PTR(p) ((__attribute__((address_space(3))) unsigned*)(p))
; template <int PIPE>
; DI void gemm_loop_g(const u16* __restrict__ Xp, long ldx_l, long ldx_i, long kxs,
;                     const u16* __restrict__ Yp, long ldy_l, long ldy_i, long kys, int K,
;                     f32x4 (&acc)[4][8], unsigned char* smem) {
;   const int t = tid_opaque(), l = t & 63, w = __builtin_amdgcn_readfirstlane(t >> 6), wx = w >> 1, wy = w & 1;
;   const int lrow = t >> 3, gch = (t & 7) ^ ((t >> 4) & 7);
;   const u16* xs = Xp + (long)lrow * ldx_l + gch * 8;
;   const u16* ys = Yp + (long)lrow * ldy_l + gch * 8;
;   const int fsw = (l >> 1) & 7, lg = l >> 4;
;   const unsigned fr0 = (l & 15) * 128 + ((lg ^ fsw) << 4);
;   const unsigned fr1 = (l & 15) * 128 + (((lg + 4) ^ fsw) << 4);
;   const unsigned ub = wx * 8192, vb = 32768 + wy * 16384;
;   const int nk = K >> 6;
;   const int rot = (int)((blockIdx.x >> 3) + (blockIdx.x & 7) * 5) % nk;
;   auto issue = [&](int kt0, int stage) {
;     int kt = kt0 + rot; if (kt >= nk) kt -= nk;
;     unsigned char* sb = smem + stage * 65536 + t * 16;
; #pragma unroll
;     for (int i = 0; i < 4; ++i)
;       __builtin_amdgcn_global_load_lds((const unsigned*)(xs + i * ldx_i + kt * kxs), LDS_PTR(sb + i * 8192), 16, 0, 0);
; #pragma unroll
;     for (int i = 0; i < 4; ++i)
;       __builtin_amdgcn_global_load_lds((const unsigned*)(ys + i * ldy_i + kt * kys), LDS_PTR(sb + 32768 + i * 8192), 16, 0, 0);
;   };
;   __syncthreads();
;   issue(0, 0);
;   asm volatile("s_waitcnt vmcnt(0)" ::: "memory");
;   __syncthreads();
; template <int MODE>
; DI void gemm_phase(const Params& p, const GP& g, unsigned char* smem) {
;     ...
;     if (MODE == M_PLE) {
;       const u16* pb = (const u16*)g.d1;
;       gemm_loop(g.W2 + (long)n0 * 256, 256, pb + (long)m0 * 256, 256, 256, acc, smem);
.LBB0_314:
	s_lshl_b32 s6, s69, 9
	s_and_b32 s6, s6, 0xfffff800
	s_or_b32 s12, s6, s66
	s_lshl_b32 s6, s69, 8
	s_and_b32 s6, s6, 0x300
	s_lshl_b32 s7, s6, 9
	s_add_u32 s8, s64, s7
	v_mov_b32_e32 v6, v182
	s_addc_u32 s9, s65, 0
	s_ashr_i32 s13, s12, 31
	s_lshl_b64 s[10:11], s[12:13], 9
	v_ashrrev_i32_e32 v2, 3, v6
	v_lshrrev_b32_e32 v7, 4, v6
	v_xor_b32_e32 v8, v7, v6
	v_ashrrev_i32_e32 v3, 31, v2
	s_waitcnt lgkmcnt(0)
	v_lshl_add_u64 v[0:1], v[128:129], 0, s[10:11]
	v_lshlrev_b64 v[2:3], 9, v[2:3]
	v_lshlrev_b32_e32 v8, 4, v8
	v_lshl_add_u64 v[4:5], s[8:9], 0, v[2:3]
	v_and_b32_e32 v130, 0x70, v8
	v_lshl_add_u64 v[0:1], v[0:1], 0, v[2:3]
	v_lshl_add_u64 v[132:133], v[4:5], 0, v[130:131]
	v_lshl_add_u64 v[134:135], v[0:1], 0, v[130:131]
	v_lshlrev_b32_e32 v130, 4, v6
	v_add_u32_e32 v2, 0x2000, v130
	v_readfirstlane_b32 s7, v130
	v_lshl_add_u64 v[0:1], v[132:133], 0, s[18:19]
	s_mov_b32 m0, s7
	v_lshl_add_u64 v[136:137], v[132:133], 0, s[24:25]
	v_readfirstlane_b32 s7, v2
	v_add_u32_e32 v2, 0x4000, v130
	s_barrier
	global_load_lds_dwordx4 v[0:1], off
	v_lshl_add_u64 v[0:1], v[136:137], 0, s[18:19]
	s_mov_b32 m0, s7
	v_lshl_add_u64 v[138:139], v[132:133], 0, s[26:27]
	v_readfirstlane_b32 s7, v2
	v_add_u32_e32 v2, 0x6000, v130
	global_load_lds_dwordx4 v[0:1], off
	v_lshl_add_u64 v[0:1], v[138:139], 0, s[18:19]
	s_mov_b32 m0, s7
	v_lshl_add_u64 v[140:141], v[132:133], 0, s[28:29]
	v_readfirstlane_b32 s7, v2
	v_add_u32_e32 v2, 0x8000, v130
	global_load_lds_dwordx4 v[0:1], off
	v_lshl_add_u64 v[0:1], v[140:141], 0, s[18:19]
	s_mov_b32 m0, s7
	v_readfirstlane_b32 s7, v2
	v_add_u32_e32 v2, 0xa000, v130
	global_load_lds_dwordx4 v[0:1], off
	v_lshl_add_u64 v[0:1], v[134:135], 0, s[18:19]
	s_mov_b32 m0, s7
	v_lshl_add_u64 v[142:143], v[134:135], 0, s[24:25]
	v_readfirstlane_b32 s7, v2
	v_add_u32_e32 v2, 0xc000, v130
	global_load_lds_dwordx4 v[0:1], off
	v_lshl_add_u64 v[0:1], v[142:143], 0, s[18:19]
	s_mov_b32 m0, s7
	v_lshl_add_u64 v[144:145], v[134:135], 0, s[26:27]
	v_readfirstlane_b32 s7, v2
	v_add_u32_e32 v2, 0xe000, v130
	global_load_lds_dwordx4 v[0:1], off
	v_lshl_add_u64 v[0:1], v[144:145], 0, s[18:19]
	s_mov_b32 m0, s7
	v_lshl_add_u64 v[146:147], v[134:135], 0, s[28:29]
	v_readfirstlane_b32 s7, v2
	global_load_lds_dwordx4 v[0:1], off
	v_lshl_add_u64 v[0:1], v[146:147], 0, s[18:19]
	s_mov_b32 m0, s7
	v_lshlrev_b32_e32 v2, 7, v6
	global_load_lds_dwordx4 v[0:1], off
	v_bfe_u32 v0, v6, 4, 2
	v_bfe_u32 v1, v6, 1, 3
	v_readfirstlane_b32 s10, v6
	s_nop 0
	v_bitop3_b32 v0, v0, v1, 4 bitop3:0x36
	v_and_b32_e32 v2, 0x780, v2
	s_lshl_b32 s7, s10, 8
	s_lshl_b32 s8, s10, 6
	v_lshl_or_b32 v148, v0, 4, v2
	v_bitop3_b32 v0, v7, v1, 3 bitop3:0x6c
	s_and_b32 s7, s7, 0x4000
	s_and_b32 s10, s8, 0xffffe000
	v_lshl_or_b32 v149, v0, 4, v2
	s_mov_b32 s11, 0x10000
	s_mov_b32 s33, 0
	v_mov_b32_e32 v40, 0
	v_mov_b32_e32 v41, v131
	v_mov_b32_e32 v42, v131
	v_mov_b32_e32 v43, v131
	v_mov_b32_e32 v0, 0
	v_mov_b32_e32 v1, v131
	v_mov_b32_e32 v2, v131
	v_mov_b32_e32 v3, v131
	v_mov_b32_e32 v8, 0
	v_mov_b32_e32 v9, v131
	v_mov_b32_e32 v10, v131
	v_mov_b32_e32 v11, v131
	v_mov_b32_e32 v20, 0
	v_mov_b32_e32 v21, v131
	v_mov_b32_e32 v22, v131
	v_mov_b32_e32 v23, v131
	v_mov_b32_e32 v36, 0
	v_mov_b32_e32 v37, v131
	v_mov_b32_e32 v38, v131
	v_mov_b32_e32 v39, v131
	v_mov_b32_e32 v56, 0
	v_mov_b32_e32 v57, v131
	v_mov_b32_e32 v58, v131
	v_mov_b32_e32 v59, v131
	v_mov_b32_e32 v72, 0
	v_mov_b32_e32 v73, v131
	v_mov_b32_e32 v74, v131
	v_mov_b32_e32 v75, v131
	v_mov_b32_e32 v96, 0
	v_mov_b32_e32 v97, v131
	v_mov_b32_e32 v98, v131
	v_mov_b32_e32 v99, v131
	v_mov_b32_e32 v4, 0
	v_mov_b32_e32 v5, v131
	v_mov_b32_e32 v6, v131
	v_mov_b32_e32 v7, v131
	v_mov_b32_e32 v12, 0
	v_mov_b32_e32 v13, v131
	v_mov_b32_e32 v14, v131
	v_mov_b32_e32 v15, v131
	v_mov_b32_e32 v24, 0
	v_mov_b32_e32 v25, v131
	v_mov_b32_e32 v26, v131
	v_mov_b32_e32 v27, v131
	v_mov_b32_e32 v44, 0
	v_mov_b32_e32 v45, v131
	v_mov_b32_e32 v46, v131
	v_mov_b32_e32 v47, v131
	v_mov_b32_e32 v64, 0
	v_mov_b32_e32 v65, v131
	v_mov_b32_e32 v66, v131
	v_mov_b32_e32 v67, v131
	v_mov_b32_e32 v76, 0
	v_mov_b32_e32 v77, v131
	v_mov_b32_e32 v78, v131
	v_mov_b32_e32 v79, v131
	v_mov_b32_e32 v88, 0
	v_mov_b32_e32 v89, v131
	v_mov_b32_e32 v90, v131
	v_mov_b32_e32 v91, v131
	v_mov_b32_e32 v112, 0
	v_mov_b32_e32 v113, v131
	v_mov_b32_e32 v114, v131
	v_mov_b32_e32 v115, v131
	v_mov_b32_e32 v16, 0
	v_mov_b32_e32 v17, v131
	v_mov_b32_e32 v18, v131
	v_mov_b32_e32 v19, v131
	v_mov_b32_e32 v28, 0
	v_mov_b32_e32 v29, v131
	v_mov_b32_e32 v30, v131
	v_mov_b32_e32 v31, v131
	v_mov_b32_e32 v48, 0
	v_mov_b32_e32 v49, v131
	v_mov_b32_e32 v50, v131
	v_mov_b32_e32 v51, v131
	v_mov_b32_e32 v60, 0
	v_mov_b32_e32 v61, v131
	v_mov_b32_e32 v62, v131
	v_mov_b32_e32 v63, v131
	v_mov_b32_e32 v80, 0
	v_mov_b32_e32 v81, v131
	v_mov_b32_e32 v82, v131
	v_mov_b32_e32 v83, v131
	v_mov_b32_e32 v92, 0
	v_mov_b32_e32 v93, v131
	v_mov_b32_e32 v94, v131
	v_mov_b32_e32 v95, v131
	v_mov_b32_e32 v108, 0
	v_mov_b32_e32 v109, v131
	v_mov_b32_e32 v110, v131
	v_mov_b32_e32 v111, v131
	v_mov_b32_e32 v116, 0
	v_mov_b32_e32 v117, v131
	v_mov_b32_e32 v118, v131
	v_mov_b32_e32 v119, v131
	v_mov_b32_e32 v32, 0
	v_mov_b32_e32 v33, v131
	v_mov_b32_e32 v34, v131
	v_mov_b32_e32 v35, v131
	v_mov_b32_e32 v52, 0
	v_mov_b32_e32 v53, v131
	v_mov_b32_e32 v54, v131
	v_mov_b32_e32 v55, v131
	v_mov_b32_e32 v68, 0
	v_mov_b32_e32 v69, v131
	v_mov_b32_e32 v70, v131
	v_mov_b32_e32 v71, v131
	v_mov_b32_e32 v84, 0
	v_mov_b32_e32 v85, v131
	v_mov_b32_e32 v86, v131
	v_mov_b32_e32 v87, v131
	v_mov_b32_e32 v100, 0
	v_mov_b32_e32 v101, v131
	v_mov_b32_e32 v102, v131
	v_mov_b32_e32 v103, v131
	v_mov_b32_e32 v104, 0
	v_mov_b32_e32 v105, v131
	v_mov_b32_e32 v106, v131
	v_mov_b32_e32 v107, v131
	v_mov_b32_e32 v120, 0
	v_mov_b32_e32 v121, v131
	v_mov_b32_e32 v122, v131
	v_mov_b32_e32 v123, v131
	v_mov_b32_e32 v124, 0
	v_mov_b32_e32 v125, v131
	v_mov_b32_e32 v126, v131
	v_mov_b32_e32 v127, v131
	s_waitcnt vmcnt(0) lgkmcnt(0)
	s_barrier
	s_branch .LBB0_316

; DI int tid_opaque() { int t = threadIdx.x; asm volatile("" : "+v"(t)); return t; }
; DI u32x2 pack4(float a, float b, float c, float d) { u32x2 r; r.x = pack2(a, b); r.y = pack2(c, d); return r; }
; #define LDS_PTR(p) ((__attribute__((address_space(3))) unsigned*)(p))
; #define EPI_END if (i == 3 && (j & 3) == 3) __builtin_amdgcn_sched_barrier(0); }
; template <int PIPE>
; DI void gemm_loop_g(const u16* __restrict__ Xp, long ldx_l, long ldx_i, long kxs,
;                     const u16* __restrict__ Yp, long ldy_l, long ldy_i, long kys, int K,
;                     f32x4 (&acc)[4][8], unsigned char* smem) {
;   const int t = tid_opaque(), l = t & 63, w = __builtin_amdgcn_readfirstlane(t >> 6), wx = w >> 1, wy = w & 1;
;   const int lrow = t >> 3, gch = (t & 7) ^ ((t >> 4) & 7);
;   const u16* xs = Xp + (long)lrow * ldx_l + gch * 8;
;   const u16* ys = Yp + (long)lrow * ldy_l + gch * 8;
;   const int fsw = (l >> 1) & 7, lg = l >> 4;
;   const unsigned fr0 = (l & 15) * 128 + ((lg ^ fsw) << 4);
;   const unsigned fr1 = (l & 15) * 128 + (((lg + 4) ^ fsw) << 4);
;   const unsigned ub = wx * 8192, vb = 32768 + wy * 16384;
;   const int nk = K >> 6;
;   const int rot = (int)((blockIdx.x >> 3) + (blockIdx.x & 7) * 5) % nk;
;   auto issue = [&](int kt0, int stage) {
;     int kt = kt0 + rot; if (kt >= nk) kt -= nk;
;     unsigned char* sb = smem + stage * 65536 + t * 16;
; #pragma unroll
;     for (int i = 0; i < 4; ++i)
;       __builtin_amdgcn_global_load_lds((const unsigned*)(xs + i * ldx_i + kt * kxs), LDS_PTR(sb + i * 8192), 16, 0, 0);
; #pragma unroll
;     for (int i = 0; i < 4; ++i)
;       __builtin_amdgcn_global_load_lds((const unsigned*)(ys + i * ldy_i + kt * kys), LDS_PTR(sb + 32768 + i * 8192), 16, 0, 0);
;   };
;   __syncthreads();
;   issue(0, 0);
; template <int MODE>
; DI void gemm_phase(const Params& p, const GP& g, unsigned char* smem) {
;     ...
;       u16* xb = (u16*)g.d0;
;       EPI_STD_BEGIN
;         *(u32x2*)(xb + (long)m * 1024 + n4) = pack4(v[0], v[1], v[2], v[3]);
;       EPI_END
;       zero_acc(acc);
.LBB0_318:
	v_or_b32_e32 v160, s12, v185
	v_add_u32_e32 v134, s6, v184
	v_ashrrev_i32_e32 v161, 31, v160
	v_lshlrev_b64 v[164:165], 11, v[160:161]
	v_ashrrev_i32_e32 v135, 31, v134
	v_or_b32_e32 v156, 16, v160
	v_lshl_add_u64 v[132:133], s[36:37], 0, v[164:165]
	v_cvt_pk_bf16_f32 v124, v124, v125
	v_cvt_pk_bf16_f32 v125, v126, v127
	v_lshlrev_b64 v[126:127], 1, v[134:135]
	v_ashrrev_i32_e32 v157, 31, v156
	v_lshl_add_u64 v[132:133], v[132:133], 0, v[126:127]
	v_cvt_pk_bf16_f32 v96, v96, v97
	v_cvt_pk_bf16_f32 v97, v98, v99
	v_lshlrev_b64 v[162:163], 11, v[156:157]
	v_or_b32_e32 v152, 32, v160
	global_store_dwordx2 v[132:133], v[96:97], off offset:96
	v_lshl_add_u64 v[96:97], s[36:37], 0, v[162:163]
	v_ashrrev_i32_e32 v153, 31, v152
	v_lshl_add_u64 v[96:97], v[96:97], 0, v[126:127]
	v_cvt_pk_bf16_f32 v72, v72, v73
	v_cvt_pk_bf16_f32 v73, v74, v75
	v_lshlrev_b64 v[158:159], 11, v[152:153]
	v_or_b32_e32 v148, 48, v160
	global_store_dwordx2 v[96:97], v[72:73], off offset:96
	v_lshl_add_u64 v[72:73], s[36:37], 0, v[158:159]
	v_ashrrev_i32_e32 v149, 31, v148
	v_lshl_add_u64 v[72:73], v[72:73], 0, v[126:127]
	v_cvt_pk_bf16_f32 v56, v56, v57
	v_cvt_pk_bf16_f32 v57, v58, v59
	v_lshlrev_b64 v[154:155], 11, v[148:149]
	global_store_dwordx2 v[72:73], v[56:57], off offset:96
	v_lshl_add_u64 v[56:57], s[36:37], 0, v[154:155]
	v_cvt_pk_bf16_f32 v74, v104, v105
	v_cvt_pk_bf16_f32 v75, v106, v107
	v_cvt_pk_bf16_f32 v58, v100, v101
	v_cvt_pk_bf16_f32 v59, v102, v103
	v_lshl_add_u64 v[56:57], v[56:57], 0, v[126:127]
	v_cvt_pk_bf16_f32 v98, v120, v121
	v_cvt_pk_bf16_f32 v99, v122, v123
	global_store_dwordx2 v[72:73], v[74:75], off
	v_cvt_pk_bf16_f32 v74, v92, v93
	v_cvt_pk_bf16_f32 v75, v94, v95
	global_store_dwordx2 v[56:57], v[58:59], off
	v_cvt_pk_bf16_f32 v58, v80, v81
	v_cvt_pk_bf16_f32 v59, v82, v83
	v_cvt_pk_bf16_f32 v116, v116, v117
	v_cvt_pk_bf16_f32 v117, v118, v119
	v_cvt_pk_bf16_f32 v112, v112, v113
	v_cvt_pk_bf16_f32 v113, v114, v115
	global_store_dwordx2 v[96:97], v[98:99], off
	v_cvt_pk_bf16_f32 v98, v108, v109
	v_cvt_pk_bf16_f32 v99, v110, v111
	v_cvt_pk_bf16_f32 v88, v88, v89
	v_cvt_pk_bf16_f32 v89, v90, v91
	global_store_dwordx2 v[72:73], v[74:75], off offset:32
	v_cvt_pk_bf16_f32 v74, v76, v77
	v_cvt_pk_bf16_f32 v75, v78, v79
	global_store_dwordx2 v[56:57], v[58:59], off offset:32
	v_cvt_pk_bf16_f32 v58, v64, v65
	v_cvt_pk_bf16_f32 v59, v66, v67
	v_cvt_pk_bf16_f32 v36, v36, v37
	v_cvt_pk_bf16_f32 v37, v38, v39
	global_store_dwordx2 v[132:133], v[124:125], off
	global_store_dwordx2 v[132:133], v[116:117], off offset:32
	global_store_dwordx2 v[132:133], v[112:113], off offset:64
	global_store_dwordx2 v[96:97], v[98:99], off offset:32
	global_store_dwordx2 v[96:97], v[88:89], off offset:64
	global_store_dwordx2 v[72:73], v[74:75], off offset:64
	global_store_dwordx2 v[56:57], v[58:59], off offset:64
	global_store_dwordx2 v[56:57], v[36:37], off offset:96
	v_or_b32_e32 v144, 64, v160
	v_ashrrev_i32_e32 v145, 31, v144
	v_lshlrev_b64 v[150:151], 11, v[144:145]
	v_or_b32_e32 v140, 0x50, v160
	v_lshl_add_u64 v[36:37], s[36:37], 0, v[150:151]
	v_ashrrev_i32_e32 v141, 31, v140
	v_lshl_add_u64 v[36:37], v[36:37], 0, v[126:127]
	v_cvt_pk_bf16_f32 v20, v20, v21
	v_cvt_pk_bf16_f32 v21, v22, v23
	v_lshlrev_b64 v[146:147], 11, v[140:141]
	v_or_b32_e32 v136, 0x60, v160
	global_store_dwordx2 v[36:37], v[20:21], off offset:96
	v_lshl_add_u64 v[20:21], s[36:37], 0, v[146:147]
	v_ashrrev_i32_e32 v137, 31, v136
	v_lshl_add_u64 v[20:21], v[20:21], 0, v[126:127]
	v_cvt_pk_bf16_f32 v8, v8, v9
	v_cvt_pk_bf16_f32 v9, v10, v11
	v_lshlrev_b64 v[142:143], 11, v[136:137]
	v_or_b32_e32 v132, 0x70, v160
	global_store_dwordx2 v[20:21], v[8:9], off offset:96
	v_lshl_add_u64 v[8:9], s[36:37], 0, v[142:143]
	v_ashrrev_i32_e32 v133, 31, v132
	v_lshl_add_u64 v[8:9], v[8:9], 0, v[126:127]
	v_cvt_pk_bf16_f32 v0, v0, v1
	v_cvt_pk_bf16_f32 v1, v2, v3
	v_lshlrev_b64 v[138:139], 11, v[132:133]
	global_store_dwordx2 v[8:9], v[0:1], off offset:96
	v_lshl_add_u64 v[0:1], s[36:37], 0, v[138:139]
	v_cvt_pk_bf16_f32 v2, v32, v33
	v_cvt_pk_bf16_f32 v3, v34, v35
	v_lshl_add_u64 v[0:1], v[0:1], 0, v[126:127]
	v_cvt_pk_bf16_f32 v38, v84, v85
	v_cvt_pk_bf16_f32 v39, v86, v87
	v_cvt_pk_bf16_f32 v22, v68, v69
	v_cvt_pk_bf16_f32 v23, v70, v71
	v_cvt_pk_bf16_f32 v10, v52, v53
	v_cvt_pk_bf16_f32 v11, v54, v55
	global_store_dwordx2 v[0:1], v[2:3], off
	v_cvt_pk_bf16_f32 v2, v16, v17
	v_cvt_pk_bf16_f32 v3, v18, v19
	global_store_dwordx2 v[36:37], v[38:39], off
	v_cvt_pk_bf16_f32 v38, v60, v61
	v_cvt_pk_bf16_f32 v39, v62, v63
	global_store_dwordx2 v[20:21], v[22:23], off
	v_cvt_pk_bf16_f32 v22, v48, v49
	v_cvt_pk_bf16_f32 v23, v50, v51
	global_store_dwordx2 v[8:9], v[10:11], off
	v_cvt_pk_bf16_f32 v10, v28, v29
	v_cvt_pk_bf16_f32 v11, v30, v31
	global_store_dwordx2 v[0:1], v[2:3], off offset:32
	v_cvt_pk_bf16_f32 v2, v4, v5
	v_cvt_pk_bf16_f32 v3, v6, v7
	global_store_dwordx2 v[36:37], v[38:39], off offset:32
	v_cvt_pk_bf16_f32 v38, v44, v45
	v_cvt_pk_bf16_f32 v39, v46, v47
	global_store_dwordx2 v[20:21], v[22:23], off offset:32
	v_cvt_pk_bf16_f32 v22, v24, v25
	v_cvt_pk_bf16_f32 v23, v26, v27
	global_store_dwordx2 v[8:9], v[10:11], off offset:32
	v_cvt_pk_bf16_f32 v10, v12, v13
	v_cvt_pk_bf16_f32 v11, v14, v15
	global_store_dwordx2 v[0:1], v[2:3], off offset:64
	v_cvt_pk_bf16_f32 v2, v40, v41
	v_cvt_pk_bf16_f32 v3, v42, v43
	global_store_dwordx2 v[36:37], v[38:39], off offset:64
	global_store_dwordx2 v[20:21], v[22:23], off offset:64
	global_store_dwordx2 v[8:9], v[10:11], off offset:64
	global_store_dwordx2 v[0:1], v[2:3], off offset:96
	s_lshl_b32 s6, s6, 11
	s_add_u32 s6, s62, s6
	v_mov_b32_e32 v4, v182
	s_addc_u32 s7, s63, 0
	s_lshl_b64 s[8:9], s[12:13], 11
	s_add_u32 s8, s38, s8
	v_ashrrev_i32_e32 v0, 3, v4
	v_lshrrev_b32_e32 v5, 4, v4
	v_xor_b32_e32 v6, v5, v4
	v_ashrrev_i32_e32 v1, 31, v0
	s_addc_u32 s9, s39, s9
	v_lshlrev_b64 v[0:1], 11, v[0:1]
	v_lshlrev_b32_e32 v6, 4, v6
	v_lshl_add_u64 v[2:3], s[6:7], 0, v[0:1]
	v_and_b32_e32 v130, 0x70, v6
	v_lshl_add_u64 v[0:1], s[8:9], 0, v[0:1]
	v_lshl_add_u64 v[166:167], v[2:3], 0, v[130:131]
	v_lshl_add_u64 v[168:169], v[0:1], 0, v[130:131]
	v_lshlrev_b32_e32 v130, 4, v4
	v_add_u32_e32 v2, 0x2000, v130
	v_readfirstlane_b32 s6, v130
	v_lshl_add_u64 v[0:1], v[166:167], 0, s[30:31]
	s_mov_b32 m0, s6
	v_lshl_add_u64 v[170:171], v[166:167], 0, s[54:55]
	v_readfirstlane_b32 s6, v2
	v_add_u32_e32 v2, 0x4000, v130
	s_barrier
; #define LDS_PTR(p) ((__attribute__((address_space(3))) unsigned*)(p))
; template <int PIPE>
; DI void gemm_loop_g(const u16* __restrict__ Xp, long ldx_l, long ldx_i, long kxs,
;                     const u16* __restrict__ Yp, long ldy_l, long ldy_i, long kys, int K,
;                     f32x4 (&acc)[4][8], unsigned char* smem) {
;     ...
;   auto issue = [&](int kt0, int stage) {
;     int kt = kt0 + rot; if (kt >= nk) kt -= nk;
;     unsigned char* sb = smem + stage * 65536 + t * 16;
; #pragma unroll
;     for (int i = 0; i < 4; ++i)
;       __builtin_amdgcn_global_load_lds((const unsigned*)(xs + i * ldx_i + kt * kxs), LDS_PTR(sb + i * 8192), 16, 0, 0);
; #pragma unroll
;     for (int i = 0; i < 4; ++i)
;       __builtin_amdgcn_global_load_lds((const unsigned*)(ys + i * ldy_i + kt * kys), LDS_PTR(sb + 32768 + i * 8192), 16, 0, 0);
;   };
;   __syncthreads();
;   issue(0, 0);
;   asm volatile("s_waitcnt vmcnt(0)" ::: "memory");
;   __syncthreads();
; DI void zero_acc(f32x4 (&acc)[4][8]) {
; #pragma unroll
;   for (int i = 0; i < 4; ++i)
; #pragma unroll
;     for (int j = 0; j < 8; ++j) acc[i][j] = f32x4{0.f, 0.f, 0.f, 0.f};
; }
	global_load_lds_dwordx4 v[0:1], off
	v_lshl_add_u64 v[0:1], v[170:171], 0, s[30:31]
	s_mov_b32 m0, s6
	v_lshl_add_u64 v[172:173], v[166:167], 0, s[56:57]
	v_readfirstlane_b32 s6, v2
	v_add_u32_e32 v2, 0x6000, v130
	global_load_lds_dwordx4 v[0:1], off
	v_lshl_add_u64 v[0:1], v[172:173], 0, s[30:31]
	s_mov_b32 m0, s6
	v_lshl_add_u64 v[174:175], v[166:167], 0, s[58:59]
	v_readfirstlane_b32 s6, v2
	v_add_u32_e32 v2, 0x8000, v130
	global_load_lds_dwordx4 v[0:1], off
	v_lshl_add_u64 v[0:1], v[174:175], 0, s[30:31]
	s_mov_b32 m0, s6
	v_readfirstlane_b32 s6, v2
	v_add_u32_e32 v2, 0xa000, v130
	global_load_lds_dwordx4 v[0:1], off
	v_lshl_add_u64 v[0:1], v[168:169], 0, s[30:31]
	s_mov_b32 m0, s6
	v_lshl_add_u64 v[176:177], v[168:169], 0, s[54:55]
	v_readfirstlane_b32 s6, v2
	v_add_u32_e32 v2, 0xc000, v130
	global_load_lds_dwordx4 v[0:1], off
	v_lshl_add_u64 v[0:1], v[176:177], 0, s[30:31]
	s_mov_b32 m0, s6
	v_lshl_add_u64 v[178:179], v[168:169], 0, s[56:57]
	v_readfirstlane_b32 s6, v2
	v_add_u32_e32 v2, 0xe000, v130
	global_load_lds_dwordx4 v[0:1], off
	v_lshl_add_u64 v[0:1], v[178:179], 0, s[30:31]
	s_mov_b32 m0, s6
	v_lshl_add_u64 v[180:181], v[168:169], 0, s[58:59]
	v_readfirstlane_b32 s6, v2
	global_load_lds_dwordx4 v[0:1], off
	v_lshl_add_u64 v[0:1], v[180:181], 0, s[30:31]
	s_mov_b32 m0, s6
	v_lshlrev_b32_e32 v2, 7, v4
	global_load_lds_dwordx4 v[0:1], off
	v_bfe_u32 v0, v4, 4, 2
	v_bfe_u32 v1, v4, 1, 3
	v_readfirstlane_b32 s10, v4
	s_nop 0
	v_bitop3_b32 v0, v0, v1, 4 bitop3:0x36
	v_and_b32_e32 v2, 0x780, v2
	s_lshl_b32 s6, s10, 8
	s_lshl_b32 s7, s10, 6
	v_lshl_or_b32 v187, v0, 4, v2
	v_bitop3_b32 v0, v5, v1, 3 bitop3:0x6c
	v_mov_b32_e32 v4, 0
	s_and_b32 s6, s6, 0x4000
	s_and_b32 s7, s7, 0xffffe000
	v_lshl_or_b32 v188, v0, 4, v2
	s_mov_b32 s10, 0
	s_mov_b32 s11, 0x10000
	v_mov_b32_e32 v5, v4
	v_mov_b32_e32 v6, v4
	v_mov_b32_e32 v7, v4
	v_mov_b32_e32 v16, v4
	v_mov_b32_e32 v17, v4
	v_mov_b32_e32 v18, v4
	v_mov_b32_e32 v19, v4
	v_mov_b32_e32 v32, v4
	v_mov_b32_e32 v33, v4
	v_mov_b32_e32 v34, v4
	v_mov_b32_e32 v35, v4
	v_mov_b32_e32 v48, v4
	v_mov_b32_e32 v49, v4
	v_mov_b32_e32 v50, v4
	v_mov_b32_e32 v51, v4
	v_mov_b32_e32 v64, v4
	v_mov_b32_e32 v65, v4
	v_mov_b32_e32 v66, v4
	v_mov_b32_e32 v67, v4
	v_mov_b32_e32 v80, v4
	v_mov_b32_e32 v81, v4
	v_mov_b32_e32 v82, v4
	v_mov_b32_e32 v83, v4
	v_mov_b32_e32 v96, v4
	v_mov_b32_e32 v97, v4
	v_mov_b32_e32 v98, v4
	v_mov_b32_e32 v99, v4
	v_mov_b32_e32 v112, v4
	v_mov_b32_e32 v113, v4
	v_mov_b32_e32 v114, v4
	v_mov_b32_e32 v115, v4
	v_mov_b32_e32 v0, v4
	v_mov_b32_e32 v1, v4
	v_mov_b32_e32 v2, v4
	v_mov_b32_e32 v3, v4
	v_mov_b32_e32 v20, v4
	v_mov_b32_e32 v21, v4
	v_mov_b32_e32 v22, v4
	v_mov_b32_e32 v23, v4
	v_mov_b32_e32 v36, v4
	v_mov_b32_e32 v37, v4
	v_mov_b32_e32 v38, v4
	v_mov_b32_e32 v39, v4
	v_mov_b32_e32 v52, v4
	v_mov_b32_e32 v53, v4
	v_mov_b32_e32 v54, v4
	v_mov_b32_e32 v55, v4
	v_mov_b32_e32 v68, v4
	v_mov_b32_e32 v69, v4
	v_mov_b32_e32 v70, v4
	v_mov_b32_e32 v71, v4
	v_mov_b32_e32 v84, v4
	v_mov_b32_e32 v85, v4
	v_mov_b32_e32 v86, v4
	v_mov_b32_e32 v87, v4
	v_mov_b32_e32 v100, v4
	v_mov_b32_e32 v101, v4
	v_mov_b32_e32 v102, v4
	v_mov_b32_e32 v103, v4
	v_mov_b32_e32 v116, v4
	v_mov_b32_e32 v117, v4
	v_mov_b32_e32 v118, v4
	v_mov_b32_e32 v119, v4
	v_mov_b32_e32 v8, v4
	v_mov_b32_e32 v9, v4
	v_mov_b32_e32 v10, v4
	v_mov_b32_e32 v11, v4
	v_mov_b32_e32 v24, v4
	v_mov_b32_e32 v25, v4
	v_mov_b32_e32 v26, v4
	v_mov_b32_e32 v27, v4
	v_mov_b32_e32 v40, v4
	v_mov_b32_e32 v41, v4
	v_mov_b32_e32 v42, v4
	v_mov_b32_e32 v43, v4
	v_mov_b32_e32 v56, v4
	v_mov_b32_e32 v57, v4
	v_mov_b32_e32 v58, v4
	v_mov_b32_e32 v59, v4
	v_mov_b32_e32 v72, v4
	v_mov_b32_e32 v73, v4
	v_mov_b32_e32 v74, v4
	v_mov_b32_e32 v75, v4
	v_mov_b32_e32 v88, v4
	v_mov_b32_e32 v89, v4
	v_mov_b32_e32 v90, v4
	v_mov_b32_e32 v91, v4
	v_mov_b32_e32 v104, v4
	v_mov_b32_e32 v105, v4
	v_mov_b32_e32 v106, v4
	v_mov_b32_e32 v107, v4
	v_mov_b32_e32 v120, v4
	v_mov_b32_e32 v121, v4
	v_mov_b32_e32 v122, v4
	v_mov_b32_e32 v123, v4
	v_mov_b32_e32 v12, v4
	v_mov_b32_e32 v13, v4
	v_mov_b32_e32 v14, v4
	v_mov_b32_e32 v15, v4
	v_mov_b32_e32 v28, v4
	v_mov_b32_e32 v29, v4
	v_mov_b32_e32 v30, v4
	v_mov_b32_e32 v31, v4
	v_mov_b32_e32 v44, v4
	v_mov_b32_e32 v45, v4
	v_mov_b32_e32 v46, v4
	v_mov_b32_e32 v47, v4
	v_mov_b32_e32 v60, v4
	v_mov_b32_e32 v61, v4
	v_mov_b32_e32 v62, v4
	v_mov_b32_e32 v63, v4
	v_mov_b32_e32 v76, v4
	v_mov_b32_e32 v77, v4
	v_mov_b32_e32 v78, v4
	v_mov_b32_e32 v79, v4
	v_mov_b32_e32 v92, v4
	v_mov_b32_e32 v93, v4
	v_mov_b32_e32 v94, v4
	v_mov_b32_e32 v95, v4
	v_mov_b32_e32 v108, v4
	v_mov_b32_e32 v109, v4
	v_mov_b32_e32 v110, v4
	v_mov_b32_e32 v111, v4
	v_mov_b32_e32 v124, v4
	v_mov_b32_e32 v125, v4
	v_mov_b32_e32 v126, v4
	v_mov_b32_e32 v127, v4
	s_waitcnt vmcnt(0) lgkmcnt(0)
	s_barrier
	s_branch .LBB0_320

; DI int tid_opaque() { int t = threadIdx.x; asm volatile("" : "+v"(t)); return t; }
; #define LDS_PTR(p) ((__attribute__((address_space(3))) unsigned*)(p))
; template <int PIPE>
; DI void gemm_loop_g(const u16* __restrict__ Xp, long ldx_l, long ldx_i, long kxs,
;                     const u16* __restrict__ Yp, long ldy_l, long ldy_i, long kys, int K,
;                     f32x4 (&acc)[4][8], unsigned char* smem) {
;   const int t = tid_opaque(), l = t & 63, w = __builtin_amdgcn_readfirstlane(t >> 6), wx = w >> 1, wy = w & 1;
;   const int lrow = t >> 3, gch = (t & 7) ^ ((t >> 4) & 7);
;   const u16* xs = Xp + (long)lrow * ldx_l + gch * 8;
;   const u16* ys = Yp + (long)lrow * ldy_l + gch * 8;
;   const int fsw = (l >> 1) & 7, lg = l >> 4;
;   const unsigned fr0 = (l & 15) * 128 + ((lg ^ fsw) << 4);
;   const unsigned fr1 = (l & 15) * 128 + (((lg + 4) ^ fsw) << 4);
;   const unsigned ub = wx * 8192, vb = 32768 + wy * 16384;
;   const int nk = K >> 6;
;   const int rot = (int)((blockIdx.x >> 3) + (blockIdx.x & 7) * 5) % nk;
;   auto issue = [&](int kt0, int stage) {
;     int kt = kt0 + rot; if (kt >= nk) kt -= nk;
;     unsigned char* sb = smem + stage * 65536 + t * 16;
; #pragma unroll
;     for (int i = 0; i < 4; ++i)
;       __builtin_amdgcn_global_load_lds((const unsigned*)(xs + i * ldx_i + kt * kxs), LDS_PTR(sb + i * 8192), 16, 0, 0);
; #pragma unroll
;     for (int i = 0; i < 4; ++i)
;       __builtin_amdgcn_global_load_lds((const unsigned*)(ys + i * ldy_i + kt * kys), LDS_PTR(sb + 32768 + i * 8192), 16, 0, 0);
;   };
;   __syncthreads();
;   issue(0, 0);
;   asm volatile("s_waitcnt vmcnt(0)" ::: "memory");
;   __syncthreads();
; DI void zero_acc(f32x4 (&acc)[4][8]) {
; #pragma unroll
;   for (int i = 0; i < 4; ++i)
; #pragma unroll
;     for (int j = 0; j < 8; ++j) acc[i][j] = f32x4{0.f, 0.f, 0.f, 0.f};
; }
.LBB0_352:
	s_mul_hi_u32 s6, s69, 0xaaaaaaab
	s_lshr_b32 s7, s6, 1
	s_mul_i32 s6, s7, -3
	s_add_i32 s6, s6, s69
	s_lshl_b32 s58, s6, 8
	s_lshl_b32 s7, s7, 11
	s_ashr_i32 s59, s58, 31
	s_or_b32 s60, s7, s65
	s_lshl_b64 s[8:9], s[58:59], 11
	s_add_u32 s8, s26, s8
	s_addc_u32 s9, s27, s9
	s_ashr_i32 s61, s60, 31
	v_mov_b32_e32 v4, v182
	s_lshl_b64 s[10:11], s[60:61], 11
	s_add_u32 s10, s36, s10
	v_ashrrev_i32_e32 v0, 3, v4
	v_lshrrev_b32_e32 v5, 4, v4
	v_xor_b32_e32 v6, v5, v4
	s_waitcnt lgkmcnt(0)
	v_ashrrev_i32_e32 v1, 31, v0
	s_addc_u32 s11, s37, s11
	v_lshlrev_b64 v[0:1], 11, v[0:1]
	v_lshlrev_b32_e32 v6, 4, v6
	v_lshl_add_u64 v[2:3], s[8:9], 0, v[0:1]
	v_and_b32_e32 v128, 0x70, v6
	v_lshl_add_u64 v[0:1], s[10:11], 0, v[0:1]
	v_lshl_add_u64 v[132:133], v[2:3], 0, v[128:129]
	v_lshl_add_u64 v[134:135], v[0:1], 0, v[128:129]
	v_lshlrev_b32_e32 v128, 4, v4
	v_add_u32_e32 v2, 0x2000, v128
	v_readfirstlane_b32 s7, v128
	v_lshl_add_u64 v[0:1], v[132:133], 0, s[24:25]
	s_mov_b32 m0, s7
	v_lshl_add_u64 v[136:137], v[132:133], 0, s[30:31]
	v_readfirstlane_b32 s7, v2
	v_add_u32_e32 v2, 0x4000, v128
	s_barrier
	global_load_lds_dwordx4 v[0:1], off
	v_lshl_add_u64 v[0:1], v[136:137], 0, s[24:25]
	s_mov_b32 m0, s7
	v_lshl_add_u64 v[138:139], v[132:133], 0, s[54:55]
	v_readfirstlane_b32 s7, v2
	v_add_u32_e32 v2, 0x6000, v128
	global_load_lds_dwordx4 v[0:1], off
	v_lshl_add_u64 v[0:1], v[138:139], 0, s[24:25]
	s_mov_b32 m0, s7
	v_lshl_add_u64 v[140:141], v[132:133], 0, s[56:57]
	v_readfirstlane_b32 s7, v2
	v_add_u32_e32 v2, 0x8000, v128
	global_load_lds_dwordx4 v[0:1], off
	v_lshl_add_u64 v[0:1], v[140:141], 0, s[24:25]
	s_mov_b32 m0, s7
	v_readfirstlane_b32 s7, v2
	v_add_u32_e32 v2, 0xa000, v128
	global_load_lds_dwordx4 v[0:1], off
	v_lshl_add_u64 v[0:1], v[134:135], 0, s[24:25]
	s_mov_b32 m0, s7
	v_lshl_add_u64 v[142:143], v[134:135], 0, s[30:31]
	v_readfirstlane_b32 s7, v2
	v_add_u32_e32 v2, 0xc000, v128
	global_load_lds_dwordx4 v[0:1], off
	v_lshl_add_u64 v[0:1], v[142:143], 0, s[24:25]
	s_mov_b32 m0, s7
	v_lshl_add_u64 v[144:145], v[134:135], 0, s[54:55]
	v_readfirstlane_b32 s7, v2
	v_add_u32_e32 v2, 0xe000, v128
	global_load_lds_dwordx4 v[0:1], off
	v_lshl_add_u64 v[0:1], v[144:145], 0, s[24:25]
	s_mov_b32 m0, s7
	v_lshl_add_u64 v[146:147], v[134:135], 0, s[56:57]
	v_readfirstlane_b32 s7, v2
	global_load_lds_dwordx4 v[0:1], off
	v_lshl_add_u64 v[0:1], v[146:147], 0, s[24:25]
	s_mov_b32 m0, s7
	v_lshlrev_b32_e32 v2, 7, v4
	global_load_lds_dwordx4 v[0:1], off
	v_bfe_u32 v0, v4, 4, 2
	v_bfe_u32 v1, v4, 1, 3
	v_readfirstlane_b32 s33, v4
	s_nop 0
	v_bitop3_b32 v0, v0, v1, 4 bitop3:0x36
	v_and_b32_e32 v2, 0x780, v2
	s_lshl_b32 s7, s33, 8
	s_lshl_b32 s8, s33, 6
	v_lshl_or_b32 v154, v0, 4, v2
	v_bitop3_b32 v0, v5, v1, 3 bitop3:0x6c
	s_and_b32 s7, s7, 0x4000
	s_and_b32 s10, s8, 0xffffe000
	v_lshl_or_b32 v155, v0, 4, v2
	s_mov_b32 s11, 0x10000
	s_mov_b32 s33, 0
	v_mov_b32_e32 v8, 0
	v_mov_b32_e32 v9, v129
	v_mov_b32_e32 v10, v129
	v_mov_b32_e32 v11, v129
	v_mov_b32_e32 v12, 0
	v_mov_b32_e32 v13, v129
	v_mov_b32_e32 v14, v129
	v_mov_b32_e32 v15, v129
	v_mov_b32_e32 v28, 0
	v_mov_b32_e32 v29, v129
	v_mov_b32_e32 v30, v129
	v_mov_b32_e32 v31, v129
	v_mov_b32_e32 v44, 0
	v_mov_b32_e32 v45, v129
	v_mov_b32_e32 v46, v129
	v_mov_b32_e32 v47, v129
	v_mov_b32_e32 v60, 0
	v_mov_b32_e32 v61, v129
	v_mov_b32_e32 v62, v129
	v_mov_b32_e32 v63, v129
	v_mov_b32_e32 v76, 0
	v_mov_b32_e32 v77, v129
	v_mov_b32_e32 v78, v129
	v_mov_b32_e32 v79, v129
	v_mov_b32_e32 v92, 0
	v_mov_b32_e32 v93, v129
	v_mov_b32_e32 v94, v129
	v_mov_b32_e32 v95, v129
	v_mov_b32_e32 v108, 0
	v_mov_b32_e32 v109, v129
	v_mov_b32_e32 v110, v129
	v_mov_b32_e32 v111, v129
	v_mov_b32_e32 v0, 0
	v_mov_b32_e32 v1, v129
	v_mov_b32_e32 v2, v129
	v_mov_b32_e32 v3, v129
	v_mov_b32_e32 v20, 0
	v_mov_b32_e32 v21, v129
	v_mov_b32_e32 v22, v129
	v_mov_b32_e32 v23, v129
	v_mov_b32_e32 v36, 0
	v_mov_b32_e32 v37, v129
	v_mov_b32_e32 v38, v129
	v_mov_b32_e32 v39, v129
	v_mov_b32_e32 v52, 0
	v_mov_b32_e32 v53, v129
	v_mov_b32_e32 v54, v129
	v_mov_b32_e32 v55, v129
	v_mov_b32_e32 v68, 0
	v_mov_b32_e32 v69, v129
	v_mov_b32_e32 v70, v129
	v_mov_b32_e32 v71, v129
	v_mov_b32_e32 v84, 0
	v_mov_b32_e32 v85, v129
	v_mov_b32_e32 v86, v129
	v_mov_b32_e32 v87, v129
	v_mov_b32_e32 v100, 0
	v_mov_b32_e32 v101, v129
	v_mov_b32_e32 v102, v129
	v_mov_b32_e32 v103, v129
	v_mov_b32_e32 v116, 0
	v_mov_b32_e32 v117, v129
	v_mov_b32_e32 v118, v129
	v_mov_b32_e32 v119, v129
	v_mov_b32_e32 v4, 0
	v_mov_b32_e32 v5, v129
	v_mov_b32_e32 v6, v129
	v_mov_b32_e32 v7, v129
	v_mov_b32_e32 v24, 0
	v_mov_b32_e32 v25, v129
	v_mov_b32_e32 v26, v129
	v_mov_b32_e32 v27, v129
	v_mov_b32_e32 v40, 0
	v_mov_b32_e32 v41, v129
	v_mov_b32_e32 v42, v129
	v_mov_b32_e32 v43, v129
	v_mov_b32_e32 v56, 0
	v_mov_b32_e32 v57, v129
	v_mov_b32_e32 v58, v129
	v_mov_b32_e32 v59, v129
	v_mov_b32_e32 v72, 0
	v_mov_b32_e32 v73, v129
	v_mov_b32_e32 v74, v129
	v_mov_b32_e32 v75, v129
	v_mov_b32_e32 v88, 0
	v_mov_b32_e32 v89, v129
	v_mov_b32_e32 v90, v129
	v_mov_b32_e32 v91, v129
	v_mov_b32_e32 v104, 0
	v_mov_b32_e32 v105, v129
	v_mov_b32_e32 v106, v129
	v_mov_b32_e32 v107, v129
	v_mov_b32_e32 v120, 0
	v_mov_b32_e32 v121, v129
	v_mov_b32_e32 v122, v129
	v_mov_b32_e32 v123, v129
	v_mov_b32_e32 v16, 0
	v_mov_b32_e32 v17, v129
	v_mov_b32_e32 v18, v129
	v_mov_b32_e32 v19, v129
	v_mov_b32_e32 v32, 0
	v_mov_b32_e32 v33, v129
	v_mov_b32_e32 v34, v129
	v_mov_b32_e32 v35, v129
	v_mov_b32_e32 v48, 0
	v_mov_b32_e32 v49, v129
	v_mov_b32_e32 v50, v129
	v_mov_b32_e32 v51, v129
	v_mov_b32_e32 v64, 0
	v_mov_b32_e32 v65, v129
	v_mov_b32_e32 v66, v129
	v_mov_b32_e32 v67, v129
	v_mov_b32_e32 v80, 0
	v_mov_b32_e32 v81, v129
	v_mov_b32_e32 v82, v129
	v_mov_b32_e32 v83, v129
	v_mov_b32_e32 v96, 0
	v_mov_b32_e32 v97, v129
	v_mov_b32_e32 v98, v129
	v_mov_b32_e32 v99, v129
	v_mov_b32_e32 v112, 0
	v_mov_b32_e32 v113, v129
	v_mov_b32_e32 v114, v129
	v_mov_b32_e32 v115, v129
	v_mov_b32_e32 v124, 0
	v_mov_b32_e32 v125, v129
	v_mov_b32_e32 v126, v129
	v_mov_b32_e32 v127, v129
	s_waitcnt vmcnt(0) lgkmcnt(0)
	s_barrier
	s_branch .LBB0_354

; DI int tid_opaque() { int t = threadIdx.x; asm volatile("" : "+v"(t)); return t; }
; #define LDS_PTR(p) ((__attribute__((address_space(3))) unsigned*)(p))
; template <int PIPE>
; DI void gemm_loop_g(const u16* __restrict__ Xp, long ldx_l, long ldx_i, long kxs,
;                     const u16* __restrict__ Yp, long ldy_l, long ldy_i, long kys, int K,
;                     f32x4 (&acc)[4][8], unsigned char* smem) {
;   const int t = tid_opaque(), l = t & 63, w = __builtin_amdgcn_readfirstlane(t >> 6), wx = w >> 1, wy = w & 1;
;   const int lrow = t >> 3, gch = (t & 7) ^ ((t >> 4) & 7);
;   const u16* xs = Xp + (long)lrow * ldx_l + gch * 8;
;   const u16* ys = Yp + (long)lrow * ldy_l + gch * 8;
;   const int fsw = (l >> 1) & 7, lg = l >> 4;
;   const unsigned fr0 = (l & 15) * 128 + ((lg ^ fsw) << 4);
;   const unsigned fr1 = (l & 15) * 128 + (((lg + 4) ^ fsw) << 4);
;   const unsigned ub = wx * 8192, vb = 32768 + wy * 16384;
;   const int nk = K >> 6;
;   const int rot = (int)((blockIdx.x >> 3) + (blockIdx.x & 7) * 5) % nk;
;   auto issue = [&](int kt0, int stage) {
;     int kt = kt0 + rot; if (kt >= nk) kt -= nk;
;     unsigned char* sb = smem + stage * 65536 + t * 16;
; #pragma unroll
;     for (int i = 0; i < 4; ++i)
;       __builtin_amdgcn_global_load_lds((const unsigned*)(xs + i * ldx_i + kt * kxs), LDS_PTR(sb + i * 8192), 16, 0, 0);
; #pragma unroll
;     for (int i = 0; i < 4; ++i)
;       __builtin_amdgcn_global_load_lds((const unsigned*)(ys + i * ldy_i + kt * kys), LDS_PTR(sb + 32768 + i * 8192), 16, 0, 0);
;   };
;   __syncthreads();
;   issue(0, 0);
;   asm volatile("s_waitcnt vmcnt(0)" ::: "memory");
;   __syncthreads();
; DI void zero_acc(f32x4 (&acc)[4][8]) {
; #pragma unroll
;   for (int i = 0; i < 4; ++i)
; #pragma unroll
;     for (int j = 0; j < 8; ++j) acc[i][j] = f32x4{0.f, 0.f, 0.f, 0.f};
; }
.LBB0_390:
	s_mul_hi_u32 s6, s62, 0xaaaaaaab
	s_lshr_b32 s6, s6, 2
	s_mul_i32 s10, s6, -6
	s_add_i32 s10, s10, s62
	s_lshl_b32 s6, s6, 11
	s_or_b32 s7, s6, s57
	s_lshl_b32 s6, s10, 8
	s_mul_i32 s8, s10, 0x30000
	v_mov_b32_e32 v2, v182
	s_mul_hi_i32 s9, s6, 0x300
	s_waitcnt lgkmcnt(0)
	s_add_u32 s8, s14, s8
	s_addc_u32 s9, s15, s9
	v_lshrrev_b32_e32 v4, 4, v2
	s_mul_i32 s33, s7, 0x300
	v_xor_b32_e32 v5, v4, v2
	s_mul_hi_i32 s11, s7, 0x300
	s_add_u32 s40, s38, s33
	v_ashrrev_i32_e32 v3, 3, v2
	v_mov_b64_e32 v[0:1], s[8:9]
	v_lshlrev_b32_e32 v5, 4, v5
	s_addc_u32 s41, s39, s11
	v_mad_i64_i32 v[0:1], s[8:9], v3, s59, v[0:1]
	v_and_b32_e32 v130, 0x70, v5
	v_lshl_add_u64 v[132:133], v[0:1], 0, v[130:131]
	v_mov_b64_e32 v[0:1], s[40:41]
	v_mad_i64_i32 v[0:1], s[8:9], v3, s59, v[0:1]
	v_lshl_add_u64 v[134:135], v[0:1], 0, v[130:131]
	v_lshlrev_b32_e32 v130, 4, v2
	v_add_u32_e32 v3, 0x2000, v130
	v_readfirstlane_b32 s8, v130
	v_lshl_add_u64 v[0:1], v[132:133], 0, s[12:13]
	s_mov_b32 m0, s8
	v_lshl_add_u64 v[136:137], v[132:133], 0, s[26:27]
	v_readfirstlane_b32 s8, v3
	v_add_u32_e32 v3, 0x4000, v130
	s_barrier
	global_load_lds_dwordx4 v[0:1], off
	v_lshl_add_u64 v[0:1], v[136:137], 0, s[12:13]
	s_mov_b32 m0, s8
	v_lshl_add_u64 v[138:139], v[132:133], 0, s[28:29]
	v_readfirstlane_b32 s8, v3
	v_add_u32_e32 v3, 0x6000, v130
	global_load_lds_dwordx4 v[0:1], off
	v_lshl_add_u64 v[0:1], v[138:139], 0, s[12:13]
	s_mov_b32 m0, s8
	v_lshl_add_u64 v[140:141], v[132:133], 0, s[30:31]
	v_readfirstlane_b32 s8, v3
	v_add_u32_e32 v3, 0x8000, v130
	global_load_lds_dwordx4 v[0:1], off
	v_lshl_add_u64 v[0:1], v[140:141], 0, s[12:13]
	s_mov_b32 m0, s8
	v_readfirstlane_b32 s8, v3
	v_add_u32_e32 v3, 0xa000, v130
	global_load_lds_dwordx4 v[0:1], off
	v_lshl_add_u64 v[0:1], v[134:135], 0, s[12:13]
	s_mov_b32 m0, s8
	v_lshl_add_u64 v[142:143], v[134:135], 0, s[26:27]
	v_readfirstlane_b32 s8, v3
	v_add_u32_e32 v3, 0xc000, v130
	global_load_lds_dwordx4 v[0:1], off
	v_lshl_add_u64 v[0:1], v[142:143], 0, s[12:13]
	s_mov_b32 m0, s8
	v_lshl_add_u64 v[144:145], v[134:135], 0, s[28:29]
	v_readfirstlane_b32 s8, v3
	v_add_u32_e32 v3, 0xe000, v130
	global_load_lds_dwordx4 v[0:1], off
	v_lshl_add_u64 v[0:1], v[144:145], 0, s[12:13]
	s_mov_b32 m0, s8
	v_lshl_add_u64 v[146:147], v[134:135], 0, s[30:31]
	v_readfirstlane_b32 s8, v3
	global_load_lds_dwordx4 v[0:1], off
	v_lshl_add_u64 v[0:1], v[146:147], 0, s[12:13]
	s_mov_b32 m0, s8
	v_readfirstlane_b32 s33, v2
	global_load_lds_dwordx4 v[0:1], off
	v_bfe_u32 v0, v2, 4, 2
	v_bfe_u32 v1, v2, 1, 3
	v_lshlrev_b32_e32 v2, 7, v2
	s_nop 0
	s_lshl_b32 s8, s33, 8
	v_bitop3_b32 v0, v0, v1, 4 bitop3:0x36
	v_and_b32_e32 v2, 0x780, v2
	s_and_b32 s11, s8, 0x4000
	s_lshl_b32 s8, s33, 6
	v_lshl_or_b32 v151, v0, 4, v2
	v_bitop3_b32 v0, v4, v1, 3 bitop3:0x6c
	s_and_b32 s33, s8, 0xffffe000
	v_lshl_or_b32 v152, v0, 4, v2
	s_mov_b32 s48, 0x10000
	s_mov_b32 s49, 0
	v_mov_b32_e32 v8, 0
	v_mov_b32_e32 v9, v131
	v_mov_b32_e32 v10, v131
	v_mov_b32_e32 v11, v131
	v_mov_b32_e32 v12, 0
	v_mov_b32_e32 v13, v131
	v_mov_b32_e32 v14, v131
	v_mov_b32_e32 v15, v131
	v_mov_b32_e32 v28, 0
	v_mov_b32_e32 v29, v131
	v_mov_b32_e32 v30, v131
	v_mov_b32_e32 v31, v131
	v_mov_b32_e32 v44, 0
	v_mov_b32_e32 v45, v131
	v_mov_b32_e32 v46, v131
	v_mov_b32_e32 v47, v131
	v_mov_b32_e32 v60, 0
	v_mov_b32_e32 v61, v131
	v_mov_b32_e32 v62, v131
	v_mov_b32_e32 v63, v131
	v_mov_b32_e32 v76, 0
	v_mov_b32_e32 v77, v131
	v_mov_b32_e32 v78, v131
	v_mov_b32_e32 v79, v131
	v_mov_b32_e32 v92, 0
	v_mov_b32_e32 v93, v131
	v_mov_b32_e32 v94, v131
	v_mov_b32_e32 v95, v131
	v_mov_b32_e32 v108, 0
	v_mov_b32_e32 v109, v131
	v_mov_b32_e32 v110, v131
	v_mov_b32_e32 v111, v131
	v_mov_b32_e32 v4, 0
	v_mov_b32_e32 v5, v131
	v_mov_b32_e32 v6, v131
	v_mov_b32_e32 v7, v131
	v_mov_b32_e32 v24, 0
	v_mov_b32_e32 v25, v131
	v_mov_b32_e32 v26, v131
	v_mov_b32_e32 v27, v131
	v_mov_b32_e32 v40, 0
	v_mov_b32_e32 v41, v131
	v_mov_b32_e32 v42, v131
	v_mov_b32_e32 v43, v131
	v_mov_b32_e32 v56, 0
	v_mov_b32_e32 v57, v131
	v_mov_b32_e32 v58, v131
	v_mov_b32_e32 v59, v131
	v_mov_b32_e32 v72, 0
	v_mov_b32_e32 v73, v131
	v_mov_b32_e32 v74, v131
	v_mov_b32_e32 v75, v131
	v_mov_b32_e32 v88, 0
	v_mov_b32_e32 v89, v131
	v_mov_b32_e32 v90, v131
	v_mov_b32_e32 v91, v131
	v_mov_b32_e32 v104, 0
	v_mov_b32_e32 v105, v131
	v_mov_b32_e32 v106, v131
	v_mov_b32_e32 v107, v131
	v_mov_b32_e32 v120, 0
	v_mov_b32_e32 v121, v131
	v_mov_b32_e32 v122, v131
	v_mov_b32_e32 v123, v131
	v_mov_b32_e32 v0, 0
	v_mov_b32_e32 v1, v131
	v_mov_b32_e32 v2, v131
	v_mov_b32_e32 v3, v131
	v_mov_b32_e32 v20, 0
	v_mov_b32_e32 v21, v131
	v_mov_b32_e32 v22, v131
	v_mov_b32_e32 v23, v131
	v_mov_b32_e32 v36, 0
	v_mov_b32_e32 v37, v131
	v_mov_b32_e32 v38, v131
	v_mov_b32_e32 v39, v131
	v_mov_b32_e32 v52, 0
	v_mov_b32_e32 v53, v131
	v_mov_b32_e32 v54, v131
	v_mov_b32_e32 v55, v131
	v_mov_b32_e32 v68, 0
	v_mov_b32_e32 v69, v131
	v_mov_b32_e32 v70, v131
	v_mov_b32_e32 v71, v131
	v_mov_b32_e32 v84, 0
	v_mov_b32_e32 v85, v131
	v_mov_b32_e32 v86, v131
	v_mov_b32_e32 v87, v131
	v_mov_b32_e32 v100, 0
	v_mov_b32_e32 v101, v131
	v_mov_b32_e32 v102, v131
	v_mov_b32_e32 v103, v131
	v_mov_b32_e32 v116, 0
	v_mov_b32_e32 v117, v131
	v_mov_b32_e32 v118, v131
	v_mov_b32_e32 v119, v131
	v_mov_b32_e32 v16, 0
	v_mov_b32_e32 v17, v131
	v_mov_b32_e32 v18, v131
	v_mov_b32_e32 v19, v131
	v_mov_b32_e32 v32, 0
	v_mov_b32_e32 v33, v131
	v_mov_b32_e32 v34, v131
	v_mov_b32_e32 v35, v131
	v_mov_b32_e32 v48, 0
	v_mov_b32_e32 v49, v131
	v_mov_b32_e32 v50, v131
	v_mov_b32_e32 v51, v131
	v_mov_b32_e32 v64, 0
	v_mov_b32_e32 v65, v131
	v_mov_b32_e32 v66, v131
	v_mov_b32_e32 v67, v131
	v_mov_b32_e32 v80, 0
	v_mov_b32_e32 v81, v131
	v_mov_b32_e32 v82, v131
	v_mov_b32_e32 v83, v131
	v_mov_b32_e32 v96, 0
	v_mov_b32_e32 v97, v131
	v_mov_b32_e32 v98, v131
	v_mov_b32_e32 v99, v131
	v_mov_b32_e32 v112, 0
	v_mov_b32_e32 v113, v131
	v_mov_b32_e32 v114, v131
	v_mov_b32_e32 v115, v131
	v_mov_b32_e32 v124, 0
	v_mov_b32_e32 v125, v131
	v_mov_b32_e32 v126, v131
	v_mov_b32_e32 v127, v131
	s_waitcnt vmcnt(0) lgkmcnt(0)
	s_barrier
	s_branch .LBB0_392

; DI int tid_opaque() { int t = threadIdx.x; asm volatile("" : "+v"(t)); return t; }
; #define LDS_PTR(p) ((__attribute__((address_space(3))) unsigned*)(p))
; template <int PIPE>
; DI void gemm_loop_g(const u16* __restrict__ Xp, long ldx_l, long ldx_i, long kxs,
;                     const u16* __restrict__ Yp, long ldy_l, long ldy_i, long kys, int K,
;                     f32x4 (&acc)[4][8], unsigned char* smem) {
;   const int t = tid_opaque(), l = t & 63, w = __builtin_amdgcn_readfirstlane(t >> 6), wx = w >> 1, wy = w & 1;
;   const int lrow = t >> 3, gch = (t & 7) ^ ((t >> 4) & 7);
;   const u16* xs = Xp + (long)lrow * ldx_l + gch * 8;
;   const u16* ys = Yp + (long)lrow * ldy_l + gch * 8;
;   const int fsw = (l >> 1) & 7, lg = l >> 4;
;   const unsigned fr0 = (l & 15) * 128 + ((lg ^ fsw) << 4);
;   const unsigned fr1 = (l & 15) * 128 + (((lg + 4) ^ fsw) << 4);
;   const unsigned ub = wx * 8192, vb = 32768 + wy * 16384;
;   const int nk = K >> 6;
;   const int rot = (int)((blockIdx.x >> 3) + (blockIdx.x & 7) * 5) % nk;
;   auto issue = [&](int kt0, int stage) {
;     int kt = kt0 + rot; if (kt >= nk) kt -= nk;
;     unsigned char* sb = smem + stage * 65536 + t * 16;
; #pragma unroll
;     for (int i = 0; i < 4; ++i)
;       __builtin_amdgcn_global_load_lds((const unsigned*)(xs + i * ldx_i + kt * kxs), LDS_PTR(sb + i * 8192), 16, 0, 0);
; #pragma unroll
;     for (int i = 0; i < 4; ++i)
;       __builtin_amdgcn_global_load_lds((const unsigned*)(ys + i * ldy_i + kt * kys), LDS_PTR(sb + 32768 + i * 8192), 16, 0, 0);
;   };
;   __syncthreads();
;   issue(0, 0);
;   asm volatile("s_waitcnt vmcnt(0)" ::: "memory");
;   __syncthreads();
; DI void zero_acc(f32x4 (&acc)[4][8]) {
; #pragma unroll
;   for (int i = 0; i < 4; ++i)
; #pragma unroll
;     for (int j = 0; j < 8; ++j) acc[i][j] = f32x4{0.f, 0.f, 0.f, 0.f};
; }
.LBB0_401:
	s_lshl_b32 s6, s78, 8
	s_and_b32 s6, s6, 0xfffff800
	s_and_b32 s79, s78, 7
	s_or_b32 s12, s6, s67
	s_cmp_lt_u32 s79, 4
	s_cselect_b64 s[14:15], -1, 0
	s_ashr_i32 s13, s12, 31
	s_lshl_b64 s[6:7], s[12:13], 9
	s_add_u32 s68, s63, s6
	s_addc_u32 s69, s65, s7
	s_lshl_b32 s6, s79, 17
	s_waitcnt lgkmcnt(0)
	s_add_u32 s16, s28, s6
	s_addc_u32 s17, s29, 0
	s_mov_b64 s[70:71], -1
	s_and_b64 vcc, exec, s[14:15]
	s_cbranch_vccz .LBB0_407
	v_mov_b32_e32 v4, v182
	s_nop 0
	v_ashrrev_i32_e32 v0, 3, v4
	v_lshrrev_b32_e32 v5, 4, v4
	v_xor_b32_e32 v6, v5, v4
	v_ashrrev_i32_e32 v1, 31, v0
	v_lshlrev_b64 v[0:1], 9, v[0:1]
	v_lshlrev_b32_e32 v6, 4, v6
	v_lshl_add_u64 v[2:3], s[16:17], 0, v[0:1]
	v_and_b32_e32 v128, 0x70, v6
	v_lshl_add_u64 v[0:1], s[68:69], 0, v[0:1]
	v_lshl_add_u64 v[130:131], v[2:3], 0, v[128:129]
	v_lshl_add_u64 v[132:133], v[0:1], 0, v[128:129]
	v_lshlrev_b32_e32 v128, 4, v4
	v_add_u32_e32 v2, 0x2000, v128
	v_readfirstlane_b32 s6, v128
	v_lshl_add_u64 v[0:1], v[130:131], 0, s[54:55]
	s_mov_b32 m0, s6
	v_lshl_add_u64 v[134:135], v[130:131], 0, s[56:57]
	v_readfirstlane_b32 s6, v2
	v_add_u32_e32 v2, 0x4000, v128
	s_barrier
	global_load_lds_dwordx4 v[0:1], off
	v_lshl_add_u64 v[0:1], v[134:135], 0, s[54:55]
	s_mov_b32 m0, s6
	v_lshl_add_u64 v[136:137], v[130:131], 0, s[58:59]
	v_readfirstlane_b32 s6, v2
	v_add_u32_e32 v2, 0x6000, v128
	global_load_lds_dwordx4 v[0:1], off
	v_lshl_add_u64 v[0:1], v[136:137], 0, s[54:55]
	s_mov_b32 m0, s6
	v_lshl_add_u64 v[138:139], v[130:131], 0, s[60:61]
	v_readfirstlane_b32 s6, v2
	v_add_u32_e32 v2, 0x8000, v128
	global_load_lds_dwordx4 v[0:1], off
	v_lshl_add_u64 v[0:1], v[138:139], 0, s[54:55]
	s_mov_b32 m0, s6
	v_readfirstlane_b32 s6, v2
	v_add_u32_e32 v2, 0xa000, v128
	global_load_lds_dwordx4 v[0:1], off
	v_lshl_add_u64 v[0:1], v[132:133], 0, s[54:55]
	s_mov_b32 m0, s6
	v_lshl_add_u64 v[140:141], v[132:133], 0, s[56:57]
	v_readfirstlane_b32 s6, v2
	v_add_u32_e32 v2, 0xc000, v128
	global_load_lds_dwordx4 v[0:1], off
	v_lshl_add_u64 v[0:1], v[140:141], 0, s[54:55]
	s_mov_b32 m0, s6
	v_lshl_add_u64 v[142:143], v[132:133], 0, s[58:59]
	v_readfirstlane_b32 s6, v2
	v_add_u32_e32 v2, 0xe000, v128
	global_load_lds_dwordx4 v[0:1], off
	v_lshl_add_u64 v[0:1], v[142:143], 0, s[54:55]
	s_mov_b32 m0, s6
	v_lshl_add_u64 v[144:145], v[132:133], 0, s[60:61]
	v_readfirstlane_b32 s6, v2
	global_load_lds_dwordx4 v[0:1], off
	v_lshl_add_u64 v[0:1], v[144:145], 0, s[54:55]
	s_mov_b32 m0, s6
	v_lshlrev_b32_e32 v2, 7, v4
	global_load_lds_dwordx4 v[0:1], off
	v_bfe_u32 v0, v4, 4, 2
	v_bfe_u32 v1, v4, 1, 3
	v_readfirstlane_b32 s7, v4
	s_nop 0
	v_bitop3_b32 v0, v0, v1, 4 bitop3:0x36
	v_and_b32_e32 v2, 0x780, v2
	s_lshl_b32 s6, s7, 8
	s_lshl_b32 s7, s7, 6
	v_lshl_or_b32 v152, v0, 4, v2
	v_bitop3_b32 v0, v5, v1, 3 bitop3:0x6c
	v_mov_b32_e32 v8, 0
	s_and_b32 s6, s6, 0x4000
	s_and_b32 s7, s7, 0xffffe000
	v_lshl_or_b32 v153, v0, 4, v2
	s_mov_b32 s10, 0
	s_mov_b32 s11, 0x10000
	v_mov_b32_e32 v9, v8
	v_mov_b32_e32 v10, v8
	v_mov_b32_e32 v11, v8
	v_mov_b32_e32 v12, v8
	v_mov_b32_e32 v13, v8
	v_mov_b32_e32 v14, v8
	v_mov_b32_e32 v15, v8
	v_mov_b32_e32 v28, v8
	v_mov_b32_e32 v29, v8
	v_mov_b32_e32 v30, v8
	v_mov_b32_e32 v31, v8
	v_mov_b32_e32 v44, v8
	v_mov_b32_e32 v45, v8
	v_mov_b32_e32 v46, v8
	v_mov_b32_e32 v47, v8
	v_mov_b32_e32 v60, v8
	v_mov_b32_e32 v61, v8
	v_mov_b32_e32 v62, v8
	v_mov_b32_e32 v63, v8
	v_mov_b32_e32 v76, v8
	v_mov_b32_e32 v77, v8
	v_mov_b32_e32 v78, v8
	v_mov_b32_e32 v79, v8
	v_mov_b32_e32 v92, v8
	v_mov_b32_e32 v93, v8
	v_mov_b32_e32 v94, v8
	v_mov_b32_e32 v95, v8
	v_mov_b32_e32 v108, v8
	v_mov_b32_e32 v109, v8
	v_mov_b32_e32 v110, v8
	v_mov_b32_e32 v111, v8
	v_mov_b32_e32 v0, v8
	v_mov_b32_e32 v1, v8
	v_mov_b32_e32 v2, v8
	v_mov_b32_e32 v3, v8
	v_mov_b32_e32 v20, v8
	v_mov_b32_e32 v21, v8
	v_mov_b32_e32 v22, v8
	v_mov_b32_e32 v23, v8
	v_mov_b32_e32 v36, v8
	v_mov_b32_e32 v37, v8
	v_mov_b32_e32 v38, v8
	v_mov_b32_e32 v39, v8
	v_mov_b32_e32 v52, v8
	v_mov_b32_e32 v53, v8
	v_mov_b32_e32 v54, v8
	v_mov_b32_e32 v55, v8
	v_mov_b32_e32 v68, v8
	v_mov_b32_e32 v69, v8
	v_mov_b32_e32 v70, v8
	v_mov_b32_e32 v71, v8
	v_mov_b32_e32 v84, v8
	v_mov_b32_e32 v85, v8
	v_mov_b32_e32 v86, v8
	v_mov_b32_e32 v87, v8
	v_mov_b32_e32 v100, v8
	v_mov_b32_e32 v101, v8
	v_mov_b32_e32 v102, v8
	v_mov_b32_e32 v103, v8
	v_mov_b32_e32 v116, v8
	v_mov_b32_e32 v117, v8
	v_mov_b32_e32 v118, v8
	v_mov_b32_e32 v119, v8
	v_mov_b32_e32 v4, v8
	v_mov_b32_e32 v5, v8
	v_mov_b32_e32 v6, v8
	v_mov_b32_e32 v7, v8
	v_mov_b32_e32 v24, v8
	v_mov_b32_e32 v25, v8
	v_mov_b32_e32 v26, v8
	v_mov_b32_e32 v27, v8
	v_mov_b32_e32 v40, v8
	v_mov_b32_e32 v41, v8
	v_mov_b32_e32 v42, v8
	v_mov_b32_e32 v43, v8
	v_mov_b32_e32 v56, v8
	v_mov_b32_e32 v57, v8
	v_mov_b32_e32 v58, v8
	v_mov_b32_e32 v59, v8
	v_mov_b32_e32 v72, v8
	v_mov_b32_e32 v73, v8
	v_mov_b32_e32 v74, v8
	v_mov_b32_e32 v75, v8
	v_mov_b32_e32 v88, v8
	v_mov_b32_e32 v89, v8
	v_mov_b32_e32 v90, v8
	v_mov_b32_e32 v91, v8
	v_mov_b32_e32 v104, v8
	v_mov_b32_e32 v105, v8
	v_mov_b32_e32 v106, v8
	v_mov_b32_e32 v107, v8
	v_mov_b32_e32 v120, v8
	v_mov_b32_e32 v121, v8
	v_mov_b32_e32 v122, v8
	v_mov_b32_e32 v123, v8
	v_mov_b32_e32 v16, v8
	v_mov_b32_e32 v17, v8
	v_mov_b32_e32 v18, v8
	v_mov_b32_e32 v19, v8
	v_mov_b32_e32 v32, v8
	v_mov_b32_e32 v33, v8
	v_mov_b32_e32 v34, v8
	v_mov_b32_e32 v35, v8
	v_mov_b32_e32 v48, v8
	v_mov_b32_e32 v49, v8
	v_mov_b32_e32 v50, v8
	v_mov_b32_e32 v51, v8
	v_mov_b32_e32 v64, v8
	v_mov_b32_e32 v65, v8
	v_mov_b32_e32 v66, v8
	v_mov_b32_e32 v67, v8
	v_mov_b32_e32 v80, v8
	v_mov_b32_e32 v81, v8
	v_mov_b32_e32 v82, v8
	v_mov_b32_e32 v83, v8
	v_mov_b32_e32 v96, v8
	v_mov_b32_e32 v97, v8
	v_mov_b32_e32 v98, v8
	v_mov_b32_e32 v99, v8
	v_mov_b32_e32 v112, v8
	v_mov_b32_e32 v113, v8
	v_mov_b32_e32 v114, v8
	v_mov_b32_e32 v115, v8
	v_mov_b32_e32 v124, v8
	v_mov_b32_e32 v125, v8
	v_mov_b32_e32 v126, v8
	v_mov_b32_e32 v127, v8
	s_waitcnt vmcnt(0) lgkmcnt(0)
	s_barrier
	s_branch .LBB0_404

; DI int tid_opaque() { int t = threadIdx.x; asm volatile("" : "+v"(t)); return t; }
; #define LDS_PTR(p) ((__attribute__((address_space(3))) unsigned*)(p))
; template <int PIPE>
; DI void gemm_loop_g(const u16* __restrict__ Xp, long ldx_l, long ldx_i, long kxs,
;                     const u16* __restrict__ Yp, long ldy_l, long ldy_i, long kys, int K,
;                     f32x4 (&acc)[4][8], unsigned char* smem) {
;   const int t = tid_opaque(), l = t & 63, w = __builtin_amdgcn_readfirstlane(t >> 6), wx = w >> 1, wy = w & 1;
;   const int lrow = t >> 3, gch = (t & 7) ^ ((t >> 4) & 7);
;   const u16* xs = Xp + (long)lrow * ldx_l + gch * 8;
;   const u16* ys = Yp + (long)lrow * ldy_l + gch * 8;
;   const int fsw = (l >> 1) & 7, lg = l >> 4;
;   const unsigned fr0 = (l & 15) * 128 + ((lg ^ fsw) << 4);
;   const unsigned fr1 = (l & 15) * 128 + (((lg + 4) ^ fsw) << 4);
;   const unsigned ub = wx * 8192, vb = 32768 + wy * 16384;
;   const int nk = K >> 6;
;   const int rot = (int)((blockIdx.x >> 3) + (blockIdx.x & 7) * 5) % nk;
;   auto issue = [&](int kt0, int stage) {
;     int kt = kt0 + rot; if (kt >= nk) kt -= nk;
;     unsigned char* sb = smem + stage * 65536 + t * 16;
; #pragma unroll
;     for (int i = 0; i < 4; ++i)
;       __builtin_amdgcn_global_load_lds((const unsigned*)(xs + i * ldx_i + kt * kxs), LDS_PTR(sb + i * 8192), 16, 0, 0);
; #pragma unroll
;     for (int i = 0; i < 4; ++i)
;       __builtin_amdgcn_global_load_lds((const unsigned*)(ys + i * ldy_i + kt * kys), LDS_PTR(sb + 32768 + i * 8192), 16, 0, 0);
;   };
;   __syncthreads();
;   issue(0, 0);
;   asm volatile("s_waitcnt vmcnt(0)" ::: "memory");
;   __syncthreads();
; DI void zero_acc(f32x4 (&acc)[4][8]) {
; #pragma unroll
;   for (int i = 0; i < 4; ++i)
; #pragma unroll
;     for (int j = 0; j < 8; ++j) acc[i][j] = f32x4{0.f, 0.f, 0.f, 0.f};
; }
.LBB0_407:
	s_and_b64 vcc, exec, s[70:71]
	s_cbranch_vccz .LBB0_412
	s_nop 1
	v_mov_b32_e32 v4, v182
	s_nop 0
	v_ashrrev_i32_e32 v0, 3, v4
	v_lshrrev_b32_e32 v5, 4, v4
	v_xor_b32_e32 v6, v5, v4
	v_ashrrev_i32_e32 v1, 31, v0
	v_lshlrev_b64 v[0:1], 9, v[0:1]
	v_lshlrev_b32_e32 v6, 4, v6
	v_lshl_add_u64 v[2:3], s[68:69], 0, v[0:1]
	v_and_b32_e32 v128, 0x70, v6
	v_lshl_add_u64 v[0:1], s[16:17], 0, v[0:1]
	v_lshl_add_u64 v[130:131], v[2:3], 0, v[128:129]
	v_lshl_add_u64 v[132:133], v[0:1], 0, v[128:129]
	v_lshlrev_b32_e32 v128, 4, v4
	v_add_u32_e32 v2, 0x2000, v128
	v_readfirstlane_b32 s6, v128
	v_lshl_add_u64 v[0:1], v[130:131], 0, s[54:55]
	s_mov_b32 m0, s6
	v_lshl_add_u64 v[134:135], v[130:131], 0, s[56:57]
	v_readfirstlane_b32 s6, v2
	v_add_u32_e32 v2, 0x4000, v128
	s_barrier
	global_load_lds_dwordx4 v[0:1], off
	v_lshl_add_u64 v[0:1], v[134:135], 0, s[54:55]
	s_mov_b32 m0, s6
	v_lshl_add_u64 v[136:137], v[130:131], 0, s[58:59]
	v_readfirstlane_b32 s6, v2
	v_add_u32_e32 v2, 0x6000, v128
	global_load_lds_dwordx4 v[0:1], off
	v_lshl_add_u64 v[0:1], v[136:137], 0, s[54:55]
	s_mov_b32 m0, s6
	v_lshl_add_u64 v[138:139], v[130:131], 0, s[60:61]
	v_readfirstlane_b32 s6, v2
	v_add_u32_e32 v2, 0x8000, v128
	global_load_lds_dwordx4 v[0:1], off
	v_lshl_add_u64 v[0:1], v[138:139], 0, s[54:55]
	s_mov_b32 m0, s6
	v_readfirstlane_b32 s6, v2
	v_add_u32_e32 v2, 0xa000, v128
	global_load_lds_dwordx4 v[0:1], off
	v_lshl_add_u64 v[0:1], v[132:133], 0, s[54:55]
	s_mov_b32 m0, s6
	v_lshl_add_u64 v[140:141], v[132:133], 0, s[56:57]
	v_readfirstlane_b32 s6, v2
	v_add_u32_e32 v2, 0xc000, v128
	global_load_lds_dwordx4 v[0:1], off
	v_lshl_add_u64 v[0:1], v[140:141], 0, s[54:55]
	s_mov_b32 m0, s6
	v_lshl_add_u64 v[142:143], v[132:133], 0, s[58:59]
	v_readfirstlane_b32 s6, v2
	v_add_u32_e32 v2, 0xe000, v128
	global_load_lds_dwordx4 v[0:1], off
	v_lshl_add_u64 v[0:1], v[142:143], 0, s[54:55]
	s_mov_b32 m0, s6
	v_lshl_add_u64 v[144:145], v[132:133], 0, s[60:61]
	v_readfirstlane_b32 s6, v2
	global_load_lds_dwordx4 v[0:1], off
	v_lshl_add_u64 v[0:1], v[144:145], 0, s[54:55]
	s_mov_b32 m0, s6
	v_lshlrev_b32_e32 v2, 7, v4
	global_load_lds_dwordx4 v[0:1], off
	v_bfe_u32 v0, v4, 4, 2
	v_bfe_u32 v1, v4, 1, 3
	v_readfirstlane_b32 s7, v4
	s_nop 0
	v_bitop3_b32 v0, v0, v1, 4 bitop3:0x36
	v_and_b32_e32 v2, 0x780, v2
	s_lshl_b32 s6, s7, 8
	s_lshl_b32 s7, s7, 6
	v_lshl_or_b32 v152, v0, 4, v2
	v_bitop3_b32 v0, v5, v1, 3 bitop3:0x6c
	v_mov_b32_e32 v8, 0
	s_and_b32 s6, s6, 0x4000
	s_and_b32 s7, s7, 0xffffe000
	v_lshl_or_b32 v153, v0, 4, v2
	s_mov_b32 s10, 0
	s_mov_b32 s11, 0x10000
	v_mov_b32_e32 v9, v8
	v_mov_b32_e32 v10, v8
	v_mov_b32_e32 v11, v8
	v_mov_b32_e32 v12, v8
	v_mov_b32_e32 v13, v8
	v_mov_b32_e32 v14, v8
	v_mov_b32_e32 v15, v8
	v_mov_b32_e32 v28, v8
	v_mov_b32_e32 v29, v8
	v_mov_b32_e32 v30, v8
	v_mov_b32_e32 v31, v8
	v_mov_b32_e32 v44, v8
	v_mov_b32_e32 v45, v8
	v_mov_b32_e32 v46, v8
	v_mov_b32_e32 v47, v8
	v_mov_b32_e32 v60, v8
	v_mov_b32_e32 v61, v8
	v_mov_b32_e32 v62, v8
	v_mov_b32_e32 v63, v8
	v_mov_b32_e32 v76, v8
	v_mov_b32_e32 v77, v8
	v_mov_b32_e32 v78, v8
	v_mov_b32_e32 v79, v8
	v_mov_b32_e32 v92, v8
	v_mov_b32_e32 v93, v8
	v_mov_b32_e32 v94, v8
	v_mov_b32_e32 v95, v8
	v_mov_b32_e32 v108, v8
	v_mov_b32_e32 v109, v8
	v_mov_b32_e32 v110, v8
	v_mov_b32_e32 v111, v8
	v_mov_b32_e32 v0, v8
	v_mov_b32_e32 v1, v8
	v_mov_b32_e32 v2, v8
	v_mov_b32_e32 v3, v8
	v_mov_b32_e32 v20, v8
	v_mov_b32_e32 v21, v8
	v_mov_b32_e32 v22, v8
	v_mov_b32_e32 v23, v8
	v_mov_b32_e32 v36, v8
	v_mov_b32_e32 v37, v8
	v_mov_b32_e32 v38, v8
	v_mov_b32_e32 v39, v8
	v_mov_b32_e32 v52, v8
	v_mov_b32_e32 v53, v8
	v_mov_b32_e32 v54, v8
	v_mov_b32_e32 v55, v8
	v_mov_b32_e32 v68, v8
	v_mov_b32_e32 v69, v8
	v_mov_b32_e32 v70, v8
	v_mov_b32_e32 v71, v8
	v_mov_b32_e32 v84, v8
	v_mov_b32_e32 v85, v8
	v_mov_b32_e32 v86, v8
	v_mov_b32_e32 v87, v8
	v_mov_b32_e32 v100, v8
	v_mov_b32_e32 v101, v8
	v_mov_b32_e32 v102, v8
	v_mov_b32_e32 v103, v8
	v_mov_b32_e32 v116, v8
	v_mov_b32_e32 v117, v8
	v_mov_b32_e32 v118, v8
	v_mov_b32_e32 v119, v8
	v_mov_b32_e32 v4, v8
	v_mov_b32_e32 v5, v8
	v_mov_b32_e32 v6, v8
	v_mov_b32_e32 v7, v8
	v_mov_b32_e32 v24, v8
	v_mov_b32_e32 v25, v8
	v_mov_b32_e32 v26, v8
	v_mov_b32_e32 v27, v8
	v_mov_b32_e32 v40, v8
	v_mov_b32_e32 v41, v8
	v_mov_b32_e32 v42, v8
	v_mov_b32_e32 v43, v8
	v_mov_b32_e32 v56, v8
	v_mov_b32_e32 v57, v8
	v_mov_b32_e32 v58, v8
	v_mov_b32_e32 v59, v8
	v_mov_b32_e32 v72, v8
	v_mov_b32_e32 v73, v8
	v_mov_b32_e32 v74, v8
	v_mov_b32_e32 v75, v8
	v_mov_b32_e32 v88, v8
	v_mov_b32_e32 v89, v8
	v_mov_b32_e32 v90, v8
	v_mov_b32_e32 v91, v8
	v_mov_b32_e32 v104, v8
	v_mov_b32_e32 v105, v8
	v_mov_b32_e32 v106, v8
	v_mov_b32_e32 v107, v8
	v_mov_b32_e32 v120, v8
	v_mov_b32_e32 v121, v8
	v_mov_b32_e32 v122, v8
	v_mov_b32_e32 v123, v8
	v_mov_b32_e32 v16, v8
	v_mov_b32_e32 v17, v8
	v_mov_b32_e32 v18, v8
	v_mov_b32_e32 v19, v8
	v_mov_b32_e32 v32, v8
	v_mov_b32_e32 v33, v8
	v_mov_b32_e32 v34, v8
	v_mov_b32_e32 v35, v8
	v_mov_b32_e32 v48, v8
	v_mov_b32_e32 v49, v8
	v_mov_b32_e32 v50, v8
	v_mov_b32_e32 v51, v8
	v_mov_b32_e32 v64, v8
	v_mov_b32_e32 v65, v8
	v_mov_b32_e32 v66, v8
	v_mov_b32_e32 v67, v8
	v_mov_b32_e32 v80, v8
	v_mov_b32_e32 v81, v8
	v_mov_b32_e32 v82, v8
	v_mov_b32_e32 v83, v8
	v_mov_b32_e32 v96, v8
	v_mov_b32_e32 v97, v8
	v_mov_b32_e32 v98, v8
	v_mov_b32_e32 v99, v8
	v_mov_b32_e32 v112, v8
	v_mov_b32_e32 v113, v8
	v_mov_b32_e32 v114, v8
	v_mov_b32_e32 v115, v8
	v_mov_b32_e32 v124, v8
	v_mov_b32_e32 v125, v8
	v_mov_b32_e32 v126, v8
	v_mov_b32_e32 v127, v8
	s_waitcnt vmcnt(0) lgkmcnt(0)
	s_barrier
	s_branch .LBB0_410

; DI int tid_opaque() { int t = threadIdx.x; asm volatile("" : "+v"(t)); return t; }
; #define LDS_PTR(p) ((__attribute__((address_space(3))) unsigned*)(p))
; DI void mla_attn(const u16* q, const u16* kn, const u16* kpe, const u16* vt, u16* o, unsigned char* smem) {
;     ...
;   for (int item = blockIdx.x; item < 20 * 8 * NQB; item += gridDim.x) {
;     const int qb = item % NQB, h = (item / NQB) & 7, b = item / (NQB * 8);
;     const long tb = (long)b * 4096;
;     bf16x8 qf[NQT][6];
; #pragma unroll
;     for (int qt = 0; qt < NQT; ++qt)
; #pragma unroll
;       for (int ks = 0; ks < 6; ++ks)
;         qf[qt][ks] = *(const bf16x8*)(q + (tb + qb * QPB + w * 16 * NQT + qt * 16 + lq) * 1536 + h * 192 + ks * 32 + lg * 8);
;     f32x4 oacc[8][NQT];
; #pragma unroll
;     for (int dt = 0; dt < 8; ++dt)
; #pragma unroll
;       for (int qt = 0; qt < NQT; ++qt) oacc[dt][qt] = f32x4{0.f, 0.f, 0.f, 0.f};
;     float mrun[NQT], lrun[NQT];
; #pragma unroll
;     for (int qt = 0; qt < NQT; ++qt) { mrun[qt] = -1e30f; lrun[qt] = 0.f; }
;     auto issue = [&](int kt, int stage) {
;       const int t2 = tid_opaque();
;       unsigned char* sb = smem + stage * MSTAGE + t2 * 16;
;       const long k0 = tb + kt * 64;
; #pragma unroll
;       for (int i = 0; i < 3; ++i) {
;         const int cid = t2 + 512 * i, row = cid / 24, c = (cid - row * 24) ^ ((row >> 1) & 7);
;         const u16* src = c < 16 ? kn + (k0 + row) * 1024 + h * 128 + c * 8 : kpe + (k0 + row) * 64 + (c - 16) * 8;
;         __builtin_amdgcn_global_load_lds((const unsigned*)src, LDS_PTR(sb + i * 8192), 16, 0, 0);
;       }
.LBB0_429:
	s_and_b32 s99, s64, 7
	s_mul_i32 s99, s99, 0x140
	s_lshr_b32 s98, s64, 3
	s_add_i32 s99, s99, s98
	s_ashr_i32 s7, s99, 31
	s_lshr_b32 s6, s7, 28
	s_add_i32 s6, s99, s6
	s_lshr_b32 s7, s7, 25
	s_and_b32 s8, s6, 0xfffff0
	s_add_i32 s7, s99, s7
	s_sub_i32 s8, s99, s8
	s_ashr_i32 s54, s7, 7
	s_ashr_i32 s55, s54, 31
	s_lshl_b32 s7, s8, 8
	s_bfe_u32 s6, s6, 0x30004
	s_lshl_b64 s[30:31], s[54:55], 12
	s_ashr_i32 s9, s7, 31
	s_add_u32 s8, s30, s7
	s_addc_u32 s9, s31, s9
	s_mul_i32 s14, s6, 0x180
	v_lshl_add_u64 v[124:125], s[8:9], 0, v[116:117]
	v_lshl_add_u64 v[0:1], v[120:121], 0, s[14:15]
	v_mad_u64_u32 v[24:25], s[8:9], v124, s60, v[0:1]
	v_mov_b32_e32 v0, v25
	v_mad_u64_u32 v[26:27], s[8:9], v125, s60, v[0:1]
	v_mov_b32_e32 v25, v26
	v_add_co_u32_e32 v40, vcc, s61, v24
	v_lshl_add_u64 v[44:45], v[24:25], 0, s[16:17]
	s_nop 0
	v_addc_co_u32_e32 v41, vcc, 0, v26, vcc
	global_load_dwordx4 v[0:3], v[24:25], off
	global_load_dwordx4 v[4:7], v[24:25], off offset:64
	global_load_dwordx4 v[8:11], v[24:25], off offset:128
	global_load_dwordx4 v[12:15], v[24:25], off offset:192
	global_load_dwordx4 v[16:19], v[24:25], off offset:256
	global_load_dwordx4 v[20:23], v[24:25], off offset:320
	s_nop 0
	global_load_dwordx4 v[24:27], v[44:45], off offset:64
	global_load_dwordx4 v[28:31], v[44:45], off offset:128
	global_load_dwordx4 v[32:35], v[44:45], off offset:192
	global_load_dwordx4 v[36:39], v[44:45], off offset:256
	s_nop 0
	global_load_dwordx4 v[40:43], v[40:41], off
	s_nop 0
	global_load_dwordx4 v[44:47], v[44:45], off offset:320
	v_mov_b32_e32 v48, v182
	s_barrier
	s_nop 0
	v_mul_hi_i32 v49, v48, s62
	v_lshrrev_b32_e32 v50, 31, v49
	v_ashrrev_i32_e32 v49, 2, v49
	v_add_u32_e32 v50, v49, v50
	v_mad_u64_u32 v[52:53], s[8:9], v50, s63, v[48:49]
	v_lshrrev_b32_e32 v49, 1, v50
	v_bitop3_b32 v49, v52, v49, 7 bitop3:0x78
	v_ashrrev_i32_e32 v51, 31, v50
	v_cmp_lt_i32_e32 vcc, 15, v49
	v_lshl_add_u64 v[52:53], s[30:31], 0, v[50:51]
	s_and_saveexec_b64 s[8:9], vcc
	s_xor_b64 s[56:57], exec, s[8:9]
	v_lshlrev_b64 v[50:51], 7, v[52:53]
	v_lshl_add_u64 v[50:51], s[18:19], 0, v[50:51]
	v_lshl_add_u32 v118, v49, 3, v165
	v_lshl_add_u64 v[50:51], v[118:119], 1, v[50:51]
	s_andn2_saveexec_b64 s[56:57], s[56:57]
	v_lshlrev_b64 v[50:51], 11, v[52:53]
	v_lshl_add_u64 v[50:51], s[24:25], 0, v[50:51]
	s_lshl_b32 s14, s6, 8
	v_lshlrev_b32_e32 v52, 3, v49
	v_lshl_add_u64 v[50:51], v[50:51], 0, s[14:15]
	v_ashrrev_i32_e32 v53, 31, v52
	v_lshl_add_u64 v[50:51], v[52:53], 1, v[50:51]
	s_or_b64 exec, exec, s[56:57]
	v_lshlrev_b32_e32 v49, 4, v48
	s_nop 0
	v_readfirstlane_b32 s7, v49
	s_mov_b32 m0, s7
	s_nop 0
	global_load_lds_dwordx4 v[50:51], off
	v_add_u32_e32 v50, 0x200, v48
	v_mul_hi_i32 v51, v50, s62
	v_lshrrev_b32_e32 v52, 31, v51
	v_ashrrev_i32_e32 v51, 2, v51
	v_add_u32_e32 v52, v51, v52
	v_mad_u64_u32 v[54:55], s[8:9], v52, s63, v[50:51]
	v_lshrrev_b32_e32 v51, 1, v52
	v_bitop3_b32 v51, v54, v51, 7 bitop3:0x78
	v_ashrrev_i32_e32 v53, 31, v52
	v_cmp_lt_i32_e32 vcc, 15, v51
	v_lshl_add_u64 v[54:55], s[30:31], 0, v[52:53]
	s_and_saveexec_b64 s[8:9], vcc
	s_xor_b64 s[56:57], exec, s[8:9]
	v_lshlrev_b64 v[52:53], 7, v[54:55]
	v_lshl_add_u64 v[52:53], s[18:19], 0, v[52:53]
	v_lshl_add_u32 v118, v51, 3, v165
	v_lshl_add_u64 v[52:53], v[118:119], 1, v[52:53]
	s_andn2_saveexec_b64 s[56:57], s[56:57]
	v_lshlrev_b64 v[52:53], 11, v[54:55]
	v_lshl_add_u64 v[52:53], s[24:25], 0, v[52:53]
	s_lshl_b32 s14, s6, 8
	v_lshlrev_b32_e32 v54, 3, v51
	v_lshl_add_u64 v[52:53], v[52:53], 0, s[14:15]
	v_ashrrev_i32_e32 v55, 31, v54
	v_lshl_add_u64 v[52:53], v[54:55], 1, v[52:53]
	s_or_b64 exec, exec, s[56:57]
	v_add_u32_e32 v51, 0x2000, v49
	s_nop 0
	v_readfirstlane_b32 s7, v51
	s_mov_b32 m0, s7
	s_nop 0
	global_load_lds_dwordx4 v[52:53], off
	v_add_u32_e32 v52, 0x400, v48
	v_mul_hi_i32 v51, v52, s62
	v_lshrrev_b32_e32 v53, 31, v51
	v_ashrrev_i32_e32 v51, 2, v51
	v_add_u32_e32 v54, v51, v53
	v_mad_u64_u32 v[52:53], s[8:9], v54, s63, v[52:53]
	v_lshrrev_b32_e32 v51, 1, v54
	v_bitop3_b32 v51, v52, v51, 7 bitop3:0x78
	v_ashrrev_i32_e32 v55, 31, v54
	v_cmp_lt_i32_e32 vcc, 15, v51
	v_lshl_add_u64 v[54:55], s[30:31], 0, v[54:55]
	s_and_saveexec_b64 s[8:9], vcc
	s_xor_b64 s[56:57], exec, s[8:9]
	v_lshlrev_b64 v[52:53], 7, v[54:55]
	v_lshl_add_u64 v[52:53], s[18:19], 0, v[52:53]
	v_lshl_add_u32 v118, v51, 3, v165
	v_lshl_add_u64 v[52:53], v[118:119], 1, v[52:53]
	s_lshl_b32 s7, s6, 7
	s_or_saveexec_b64 s[56:57], s[56:57]
	v_mov_b32_e32 v118, s7
	s_xor_b64 exec, exec, s[56:57]
	v_lshlrev_b64 v[52:53], 11, v[54:55]
	v_lshl_add_u64 v[52:53], s[24:25], 0, v[52:53]
	s_lshl_b32 s14, s6, 8
	v_lshlrev_b32_e32 v54, 3, v51
	s_lshl_b32 s7, s6, 7
	v_lshl_add_u64 v[52:53], v[52:53], 0, s[14:15]
	v_ashrrev_i32_e32 v55, 31, v54
	v_lshl_add_u64 v[52:53], v[54:55], 1, v[52:53]
	v_mov_b32_e32 v118, s7
	s_or_b64 exec, exec, s[56:57]
	v_add_u32_e32 v51, 0x4000, v49
	v_lshl_add_u32 v167, s54, 10, v118
	v_readfirstlane_b32 s6, v51
	v_lshrrev_b32_e32 v51, 4, v48
	s_mov_b32 m0, s6
	v_xor_b32_e32 v51, v51, v48
	v_ashrrev_i32_e32 v48, 3, v48
	global_load_lds_dwordx4 v[52:53], off
	v_add_u32_e32 v52, v167, v48
	v_lshlrev_b32_e32 v48, 4, v51
	v_and_b32_e32 v54, 0x70, v48
	v_add_u32_e32 v48, 0x6000, v49
	v_ashrrev_i32_e32 v53, 31, v52
	v_readfirstlane_b32 s6, v48
	v_ashrrev_i32_e32 v48, 3, v50
	v_add_u32_e32 v50, v167, v48
	v_lshlrev_b64 v[52:53], 13, v[52:53]
	v_ashrrev_i32_e32 v51, 31, v50
	v_lshl_add_u64 v[52:53], s[26:27], 0, v[52:53]
	v_mov_b32_e32 v55, v119
	v_lshlrev_b64 v[50:51], 13, v[50:51]
	v_add_u32_e32 v48, 0x8000, v49
	v_lshl_add_u64 v[52:53], v[52:53], 0, v[54:55]
	s_mov_b32 m0, s6
; #define LDS_PTR(p) ((__attribute__((address_space(3))) unsigned*)(p))
; DI void mla_attn(const u16* q, const u16* kn, const u16* kpe, const u16* vt, u16* o, unsigned char* smem) {
;     ...
;     f32x4 oacc[8][NQT];
; #pragma unroll
;     for (int dt = 0; dt < 8; ++dt)
; #pragma unroll
;       for (int qt = 0; qt < NQT; ++qt) oacc[dt][qt] = f32x4{0.f, 0.f, 0.f, 0.f};
;     float mrun[NQT], lrun[NQT];
; #pragma unroll
;     for (int qt = 0; qt < NQT; ++qt) { mrun[qt] = -1e30f; lrun[qt] = 0.f; }
;     ...
; #pragma unroll
;       for (int i = 0; i < 2; ++i) {
;         const int cid = t2 + 512 * i, d = cid >> 3, c = (cid & 7) ^ ((d >> 1) & 7);
;         __builtin_amdgcn_global_load_lds((const unsigned*)(vt + ((long)(b * 1024 + h * 128 + d)) * 4096 + kt * 64 + c * 8),
;                                          LDS_PTR(sb + 24576 + i * 8192), 16, 0, 0);
;       }
;     };
;     __syncthreads();
;     issue(0, 0);
;     issue(1, 1);
;     int st = 0;
	v_lshl_add_u64 v[50:51], s[26:27], 0, v[50:51]
	v_readfirstlane_b32 s6, v48
	global_load_lds_dwordx4 v[52:53], off
	v_lshl_add_u64 v[50:51], v[50:51], 0, v[54:55]
	s_mov_b32 m0, s6
	v_mov_b32_e32 v48, v182
	global_load_lds_dwordx4 v[50:51], off
	s_or_b32 s54, s30, 64
	v_mul_hi_i32 v49, v48, s62
	v_lshrrev_b32_e32 v50, 31, v49
	v_ashrrev_i32_e32 v49, 2, v49
	v_add_u32_e32 v50, v49, v50
	v_mad_u64_u32 v[52:53], s[6:7], v50, s63, v[48:49]
	v_lshrrev_b32_e32 v49, 1, v50
	s_mov_b32 s55, s31
	v_bitop3_b32 v49, v52, v49, 7 bitop3:0x78
	v_ashrrev_i32_e32 v51, 31, v50
	v_cmp_lt_i32_e32 vcc, 15, v49
	v_lshl_add_u64 v[52:53], s[54:55], 0, v[50:51]
	s_and_saveexec_b64 s[6:7], vcc
	s_xor_b64 s[56:57], exec, s[6:7]
	v_lshlrev_b64 v[50:51], 7, v[52:53]
	v_lshl_add_u64 v[50:51], s[18:19], 0, v[50:51]
	v_lshl_add_u32 v52, v49, 3, v165
	v_mov_b32_e32 v53, v119
	v_lshl_add_u64 v[50:51], v[52:53], 1, v[50:51]
	s_andn2_saveexec_b64 s[56:57], s[56:57]
	v_lshlrev_b64 v[50:51], 11, v[52:53]
	v_lshl_add_u64 v[50:51], s[24:25], 0, v[50:51]
	v_lshlrev_b32_e32 v52, 3, v49
	v_lshl_add_u64 v[50:51], v[118:119], 1, v[50:51]
	v_ashrrev_i32_e32 v53, 31, v52
	v_lshl_add_u64 v[50:51], v[52:53], 1, v[50:51]
	s_or_b64 exec, exec, s[56:57]
	v_lshlrev_b32_e32 v56, 4, v48
	v_add_u32_e32 v49, 0xa000, v56
	s_nop 0
	v_readfirstlane_b32 s6, v49
	s_mov_b32 m0, s6
	s_nop 0
	global_load_lds_dwordx4 v[50:51], off
	v_add_u32_e32 v50, 0x200, v48
	v_mul_hi_i32 v51, v50, s62
	v_lshrrev_b32_e32 v52, 31, v51
	v_ashrrev_i32_e32 v51, 2, v51
	v_add_u32_e32 v52, v51, v52
	v_mad_u64_u32 v[54:55], s[6:7], v52, s63, v[50:51]
	v_lshrrev_b32_e32 v51, 1, v52
	v_bitop3_b32 v51, v54, v51, 7 bitop3:0x78
	v_ashrrev_i32_e32 v53, 31, v52
	v_cmp_lt_i32_e32 vcc, 15, v51
	v_lshl_add_u64 v[54:55], s[54:55], 0, v[52:53]
	s_and_saveexec_b64 s[6:7], vcc
	s_xor_b64 s[56:57], exec, s[6:7]
	v_lshlrev_b64 v[52:53], 7, v[54:55]
	v_lshl_add_u64 v[52:53], s[18:19], 0, v[52:53]
	v_lshl_add_u32 v54, v51, 3, v165
	v_mov_b32_e32 v55, v119
	v_lshl_add_u64 v[52:53], v[54:55], 1, v[52:53]
	s_andn2_saveexec_b64 s[56:57], s[56:57]
	v_lshlrev_b64 v[52:53], 11, v[54:55]
	v_lshl_add_u64 v[52:53], s[24:25], 0, v[52:53]
	v_lshlrev_b32_e32 v54, 3, v51
	v_lshl_add_u64 v[52:53], v[118:119], 1, v[52:53]
	v_ashrrev_i32_e32 v55, 31, v54
	v_lshl_add_u64 v[52:53], v[54:55], 1, v[52:53]
	s_or_b64 exec, exec, s[56:57]
	v_add_u32_e32 v51, 0xc000, v56
	v_mov_b64_e32 v[126:127], v[118:119]
	v_readfirstlane_b32 s6, v51
	s_mov_b32 m0, s6
	s_nop 0
	global_load_lds_dwordx4 v[52:53], off
	v_add_u32_e32 v52, 0x400, v48
	v_mul_hi_i32 v51, v52, s62
	v_lshrrev_b32_e32 v53, 31, v51
	v_ashrrev_i32_e32 v51, 2, v51
	v_add_u32_e32 v54, v51, v53
	v_mad_u64_u32 v[52:53], s[6:7], v54, s63, v[52:53]
	v_lshrrev_b32_e32 v51, 1, v54
	v_bitop3_b32 v51, v52, v51, 7 bitop3:0x78
	v_ashrrev_i32_e32 v55, 31, v54
	v_cmp_lt_i32_e32 vcc, 15, v51
	v_lshl_add_u64 v[54:55], s[54:55], 0, v[54:55]
	s_and_saveexec_b64 s[6:7], vcc
	s_xor_b64 s[54:55], exec, s[6:7]
	v_lshlrev_b64 v[52:53], 7, v[54:55]
	v_lshl_add_u64 v[52:53], s[18:19], 0, v[52:53]
	v_lshl_add_u32 v54, v51, 3, v165
	v_mov_b32_e32 v55, v119
	v_lshl_add_u64 v[52:53], v[54:55], 1, v[52:53]
	v_mov_b64_e32 v[126:127], v[118:119]
	s_andn2_saveexec_b64 s[54:55], s[54:55]
	v_lshlrev_b64 v[52:53], 11, v[54:55]
	v_lshl_add_u64 v[52:53], s[24:25], 0, v[52:53]
	v_lshlrev_b32_e32 v54, 3, v51
	v_lshl_add_u64 v[52:53], v[118:119], 1, v[52:53]
	v_ashrrev_i32_e32 v55, 31, v54
	v_lshl_add_u64 v[52:53], v[54:55], 1, v[52:53]
	s_or_b64 exec, exec, s[54:55]
	v_add_u32_e32 v51, 0xe000, v56
	v_add_u32_e32 v54, 0x6000, v49
	v_readfirstlane_b32 s6, v51
	v_lshrrev_b32_e32 v51, 4, v48
	s_mov_b32 m0, s6
	v_xor_b32_e32 v51, v51, v48
	v_ashrrev_i32_e32 v48, 3, v48
	global_load_lds_dwordx4 v[52:53], off
	v_add_u32_e32 v52, v48, v167
	v_lshlrev_b32_e32 v48, 4, v51
	v_and_b32_e32 v118, 0x70, v48
	v_ashrrev_i32_e32 v48, 3, v50
	v_ashrrev_i32_e32 v53, 31, v52
	v_add_u32_e32 v50, v48, v167
	v_lshlrev_b64 v[52:53], 13, v[52:53]
	v_ashrrev_i32_e32 v51, 31, v50
	v_lshl_add_u64 v[52:53], s[26:27], 0, v[52:53]
	v_lshlrev_b64 v[50:51], 13, v[50:51]
	v_lshl_add_u64 v[52:53], v[52:53], 0, v[118:119]
	v_readfirstlane_b32 s6, v54
	v_lshl_add_u64 v[50:51], s[26:27], 0, v[50:51]
	v_add_u32_e32 v48, 0x8000, v49
	v_lshl_add_u64 v[52:53], v[52:53], 0, s[28:29]
	s_mov_b32 m0, s6
	v_lshl_add_u64 v[50:51], v[50:51], 0, v[118:119]
	v_readfirstlane_b32 s6, v48
	global_load_lds_dwordx4 v[52:53], off
	v_lshl_add_u64 v[50:51], v[50:51], 0, s[28:29]
	s_mov_b32 m0, s6
	s_add_u32 s6, s30, 0x80
	global_load_lds_dwordx4 v[50:51], off
	v_mov_b32_e32 v48, 0
	v_lshl_add_u64 v[130:131], v[126:127], 1, s[24:25]
	s_addc_u32 s7, s31, 0
	s_mov_b32 s10, 0
	s_mov_b64 s[30:31], 0
	s_mov_b64 s[54:55], s[12:13]
	s_mov_b32 s11, 0
	v_mov_b32_e32 v49, v48
	v_mov_b32_e32 v50, v48
	v_mov_b32_e32 v51, v48
	v_mov_b32_e32 v76, v48
	v_mov_b32_e32 v77, v48
	v_mov_b32_e32 v78, v48
	v_mov_b32_e32 v79, v48
	v_mov_b32_e32 v52, v48
	v_mov_b32_e32 v53, v48
	v_mov_b32_e32 v54, v48
	v_mov_b32_e32 v55, v48
	v_mov_b32_e32 v88, v48
	v_mov_b32_e32 v89, v48
	v_mov_b32_e32 v90, v48
	v_mov_b32_e32 v91, v48
	v_mov_b32_e32 v56, v48
	v_mov_b32_e32 v57, v48
	v_mov_b32_e32 v58, v48
	v_mov_b32_e32 v59, v48
	v_mov_b32_e32 v96, v48
	v_mov_b32_e32 v97, v48
	v_mov_b32_e32 v98, v48
	v_mov_b32_e32 v99, v48
	v_mov_b32_e32 v64, v48
	v_mov_b32_e32 v65, v48
	v_mov_b32_e32 v66, v48
	v_mov_b32_e32 v67, v48
	v_mov_b32_e32 v100, v48
	v_mov_b32_e32 v101, v48
	v_mov_b32_e32 v102, v48
	v_mov_b32_e32 v103, v48
	v_mov_b32_e32 v68, v48
	v_mov_b32_e32 v69, v48
	v_mov_b32_e32 v70, v48
	v_mov_b32_e32 v71, v48
	v_mov_b32_e32 v104, v48
	v_mov_b32_e32 v105, v48
	v_mov_b32_e32 v106, v48
	v_mov_b32_e32 v107, v48
	v_mov_b32_e32 v72, v48
	v_mov_b32_e32 v73, v48
	v_mov_b32_e32 v74, v48
	v_mov_b32_e32 v75, v48
	v_mov_b32_e32 v108, v48
	v_mov_b32_e32 v109, v48
	v_mov_b32_e32 v110, v48
	v_mov_b32_e32 v111, v48
	v_mov_b32_e32 v92, v48
	v_mov_b32_e32 v93, v48
	v_mov_b32_e32 v94, v48
	v_mov_b32_e32 v95, v48
	v_mov_b32_e32 v60, v48
	v_mov_b32_e32 v61, v48
	v_mov_b32_e32 v62, v48
	v_mov_b32_e32 v63, v48
	v_mov_b32_e32 v80, v48
	v_mov_b32_e32 v81, v48
	v_mov_b32_e32 v82, v48
	v_mov_b32_e32 v83, v48
	v_mov_b32_e32 v84, v48
	v_mov_b32_e32 v85, v48
	v_mov_b32_e32 v86, v48
	v_mov_b32_e32 v87, v48
	v_mov_b32_e32 v128, v48
	v_mov_b32_e32 v129, v48
	s_waitcnt vmcnt(0)
; DI int tid_opaque() { int t = threadIdx.x; asm volatile("" : "+v"(t)); return t; }
; #define LDS_PTR(p) ((__attribute__((address_space(3))) unsigned*)(p))
; DI void mla_attn(const u16* q, const u16* kn, const u16* kpe, const u16* vt, u16* o, unsigned char* smem) {
;     ...
;     auto issue = [&](int kt, int stage) {
;       const int t2 = tid_opaque();
;       unsigned char* sb = smem + stage * MSTAGE + t2 * 16;
;       const long k0 = tb + kt * 64;
; #pragma unroll
;       for (int i = 0; i < 3; ++i) {
;         const int cid = t2 + 512 * i, row = cid / 24, c = (cid - row * 24) ^ ((row >> 1) & 7);
;         const u16* src = c < 16 ? kn + (k0 + row) * 1024 + h * 128 + c * 8 : kpe + (k0 + row) * 64 + (c - 16) * 8;
;         __builtin_amdgcn_global_load_lds((const unsigned*)src, LDS_PTR(sb + i * 8192), 16, 0, 0);
;       }
; #pragma unroll
;       for (int i = 0; i < 2; ++i) {
;         const int cid = t2 + 512 * i, d = cid >> 3, c = (cid & 7) ^ ((d >> 1) & 7);
;         __builtin_amdgcn_global_load_lds((const unsigned*)(vt + ((long)(b * 1024 + h * 128 + d)) * 4096 + kt * 64 + c * 8),
;                                          LDS_PTR(sb + 24576 + i * 8192), 16, 0, 0);
;       }
;     };
;     __syncthreads();
;     issue(0, 0);
;     issue(1, 1);
;     int st = 0;
; #pragma unroll 1
;     for (int kt = 0; kt < 64; ++kt) {
;       if (kt + 1 < 64) asm volatile("s_waitcnt vmcnt(5)" ::: "memory");
;       else asm volatile("s_waitcnt vmcnt(0)" ::: "memory");
;       __builtin_amdgcn_s_barrier();
;       if (kt + 2 < 64) { int s2 = st + 2; if (s2 >= 3) s2 -= 3; issue(kt + 2, s2); }
;       const unsigned char* Kt = smem + st * MSTAGE;
	s_and_b32 s6, s64, 7
	s_mul_i32 s6, s6, 0x140
	s_lshr_b32 s7, s64, 3
	s_add_i32 s7, s6, s7
	s_lshr_b32 s6, s7, 7
	s_bfe_u32 s7, s7, 0x30004
	s_lshl_b32 s8, s6, 23
	s_lshl_b32 s9, s7, 8
	s_add_u32 s9, s9, 0x40000
	s_add_u32 s56, s24, s8
	s_addc_u32 s57, s25, 0
	s_add_u32 s56, s56, s9
	s_addc_u32 s57, s57, 0
	s_lshl_b32 s9, s6, 19
	s_add_u32 s9, s9, 0x4000
	s_add_u32 s58, s18, s9
	s_addc_u32 s59, s19, 0
	s_lshl_b32 s9, s7, 20
	s_add_u32 s9, s9, 0x100
	s_add_u32 s8, s26, s8
	s_addc_u32 s14, s27, 0
	s_add_u32 s8, s8, s9
	s_addc_u32 s9, s14, 0
	v_readfirstlane_b32 s100, v182
	s_mov_b32 s101, 0x42c80000
	s_lshl_b32 s100, s100, 4
	s_mov_b32 s14, 0xaaab
	v_add_u32_e32 v244, 0, v182
	v_mul_u32_u24_e32 v245, s14, v244
	v_lshrrev_b32_e32 v245, 20, v245
	v_mul_u32_u24_e32 v246, 24, v245
	v_sub_u32_e32 v246, v244, v246
	v_bfe_u32 v247, v245, 1, 3
	v_xor_b32_e32 v246, v246, v247
	v_cmp_gt_u32_e32 vcc, 16, v246
	v_lshlrev_b32_e32 v247, 4, v246
	v_lshl_add_u32 v248, v245, 11, v247
	v_lshl_add_u32 v249, v245, 7, v247
	v_add_u32_e32 v249, 0xffffff00, v249
	v_cndmask_b32_e32 v248, v249, v248, vcc
	v_mov_b32_e32 v249, s58
	v_mov_b32_e32 v250, s56
	v_cndmask_b32_e32 v249, v249, v250, vcc
	v_mov_b32_e32 v250, s59
	v_mov_b32_e32 v251, s57
	v_cndmask_b32_e32 v250, v250, v251, vcc
	v_mov_b32_e32 v251, 0x2000
	v_mov_b32_e32 v244, 0x20000
	v_cndmask_b32_e32 v226, v251, v244, vcc
	v_mov_b32_e32 v227, 0
	v_add_co_u32_e32 v216, vcc, v249, v248
	s_nop 1
	v_addc_co_u32_e32 v217, vcc, 0, v250, vcc
	v_add_u32_e32 v244, 512, v182
	v_mul_u32_u24_e32 v245, s14, v244
	v_lshrrev_b32_e32 v245, 20, v245
	v_mul_u32_u24_e32 v246, 24, v245
	v_sub_u32_e32 v246, v244, v246
	v_bfe_u32 v247, v245, 1, 3
	v_xor_b32_e32 v246, v246, v247
	v_cmp_gt_u32_e32 vcc, 16, v246
	v_lshlrev_b32_e32 v247, 4, v246
	v_lshl_add_u32 v248, v245, 11, v247
	v_lshl_add_u32 v249, v245, 7, v247
	v_add_u32_e32 v249, 0xffffff00, v249
	v_cndmask_b32_e32 v248, v249, v248, vcc
	v_mov_b32_e32 v249, s58
	v_mov_b32_e32 v250, s56
	v_cndmask_b32_e32 v249, v249, v250, vcc
	v_mov_b32_e32 v250, s59
	v_mov_b32_e32 v251, s57
	v_cndmask_b32_e32 v250, v250, v251, vcc
	v_mov_b32_e32 v251, 0x2000
	v_mov_b32_e32 v244, 0x20000
	v_cndmask_b32_e32 v228, v251, v244, vcc
	v_mov_b32_e32 v229, 0
	v_add_co_u32_e32 v218, vcc, v249, v248
	s_nop 1
	v_addc_co_u32_e32 v219, vcc, 0, v250, vcc
	v_add_u32_e32 v244, 1024, v182
	v_mul_u32_u24_e32 v245, s14, v244
	v_lshrrev_b32_e32 v245, 20, v245
	v_mul_u32_u24_e32 v246, 24, v245
	v_sub_u32_e32 v246, v244, v246
	v_bfe_u32 v247, v245, 1, 3
	v_xor_b32_e32 v246, v246, v247
	v_cmp_gt_u32_e32 vcc, 16, v246
	v_lshlrev_b32_e32 v247, 4, v246
	v_lshl_add_u32 v248, v245, 11, v247
	v_lshl_add_u32 v249, v245, 7, v247
	v_add_u32_e32 v249, 0xffffff00, v249
	v_cndmask_b32_e32 v248, v249, v248, vcc
	v_mov_b32_e32 v249, s58
	v_mov_b32_e32 v250, s56
	v_cndmask_b32_e32 v249, v249, v250, vcc
	v_mov_b32_e32 v250, s59
	v_mov_b32_e32 v251, s57
	v_cndmask_b32_e32 v250, v250, v251, vcc
	v_mov_b32_e32 v251, 0x2000
	v_mov_b32_e32 v244, 0x20000
	v_cndmask_b32_e32 v230, v251, v244, vcc
	v_mov_b32_e32 v231, 0
	v_add_co_u32_e32 v220, vcc, v249, v248
	s_nop 1
	v_addc_co_u32_e32 v221, vcc, 0, v250, vcc
	v_add_u32_e32 v244, 0, v182
	v_lshrrev_b32_e32 v245, 3, v244
	v_bfe_u32 v246, v245, 1, 3
	v_and_b32_e32 v247, 7, v244
	v_xor_b32_e32 v246, v246, v247
	v_lshlrev_b32_e32 v246, 4, v246
	v_lshl_add_u32 v246, v245, 13, v246
	v_mov_b32_e32 v247, s9
	v_add_co_u32_e32 v222, vcc, s8, v246
	s_nop 1
	v_addc_co_u32_e32 v223, vcc, 0, v247, vcc
	v_add_u32_e32 v244, 512, v182
	v_lshrrev_b32_e32 v245, 3, v244
	v_bfe_u32 v246, v245, 1, 3
	v_and_b32_e32 v247, 7, v244
	v_xor_b32_e32 v246, v246, v247
	v_lshlrev_b32_e32 v246, 4, v246
	v_lshl_add_u32 v246, v245, 13, v246
	v_mov_b32_e32 v247, s9
	v_add_co_u32_e32 v224, vcc, s8, v246
	s_nop 1
	v_addc_co_u32_e32 v225, vcc, 0, v247, vcc
	s_mov_b64 s[56:57], 0x80
	v_add_u32_e32 v232, v155, v154
	v_add_u32_e32 v233, v155, v156
	v_add_u32_e32 v244, v152, v153
	v_add_u32_e32 v234, v244, v161
	v_add_u32_e32 v235, v244, v162
	v_add_u32_e32 v236, v244, v163
	v_add_u32_e32 v237, v244, v164
	s_branch .Lmla_top
.Lmla_top:
	s_waitcnt vmcnt(5)
	s_barrier
	s_mul_i32 s98, s10, 0xa000
	v_add_u32_e32 v238, s98, v232
	v_add_u32_e32 v239, s98, v233
	ds_read_b128 v[184:187], v238 offset:0
	ds_read_b128 v[188:191], v239 offset:0
	ds_read_b128 v[192:195], v238 offset:128
	ds_read_b128 v[196:199], v239 offset:128
	ds_read_b128 v[200:203], v238 offset:256
	ds_read_b128 v[204:207], v239 offset:256
	v_add_u32_e32 v240, s98, v234
	v_add_u32_e32 v241, s98, v235
	v_add_u32_e32 v242, s98, v236
	v_add_u32_e32 v243, s98, v237
	s_add_i32 s99, s10, 2
	s_cmp_gt_u32 s99, 2
	s_cselect_b32 s14, 3, 0
	s_sub_i32 s99, s99, s14
	s_mul_i32 s99, s99, 0xa000
	s_add_i32 s99, s99, s100
	s_cmp_lt_u32 s11, 61
	s_cbranch_scc1 .Lmla_adv
	v_mov_b32_e32 v226, 0
	v_mov_b32_e32 v228, 0
	v_mov_b32_e32 v230, 0
	s_mov_b64 s[56:57], 0
; #define MFMA16(a, b, c) __builtin_amdgcn_mfma_f32_16x16x32_bf16((a), (b), (c), 0, 0, 0)
; DI void mla_attn(const u16* q, const u16* kn, const u16* kpe, const u16* vt, u16* o, unsigned char* smem) {
;     ...
;       f32x4 s[4][NQT];
; #pragma unroll
;       for (int k16 = 0; k16 < 4; ++k16)
; #pragma unroll
;         for (int qt = 0; qt < NQT; ++qt) s[k16][qt] = f32x4{0.f, 0.f, 0.f, 0.f};
; #pragma unroll
;       for (int ks = 0; ks < 6; ++ks) {
; #pragma unroll
;         for (int k16 = 0; k16 < 4; ++k16) {
;           const bf16x8 kf = *(const bf16x8*)(Kt + (k16 * 16 + lq) * 384 + (((ks * 4 + lg) ^ fsw) << 4));
; #pragma unroll
;           for (int qt = 0; qt < NQT; ++qt) s[k16][qt] = MFMA16(kf, qf[qt][ks], s[k16][qt]);
;         }
;         if (ks & 1) __builtin_amdgcn_sched_barrier(0);
;       }
;       bf16x8 pf[NQT][2];
; #pragma unroll
;       for (int qt = 0; qt < NQT; ++qt) {
;         float ps = 0.f;
; #pragma unroll
;         for (int k16 = 0; k16 < 4; ++k16)
; #pragma unroll
;           for (int rr = 0; rr < 4; ++rr) { const float e = __builtin_amdgcn_exp2f(fminf(s[k16][qt][rr], 100.f)); s[k16][qt][rr] = e; ps += e; }
;         lrun[qt] += ps;
;         pf[qt][0] = pack8(s[0][qt], s[1][qt]);
;         pf[qt][1] = pack8(s[2][qt], s[3][qt]);
.Lmla_adv:
	s_waitcnt lgkmcnt(5)
	v_mfma_f32_16x16x32_bf16 v[132:135], v[184:187], v[0:3], 0
	v_mfma_f32_16x16x32_bf16 v[136:139], v[184:187], v[40:43], 0
	ds_read_b128 v[208:211], v238 offset:6144
	s_mov_b32 m0, s99
	s_nop 0
	global_load_lds_dwordx4 v[216:217], off
	s_waitcnt lgkmcnt(5)
	v_mfma_f32_16x16x32_bf16 v[132:135], v[188:191], v[4:7], v[132:135]
	v_mfma_f32_16x16x32_bf16 v[136:139], v[188:191], v[24:27], v[136:139]
	ds_read_b128 v[212:215], v239 offset:6144
	s_add_i32 m0, s99, 0x2000
	v_lshl_add_u64 v[216:217], v[216:217], 0, v[226:227]
	global_load_lds_dwordx4 v[218:219], off
	s_waitcnt lgkmcnt(5)
	v_mfma_f32_16x16x32_bf16 v[132:135], v[192:195], v[8:11], v[132:135]
	v_mfma_f32_16x16x32_bf16 v[136:139], v[192:195], v[28:31], v[136:139]
	ds_read_b128 v[184:187], v238 offset:6272
	s_add_i32 m0, s99, 0x4000
	v_lshl_add_u64 v[218:219], v[218:219], 0, v[228:229]
	global_load_lds_dwordx4 v[220:221], off
	s_waitcnt lgkmcnt(5)
	v_mfma_f32_16x16x32_bf16 v[132:135], v[196:199], v[12:15], v[132:135]
	v_mfma_f32_16x16x32_bf16 v[136:139], v[196:199], v[32:35], v[136:139]
	ds_read_b128 v[188:191], v239 offset:6272
	s_add_i32 m0, s99, 0x6000
	v_lshl_add_u64 v[220:221], v[220:221], 0, v[230:231]
	global_load_lds_dwordx4 v[222:223], off
	s_waitcnt lgkmcnt(5)
	v_mfma_f32_16x16x32_bf16 v[132:135], v[200:203], v[16:19], v[132:135]
	v_mfma_f32_16x16x32_bf16 v[136:139], v[200:203], v[36:39], v[136:139]
	ds_read_b128 v[192:195], v238 offset:6400
	s_add_i32 m0, s99, 0x8000
	v_lshl_add_u64 v[222:223], v[222:223], 0, s[56:57]
	global_load_lds_dwordx4 v[224:225], off
	v_lshl_add_u64 v[224:225], v[224:225], 0, s[56:57]
	s_waitcnt lgkmcnt(5)
	v_mfma_f32_16x16x32_bf16 v[132:135], v[204:207], v[20:23], v[132:135]
	v_mfma_f32_16x16x32_bf16 v[136:139], v[204:207], v[44:47], v[136:139]
	ds_read_b128 v[196:199], v239 offset:6400
	s_waitcnt lgkmcnt(5)
	v_mfma_f32_16x16x32_bf16 v[140:143], v[208:211], v[0:3], 0
	v_mfma_f32_16x16x32_bf16 v[144:147], v[208:211], v[40:43], 0
	ds_read_b128 v[200:203], v238 offset:12288
	s_waitcnt lgkmcnt(5)
	v_mfma_f32_16x16x32_bf16 v[140:143], v[212:215], v[4:7], v[140:143]
	v_mfma_f32_16x16x32_bf16 v[144:147], v[212:215], v[24:27], v[144:147]
	ds_read_b128 v[204:207], v239 offset:12288
	s_waitcnt lgkmcnt(5)
	v_mfma_f32_16x16x32_bf16 v[140:143], v[184:187], v[8:11], v[140:143]
	v_min_f32_e32 v132, s101, v132
	v_min_f32_e32 v133, s101, v133
	v_min_f32_e32 v134, s101, v134
	v_mfma_f32_16x16x32_bf16 v[144:147], v[184:187], v[28:31], v[144:147]
	ds_read_b128 v[208:211], v238 offset:12416
	v_min_f32_e32 v135, s101, v135
	v_exp_f32_e32 v132, v132
	v_exp_f32_e32 v133, v133
	s_waitcnt lgkmcnt(5)
	v_mfma_f32_16x16x32_bf16 v[140:143], v[188:191], v[12:15], v[140:143]
	v_exp_f32_e32 v134, v134
	v_exp_f32_e32 v135, v135
	v_min_f32_e32 v136, s101, v136
	v_mfma_f32_16x16x32_bf16 v[144:147], v[188:191], v[32:35], v[144:147]
	ds_read_b128 v[212:215], v239 offset:12416
	v_min_f32_e32 v137, s101, v137
	v_min_f32_e32 v138, s101, v138
	v_min_f32_e32 v139, s101, v139
	s_waitcnt lgkmcnt(5)
	v_mfma_f32_16x16x32_bf16 v[140:143], v[192:195], v[16:19], v[140:143]
	v_exp_f32_e32 v136, v136
	v_exp_f32_e32 v137, v137
	v_exp_f32_e32 v138, v138
	v_mfma_f32_16x16x32_bf16 v[144:147], v[192:195], v[36:39], v[144:147]
	ds_read_b128 v[184:187], v238 offset:12544
	v_exp_f32_e32 v139, v139
	v_add_f32_e32 v244, v132, v133
	v_add_f32_e32 v245, v134, v135
	s_waitcnt lgkmcnt(5)
	v_mfma_f32_16x16x32_bf16 v[140:143], v[196:199], v[20:23], v[140:143]
	v_add_f32_e32 v246, v136, v137
	v_add_f32_e32 v247, v138, v139
	v_add_f32_e32 v244, v244, v245
	v_mfma_f32_16x16x32_bf16 v[144:147], v[196:199], v[44:47], v[144:147]
	ds_read_b128 v[188:191], v239 offset:12544
	v_add_f32_e32 v246, v246, v247
	v_add_f32_e32 v129, v129, v244
	v_add_f32_e32 v128, v128, v246
	s_waitcnt lgkmcnt(5)
	v_mfma_f32_16x16x32_bf16 v[148:151], v[200:203], v[0:3], 0
	v_mfma_f32_16x16x32_bf16 v[168:171], v[200:203], v[40:43], 0
	ds_read_b128 v[192:195], v238 offset:18432
	s_waitcnt lgkmcnt(5)
	v_mfma_f32_16x16x32_bf16 v[148:151], v[204:207], v[4:7], v[148:151]
	v_mfma_f32_16x16x32_bf16 v[168:171], v[204:207], v[24:27], v[168:171]
	ds_read_b128 v[196:199], v239 offset:18432
	s_waitcnt lgkmcnt(5)
	v_mfma_f32_16x16x32_bf16 v[148:151], v[208:211], v[8:11], v[148:151]
	v_min_f32_e32 v140, s101, v140
	v_min_f32_e32 v141, s101, v141
	v_min_f32_e32 v142, s101, v142
	v_min_f32_e32 v143, s101, v143
	v_mfma_f32_16x16x32_bf16 v[168:171], v[208:211], v[28:31], v[168:171]
	ds_read_b128 v[200:203], v238 offset:18560
	v_exp_f32_e32 v140, v140
	v_exp_f32_e32 v141, v141
	v_exp_f32_e32 v142, v142
	v_exp_f32_e32 v143, v143
	s_waitcnt lgkmcnt(5)
	v_mfma_f32_16x16x32_bf16 v[148:151], v[212:215], v[12:15], v[148:151]
	v_min_f32_e32 v144, s101, v144
	v_min_f32_e32 v145, s101, v145
	v_min_f32_e32 v146, s101, v146
	v_min_f32_e32 v147, s101, v147
	v_mfma_f32_16x16x32_bf16 v[168:171], v[212:215], v[32:35], v[168:171]
	ds_read_b128 v[204:207], v239 offset:18560
	v_exp_f32_e32 v144, v144
	v_exp_f32_e32 v145, v145
	v_exp_f32_e32 v146, v146
	v_exp_f32_e32 v147, v147
	s_waitcnt lgkmcnt(5)
	v_mfma_f32_16x16x32_bf16 v[148:151], v[184:187], v[16:19], v[148:151]
	v_add_f32_e32 v244, v140, v141
	v_add_f32_e32 v245, v142, v143
	v_add_f32_e32 v246, v144, v145
	v_add_f32_e32 v247, v146, v147
	v_mfma_f32_16x16x32_bf16 v[168:171], v[184:187], v[36:39], v[168:171]
	ds_read_b128 v[208:211], v238 offset:18688
	v_add_f32_e32 v244, v244, v245
	v_add_f32_e32 v246, v246, v247
	v_add_f32_e32 v129, v129, v244
	v_add_f32_e32 v128, v128, v246
	s_waitcnt lgkmcnt(5)
; #define MFMA16(a, b, c) __builtin_amdgcn_mfma_f32_16x16x32_bf16((a), (b), (c), 0, 0, 0)
; DI bf16x8 cat8(s16x4 lo, s16x4 hi) { return __builtin_shufflevector(lo, hi, 0, 1, 2, 3, 4, 5, 6, 7); }
; DI void mla_attn(const u16* q, const u16* kn, const u16* kpe, const u16* vt, u16* o, unsigned char* smem) {
;     ...
;       for (int ks = 0; ks < 6; ++ks) {
; #pragma unroll
;         for (int k16 = 0; k16 < 4; ++k16) {
;           const bf16x8 kf = *(const bf16x8*)(Kt + (k16 * 16 + lq) * 384 + (((ks * 4 + lg) ^ fsw) << 4));
; #pragma unroll
;           for (int qt = 0; qt < NQT; ++qt) s[k16][qt] = MFMA16(kf, qf[qt][ks], s[k16][qt]);
;         }
;         if (ks & 1) __builtin_amdgcn_sched_barrier(0);
;       }
;       bf16x8 pf[NQT][2];
; #pragma unroll
;       for (int qt = 0; qt < NQT; ++qt) {
;         float ps = 0.f;
; #pragma unroll
;         for (int k16 = 0; k16 < 4; ++k16)
; #pragma unroll
;           for (int rr = 0; rr < 4; ++rr) { const float e = __builtin_amdgcn_exp2f(fminf(s[k16][qt][rr], 100.f)); s[k16][qt][rr] = e; ps += e; }
;         lrun[qt] += ps;
;         pf[qt][0] = pack8(s[0][qt], s[1][qt]);
;         pf[qt][1] = pack8(s[2][qt], s[3][qt]);
;       }
; #pragma unroll
;       for (int kk = 0; kk < 2; ++kk)
; #pragma unroll
;         for (int dt = 0; dt < 8; ++dt) {
;           const unsigned char* vr = Vt + (dt * 16 + lq) * 128 + (lg & 1) * 8;
;           const s16x4 lo = *(const s16x4*)(vr + (((kk * 4 + (lg >> 1)) ^ fsw) << 4));
;           const s16x4 hi = *(const s16x4*)(vr + (((kk * 4 + (lg >> 1) + 2) ^ fsw) << 4));
;           const bf16x8 vf = cat8(lo, hi);
; #pragma unroll
;           for (int qt = 0; qt < NQT; ++qt) oacc[dt][qt] = MFMA16(vf, pf[qt][kk], oacc[dt][qt]);
;         }
	v_mfma_f32_16x16x32_bf16 v[148:151], v[188:191], v[20:23], v[148:151]
	v_cvt_pk_bf16_f32 v132, v132, v133
	v_cvt_pk_bf16_f32 v133, v134, v135
	v_cvt_pk_bf16_f32 v134, v140, v141
	v_cvt_pk_bf16_f32 v135, v142, v143
	v_mfma_f32_16x16x32_bf16 v[168:171], v[188:191], v[44:47], v[168:171]
	ds_read_b128 v[212:215], v239 offset:18688
	v_cvt_pk_bf16_f32 v136, v136, v137
	v_cvt_pk_bf16_f32 v137, v138, v139
	v_cvt_pk_bf16_f32 v138, v144, v145
	v_cvt_pk_bf16_f32 v139, v146, v147
	s_waitcnt lgkmcnt(5)
	v_mfma_f32_16x16x32_bf16 v[172:175], v[192:195], v[0:3], 0
	v_mfma_f32_16x16x32_bf16 v[176:179], v[192:195], v[40:43], 0
	ds_read_b64 v[184:185], v240 offset:24576
	ds_read_b64 v[186:187], v241 offset:24576
	s_waitcnt lgkmcnt(6)
	v_mfma_f32_16x16x32_bf16 v[172:175], v[196:199], v[4:7], v[172:175]
	v_mfma_f32_16x16x32_bf16 v[176:179], v[196:199], v[24:27], v[176:179]
	ds_read_b64 v[188:189], v240 offset:26624
	ds_read_b64 v[190:191], v241 offset:26624
	s_waitcnt lgkmcnt(7)
	v_mfma_f32_16x16x32_bf16 v[172:175], v[200:203], v[8:11], v[172:175]
	v_min_f32_e32 v148, s101, v148
	v_min_f32_e32 v149, s101, v149
	v_min_f32_e32 v150, s101, v150
	v_mfma_f32_16x16x32_bf16 v[176:179], v[200:203], v[28:31], v[176:179]
	ds_read_b64 v[192:193], v240 offset:28672
	ds_read_b64 v[194:195], v241 offset:28672
	v_min_f32_e32 v151, s101, v151
	v_exp_f32_e32 v148, v148
	v_exp_f32_e32 v149, v149
	s_waitcnt lgkmcnt(8)
	v_mfma_f32_16x16x32_bf16 v[172:175], v[204:207], v[12:15], v[172:175]
	v_exp_f32_e32 v150, v150
	v_exp_f32_e32 v151, v151
	v_min_f32_e32 v168, s101, v168
	v_mfma_f32_16x16x32_bf16 v[176:179], v[204:207], v[32:35], v[176:179]
	ds_read_b64 v[196:197], v240 offset:30720
	ds_read_b64 v[198:199], v241 offset:30720
	v_min_f32_e32 v169, s101, v169
	v_min_f32_e32 v170, s101, v170
	v_min_f32_e32 v171, s101, v171
	s_waitcnt lgkmcnt(9)
	v_mfma_f32_16x16x32_bf16 v[172:175], v[208:211], v[16:19], v[172:175]
	v_exp_f32_e32 v168, v168
	v_exp_f32_e32 v169, v169
	v_exp_f32_e32 v170, v170
	v_mfma_f32_16x16x32_bf16 v[176:179], v[208:211], v[36:39], v[176:179]
	ds_read_b64 v[200:201], v240 offset:32768
	ds_read_b64 v[202:203], v241 offset:32768
	v_exp_f32_e32 v171, v171
	v_add_f32_e32 v244, v148, v149
	v_add_f32_e32 v245, v150, v151
	s_waitcnt lgkmcnt(10)
	v_mfma_f32_16x16x32_bf16 v[172:175], v[212:215], v[20:23], v[172:175]
	v_add_f32_e32 v246, v168, v169
	v_add_f32_e32 v247, v170, v171
	v_add_f32_e32 v244, v244, v245
	v_mfma_f32_16x16x32_bf16 v[176:179], v[212:215], v[44:47], v[176:179]
	ds_read_b64 v[204:205], v240 offset:34816
	ds_read_b64 v[206:207], v241 offset:34816
	v_add_f32_e32 v246, v246, v247
	v_add_f32_e32 v129, v129, v244
	v_add_f32_e32 v128, v128, v246
	s_waitcnt lgkmcnt(10)
	v_mfma_f32_16x16x32_bf16 v[108:111], v[184:187], v[132:135], v[108:111]
	v_mfma_f32_16x16x32_bf16 v[72:75], v[184:187], v[136:139], v[72:75]
	ds_read_b64 v[208:209], v240 offset:36864
	ds_read_b64 v[210:211], v241 offset:36864
	s_waitcnt lgkmcnt(10)
	v_mfma_f32_16x16x32_bf16 v[104:107], v[188:191], v[132:135], v[104:107]
	v_mfma_f32_16x16x32_bf16 v[68:71], v[188:191], v[136:139], v[68:71]
	ds_read_b64 v[212:213], v240 offset:38912
	ds_read_b64 v[214:215], v241 offset:38912
	s_waitcnt lgkmcnt(10)
	v_mfma_f32_16x16x32_bf16 v[100:103], v[192:195], v[132:135], v[100:103]
	v_min_f32_e32 v172, s101, v172
	v_min_f32_e32 v173, s101, v173
	v_min_f32_e32 v174, s101, v174
	v_mfma_f32_16x16x32_bf16 v[64:67], v[192:195], v[136:139], v[64:67]
	ds_read_b64 v[184:185], v242 offset:24576
	ds_read_b64 v[186:187], v243 offset:24576
	v_min_f32_e32 v175, s101, v175
	v_exp_f32_e32 v172, v172
	v_exp_f32_e32 v173, v173
	s_waitcnt lgkmcnt(10)
; #define MFMA16(a, b, c) __builtin_amdgcn_mfma_f32_16x16x32_bf16((a), (b), (c), 0, 0, 0)
; DI bf16x8 cat8(s16x4 lo, s16x4 hi) { return __builtin_shufflevector(lo, hi, 0, 1, 2, 3, 4, 5, 6, 7); }
; DI void mla_attn(const u16* q, const u16* kn, const u16* kpe, const u16* vt, u16* o, unsigned char* smem) {
;     ...
;         for (int k16 = 0; k16 < 4; ++k16)
; #pragma unroll
;           for (int rr = 0; rr < 4; ++rr) { const float e = __builtin_amdgcn_exp2f(fminf(s[k16][qt][rr], 100.f)); s[k16][qt][rr] = e; ps += e; }
;         lrun[qt] += ps;
;         pf[qt][0] = pack8(s[0][qt], s[1][qt]);
;         pf[qt][1] = pack8(s[2][qt], s[3][qt]);
;       }
; #pragma unroll
;       for (int kk = 0; kk < 2; ++kk)
; #pragma unroll
;         for (int dt = 0; dt < 8; ++dt) {
;           const unsigned char* vr = Vt + (dt * 16 + lq) * 128 + (lg & 1) * 8;
;           const s16x4 lo = *(const s16x4*)(vr + (((kk * 4 + (lg >> 1)) ^ fsw) << 4));
;           const s16x4 hi = *(const s16x4*)(vr + (((kk * 4 + (lg >> 1) + 2) ^ fsw) << 4));
;           const bf16x8 vf = cat8(lo, hi);
; #pragma unroll
;           for (int qt = 0; qt < NQT; ++qt) oacc[dt][qt] = MFMA16(vf, pf[qt][kk], oacc[dt][qt]);
;         }
;       st = (st == 2) ? 0 : st + 1;
	v_mfma_f32_16x16x32_bf16 v[96:99], v[196:199], v[132:135], v[96:99]
	v_exp_f32_e32 v174, v174
	v_exp_f32_e32 v175, v175
	v_min_f32_e32 v176, s101, v176
	v_mfma_f32_16x16x32_bf16 v[56:59], v[196:199], v[136:139], v[56:59]
	ds_read_b64 v[188:189], v242 offset:26624
	ds_read_b64 v[190:191], v243 offset:26624
	v_min_f32_e32 v177, s101, v177
	v_min_f32_e32 v178, s101, v178
	v_min_f32_e32 v179, s101, v179
	s_waitcnt lgkmcnt(10)
	v_mfma_f32_16x16x32_bf16 v[88:91], v[200:203], v[132:135], v[88:91]
	v_exp_f32_e32 v176, v176
	v_exp_f32_e32 v177, v177
	v_exp_f32_e32 v178, v178
	v_mfma_f32_16x16x32_bf16 v[52:55], v[200:203], v[136:139], v[52:55]
	ds_read_b64 v[192:193], v242 offset:28672
	ds_read_b64 v[194:195], v243 offset:28672
	v_exp_f32_e32 v179, v179
	v_add_f32_e32 v244, v172, v173
	v_add_f32_e32 v245, v174, v175
	s_waitcnt lgkmcnt(10)
	v_mfma_f32_16x16x32_bf16 v[76:79], v[204:207], v[132:135], v[76:79]
	v_add_f32_e32 v246, v176, v177
	v_add_f32_e32 v247, v178, v179
	v_add_f32_e32 v244, v244, v245
	v_mfma_f32_16x16x32_bf16 v[48:51], v[204:207], v[136:139], v[48:51]
	ds_read_b64 v[196:197], v242 offset:30720
	ds_read_b64 v[198:199], v243 offset:30720
	v_add_f32_e32 v246, v246, v247
	v_add_f32_e32 v129, v129, v244
	v_add_f32_e32 v128, v128, v246
	s_waitcnt lgkmcnt(10)
	v_mfma_f32_16x16x32_bf16 v[92:95], v[208:211], v[132:135], v[92:95]
	v_cvt_pk_bf16_f32 v148, v148, v149
	v_cvt_pk_bf16_f32 v149, v150, v151
	v_cvt_pk_bf16_f32 v150, v172, v173
	v_mfma_f32_16x16x32_bf16 v[60:63], v[208:211], v[136:139], v[60:63]
	ds_read_b64 v[200:201], v242 offset:32768
	ds_read_b64 v[202:203], v243 offset:32768
	v_cvt_pk_bf16_f32 v151, v174, v175
	v_cvt_pk_bf16_f32 v168, v168, v169
	v_cvt_pk_bf16_f32 v169, v170, v171
	s_waitcnt lgkmcnt(10)
	v_mfma_f32_16x16x32_bf16 v[80:83], v[212:215], v[132:135], v[80:83]
	v_cvt_pk_bf16_f32 v170, v176, v177
	v_cvt_pk_bf16_f32 v171, v178, v179
	v_mfma_f32_16x16x32_bf16 v[84:87], v[212:215], v[136:139], v[84:87]
	ds_read_b64 v[204:205], v242 offset:34816
	ds_read_b64 v[206:207], v243 offset:34816
	s_waitcnt lgkmcnt(10)
	v_mfma_f32_16x16x32_bf16 v[108:111], v[184:187], v[148:151], v[108:111]
	v_mfma_f32_16x16x32_bf16 v[72:75], v[184:187], v[168:171], v[72:75]
	ds_read_b64 v[208:209], v242 offset:36864
	ds_read_b64 v[210:211], v243 offset:36864
	s_waitcnt lgkmcnt(10)
	v_mfma_f32_16x16x32_bf16 v[104:107], v[188:191], v[148:151], v[104:107]
	v_mfma_f32_16x16x32_bf16 v[68:71], v[188:191], v[168:171], v[68:71]
	ds_read_b64 v[212:213], v242 offset:38912
	ds_read_b64 v[214:215], v243 offset:38912
	s_waitcnt lgkmcnt(10)
	v_mfma_f32_16x16x32_bf16 v[100:103], v[192:195], v[148:151], v[100:103]
	v_mfma_f32_16x16x32_bf16 v[64:67], v[192:195], v[168:171], v[64:67]
	s_waitcnt lgkmcnt(8)
	v_mfma_f32_16x16x32_bf16 v[96:99], v[196:199], v[148:151], v[96:99]
	v_mfma_f32_16x16x32_bf16 v[56:59], v[196:199], v[168:171], v[56:59]
	s_waitcnt lgkmcnt(6)
	v_mfma_f32_16x16x32_bf16 v[88:91], v[200:203], v[148:151], v[88:91]
	v_mfma_f32_16x16x32_bf16 v[52:55], v[200:203], v[168:171], v[52:55]
	s_waitcnt lgkmcnt(4)
	v_mfma_f32_16x16x32_bf16 v[76:79], v[204:207], v[148:151], v[76:79]
	v_mfma_f32_16x16x32_bf16 v[48:51], v[204:207], v[168:171], v[48:51]
	s_waitcnt lgkmcnt(2)
	v_mfma_f32_16x16x32_bf16 v[92:95], v[208:211], v[148:151], v[92:95]
	v_mfma_f32_16x16x32_bf16 v[60:63], v[208:211], v[168:171], v[60:63]
	s_waitcnt lgkmcnt(0)
	v_mfma_f32_16x16x32_bf16 v[80:83], v[212:215], v[148:151], v[80:83]
	v_mfma_f32_16x16x32_bf16 v[84:87], v[212:215], v[168:171], v[84:87]
	s_add_i32 s10, s10, 1
	s_cmp_eq_u32 s10, 3
	s_cselect_b32 s10, 0, s10
	s_add_i32 s11, s11, 1
	s_cmp_lt_u32 s11, 64
	s_cbranch_scc1 .Lmla_top
	s_branch .LBB0_428

; template <int PIPE>
; DI void gemm_loop_g(const u16* __restrict__ Xp, long ldx_l, long ldx_i, long kxs,
;                     const u16* __restrict__ Yp, long ldy_l, long ldy_i, long kys, int K,
;                     f32x4 (&acc)[4][8], unsigned char* smem) {
;     ...
;   __syncthreads();
;   issue(0, 0);
;   asm volatile("s_waitcnt vmcnt(0)" ::: "memory");
;   __syncthreads();
; template <int MODE>
; DI void gemm_phase(const Params& p, const GP& g, unsigned char* smem) {
;     ...
;     f32x4 acc[4][8];
;     zero_acc(acc);
.LBB0_486:
	s_lshl_b32 s6, s55, 9
	s_and_b32 s6, s6, 0xfffff800
	s_or_b32 s28, s6, s30
	s_lshl_b32 s6, s55, 8
	s_and_b32 s6, s6, 0x300
	s_lshl_b32 s7, s6, 11
	s_add_u32 s8, s12, s7
	s_addc_u32 s9, s13, 0
	s_ashr_i32 s29, s28, 31
	v_mov_b32_e32 v4, v182
	s_lshl_b64 s[10:11], s[28:29], 11
	s_add_u32 s10, s36, s10
	v_ashrrev_i32_e32 v0, 3, v4
	v_lshrrev_b32_e32 v5, 4, v4
	v_xor_b32_e32 v6, v5, v4
	v_ashrrev_i32_e32 v1, 31, v0
	s_addc_u32 s11, s37, s11
	v_lshlrev_b64 v[0:1], 11, v[0:1]
	v_lshlrev_b32_e32 v6, 4, v6
	v_lshl_add_u64 v[2:3], s[8:9], 0, v[0:1]
	v_and_b32_e32 v128, 0x70, v6
	v_lshl_add_u64 v[0:1], s[10:11], 0, v[0:1]
	v_lshl_add_u64 v[130:131], v[2:3], 0, v[128:129]
	v_lshl_add_u64 v[132:133], v[0:1], 0, v[128:129]
	v_lshlrev_b32_e32 v128, 4, v4
	v_add_u32_e32 v2, 0x2000, v128
	v_readfirstlane_b32 s7, v128
	v_lshl_add_u64 v[0:1], v[130:131], 0, s[16:17]
	s_mov_b32 m0, s7
	v_lshl_add_u64 v[134:135], v[130:131], 0, s[18:19]
	v_readfirstlane_b32 s7, v2
	v_add_u32_e32 v2, 0x4000, v128
	s_barrier
	global_load_lds_dwordx4 v[0:1], off
	v_lshl_add_u64 v[0:1], v[134:135], 0, s[16:17]
	s_mov_b32 m0, s7
	v_lshl_add_u64 v[136:137], v[130:131], 0, s[24:25]
	v_readfirstlane_b32 s7, v2
	v_add_u32_e32 v2, 0x6000, v128
	global_load_lds_dwordx4 v[0:1], off
	v_lshl_add_u64 v[0:1], v[136:137], 0, s[16:17]
	s_mov_b32 m0, s7
	v_lshl_add_u64 v[138:139], v[130:131], 0, s[26:27]
	v_readfirstlane_b32 s7, v2
	v_add_u32_e32 v2, 0x8000, v128
	global_load_lds_dwordx4 v[0:1], off
	v_lshl_add_u64 v[0:1], v[138:139], 0, s[16:17]
	s_mov_b32 m0, s7
	v_readfirstlane_b32 s7, v2
	v_add_u32_e32 v2, 0xa000, v128
	global_load_lds_dwordx4 v[0:1], off
	v_lshl_add_u64 v[0:1], v[132:133], 0, s[16:17]
	s_mov_b32 m0, s7
	v_lshl_add_u64 v[140:141], v[132:133], 0, s[18:19]
	v_readfirstlane_b32 s7, v2
	v_add_u32_e32 v2, 0xc000, v128
	global_load_lds_dwordx4 v[0:1], off
	v_lshl_add_u64 v[0:1], v[140:141], 0, s[16:17]
	s_mov_b32 m0, s7
	v_lshl_add_u64 v[142:143], v[132:133], 0, s[24:25]
	v_readfirstlane_b32 s7, v2
	v_add_u32_e32 v2, 0xe000, v128
	global_load_lds_dwordx4 v[0:1], off
	v_lshl_add_u64 v[0:1], v[142:143], 0, s[16:17]
	s_mov_b32 m0, s7
	v_lshl_add_u64 v[144:145], v[132:133], 0, s[26:27]
	v_readfirstlane_b32 s7, v2
	global_load_lds_dwordx4 v[0:1], off
	v_lshl_add_u64 v[0:1], v[144:145], 0, s[16:17]
	s_mov_b32 m0, s7
	v_lshlrev_b32_e32 v2, 7, v4
	global_load_lds_dwordx4 v[0:1], off
	v_bfe_u32 v0, v4, 4, 2
	v_bfe_u32 v1, v4, 1, 3
	v_readfirstlane_b32 s29, v4
	s_nop 0
	v_bitop3_b32 v0, v0, v1, 4 bitop3:0x36
	v_and_b32_e32 v2, 0x780, v2
	s_lshl_b32 s7, s29, 8
	s_lshl_b32 s8, s29, 6
	v_lshl_or_b32 v149, v0, 4, v2
	v_bitop3_b32 v0, v5, v1, 3 bitop3:0x6c
	s_and_b32 s7, s7, 0x4000
	s_and_b32 s10, s8, 0xffffe000
	v_lshl_or_b32 v150, v0, 4, v2
	s_mov_b32 s11, 0x10000
	s_mov_b32 s29, 0
	v_mov_b32_e32 v4, 0
	v_mov_b32_e32 v5, v129
	v_mov_b32_e32 v6, v129
	v_mov_b32_e32 v7, v129
	v_mov_b32_e32 v16, 0
	v_mov_b32_e32 v17, v129
	v_mov_b32_e32 v18, v129
	v_mov_b32_e32 v19, v129
	v_mov_b32_e32 v32, 0
	v_mov_b32_e32 v33, v129
	v_mov_b32_e32 v34, v129
	v_mov_b32_e32 v35, v129
	v_mov_b32_e32 v48, 0
	v_mov_b32_e32 v49, v129
	v_mov_b32_e32 v50, v129
	v_mov_b32_e32 v51, v129
	v_mov_b32_e32 v64, 0
	v_mov_b32_e32 v65, v129
	v_mov_b32_e32 v66, v129
	v_mov_b32_e32 v67, v129
	v_mov_b32_e32 v80, 0
	v_mov_b32_e32 v81, v129
	v_mov_b32_e32 v82, v129
	v_mov_b32_e32 v83, v129
	v_mov_b32_e32 v96, 0
	v_mov_b32_e32 v97, v129
	v_mov_b32_e32 v98, v129
	v_mov_b32_e32 v99, v129
	v_mov_b32_e32 v112, 0
	v_mov_b32_e32 v113, v129
	v_mov_b32_e32 v114, v129
	v_mov_b32_e32 v115, v129
	v_mov_b32_e32 v0, 0
	v_mov_b32_e32 v1, v129
	v_mov_b32_e32 v2, v129
	v_mov_b32_e32 v3, v129
	v_mov_b32_e32 v20, 0
	v_mov_b32_e32 v21, v129
	v_mov_b32_e32 v22, v129
	v_mov_b32_e32 v23, v129
	v_mov_b32_e32 v36, 0
	v_mov_b32_e32 v37, v129
	v_mov_b32_e32 v38, v129
	v_mov_b32_e32 v39, v129
	v_mov_b32_e32 v52, 0
	v_mov_b32_e32 v53, v129
	v_mov_b32_e32 v54, v129
	v_mov_b32_e32 v55, v129
	v_mov_b32_e32 v68, 0
	v_mov_b32_e32 v69, v129
	v_mov_b32_e32 v70, v129
	v_mov_b32_e32 v71, v129
	v_mov_b32_e32 v84, 0
	v_mov_b32_e32 v85, v129
	v_mov_b32_e32 v86, v129
	v_mov_b32_e32 v87, v129
	v_mov_b32_e32 v100, 0
	v_mov_b32_e32 v101, v129
	v_mov_b32_e32 v102, v129
	v_mov_b32_e32 v103, v129
	v_mov_b32_e32 v116, 0
	v_mov_b32_e32 v117, v129
	v_mov_b32_e32 v118, v129
	v_mov_b32_e32 v119, v129
	v_mov_b32_e32 v8, 0
	v_mov_b32_e32 v9, v129
	v_mov_b32_e32 v10, v129
	v_mov_b32_e32 v11, v129
	v_mov_b32_e32 v24, 0
	v_mov_b32_e32 v25, v129
	v_mov_b32_e32 v26, v129
	v_mov_b32_e32 v27, v129
	v_mov_b32_e32 v40, 0
	v_mov_b32_e32 v41, v129
	v_mov_b32_e32 v42, v129
	v_mov_b32_e32 v43, v129
	v_mov_b32_e32 v56, 0
	v_mov_b32_e32 v57, v129
	v_mov_b32_e32 v58, v129
	v_mov_b32_e32 v59, v129
	v_mov_b32_e32 v72, 0
	v_mov_b32_e32 v73, v129
	v_mov_b32_e32 v74, v129
	v_mov_b32_e32 v75, v129
	v_mov_b32_e32 v88, 0
	v_mov_b32_e32 v89, v129
	v_mov_b32_e32 v90, v129
	v_mov_b32_e32 v91, v129
	v_mov_b32_e32 v104, 0
	v_mov_b32_e32 v105, v129
	v_mov_b32_e32 v106, v129
	v_mov_b32_e32 v107, v129
	v_mov_b32_e32 v120, 0
	v_mov_b32_e32 v121, v129
	v_mov_b32_e32 v122, v129
	v_mov_b32_e32 v123, v129
	v_mov_b32_e32 v12, 0
	v_mov_b32_e32 v13, v129
	v_mov_b32_e32 v14, v129
	v_mov_b32_e32 v15, v129
	v_mov_b32_e32 v28, 0
	v_mov_b32_e32 v29, v129
	v_mov_b32_e32 v30, v129
	v_mov_b32_e32 v31, v129
	v_mov_b32_e32 v44, 0
	v_mov_b32_e32 v45, v129
	v_mov_b32_e32 v46, v129
	v_mov_b32_e32 v47, v129
	v_mov_b32_e32 v60, 0
	v_mov_b32_e32 v61, v129
	v_mov_b32_e32 v62, v129
	v_mov_b32_e32 v63, v129
	v_mov_b32_e32 v76, 0
	v_mov_b32_e32 v77, v129
	v_mov_b32_e32 v78, v129
	v_mov_b32_e32 v79, v129
	v_mov_b32_e32 v92, 0
	v_mov_b32_e32 v93, v129
	v_mov_b32_e32 v94, v129
	v_mov_b32_e32 v95, v129
	v_mov_b32_e32 v108, 0
	v_mov_b32_e32 v109, v129
	v_mov_b32_e32 v110, v129
	v_mov_b32_e32 v111, v129
	v_mov_b32_e32 v124, 0
	v_mov_b32_e32 v125, v129
	v_mov_b32_e32 v126, v129
	v_mov_b32_e32 v127, v129
	s_waitcnt vmcnt(0) lgkmcnt(0)
	s_barrier
	s_branch .LBB0_488

; template <int PIPE>
; DI void gemm_loop_g(const u16* __restrict__ Xp, long ldx_l, long ldx_i, long kxs,
;                     const u16* __restrict__ Yp, long ldy_l, long ldy_i, long kys, int K,
;                     f32x4 (&acc)[4][8], unsigned char* smem) {
;     ...
;   __syncthreads();
;   issue(0, 0);
;   asm volatile("s_waitcnt vmcnt(0)" ::: "memory");
;   __syncthreads();
; template <int MODE>
; DI void gemm_phase(const Params& p, const GP& g, unsigned char* smem) {
;     ...
;     f32x4 acc[4][8];
;     zero_acc(acc);
.LBB0_503:
	s_lshl_b32 s6, s11, 9
	s_and_b32 s6, s6, 0xfffff800
	s_or_b32 s28, s6, s30
	s_lshl_b32 s6, s11, 8
	s_and_b32 s6, s6, 0x300
	s_lshl_b32 s7, s6, 11
	s_waitcnt lgkmcnt(0)
	s_add_u32 s8, s14, s7
	s_addc_u32 s9, s15, 0
	s_ashr_i32 s29, s28, 31
	v_mov_b32_e32 v4, v182
	s_lshl_b64 s[40:41], s[28:29], 11
	s_add_u32 s40, s38, s40
	v_ashrrev_i32_e32 v0, 3, v4
	v_lshrrev_b32_e32 v5, 4, v4
	v_xor_b32_e32 v6, v5, v4
	v_ashrrev_i32_e32 v1, 31, v0
	s_addc_u32 s41, s39, s41
	v_lshlrev_b64 v[0:1], 11, v[0:1]
	v_lshlrev_b32_e32 v6, 4, v6
	v_lshl_add_u64 v[2:3], s[8:9], 0, v[0:1]
	v_and_b32_e32 v128, 0x70, v6
	v_lshl_add_u64 v[0:1], s[40:41], 0, v[0:1]
	v_lshl_add_u64 v[130:131], v[2:3], 0, v[128:129]
	v_lshl_add_u64 v[132:133], v[0:1], 0, v[128:129]
	v_lshlrev_b32_e32 v128, 4, v4
	v_add_u32_e32 v2, 0x2000, v128
	v_readfirstlane_b32 s7, v128
	v_lshl_add_u64 v[0:1], v[130:131], 0, s[12:13]
	s_mov_b32 m0, s7
	v_lshl_add_u64 v[134:135], v[130:131], 0, s[18:19]
	v_readfirstlane_b32 s7, v2
	v_add_u32_e32 v2, 0x4000, v128
	s_barrier
	global_load_lds_dwordx4 v[0:1], off
	v_lshl_add_u64 v[0:1], v[134:135], 0, s[12:13]
	s_mov_b32 m0, s7
	v_lshl_add_u64 v[136:137], v[130:131], 0, s[24:25]
	v_readfirstlane_b32 s7, v2
	v_add_u32_e32 v2, 0x6000, v128
	global_load_lds_dwordx4 v[0:1], off
	v_lshl_add_u64 v[0:1], v[136:137], 0, s[12:13]
	s_mov_b32 m0, s7
	v_lshl_add_u64 v[138:139], v[130:131], 0, s[26:27]
	v_readfirstlane_b32 s7, v2
	v_add_u32_e32 v2, 0x8000, v128
	global_load_lds_dwordx4 v[0:1], off
	v_lshl_add_u64 v[0:1], v[138:139], 0, s[12:13]
	s_mov_b32 m0, s7
	v_readfirstlane_b32 s7, v2
	v_add_u32_e32 v2, 0xa000, v128
	global_load_lds_dwordx4 v[0:1], off
	v_lshl_add_u64 v[0:1], v[132:133], 0, s[12:13]
	s_mov_b32 m0, s7
	v_lshl_add_u64 v[140:141], v[132:133], 0, s[18:19]
	v_readfirstlane_b32 s7, v2
	v_add_u32_e32 v2, 0xc000, v128
	global_load_lds_dwordx4 v[0:1], off
	v_lshl_add_u64 v[0:1], v[140:141], 0, s[12:13]
	s_mov_b32 m0, s7
	v_lshl_add_u64 v[142:143], v[132:133], 0, s[24:25]
	v_readfirstlane_b32 s7, v2
	v_add_u32_e32 v2, 0xe000, v128
	global_load_lds_dwordx4 v[0:1], off
	v_lshl_add_u64 v[0:1], v[142:143], 0, s[12:13]
	s_mov_b32 m0, s7
	v_lshl_add_u64 v[144:145], v[132:133], 0, s[26:27]
	v_readfirstlane_b32 s7, v2
	global_load_lds_dwordx4 v[0:1], off
	v_lshl_add_u64 v[0:1], v[144:145], 0, s[12:13]
	s_mov_b32 m0, s7
	v_lshlrev_b32_e32 v2, 7, v4
	global_load_lds_dwordx4 v[0:1], off
	v_bfe_u32 v0, v4, 4, 2
	v_bfe_u32 v1, v4, 1, 3
	v_readfirstlane_b32 s29, v4
	s_nop 0
	v_bitop3_b32 v0, v0, v1, 4 bitop3:0x36
	v_and_b32_e32 v2, 0x780, v2
	s_lshl_b32 s7, s29, 8
	s_lshl_b32 s8, s29, 6
	v_lshl_or_b32 v148, v0, 4, v2
	v_bitop3_b32 v0, v5, v1, 3 bitop3:0x6c
	s_and_b32 s7, s7, 0x4000
	s_and_b32 s29, s8, 0xffffe000
	v_lshl_or_b32 v149, v0, 4, v2
	s_mov_b32 s31, 0x10000
	s_mov_b32 s33, 0
	v_mov_b32_e32 v12, 0
	v_mov_b32_e32 v13, v129
	v_mov_b32_e32 v14, v129
	v_mov_b32_e32 v15, v129
	v_mov_b32_e32 v4, 0
	v_mov_b32_e32 v5, v129
	v_mov_b32_e32 v6, v129
	v_mov_b32_e32 v7, v129
	v_mov_b32_e32 v24, 0
	v_mov_b32_e32 v25, v129
	v_mov_b32_e32 v26, v129
	v_mov_b32_e32 v27, v129
	v_mov_b32_e32 v40, 0
	v_mov_b32_e32 v41, v129
	v_mov_b32_e32 v42, v129
	v_mov_b32_e32 v43, v129
	v_mov_b32_e32 v56, 0
	v_mov_b32_e32 v57, v129
	v_mov_b32_e32 v58, v129
	v_mov_b32_e32 v59, v129
	v_mov_b32_e32 v72, 0
	v_mov_b32_e32 v73, v129
	v_mov_b32_e32 v74, v129
	v_mov_b32_e32 v75, v129
	v_mov_b32_e32 v88, 0
	v_mov_b32_e32 v89, v129
	v_mov_b32_e32 v90, v129
	v_mov_b32_e32 v91, v129
	v_mov_b32_e32 v104, 0
	v_mov_b32_e32 v105, v129
	v_mov_b32_e32 v106, v129
	v_mov_b32_e32 v107, v129
	v_mov_b32_e32 v0, 0
	v_mov_b32_e32 v1, v129
	v_mov_b32_e32 v2, v129
	v_mov_b32_e32 v3, v129
	v_mov_b32_e32 v20, 0
	v_mov_b32_e32 v21, v129
	v_mov_b32_e32 v22, v129
	v_mov_b32_e32 v23, v129
	v_mov_b32_e32 v36, 0
	v_mov_b32_e32 v37, v129
	v_mov_b32_e32 v38, v129
	v_mov_b32_e32 v39, v129
	v_mov_b32_e32 v52, 0
	v_mov_b32_e32 v53, v129
	v_mov_b32_e32 v54, v129
	v_mov_b32_e32 v55, v129
	v_mov_b32_e32 v68, 0
	v_mov_b32_e32 v69, v129
	v_mov_b32_e32 v70, v129
	v_mov_b32_e32 v71, v129
	v_mov_b32_e32 v84, 0
	v_mov_b32_e32 v85, v129
	v_mov_b32_e32 v86, v129
	v_mov_b32_e32 v87, v129
	v_mov_b32_e32 v100, 0
	v_mov_b32_e32 v101, v129
	v_mov_b32_e32 v102, v129
	v_mov_b32_e32 v103, v129
	v_mov_b32_e32 v116, 0
	v_mov_b32_e32 v117, v129
	v_mov_b32_e32 v118, v129
	v_mov_b32_e32 v119, v129
	v_mov_b32_e32 v8, 0
	v_mov_b32_e32 v9, v129
	v_mov_b32_e32 v10, v129
	v_mov_b32_e32 v11, v129
	v_mov_b32_e32 v28, 0
	v_mov_b32_e32 v29, v129
	v_mov_b32_e32 v30, v129
	v_mov_b32_e32 v31, v129
	v_mov_b32_e32 v44, 0
	v_mov_b32_e32 v45, v129
	v_mov_b32_e32 v46, v129
	v_mov_b32_e32 v47, v129
	v_mov_b32_e32 v60, 0
	v_mov_b32_e32 v61, v129
	v_mov_b32_e32 v62, v129
	v_mov_b32_e32 v63, v129
	v_mov_b32_e32 v76, 0
	v_mov_b32_e32 v77, v129
	v_mov_b32_e32 v78, v129
	v_mov_b32_e32 v79, v129
	v_mov_b32_e32 v92, 0
	v_mov_b32_e32 v93, v129
	v_mov_b32_e32 v94, v129
	v_mov_b32_e32 v95, v129
	v_mov_b32_e32 v108, 0
	v_mov_b32_e32 v109, v129
	v_mov_b32_e32 v110, v129
	v_mov_b32_e32 v111, v129
	v_mov_b32_e32 v120, 0
	v_mov_b32_e32 v121, v129
	v_mov_b32_e32 v122, v129
	v_mov_b32_e32 v123, v129
	v_mov_b32_e32 v16, 0
	v_mov_b32_e32 v17, v129
	v_mov_b32_e32 v18, v129
	v_mov_b32_e32 v19, v129
	v_mov_b32_e32 v32, 0
	v_mov_b32_e32 v33, v129
	v_mov_b32_e32 v34, v129
	v_mov_b32_e32 v35, v129
	v_mov_b32_e32 v48, 0
	v_mov_b32_e32 v49, v129
	v_mov_b32_e32 v50, v129
	v_mov_b32_e32 v51, v129
	v_mov_b32_e32 v64, 0
	v_mov_b32_e32 v65, v129
	v_mov_b32_e32 v66, v129
	v_mov_b32_e32 v67, v129
	v_mov_b32_e32 v80, 0
	v_mov_b32_e32 v81, v129
	v_mov_b32_e32 v82, v129
	v_mov_b32_e32 v83, v129
	v_mov_b32_e32 v96, 0
	v_mov_b32_e32 v97, v129
	v_mov_b32_e32 v98, v129
	v_mov_b32_e32 v99, v129
	v_mov_b32_e32 v112, 0
	v_mov_b32_e32 v113, v129
	v_mov_b32_e32 v114, v129
	v_mov_b32_e32 v115, v129
	v_mov_b32_e32 v124, 0
	v_mov_b32_e32 v125, v129
	v_mov_b32_e32 v126, v129
	v_mov_b32_e32 v127, v129
	s_waitcnt vmcnt(0) lgkmcnt(0)
	s_barrier
	s_branch .LBB0_505

; DI u32x2 pack4(float a, float b, float c, float d) { u32x2 r; r.x = pack2(a, b); r.y = pack2(c, d); return r; }
; #define EPI_END if (i == 3 && (j & 3) == 3) __builtin_amdgcn_sched_barrier(0); }
; template <int PIPE>
; DI void gemm_loop_g(const u16* __restrict__ Xp, long ldx_l, long ldx_i, long kxs,
;                     const u16* __restrict__ Yp, long ldy_l, long ldy_i, long kys, int K,
;                     f32x4 (&acc)[4][8], unsigned char* smem) {
;     ...
;   __syncthreads();
;   issue(0, 0);
; template <int MODE>
; DI void gemm_phase(const Params& p, const GP& g, unsigned char* smem) {
;     ...
;     if (MODE == M_PLE) {
;       const u16* pb = (const u16*)g.d1;
;       gemm_loop(g.W2 + (long)n0 * 256, 256, pb + (long)m0 * 256, 256, 256, acc, smem);
;       u16* xb = (u16*)g.d0;
;       EPI_STD_BEGIN
;         *(u32x2*)(xb + (long)m * 1024 + n4) = pack4(v[0], v[1], v[2], v[3]);
;       EPI_END
;       zero_acc(acc);
.LBB0_527:
	v_or_b32_e32 v160, s12, v185
	v_add_u32_e32 v134, s6, v184
	v_ashrrev_i32_e32 v161, 31, v160
	v_lshlrev_b64 v[164:165], 11, v[160:161]
	v_ashrrev_i32_e32 v135, 31, v134
	v_or_b32_e32 v156, 16, v160
	v_lshl_add_u64 v[132:133], s[38:39], 0, v[164:165]
	v_cvt_pk_bf16_f32 v124, v124, v125
	v_cvt_pk_bf16_f32 v125, v126, v127
	v_lshlrev_b64 v[126:127], 1, v[134:135]
	v_ashrrev_i32_e32 v157, 31, v156
	v_lshl_add_u64 v[132:133], v[132:133], 0, v[126:127]
	v_cvt_pk_bf16_f32 v96, v96, v97
	v_cvt_pk_bf16_f32 v97, v98, v99
	v_lshlrev_b64 v[162:163], 11, v[156:157]
	v_or_b32_e32 v152, 32, v160
	global_store_dwordx2 v[132:133], v[96:97], off offset:96
	v_lshl_add_u64 v[96:97], s[38:39], 0, v[162:163]
	v_ashrrev_i32_e32 v153, 31, v152
	v_lshl_add_u64 v[96:97], v[96:97], 0, v[126:127]
	v_cvt_pk_bf16_f32 v72, v72, v73
	v_cvt_pk_bf16_f32 v73, v74, v75
	v_lshlrev_b64 v[158:159], 11, v[152:153]
	v_or_b32_e32 v148, 48, v160
	global_store_dwordx2 v[96:97], v[72:73], off offset:96
	v_lshl_add_u64 v[72:73], s[38:39], 0, v[158:159]
	v_ashrrev_i32_e32 v149, 31, v148
	v_lshl_add_u64 v[72:73], v[72:73], 0, v[126:127]
	v_cvt_pk_bf16_f32 v56, v56, v57
	v_cvt_pk_bf16_f32 v57, v58, v59
	v_lshlrev_b64 v[154:155], 11, v[148:149]
	global_store_dwordx2 v[72:73], v[56:57], off offset:96
	v_lshl_add_u64 v[56:57], s[38:39], 0, v[154:155]
	v_cvt_pk_bf16_f32 v74, v104, v105
	v_cvt_pk_bf16_f32 v75, v106, v107
	v_cvt_pk_bf16_f32 v58, v100, v101
	v_cvt_pk_bf16_f32 v59, v102, v103
	v_lshl_add_u64 v[56:57], v[56:57], 0, v[126:127]
	v_cvt_pk_bf16_f32 v98, v120, v121
	v_cvt_pk_bf16_f32 v99, v122, v123
	global_store_dwordx2 v[72:73], v[74:75], off
	v_cvt_pk_bf16_f32 v74, v92, v93
	v_cvt_pk_bf16_f32 v75, v94, v95
	global_store_dwordx2 v[56:57], v[58:59], off
	v_cvt_pk_bf16_f32 v58, v80, v81
	v_cvt_pk_bf16_f32 v59, v82, v83
	v_cvt_pk_bf16_f32 v116, v116, v117
	v_cvt_pk_bf16_f32 v117, v118, v119
	v_cvt_pk_bf16_f32 v112, v112, v113
	v_cvt_pk_bf16_f32 v113, v114, v115
	global_store_dwordx2 v[96:97], v[98:99], off
	v_cvt_pk_bf16_f32 v98, v108, v109
	v_cvt_pk_bf16_f32 v99, v110, v111
	v_cvt_pk_bf16_f32 v88, v88, v89
	v_cvt_pk_bf16_f32 v89, v90, v91
	global_store_dwordx2 v[72:73], v[74:75], off offset:32
	v_cvt_pk_bf16_f32 v74, v76, v77
	v_cvt_pk_bf16_f32 v75, v78, v79
	global_store_dwordx2 v[56:57], v[58:59], off offset:32
	v_cvt_pk_bf16_f32 v58, v64, v65
	v_cvt_pk_bf16_f32 v59, v66, v67
	v_cvt_pk_bf16_f32 v36, v36, v37
	v_cvt_pk_bf16_f32 v37, v38, v39
	global_store_dwordx2 v[132:133], v[124:125], off
	global_store_dwordx2 v[132:133], v[116:117], off offset:32
	global_store_dwordx2 v[132:133], v[112:113], off offset:64
	global_store_dwordx2 v[96:97], v[98:99], off offset:32
	global_store_dwordx2 v[96:97], v[88:89], off offset:64
	global_store_dwordx2 v[72:73], v[74:75], off offset:64
	global_store_dwordx2 v[56:57], v[58:59], off offset:64
	global_store_dwordx2 v[56:57], v[36:37], off offset:96
	v_or_b32_e32 v144, 64, v160
	v_ashrrev_i32_e32 v145, 31, v144
	v_lshlrev_b64 v[150:151], 11, v[144:145]
	v_or_b32_e32 v140, 0x50, v160
	v_lshl_add_u64 v[36:37], s[38:39], 0, v[150:151]
	v_ashrrev_i32_e32 v141, 31, v140
	v_lshl_add_u64 v[36:37], v[36:37], 0, v[126:127]
	v_cvt_pk_bf16_f32 v20, v20, v21
	v_cvt_pk_bf16_f32 v21, v22, v23
	v_lshlrev_b64 v[146:147], 11, v[140:141]
	v_or_b32_e32 v136, 0x60, v160
	global_store_dwordx2 v[36:37], v[20:21], off offset:96
	v_lshl_add_u64 v[20:21], s[38:39], 0, v[146:147]
	v_ashrrev_i32_e32 v137, 31, v136
	v_lshl_add_u64 v[20:21], v[20:21], 0, v[126:127]
	v_cvt_pk_bf16_f32 v8, v8, v9
	v_cvt_pk_bf16_f32 v9, v10, v11
	v_lshlrev_b64 v[142:143], 11, v[136:137]
	v_or_b32_e32 v132, 0x70, v160
	global_store_dwordx2 v[20:21], v[8:9], off offset:96
	v_lshl_add_u64 v[8:9], s[38:39], 0, v[142:143]
	v_ashrrev_i32_e32 v133, 31, v132
	v_lshl_add_u64 v[8:9], v[8:9], 0, v[126:127]
	v_cvt_pk_bf16_f32 v0, v0, v1
	v_cvt_pk_bf16_f32 v1, v2, v3
	v_lshlrev_b64 v[138:139], 11, v[132:133]
	global_store_dwordx2 v[8:9], v[0:1], off offset:96
	v_lshl_add_u64 v[0:1], s[38:39], 0, v[138:139]
	v_cvt_pk_bf16_f32 v2, v32, v33
	v_cvt_pk_bf16_f32 v3, v34, v35
	v_lshl_add_u64 v[0:1], v[0:1], 0, v[126:127]
	v_cvt_pk_bf16_f32 v38, v84, v85
	v_cvt_pk_bf16_f32 v39, v86, v87
	v_cvt_pk_bf16_f32 v22, v68, v69
	v_cvt_pk_bf16_f32 v23, v70, v71
	v_cvt_pk_bf16_f32 v10, v52, v53
	v_cvt_pk_bf16_f32 v11, v54, v55
	global_store_dwordx2 v[0:1], v[2:3], off
	v_cvt_pk_bf16_f32 v2, v16, v17
	v_cvt_pk_bf16_f32 v3, v18, v19
	global_store_dwordx2 v[36:37], v[38:39], off
	v_cvt_pk_bf16_f32 v38, v60, v61
	v_cvt_pk_bf16_f32 v39, v62, v63
	global_store_dwordx2 v[20:21], v[22:23], off
	v_cvt_pk_bf16_f32 v22, v48, v49
	v_cvt_pk_bf16_f32 v23, v50, v51
	global_store_dwordx2 v[8:9], v[10:11], off
	v_cvt_pk_bf16_f32 v10, v28, v29
	v_cvt_pk_bf16_f32 v11, v30, v31
	global_store_dwordx2 v[0:1], v[2:3], off offset:32
	v_cvt_pk_bf16_f32 v2, v4, v5
	v_cvt_pk_bf16_f32 v3, v6, v7
	global_store_dwordx2 v[36:37], v[38:39], off offset:32
	v_cvt_pk_bf16_f32 v38, v44, v45
	v_cvt_pk_bf16_f32 v39, v46, v47
	global_store_dwordx2 v[20:21], v[22:23], off offset:32
	v_cvt_pk_bf16_f32 v22, v24, v25
	v_cvt_pk_bf16_f32 v23, v26, v27
	global_store_dwordx2 v[8:9], v[10:11], off offset:32
	v_cvt_pk_bf16_f32 v10, v12, v13
	v_cvt_pk_bf16_f32 v11, v14, v15
	global_store_dwordx2 v[0:1], v[2:3], off offset:64
	v_cvt_pk_bf16_f32 v2, v40, v41
	v_cvt_pk_bf16_f32 v3, v42, v43
	global_store_dwordx2 v[36:37], v[38:39], off offset:64
	global_store_dwordx2 v[20:21], v[22:23], off offset:64
	global_store_dwordx2 v[8:9], v[10:11], off offset:64
	global_store_dwordx2 v[0:1], v[2:3], off offset:96
	s_lshl_b32 s6, s6, 11
	s_add_u32 s6, s62, s6
	v_mov_b32_e32 v4, v182
	s_addc_u32 s7, s63, 0
	s_lshl_b64 s[8:9], s[12:13], 11
	s_add_u32 s8, s36, s8
	v_ashrrev_i32_e32 v0, 3, v4
	v_lshrrev_b32_e32 v5, 4, v4
	v_xor_b32_e32 v6, v5, v4
	v_ashrrev_i32_e32 v1, 31, v0
	s_addc_u32 s9, s37, s9
	v_lshlrev_b64 v[0:1], 11, v[0:1]
	v_lshlrev_b32_e32 v6, 4, v6
	v_lshl_add_u64 v[2:3], s[6:7], 0, v[0:1]
	v_and_b32_e32 v130, 0x70, v6
	v_lshl_add_u64 v[0:1], s[8:9], 0, v[0:1]
	v_lshl_add_u64 v[166:167], v[2:3], 0, v[130:131]
	v_lshl_add_u64 v[168:169], v[0:1], 0, v[130:131]
	v_lshlrev_b32_e32 v130, 4, v4
	v_add_u32_e32 v2, 0x2000, v130
	v_readfirstlane_b32 s6, v130
	v_lshl_add_u64 v[0:1], v[166:167], 0, s[30:31]
	s_mov_b32 m0, s6
	v_lshl_add_u64 v[170:171], v[166:167], 0, s[54:55]
	v_readfirstlane_b32 s6, v2
	v_add_u32_e32 v2, 0x4000, v130
	s_barrier
; template <int PIPE>
; DI void gemm_loop_g(const u16* __restrict__ Xp, long ldx_l, long ldx_i, long kxs,
;                     const u16* __restrict__ Yp, long ldy_l, long ldy_i, long kys, int K,
;                     f32x4 (&acc)[4][8], unsigned char* smem) {
;     ...
;   __syncthreads();
;   issue(0, 0);
;   asm volatile("s_waitcnt vmcnt(0)" ::: "memory");
;   __syncthreads();
; DI void zero_acc(f32x4 (&acc)[4][8]) {
; #pragma unroll
;   for (int i = 0; i < 4; ++i)
; #pragma unroll
;     for (int j = 0; j < 8; ++j) acc[i][j] = f32x4{0.f, 0.f, 0.f, 0.f};
; }
	global_load_lds_dwordx4 v[0:1], off
	v_lshl_add_u64 v[0:1], v[170:171], 0, s[30:31]
	s_mov_b32 m0, s6
	v_lshl_add_u64 v[172:173], v[166:167], 0, s[56:57]
	v_readfirstlane_b32 s6, v2
	v_add_u32_e32 v2, 0x6000, v130
	global_load_lds_dwordx4 v[0:1], off
	v_lshl_add_u64 v[0:1], v[172:173], 0, s[30:31]
	s_mov_b32 m0, s6
	v_lshl_add_u64 v[174:175], v[166:167], 0, s[58:59]
	v_readfirstlane_b32 s6, v2
	v_add_u32_e32 v2, 0x8000, v130
	global_load_lds_dwordx4 v[0:1], off
	v_lshl_add_u64 v[0:1], v[174:175], 0, s[30:31]
	s_mov_b32 m0, s6
	v_readfirstlane_b32 s6, v2
	v_add_u32_e32 v2, 0xa000, v130
	global_load_lds_dwordx4 v[0:1], off
	v_lshl_add_u64 v[0:1], v[168:169], 0, s[30:31]
	s_mov_b32 m0, s6
	v_lshl_add_u64 v[176:177], v[168:169], 0, s[54:55]
	v_readfirstlane_b32 s6, v2
	v_add_u32_e32 v2, 0xc000, v130
	global_load_lds_dwordx4 v[0:1], off
	v_lshl_add_u64 v[0:1], v[176:177], 0, s[30:31]
	s_mov_b32 m0, s6
	v_lshl_add_u64 v[178:179], v[168:169], 0, s[56:57]
	v_readfirstlane_b32 s6, v2
	v_add_u32_e32 v2, 0xe000, v130
	global_load_lds_dwordx4 v[0:1], off
	v_lshl_add_u64 v[0:1], v[178:179], 0, s[30:31]
	s_mov_b32 m0, s6
	v_lshl_add_u64 v[180:181], v[168:169], 0, s[58:59]
	v_readfirstlane_b32 s6, v2
	global_load_lds_dwordx4 v[0:1], off
	v_lshl_add_u64 v[0:1], v[180:181], 0, s[30:31]
	s_mov_b32 m0, s6
	v_lshlrev_b32_e32 v2, 7, v4
	global_load_lds_dwordx4 v[0:1], off
	v_bfe_u32 v0, v4, 4, 2
	v_bfe_u32 v1, v4, 1, 3
	v_readfirstlane_b32 s10, v4
	s_nop 0
	v_bitop3_b32 v0, v0, v1, 4 bitop3:0x36
	v_and_b32_e32 v2, 0x780, v2
	s_lshl_b32 s6, s10, 8
	s_lshl_b32 s7, s10, 6
	v_lshl_or_b32 v187, v0, 4, v2
	v_bitop3_b32 v0, v5, v1, 3 bitop3:0x6c
	v_mov_b32_e32 v4, 0
	s_and_b32 s6, s6, 0x4000
	s_and_b32 s7, s7, 0xffffe000
	v_lshl_or_b32 v188, v0, 4, v2
	s_mov_b32 s10, 0
	s_mov_b32 s11, 0x10000
	v_mov_b32_e32 v5, v4
	v_mov_b32_e32 v6, v4
	v_mov_b32_e32 v7, v4
	v_mov_b32_e32 v16, v4
	v_mov_b32_e32 v17, v4
	v_mov_b32_e32 v18, v4
	v_mov_b32_e32 v19, v4
	v_mov_b32_e32 v32, v4
	v_mov_b32_e32 v33, v4
	v_mov_b32_e32 v34, v4
	v_mov_b32_e32 v35, v4
	v_mov_b32_e32 v48, v4
	v_mov_b32_e32 v49, v4
	v_mov_b32_e32 v50, v4
	v_mov_b32_e32 v51, v4
	v_mov_b32_e32 v64, v4
	v_mov_b32_e32 v65, v4
	v_mov_b32_e32 v66, v4
	v_mov_b32_e32 v67, v4
	v_mov_b32_e32 v80, v4
	v_mov_b32_e32 v81, v4
	v_mov_b32_e32 v82, v4
	v_mov_b32_e32 v83, v4
	v_mov_b32_e32 v96, v4
	v_mov_b32_e32 v97, v4
	v_mov_b32_e32 v98, v4
	v_mov_b32_e32 v99, v4
	v_mov_b32_e32 v112, v4
	v_mov_b32_e32 v113, v4
	v_mov_b32_e32 v114, v4
	v_mov_b32_e32 v115, v4
	v_mov_b32_e32 v0, v4
	v_mov_b32_e32 v1, v4
	v_mov_b32_e32 v2, v4
	v_mov_b32_e32 v3, v4
	v_mov_b32_e32 v20, v4
	v_mov_b32_e32 v21, v4
	v_mov_b32_e32 v22, v4
	v_mov_b32_e32 v23, v4
	v_mov_b32_e32 v36, v4
	v_mov_b32_e32 v37, v4
	v_mov_b32_e32 v38, v4
	v_mov_b32_e32 v39, v4
	v_mov_b32_e32 v52, v4
	v_mov_b32_e32 v53, v4
	v_mov_b32_e32 v54, v4
	v_mov_b32_e32 v55, v4
	v_mov_b32_e32 v68, v4
	v_mov_b32_e32 v69, v4
	v_mov_b32_e32 v70, v4
	v_mov_b32_e32 v71, v4
	v_mov_b32_e32 v84, v4
	v_mov_b32_e32 v85, v4
	v_mov_b32_e32 v86, v4
	v_mov_b32_e32 v87, v4
	v_mov_b32_e32 v100, v4
	v_mov_b32_e32 v101, v4
	v_mov_b32_e32 v102, v4
	v_mov_b32_e32 v103, v4
	v_mov_b32_e32 v116, v4
	v_mov_b32_e32 v117, v4
	v_mov_b32_e32 v118, v4
	v_mov_b32_e32 v119, v4
	v_mov_b32_e32 v8, v4
	v_mov_b32_e32 v9, v4
	v_mov_b32_e32 v10, v4
	v_mov_b32_e32 v11, v4
	v_mov_b32_e32 v24, v4
	v_mov_b32_e32 v25, v4
	v_mov_b32_e32 v26, v4
	v_mov_b32_e32 v27, v4
	v_mov_b32_e32 v40, v4
	v_mov_b32_e32 v41, v4
	v_mov_b32_e32 v42, v4
	v_mov_b32_e32 v43, v4
	v_mov_b32_e32 v56, v4
	v_mov_b32_e32 v57, v4
	v_mov_b32_e32 v58, v4
	v_mov_b32_e32 v59, v4
	v_mov_b32_e32 v72, v4
	v_mov_b32_e32 v73, v4
	v_mov_b32_e32 v74, v4
	v_mov_b32_e32 v75, v4
	v_mov_b32_e32 v88, v4
	v_mov_b32_e32 v89, v4
	v_mov_b32_e32 v90, v4
	v_mov_b32_e32 v91, v4
	v_mov_b32_e32 v104, v4
	v_mov_b32_e32 v105, v4
	v_mov_b32_e32 v106, v4
	v_mov_b32_e32 v107, v4
	v_mov_b32_e32 v120, v4
	v_mov_b32_e32 v121, v4
	v_mov_b32_e32 v122, v4
	v_mov_b32_e32 v123, v4
	v_mov_b32_e32 v12, v4
	v_mov_b32_e32 v13, v4
	v_mov_b32_e32 v14, v4
	v_mov_b32_e32 v15, v4
	v_mov_b32_e32 v28, v4
	v_mov_b32_e32 v29, v4
	v_mov_b32_e32 v30, v4
	v_mov_b32_e32 v31, v4
	v_mov_b32_e32 v44, v4
	v_mov_b32_e32 v45, v4
	v_mov_b32_e32 v46, v4
	v_mov_b32_e32 v47, v4
	v_mov_b32_e32 v60, v4
	v_mov_b32_e32 v61, v4
	v_mov_b32_e32 v62, v4
	v_mov_b32_e32 v63, v4
	v_mov_b32_e32 v76, v4
	v_mov_b32_e32 v77, v4
	v_mov_b32_e32 v78, v4
	v_mov_b32_e32 v79, v4
	v_mov_b32_e32 v92, v4
	v_mov_b32_e32 v93, v4
	v_mov_b32_e32 v94, v4
	v_mov_b32_e32 v95, v4
	v_mov_b32_e32 v108, v4
	v_mov_b32_e32 v109, v4
	v_mov_b32_e32 v110, v4
	v_mov_b32_e32 v111, v4
	v_mov_b32_e32 v124, v4
	v_mov_b32_e32 v125, v4
	v_mov_b32_e32 v126, v4
	v_mov_b32_e32 v127, v4
	s_waitcnt vmcnt(0) lgkmcnt(0)
	s_barrier
	s_branch .LBB0_529

; template <int PIPE>
; DI void gemm_loop_g(const u16* __restrict__ Xp, long ldx_l, long ldx_i, long kxs,
;                     const u16* __restrict__ Yp, long ldy_l, long ldy_i, long kys, int K,
;                     f32x4 (&acc)[4][8], unsigned char* smem) {
;     ...
;   __syncthreads();
;   issue(0, 0);
;   asm volatile("s_waitcnt vmcnt(0)" ::: "memory");
;   __syncthreads();
; template <int MODE>
; DI void gemm_phase(const Params& p, const GP& g, unsigned char* smem) {
;     ...
;     if (MODE == M_HG_IN) transposed = nt >= 12;
;     ...
;       const u16* Ap = Ab + (long)m0 * g.lda; const u16* Wp = Wb + (long)n0 * g.K;
;       if (transposed) gemm_loop(Ap, g.lda, Wp, g.K, g.K, acc, smem);
;       else gemm_loop(Wp, g.K, Ap, g.lda, g.K, acc, smem);
.LBB0_560:
	s_lshl_b32 s6, s74, 7
	s_and_b32 s6, s6, 0xfffff800
	s_and_b32 s75, s74, 15
	s_or_b32 s64, s6, s59
	s_cmp_lt_u32 s75, 12
	s_cselect_b64 s[10:11], -1, 0
	s_ashr_i32 s65, s64, 31
	s_lshl_b64 s[6:7], s[64:65], 11
	s_add_u32 s14, s16, s6
	s_addc_u32 s15, s17, s7
	s_lshl_b32 s6, s75, 19
	s_add_u32 s12, s18, s6
	s_addc_u32 s13, s19, 0
	s_mov_b64 s[66:67], -1
	s_and_b64 vcc, exec, s[10:11]
	s_cbranch_vccz .LBB0_566
	v_mov_b32_e32 v4, v182
	s_nop 0
	v_ashrrev_i32_e32 v0, 3, v4
	v_lshrrev_b32_e32 v5, 4, v4
	v_xor_b32_e32 v6, v5, v4
	v_ashrrev_i32_e32 v1, 31, v0
	v_lshlrev_b64 v[0:1], 11, v[0:1]
	v_lshlrev_b32_e32 v6, 4, v6
	v_lshl_add_u64 v[2:3], s[12:13], 0, v[0:1]
	v_and_b32_e32 v128, 0x70, v6
	v_lshl_add_u64 v[0:1], s[14:15], 0, v[0:1]
	v_lshl_add_u64 v[130:131], v[2:3], 0, v[128:129]
	v_lshl_add_u64 v[132:133], v[0:1], 0, v[128:129]
	v_lshlrev_b32_e32 v128, 4, v4
	v_add_u32_e32 v2, 0x2000, v128
	v_readfirstlane_b32 s6, v128
	v_lshl_add_u64 v[0:1], v[130:131], 0, s[28:29]
	s_mov_b32 m0, s6
	v_lshl_add_u64 v[134:135], v[130:131], 0, s[30:31]
	v_readfirstlane_b32 s6, v2
	v_add_u32_e32 v2, 0x4000, v128
	s_barrier
	global_load_lds_dwordx4 v[0:1], off
	v_lshl_add_u64 v[0:1], v[134:135], 0, s[28:29]
	s_mov_b32 m0, s6
	v_lshl_add_u64 v[136:137], v[130:131], 0, s[54:55]
	v_readfirstlane_b32 s6, v2
	v_add_u32_e32 v2, 0x6000, v128
	global_load_lds_dwordx4 v[0:1], off
	v_lshl_add_u64 v[0:1], v[136:137], 0, s[28:29]
	s_mov_b32 m0, s6
	v_lshl_add_u64 v[138:139], v[130:131], 0, s[56:57]
	v_readfirstlane_b32 s6, v2
	v_add_u32_e32 v2, 0x8000, v128
	global_load_lds_dwordx4 v[0:1], off
	v_lshl_add_u64 v[0:1], v[138:139], 0, s[28:29]
	s_mov_b32 m0, s6
	v_readfirstlane_b32 s6, v2
	v_add_u32_e32 v2, 0xa000, v128
	global_load_lds_dwordx4 v[0:1], off
	v_lshl_add_u64 v[0:1], v[132:133], 0, s[28:29]
	s_mov_b32 m0, s6
	v_lshl_add_u64 v[140:141], v[132:133], 0, s[30:31]
	v_readfirstlane_b32 s6, v2
	v_add_u32_e32 v2, 0xc000, v128
	global_load_lds_dwordx4 v[0:1], off
	v_lshl_add_u64 v[0:1], v[140:141], 0, s[28:29]
	s_mov_b32 m0, s6
	v_lshl_add_u64 v[142:143], v[132:133], 0, s[54:55]
	v_readfirstlane_b32 s6, v2
	v_add_u32_e32 v2, 0xe000, v128
	global_load_lds_dwordx4 v[0:1], off
	v_lshl_add_u64 v[0:1], v[142:143], 0, s[28:29]
	s_mov_b32 m0, s6
	v_lshl_add_u64 v[144:145], v[132:133], 0, s[56:57]
	v_readfirstlane_b32 s6, v2
	global_load_lds_dwordx4 v[0:1], off
	v_lshl_add_u64 v[0:1], v[144:145], 0, s[28:29]
	s_mov_b32 m0, s6
	v_lshlrev_b32_e32 v2, 7, v4
	global_load_lds_dwordx4 v[0:1], off
	v_bfe_u32 v0, v4, 4, 2
	v_bfe_u32 v1, v4, 1, 3
	v_readfirstlane_b32 s7, v4
	s_nop 0
	v_bitop3_b32 v0, v0, v1, 4 bitop3:0x36
	v_and_b32_e32 v2, 0x780, v2
	s_lshl_b32 s6, s7, 8
	s_lshl_b32 s7, s7, 6
	v_lshl_or_b32 v154, v0, 4, v2
	v_bitop3_b32 v0, v5, v1, 3 bitop3:0x6c
	v_mov_b32_e32 v8, 0
	s_and_b32 s6, s6, 0x4000
	s_and_b32 s7, s7, 0xffffe000
	v_lshl_or_b32 v155, v0, 4, v2
	s_mov_b32 s33, 0
	s_mov_b32 s48, 0x10000
	v_mov_b32_e32 v9, v8
	v_mov_b32_e32 v10, v8
	v_mov_b32_e32 v11, v8
	v_mov_b32_e32 v12, v8
	v_mov_b32_e32 v13, v8
	v_mov_b32_e32 v14, v8
	v_mov_b32_e32 v15, v8
	v_mov_b32_e32 v28, v8
	v_mov_b32_e32 v29, v8
	v_mov_b32_e32 v30, v8
	v_mov_b32_e32 v31, v8
	v_mov_b32_e32 v44, v8
	v_mov_b32_e32 v45, v8
	v_mov_b32_e32 v46, v8
	v_mov_b32_e32 v47, v8
	v_mov_b32_e32 v60, v8
	v_mov_b32_e32 v61, v8
	v_mov_b32_e32 v62, v8
	v_mov_b32_e32 v63, v8
	v_mov_b32_e32 v76, v8
	v_mov_b32_e32 v77, v8
	v_mov_b32_e32 v78, v8
	v_mov_b32_e32 v79, v8
	v_mov_b32_e32 v92, v8
	v_mov_b32_e32 v93, v8
	v_mov_b32_e32 v94, v8
	v_mov_b32_e32 v95, v8
	v_mov_b32_e32 v108, v8
	v_mov_b32_e32 v109, v8
	v_mov_b32_e32 v110, v8
	v_mov_b32_e32 v111, v8
	v_mov_b32_e32 v0, v8
	v_mov_b32_e32 v1, v8
	v_mov_b32_e32 v2, v8
	v_mov_b32_e32 v3, v8
	v_mov_b32_e32 v20, v8
	v_mov_b32_e32 v21, v8
	v_mov_b32_e32 v22, v8
	v_mov_b32_e32 v23, v8
	v_mov_b32_e32 v36, v8
	v_mov_b32_e32 v37, v8
	v_mov_b32_e32 v38, v8
	v_mov_b32_e32 v39, v8
	v_mov_b32_e32 v52, v8
	v_mov_b32_e32 v53, v8
	v_mov_b32_e32 v54, v8
	v_mov_b32_e32 v55, v8
	v_mov_b32_e32 v68, v8
	v_mov_b32_e32 v69, v8
	v_mov_b32_e32 v70, v8
	v_mov_b32_e32 v71, v8
	v_mov_b32_e32 v84, v8
	v_mov_b32_e32 v85, v8
	v_mov_b32_e32 v86, v8
	v_mov_b32_e32 v87, v8
	v_mov_b32_e32 v100, v8
	v_mov_b32_e32 v101, v8
	v_mov_b32_e32 v102, v8
	v_mov_b32_e32 v103, v8
	v_mov_b32_e32 v116, v8
	v_mov_b32_e32 v117, v8
	v_mov_b32_e32 v118, v8
	v_mov_b32_e32 v119, v8
	v_mov_b32_e32 v4, v8
	v_mov_b32_e32 v5, v8
	v_mov_b32_e32 v6, v8
	v_mov_b32_e32 v7, v8
	v_mov_b32_e32 v24, v8
	v_mov_b32_e32 v25, v8
	v_mov_b32_e32 v26, v8
	v_mov_b32_e32 v27, v8
	v_mov_b32_e32 v40, v8
	v_mov_b32_e32 v41, v8
	v_mov_b32_e32 v42, v8
	v_mov_b32_e32 v43, v8
	v_mov_b32_e32 v56, v8
	v_mov_b32_e32 v57, v8
	v_mov_b32_e32 v58, v8
	v_mov_b32_e32 v59, v8
	v_mov_b32_e32 v72, v8
	v_mov_b32_e32 v73, v8
	v_mov_b32_e32 v74, v8
	v_mov_b32_e32 v75, v8
	v_mov_b32_e32 v88, v8
	v_mov_b32_e32 v89, v8
	v_mov_b32_e32 v90, v8
	v_mov_b32_e32 v91, v8
	v_mov_b32_e32 v104, v8
	v_mov_b32_e32 v105, v8
	v_mov_b32_e32 v106, v8
	v_mov_b32_e32 v107, v8
	v_mov_b32_e32 v120, v8
	v_mov_b32_e32 v121, v8
	v_mov_b32_e32 v122, v8
	v_mov_b32_e32 v123, v8
	v_mov_b32_e32 v16, v8
	v_mov_b32_e32 v17, v8
	v_mov_b32_e32 v18, v8
	v_mov_b32_e32 v19, v8
	v_mov_b32_e32 v32, v8
	v_mov_b32_e32 v33, v8
	v_mov_b32_e32 v34, v8
	v_mov_b32_e32 v35, v8
	v_mov_b32_e32 v48, v8
	v_mov_b32_e32 v49, v8
	v_mov_b32_e32 v50, v8
	v_mov_b32_e32 v51, v8
	v_mov_b32_e32 v64, v8
	v_mov_b32_e32 v65, v8
	v_mov_b32_e32 v66, v8
	v_mov_b32_e32 v67, v8
	v_mov_b32_e32 v80, v8
	v_mov_b32_e32 v81, v8
	v_mov_b32_e32 v82, v8
	v_mov_b32_e32 v83, v8
	v_mov_b32_e32 v96, v8
	v_mov_b32_e32 v97, v8
	v_mov_b32_e32 v98, v8
	v_mov_b32_e32 v99, v8
	v_mov_b32_e32 v112, v8
	v_mov_b32_e32 v113, v8
	v_mov_b32_e32 v114, v8
	v_mov_b32_e32 v115, v8
	v_mov_b32_e32 v124, v8
	v_mov_b32_e32 v125, v8
	v_mov_b32_e32 v126, v8
	v_mov_b32_e32 v127, v8
	s_waitcnt vmcnt(0) lgkmcnt(0)
	s_barrier
	s_branch .LBB0_563

; template <int PIPE>
; DI void gemm_loop_g(const u16* __restrict__ Xp, long ldx_l, long ldx_i, long kxs,
;                     const u16* __restrict__ Yp, long ldy_l, long ldy_i, long kys, int K,
;                     f32x4 (&acc)[4][8], unsigned char* smem) {
;     ...
;   __syncthreads();
;   issue(0, 0);
;   asm volatile("s_waitcnt vmcnt(0)" ::: "memory");
;   __syncthreads();
; template <int MODE>
; DI void gemm_phase(const Params& p, const GP& g, unsigned char* smem) {
;     ...
;     if (MODE == M_HG_IN) transposed = nt >= 12;
;     ...
;       const u16* Ap = Ab + (long)m0 * g.lda; const u16* Wp = Wb + (long)n0 * g.K;
;       if (transposed) gemm_loop(Ap, g.lda, Wp, g.K, g.K, acc, smem);
;       else gemm_loop(Wp, g.K, Ap, g.lda, g.K, acc, smem);
.LBB0_566:
	s_and_b64 vcc, exec, s[66:67]
	s_cbranch_vccz .LBB0_571
	s_nop 1
	v_mov_b32_e32 v4, v182
	s_nop 0
	v_ashrrev_i32_e32 v0, 3, v4
	v_lshrrev_b32_e32 v5, 4, v4
	v_xor_b32_e32 v6, v5, v4
	v_ashrrev_i32_e32 v1, 31, v0
	v_lshlrev_b64 v[0:1], 11, v[0:1]
	v_lshlrev_b32_e32 v6, 4, v6
	v_lshl_add_u64 v[2:3], s[14:15], 0, v[0:1]
	v_and_b32_e32 v128, 0x70, v6
	v_lshl_add_u64 v[0:1], s[12:13], 0, v[0:1]
	v_lshl_add_u64 v[130:131], v[2:3], 0, v[128:129]
	v_lshl_add_u64 v[132:133], v[0:1], 0, v[128:129]
	v_lshlrev_b32_e32 v128, 4, v4
	v_add_u32_e32 v2, 0x2000, v128
	v_readfirstlane_b32 s6, v128
	v_lshl_add_u64 v[0:1], v[130:131], 0, s[28:29]
	s_mov_b32 m0, s6
	v_lshl_add_u64 v[134:135], v[130:131], 0, s[30:31]
	v_readfirstlane_b32 s6, v2
	v_add_u32_e32 v2, 0x4000, v128
	s_barrier
	global_load_lds_dwordx4 v[0:1], off
	v_lshl_add_u64 v[0:1], v[134:135], 0, s[28:29]
	s_mov_b32 m0, s6
	v_lshl_add_u64 v[136:137], v[130:131], 0, s[54:55]
	v_readfirstlane_b32 s6, v2
	v_add_u32_e32 v2, 0x6000, v128
	global_load_lds_dwordx4 v[0:1], off
	v_lshl_add_u64 v[0:1], v[136:137], 0, s[28:29]
	s_mov_b32 m0, s6
	v_lshl_add_u64 v[138:139], v[130:131], 0, s[56:57]
	v_readfirstlane_b32 s6, v2
	v_add_u32_e32 v2, 0x8000, v128
	global_load_lds_dwordx4 v[0:1], off
	v_lshl_add_u64 v[0:1], v[138:139], 0, s[28:29]
	s_mov_b32 m0, s6
	v_readfirstlane_b32 s6, v2
	v_add_u32_e32 v2, 0xa000, v128
	global_load_lds_dwordx4 v[0:1], off
	v_lshl_add_u64 v[0:1], v[132:133], 0, s[28:29]
	s_mov_b32 m0, s6
	v_lshl_add_u64 v[140:141], v[132:133], 0, s[30:31]
	v_readfirstlane_b32 s6, v2
	v_add_u32_e32 v2, 0xc000, v128
	global_load_lds_dwordx4 v[0:1], off
	v_lshl_add_u64 v[0:1], v[140:141], 0, s[28:29]
	s_mov_b32 m0, s6
	v_lshl_add_u64 v[142:143], v[132:133], 0, s[54:55]
	v_readfirstlane_b32 s6, v2
	v_add_u32_e32 v2, 0xe000, v128
	global_load_lds_dwordx4 v[0:1], off
	v_lshl_add_u64 v[0:1], v[142:143], 0, s[28:29]
	s_mov_b32 m0, s6
	v_lshl_add_u64 v[144:145], v[132:133], 0, s[56:57]
	v_readfirstlane_b32 s6, v2
	global_load_lds_dwordx4 v[0:1], off
	v_lshl_add_u64 v[0:1], v[144:145], 0, s[28:29]
	s_mov_b32 m0, s6
	v_lshlrev_b32_e32 v2, 7, v4
	global_load_lds_dwordx4 v[0:1], off
	v_bfe_u32 v0, v4, 4, 2
	v_bfe_u32 v1, v4, 1, 3
	v_readfirstlane_b32 s7, v4
	s_nop 0
	v_bitop3_b32 v0, v0, v1, 4 bitop3:0x36
	v_and_b32_e32 v2, 0x780, v2
	s_lshl_b32 s6, s7, 8
	s_lshl_b32 s7, s7, 6
	v_lshl_or_b32 v154, v0, 4, v2
	v_bitop3_b32 v0, v5, v1, 3 bitop3:0x6c
	v_mov_b32_e32 v8, 0
	s_and_b32 s6, s6, 0x4000
	s_and_b32 s7, s7, 0xffffe000
	v_lshl_or_b32 v155, v0, 4, v2
	s_mov_b32 s12, 0
	s_mov_b32 s13, 0x10000
	v_mov_b32_e32 v9, v8
	v_mov_b32_e32 v10, v8
	v_mov_b32_e32 v11, v8
	v_mov_b32_e32 v12, v8
	v_mov_b32_e32 v13, v8
	v_mov_b32_e32 v14, v8
	v_mov_b32_e32 v15, v8
	v_mov_b32_e32 v28, v8
	v_mov_b32_e32 v29, v8
	v_mov_b32_e32 v30, v8
	v_mov_b32_e32 v31, v8
	v_mov_b32_e32 v44, v8
	v_mov_b32_e32 v45, v8
	v_mov_b32_e32 v46, v8
	v_mov_b32_e32 v47, v8
	v_mov_b32_e32 v60, v8
	v_mov_b32_e32 v61, v8
	v_mov_b32_e32 v62, v8
	v_mov_b32_e32 v63, v8
	v_mov_b32_e32 v76, v8
	v_mov_b32_e32 v77, v8
	v_mov_b32_e32 v78, v8
	v_mov_b32_e32 v79, v8
	v_mov_b32_e32 v92, v8
	v_mov_b32_e32 v93, v8
	v_mov_b32_e32 v94, v8
	v_mov_b32_e32 v95, v8
	v_mov_b32_e32 v108, v8
	v_mov_b32_e32 v109, v8
	v_mov_b32_e32 v110, v8
	v_mov_b32_e32 v111, v8
	v_mov_b32_e32 v0, v8
	v_mov_b32_e32 v1, v8
	v_mov_b32_e32 v2, v8
	v_mov_b32_e32 v3, v8
	v_mov_b32_e32 v20, v8
	v_mov_b32_e32 v21, v8
	v_mov_b32_e32 v22, v8
	v_mov_b32_e32 v23, v8
	v_mov_b32_e32 v36, v8
	v_mov_b32_e32 v37, v8
	v_mov_b32_e32 v38, v8
	v_mov_b32_e32 v39, v8
	v_mov_b32_e32 v52, v8
	v_mov_b32_e32 v53, v8
	v_mov_b32_e32 v54, v8
	v_mov_b32_e32 v55, v8
	v_mov_b32_e32 v68, v8
	v_mov_b32_e32 v69, v8
	v_mov_b32_e32 v70, v8
	v_mov_b32_e32 v71, v8
	v_mov_b32_e32 v84, v8
	v_mov_b32_e32 v85, v8
	v_mov_b32_e32 v86, v8
	v_mov_b32_e32 v87, v8
	v_mov_b32_e32 v100, v8
	v_mov_b32_e32 v101, v8
	v_mov_b32_e32 v102, v8
	v_mov_b32_e32 v103, v8
	v_mov_b32_e32 v116, v8
	v_mov_b32_e32 v117, v8
	v_mov_b32_e32 v118, v8
	v_mov_b32_e32 v119, v8
	v_mov_b32_e32 v4, v8
	v_mov_b32_e32 v5, v8
	v_mov_b32_e32 v6, v8
	v_mov_b32_e32 v7, v8
	v_mov_b32_e32 v24, v8
	v_mov_b32_e32 v25, v8
	v_mov_b32_e32 v26, v8
	v_mov_b32_e32 v27, v8
	v_mov_b32_e32 v40, v8
	v_mov_b32_e32 v41, v8
	v_mov_b32_e32 v42, v8
	v_mov_b32_e32 v43, v8
	v_mov_b32_e32 v56, v8
	v_mov_b32_e32 v57, v8
	v_mov_b32_e32 v58, v8
	v_mov_b32_e32 v59, v8
	v_mov_b32_e32 v72, v8
	v_mov_b32_e32 v73, v8
	v_mov_b32_e32 v74, v8
	v_mov_b32_e32 v75, v8
	v_mov_b32_e32 v88, v8
	v_mov_b32_e32 v89, v8
	v_mov_b32_e32 v90, v8
	v_mov_b32_e32 v91, v8
	v_mov_b32_e32 v104, v8
	v_mov_b32_e32 v105, v8
	v_mov_b32_e32 v106, v8
	v_mov_b32_e32 v107, v8
	v_mov_b32_e32 v120, v8
	v_mov_b32_e32 v121, v8
	v_mov_b32_e32 v122, v8
	v_mov_b32_e32 v123, v8
	v_mov_b32_e32 v16, v8
	v_mov_b32_e32 v17, v8
	v_mov_b32_e32 v18, v8
	v_mov_b32_e32 v19, v8
	v_mov_b32_e32 v32, v8
	v_mov_b32_e32 v33, v8
	v_mov_b32_e32 v34, v8
	v_mov_b32_e32 v35, v8
	v_mov_b32_e32 v48, v8
	v_mov_b32_e32 v49, v8
	v_mov_b32_e32 v50, v8
	v_mov_b32_e32 v51, v8
	v_mov_b32_e32 v64, v8
	v_mov_b32_e32 v65, v8
	v_mov_b32_e32 v66, v8
	v_mov_b32_e32 v67, v8
	v_mov_b32_e32 v80, v8
	v_mov_b32_e32 v81, v8
	v_mov_b32_e32 v82, v8
	v_mov_b32_e32 v83, v8
	v_mov_b32_e32 v96, v8
	v_mov_b32_e32 v97, v8
	v_mov_b32_e32 v98, v8
	v_mov_b32_e32 v99, v8
	v_mov_b32_e32 v112, v8
	v_mov_b32_e32 v113, v8
	v_mov_b32_e32 v114, v8
	v_mov_b32_e32 v115, v8
	v_mov_b32_e32 v124, v8
	v_mov_b32_e32 v125, v8
	v_mov_b32_e32 v126, v8
	v_mov_b32_e32 v127, v8
	s_waitcnt vmcnt(0) lgkmcnt(0)
	s_barrier
	s_branch .LBB0_569

; template <int PIPE>
; DI void gemm_loop_g(const u16* __restrict__ Xp, long ldx_l, long ldx_i, long kxs,
;                     const u16* __restrict__ Yp, long ldy_l, long ldy_i, long kys, int K,
;                     f32x4 (&acc)[4][8], unsigned char* smem) {
;     ...
;   __syncthreads();
;   issue(0, 0);
;   asm volatile("s_waitcnt vmcnt(0)" ::: "memory");
;   __syncthreads();
; template <int MODE>
; DI void gemm_phase(const Params& p, const GP& g, unsigned char* smem) {
;     ...
;     f32x4 acc[4][8];
;     zero_acc(acc);
.LBB0_639:
	s_lshl_b32 s6, s27, 9
	s_and_b32 s6, s6, 0xfffff800
	s_or_b32 s22, s6, s24
	s_lshl_b32 s6, s27, 8
	s_and_b32 s6, s6, 0x300
	s_lshl_b32 s7, s6, 11
	s_add_u32 s8, s10, s7
	s_addc_u32 s9, s11, 0
	s_ashr_i32 s23, s22, 31
	s_waitcnt vmcnt(0)
	v_mov_b32_e32 v4, v182
	s_lshl_b64 s[28:29], s[22:23], 11
	s_add_u32 s28, s38, s28
	v_ashrrev_i32_e32 v0, 3, v4
	v_lshrrev_b32_e32 v5, 4, v4
	v_xor_b32_e32 v6, v5, v4
	v_ashrrev_i32_e32 v1, 31, v0
	s_addc_u32 s29, s39, s29
	v_lshlrev_b64 v[0:1], 11, v[0:1]
	v_lshlrev_b32_e32 v6, 4, v6
	v_lshl_add_u64 v[2:3], s[8:9], 0, v[0:1]
	v_and_b32_e32 v128, 0x70, v6
	v_lshl_add_u64 v[0:1], s[28:29], 0, v[0:1]
	v_lshl_add_u64 v[130:131], v[2:3], 0, v[128:129]
	v_lshl_add_u64 v[132:133], v[0:1], 0, v[128:129]
	v_lshlrev_b32_e32 v128, 4, v4
	v_add_u32_e32 v2, 0x2000, v128
	v_readfirstlane_b32 s7, v128
	v_lshl_add_u64 v[0:1], v[130:131], 0, s[14:15]
	s_mov_b32 m0, s7
	v_lshl_add_u64 v[134:135], v[130:131], 0, s[16:17]
	v_readfirstlane_b32 s7, v2
	v_add_u32_e32 v2, 0x4000, v128
	s_barrier
	global_load_lds_dwordx4 v[0:1], off
	v_lshl_add_u64 v[0:1], v[134:135], 0, s[14:15]
	s_mov_b32 m0, s7
	v_lshl_add_u64 v[136:137], v[130:131], 0, s[18:19]
	v_readfirstlane_b32 s7, v2
	v_add_u32_e32 v2, 0x6000, v128
	global_load_lds_dwordx4 v[0:1], off
	v_lshl_add_u64 v[0:1], v[136:137], 0, s[14:15]
	s_mov_b32 m0, s7
	v_lshl_add_u64 v[138:139], v[130:131], 0, s[20:21]
	v_readfirstlane_b32 s7, v2
	v_add_u32_e32 v2, 0x8000, v128
	global_load_lds_dwordx4 v[0:1], off
	v_lshl_add_u64 v[0:1], v[138:139], 0, s[14:15]
	s_mov_b32 m0, s7
	v_readfirstlane_b32 s7, v2
	v_add_u32_e32 v2, 0xa000, v128
	global_load_lds_dwordx4 v[0:1], off
	v_lshl_add_u64 v[0:1], v[132:133], 0, s[14:15]
	s_mov_b32 m0, s7
	v_lshl_add_u64 v[140:141], v[132:133], 0, s[16:17]
	v_readfirstlane_b32 s7, v2
	v_add_u32_e32 v2, 0xc000, v128
	global_load_lds_dwordx4 v[0:1], off
	v_lshl_add_u64 v[0:1], v[140:141], 0, s[14:15]
	s_mov_b32 m0, s7
	v_lshl_add_u64 v[142:143], v[132:133], 0, s[18:19]
	v_readfirstlane_b32 s7, v2
	v_add_u32_e32 v2, 0xe000, v128
	global_load_lds_dwordx4 v[0:1], off
	v_lshl_add_u64 v[0:1], v[142:143], 0, s[14:15]
	s_mov_b32 m0, s7
	v_lshl_add_u64 v[144:145], v[132:133], 0, s[20:21]
	v_readfirstlane_b32 s7, v2
	global_load_lds_dwordx4 v[0:1], off
	v_lshl_add_u64 v[0:1], v[144:145], 0, s[14:15]
	s_mov_b32 m0, s7
	v_lshlrev_b32_e32 v2, 7, v4
	global_load_lds_dwordx4 v[0:1], off
	v_bfe_u32 v0, v4, 4, 2
	v_bfe_u32 v1, v4, 1, 3
	v_readfirstlane_b32 s23, v4
	s_nop 0
	v_bitop3_b32 v0, v0, v1, 4 bitop3:0x36
	v_and_b32_e32 v2, 0x780, v2
	s_lshl_b32 s7, s23, 8
	s_lshl_b32 s8, s23, 6
	v_lshl_or_b32 v149, v0, 4, v2
	v_bitop3_b32 v0, v5, v1, 3 bitop3:0x6c
	s_and_b32 s7, s7, 0x4000
	s_and_b32 s23, s8, 0xffffe000
	v_lshl_or_b32 v150, v0, 4, v2
	s_mov_b32 s28, 0x10000
	s_mov_b32 s29, 0
	v_mov_b32_e32 v4, 0
	v_mov_b32_e32 v5, v129
	v_mov_b32_e32 v6, v129
	v_mov_b32_e32 v7, v129
	v_mov_b32_e32 v16, 0
	v_mov_b32_e32 v17, v129
	v_mov_b32_e32 v18, v129
	v_mov_b32_e32 v19, v129
	v_mov_b32_e32 v32, 0
	v_mov_b32_e32 v33, v129
	v_mov_b32_e32 v34, v129
	v_mov_b32_e32 v35, v129
	v_mov_b32_e32 v48, 0
	v_mov_b32_e32 v49, v129
	v_mov_b32_e32 v50, v129
	v_mov_b32_e32 v51, v129
	v_mov_b32_e32 v64, 0
	v_mov_b32_e32 v65, v129
	v_mov_b32_e32 v66, v129
	v_mov_b32_e32 v67, v129
	v_mov_b32_e32 v80, 0
	v_mov_b32_e32 v81, v129
	v_mov_b32_e32 v82, v129
	v_mov_b32_e32 v83, v129
	v_mov_b32_e32 v96, 0
	v_mov_b32_e32 v97, v129
	v_mov_b32_e32 v98, v129
	v_mov_b32_e32 v99, v129
	v_mov_b32_e32 v112, 0
	v_mov_b32_e32 v113, v129
	v_mov_b32_e32 v114, v129
	v_mov_b32_e32 v115, v129
	v_mov_b32_e32 v0, 0
	v_mov_b32_e32 v1, v129
	v_mov_b32_e32 v2, v129
	v_mov_b32_e32 v3, v129
	v_mov_b32_e32 v20, 0
	v_mov_b32_e32 v21, v129
	v_mov_b32_e32 v22, v129
	v_mov_b32_e32 v23, v129
	v_mov_b32_e32 v36, 0
	v_mov_b32_e32 v37, v129
	v_mov_b32_e32 v38, v129
	v_mov_b32_e32 v39, v129
	v_mov_b32_e32 v52, 0
	v_mov_b32_e32 v53, v129
	v_mov_b32_e32 v54, v129
	v_mov_b32_e32 v55, v129
	v_mov_b32_e32 v68, 0
	v_mov_b32_e32 v69, v129
	v_mov_b32_e32 v70, v129
	v_mov_b32_e32 v71, v129
	v_mov_b32_e32 v84, 0
	v_mov_b32_e32 v85, v129
	v_mov_b32_e32 v86, v129
	v_mov_b32_e32 v87, v129
	v_mov_b32_e32 v100, 0
	v_mov_b32_e32 v101, v129
	v_mov_b32_e32 v102, v129
	v_mov_b32_e32 v103, v129
	v_mov_b32_e32 v116, 0
	v_mov_b32_e32 v117, v129
	v_mov_b32_e32 v118, v129
	v_mov_b32_e32 v119, v129
	v_mov_b32_e32 v8, 0
	v_mov_b32_e32 v9, v129
	v_mov_b32_e32 v10, v129
	v_mov_b32_e32 v11, v129
	v_mov_b32_e32 v24, 0
	v_mov_b32_e32 v25, v129
	v_mov_b32_e32 v26, v129
	v_mov_b32_e32 v27, v129
	v_mov_b32_e32 v40, 0
	v_mov_b32_e32 v41, v129
	v_mov_b32_e32 v42, v129
	v_mov_b32_e32 v43, v129
	v_mov_b32_e32 v56, 0
	v_mov_b32_e32 v57, v129
	v_mov_b32_e32 v58, v129
	v_mov_b32_e32 v59, v129
	v_mov_b32_e32 v72, 0
	v_mov_b32_e32 v73, v129
	v_mov_b32_e32 v74, v129
	v_mov_b32_e32 v75, v129
	v_mov_b32_e32 v88, 0
	v_mov_b32_e32 v89, v129
	v_mov_b32_e32 v90, v129
	v_mov_b32_e32 v91, v129
	v_mov_b32_e32 v104, 0
	v_mov_b32_e32 v105, v129
	v_mov_b32_e32 v106, v129
	v_mov_b32_e32 v107, v129
	v_mov_b32_e32 v120, 0
	v_mov_b32_e32 v121, v129
	v_mov_b32_e32 v122, v129
	v_mov_b32_e32 v123, v129
	v_mov_b32_e32 v12, 0
	v_mov_b32_e32 v13, v129
	v_mov_b32_e32 v14, v129
	v_mov_b32_e32 v15, v129
	v_mov_b32_e32 v28, 0
	v_mov_b32_e32 v29, v129
	v_mov_b32_e32 v30, v129
	v_mov_b32_e32 v31, v129
	v_mov_b32_e32 v44, 0
	v_mov_b32_e32 v45, v129
	v_mov_b32_e32 v46, v129
	v_mov_b32_e32 v47, v129
	v_mov_b32_e32 v60, 0
	v_mov_b32_e32 v61, v129
	v_mov_b32_e32 v62, v129
	v_mov_b32_e32 v63, v129
	v_mov_b32_e32 v76, 0
	v_mov_b32_e32 v77, v129
	v_mov_b32_e32 v78, v129
	v_mov_b32_e32 v79, v129
	v_mov_b32_e32 v92, 0
	v_mov_b32_e32 v93, v129
	v_mov_b32_e32 v94, v129
	v_mov_b32_e32 v95, v129
	v_mov_b32_e32 v108, 0
	v_mov_b32_e32 v109, v129
	v_mov_b32_e32 v110, v129
	v_mov_b32_e32 v111, v129
	v_mov_b32_e32 v124, 0
	v_mov_b32_e32 v125, v129
	v_mov_b32_e32 v126, v129
	v_mov_b32_e32 v127, v129
	s_waitcnt vmcnt(0) lgkmcnt(0)
	s_barrier
	s_branch .LBB0_641

; template <int PIPE>
; DI void gemm_loop_g(const u16* __restrict__ Xp, long ldx_l, long ldx_i, long kxs,
;                     const u16* __restrict__ Yp, long ldy_l, long ldy_i, long kys, int K,
;                     f32x4 (&acc)[4][8], unsigned char* smem) {
;     ...
;   __syncthreads();
;   issue(0, 0);
;   asm volatile("s_waitcnt vmcnt(0)" ::: "memory");
;   __syncthreads();
; template <int MODE>
; DI void gemm_phase(const Params& p, const GP& g, unsigned char* smem) {
;     ...
;     f32x4 acc[4][8];
;     zero_acc(acc);
.LBB0_656:
	s_lshl_b32 s6, s24, 9
	s_and_b32 s6, s6, 0xfffff800
	s_or_b32 s20, s6, s22
	s_lshl_b32 s6, s24, 8
	s_and_b32 s6, s6, 0x300
	s_lshl_b32 s7, s6, 11
	s_waitcnt lgkmcnt(0)
	s_add_u32 s8, s10, s7
	s_addc_u32 s9, s11, 0
	s_ashr_i32 s21, s20, 31
	s_waitcnt vmcnt(0)
	v_mov_b32_e32 v4, v182
	s_lshl_b64 s[26:27], s[20:21], 11
	s_add_u32 s26, s36, s26
	v_ashrrev_i32_e32 v0, 3, v4
	v_lshrrev_b32_e32 v5, 4, v4
	v_xor_b32_e32 v6, v5, v4
	v_ashrrev_i32_e32 v1, 31, v0
	s_addc_u32 s27, s37, s27
	v_lshlrev_b64 v[0:1], 11, v[0:1]
	v_lshlrev_b32_e32 v6, 4, v6
	v_lshl_add_u64 v[2:3], s[8:9], 0, v[0:1]
	v_and_b32_e32 v128, 0x70, v6
	v_lshl_add_u64 v[0:1], s[26:27], 0, v[0:1]
	v_lshl_add_u64 v[130:131], v[2:3], 0, v[128:129]
	v_lshl_add_u64 v[132:133], v[0:1], 0, v[128:129]
	v_lshlrev_b32_e32 v128, 4, v4
	v_add_u32_e32 v2, 0x2000, v128
	v_readfirstlane_b32 s7, v128
	v_lshl_add_u64 v[0:1], v[130:131], 0, s[4:5]
	s_mov_b32 m0, s7
	v_lshl_add_u64 v[134:135], v[130:131], 0, s[14:15]
	v_readfirstlane_b32 s7, v2
	v_add_u32_e32 v2, 0x4000, v128
	s_barrier
	global_load_lds_dwordx4 v[0:1], off
	v_lshl_add_u64 v[0:1], v[134:135], 0, s[4:5]
	s_mov_b32 m0, s7
	v_lshl_add_u64 v[136:137], v[130:131], 0, s[16:17]
	v_readfirstlane_b32 s7, v2
	v_add_u32_e32 v2, 0x6000, v128
	global_load_lds_dwordx4 v[0:1], off
	v_lshl_add_u64 v[0:1], v[136:137], 0, s[4:5]
	s_mov_b32 m0, s7
	v_lshl_add_u64 v[138:139], v[130:131], 0, s[18:19]
	v_readfirstlane_b32 s7, v2
	v_add_u32_e32 v2, 0x8000, v128
	global_load_lds_dwordx4 v[0:1], off
	v_lshl_add_u64 v[0:1], v[138:139], 0, s[4:5]
	s_mov_b32 m0, s7
	v_readfirstlane_b32 s7, v2
	v_add_u32_e32 v2, 0xa000, v128
	global_load_lds_dwordx4 v[0:1], off
	v_lshl_add_u64 v[0:1], v[132:133], 0, s[4:5]
	s_mov_b32 m0, s7
	v_lshl_add_u64 v[140:141], v[132:133], 0, s[14:15]
	v_readfirstlane_b32 s7, v2
	v_add_u32_e32 v2, 0xc000, v128
	global_load_lds_dwordx4 v[0:1], off
	v_lshl_add_u64 v[0:1], v[140:141], 0, s[4:5]
	s_mov_b32 m0, s7
	v_lshl_add_u64 v[142:143], v[132:133], 0, s[16:17]
	v_readfirstlane_b32 s7, v2
	v_add_u32_e32 v2, 0xe000, v128
	global_load_lds_dwordx4 v[0:1], off
	v_lshl_add_u64 v[0:1], v[142:143], 0, s[4:5]
	s_mov_b32 m0, s7
	v_lshl_add_u64 v[144:145], v[132:133], 0, s[18:19]
	v_readfirstlane_b32 s7, v2
	global_load_lds_dwordx4 v[0:1], off
	v_lshl_add_u64 v[0:1], v[144:145], 0, s[4:5]
	s_mov_b32 m0, s7
	v_lshlrev_b32_e32 v2, 7, v4
	global_load_lds_dwordx4 v[0:1], off
	v_bfe_u32 v0, v4, 4, 2
	v_bfe_u32 v1, v4, 1, 3
	v_readfirstlane_b32 s21, v4
	s_nop 0
	v_bitop3_b32 v0, v0, v1, 4 bitop3:0x36
	v_and_b32_e32 v2, 0x780, v2
	s_lshl_b32 s7, s21, 8
	s_lshl_b32 s8, s21, 6
	v_lshl_or_b32 v148, v0, 4, v2
	v_bitop3_b32 v0, v5, v1, 3 bitop3:0x6c
	s_and_b32 s7, s7, 0x4000
	s_and_b32 s21, s8, 0xffffe000
	v_lshl_or_b32 v149, v0, 4, v2
	s_mov_b32 s25, 0x10000
	s_mov_b32 s26, 0
	v_mov_b32_e32 v12, 0
	v_mov_b32_e32 v13, v129
	v_mov_b32_e32 v14, v129
	v_mov_b32_e32 v15, v129
	v_mov_b32_e32 v4, 0
	v_mov_b32_e32 v5, v129
	v_mov_b32_e32 v6, v129
	v_mov_b32_e32 v7, v129
	v_mov_b32_e32 v24, 0
	v_mov_b32_e32 v25, v129
	v_mov_b32_e32 v26, v129
	v_mov_b32_e32 v27, v129
	v_mov_b32_e32 v40, 0
	v_mov_b32_e32 v41, v129
	v_mov_b32_e32 v42, v129
	v_mov_b32_e32 v43, v129
	v_mov_b32_e32 v56, 0
	v_mov_b32_e32 v57, v129
	v_mov_b32_e32 v58, v129
	v_mov_b32_e32 v59, v129
	v_mov_b32_e32 v72, 0
	v_mov_b32_e32 v73, v129
	v_mov_b32_e32 v74, v129
	v_mov_b32_e32 v75, v129
	v_mov_b32_e32 v88, 0
	v_mov_b32_e32 v89, v129
	v_mov_b32_e32 v90, v129
	v_mov_b32_e32 v91, v129
	v_mov_b32_e32 v104, 0
	v_mov_b32_e32 v105, v129
	v_mov_b32_e32 v106, v129
	v_mov_b32_e32 v107, v129
	v_mov_b32_e32 v0, 0
	v_mov_b32_e32 v1, v129
	v_mov_b32_e32 v2, v129
	v_mov_b32_e32 v3, v129
	v_mov_b32_e32 v20, 0
	v_mov_b32_e32 v21, v129
	v_mov_b32_e32 v22, v129
	v_mov_b32_e32 v23, v129
	v_mov_b32_e32 v36, 0
	v_mov_b32_e32 v37, v129
	v_mov_b32_e32 v38, v129
	v_mov_b32_e32 v39, v129
	v_mov_b32_e32 v52, 0
	v_mov_b32_e32 v53, v129
	v_mov_b32_e32 v54, v129
	v_mov_b32_e32 v55, v129
	v_mov_b32_e32 v68, 0
	v_mov_b32_e32 v69, v129
	v_mov_b32_e32 v70, v129
	v_mov_b32_e32 v71, v129
	v_mov_b32_e32 v84, 0
	v_mov_b32_e32 v85, v129
	v_mov_b32_e32 v86, v129
	v_mov_b32_e32 v87, v129
	v_mov_b32_e32 v100, 0
	v_mov_b32_e32 v101, v129
	v_mov_b32_e32 v102, v129
	v_mov_b32_e32 v103, v129
	v_mov_b32_e32 v116, 0
	v_mov_b32_e32 v117, v129
	v_mov_b32_e32 v118, v129
	v_mov_b32_e32 v119, v129
	v_mov_b32_e32 v8, 0
	v_mov_b32_e32 v9, v129
	v_mov_b32_e32 v10, v129
	v_mov_b32_e32 v11, v129
	v_mov_b32_e32 v28, 0
	v_mov_b32_e32 v29, v129
	v_mov_b32_e32 v30, v129
	v_mov_b32_e32 v31, v129
	v_mov_b32_e32 v44, 0
	v_mov_b32_e32 v45, v129
	v_mov_b32_e32 v46, v129
	v_mov_b32_e32 v47, v129
	v_mov_b32_e32 v60, 0
	v_mov_b32_e32 v61, v129
	v_mov_b32_e32 v62, v129
	v_mov_b32_e32 v63, v129
	v_mov_b32_e32 v76, 0
	v_mov_b32_e32 v77, v129
	v_mov_b32_e32 v78, v129
	v_mov_b32_e32 v79, v129
	v_mov_b32_e32 v92, 0
	v_mov_b32_e32 v93, v129
	v_mov_b32_e32 v94, v129
	v_mov_b32_e32 v95, v129
	v_mov_b32_e32 v108, 0
	v_mov_b32_e32 v109, v129
	v_mov_b32_e32 v110, v129
	v_mov_b32_e32 v111, v129
	v_mov_b32_e32 v120, 0
	v_mov_b32_e32 v121, v129
	v_mov_b32_e32 v122, v129
	v_mov_b32_e32 v123, v129
	v_mov_b32_e32 v16, 0
	v_mov_b32_e32 v17, v129
	v_mov_b32_e32 v18, v129
	v_mov_b32_e32 v19, v129
	v_mov_b32_e32 v32, 0
	v_mov_b32_e32 v33, v129
	v_mov_b32_e32 v34, v129
	v_mov_b32_e32 v35, v129
	v_mov_b32_e32 v48, 0
	v_mov_b32_e32 v49, v129
	v_mov_b32_e32 v50, v129
	v_mov_b32_e32 v51, v129
	v_mov_b32_e32 v64, 0
	v_mov_b32_e32 v65, v129
	v_mov_b32_e32 v66, v129
	v_mov_b32_e32 v67, v129
	v_mov_b32_e32 v80, 0
	v_mov_b32_e32 v81, v129
	v_mov_b32_e32 v82, v129
	v_mov_b32_e32 v83, v129
	v_mov_b32_e32 v96, 0
	v_mov_b32_e32 v97, v129
	v_mov_b32_e32 v98, v129
	v_mov_b32_e32 v99, v129
	v_mov_b32_e32 v112, 0
	v_mov_b32_e32 v113, v129
	v_mov_b32_e32 v114, v129
	v_mov_b32_e32 v115, v129
	v_mov_b32_e32 v124, 0
	v_mov_b32_e32 v125, v129
	v_mov_b32_e32 v126, v129
	v_mov_b32_e32 v127, v129
	s_waitcnt vmcnt(0) lgkmcnt(0)
	s_barrier
	s_branch .LBB0_658

; template <int PIPE>
; DI void gemm_loop_g(const u16* __restrict__ Xp, long ldx_l, long ldx_i, long kxs,
;                     const u16* __restrict__ Yp, long ldy_l, long ldy_i, long kys, int K,
;                     f32x4 (&acc)[4][8], unsigned char* smem) {
;     ...
;   __syncthreads();
;   issue(0, 0);
;   asm volatile("s_waitcnt vmcnt(0)" ::: "memory");
;   __syncthreads();
; template <int MODE>
; DI void gemm_phase(const Params& p, const GP& g, unsigned char* smem) {
;     ...
;     if (MODE == M_PLE) {
;       const u16* pb = (const u16*)g.d1;
;       gemm_loop(g.W2 + (long)n0 * 256, 256, pb + (long)m0 * 256, 256, 256, acc, smem);
.LBB0_676:
	s_lshl_b32 s2, s35, 9
	s_lshl_b32 s3, s35, 8
	s_and_b32 s2, s2, 0xfffff800
	s_and_b32 s6, s3, 0x300
	s_or_b32 s2, s2, s42
	s_lshl_b32 s3, s6, 9
	s_add_u32 s26, s30, s3
	s_waitcnt vmcnt(0)
	v_mov_b32_e32 v6, v182
	s_addc_u32 s27, s31, 0
	s_ashr_i32 s3, s2, 31
	s_lshl_b64 s[40:41], s[2:3], 9
	v_ashrrev_i32_e32 v2, 3, v6
	v_lshrrev_b32_e32 v7, 4, v6
	v_xor_b32_e32 v8, v7, v6
	v_ashrrev_i32_e32 v3, 31, v2
	s_waitcnt lgkmcnt(0)
	v_lshl_add_u64 v[0:1], v[128:129], 0, s[40:41]
	v_lshlrev_b64 v[2:3], 9, v[2:3]
	v_lshlrev_b32_e32 v8, 4, v8
	v_lshl_add_u64 v[4:5], s[26:27], 0, v[2:3]
	v_and_b32_e32 v130, 0x70, v8
	v_lshl_add_u64 v[0:1], v[0:1], 0, v[2:3]
	v_lshl_add_u64 v[132:133], v[4:5], 0, v[130:131]
	v_lshl_add_u64 v[134:135], v[0:1], 0, v[130:131]
	v_lshlrev_b32_e32 v130, 4, v6
	v_add_u32_e32 v2, 0x2000, v130
	v_readfirstlane_b32 s7, v130
	v_lshl_add_u64 v[0:1], v[132:133], 0, s[10:11]
	s_mov_b32 m0, s7
	v_lshl_add_u64 v[136:137], v[132:133], 0, s[12:13]
	v_readfirstlane_b32 s7, v2
	v_add_u32_e32 v2, 0x4000, v130
	s_barrier
	global_load_lds_dwordx4 v[0:1], off
	v_lshl_add_u64 v[0:1], v[136:137], 0, s[10:11]
	s_mov_b32 m0, s7
	v_lshl_add_u64 v[138:139], v[132:133], 0, s[14:15]
	v_readfirstlane_b32 s7, v2
	v_add_u32_e32 v2, 0x6000, v130
	global_load_lds_dwordx4 v[0:1], off
	v_lshl_add_u64 v[0:1], v[138:139], 0, s[10:11]
	s_mov_b32 m0, s7
	v_lshl_add_u64 v[140:141], v[132:133], 0, s[16:17]
	v_readfirstlane_b32 s7, v2
	v_add_u32_e32 v2, 0x8000, v130
	global_load_lds_dwordx4 v[0:1], off
	v_lshl_add_u64 v[0:1], v[140:141], 0, s[10:11]
	s_mov_b32 m0, s7
	v_readfirstlane_b32 s7, v2
	v_add_u32_e32 v2, 0xa000, v130
	global_load_lds_dwordx4 v[0:1], off
	v_lshl_add_u64 v[0:1], v[134:135], 0, s[10:11]
	s_mov_b32 m0, s7
	v_lshl_add_u64 v[142:143], v[134:135], 0, s[12:13]
	v_readfirstlane_b32 s7, v2
	v_add_u32_e32 v2, 0xc000, v130
	global_load_lds_dwordx4 v[0:1], off
	v_lshl_add_u64 v[0:1], v[142:143], 0, s[10:11]
	s_mov_b32 m0, s7
	v_lshl_add_u64 v[144:145], v[134:135], 0, s[14:15]
	v_readfirstlane_b32 s7, v2
	v_add_u32_e32 v2, 0xe000, v130
	global_load_lds_dwordx4 v[0:1], off
	v_lshl_add_u64 v[0:1], v[144:145], 0, s[10:11]
	s_mov_b32 m0, s7
	v_lshl_add_u64 v[146:147], v[134:135], 0, s[16:17]
	v_readfirstlane_b32 s7, v2
	global_load_lds_dwordx4 v[0:1], off
	v_lshl_add_u64 v[0:1], v[146:147], 0, s[10:11]
	s_mov_b32 m0, s7
	v_lshlrev_b32_e32 v2, 7, v6
	global_load_lds_dwordx4 v[0:1], off
	v_bfe_u32 v0, v6, 4, 2
	v_bfe_u32 v1, v6, 1, 3
	v_readfirstlane_b32 s33, v6
	s_nop 0
	v_bitop3_b32 v0, v0, v1, 4 bitop3:0x36
	v_and_b32_e32 v2, 0x780, v2
	s_lshl_b32 s7, s33, 8
	s_lshl_b32 s26, s33, 6
	v_lshl_or_b32 v148, v0, 4, v2
	v_bitop3_b32 v0, v7, v1, 3 bitop3:0x6c
	s_and_b32 s7, s7, 0x4000
	s_and_b32 s26, s26, 0xffffe000
	v_lshl_or_b32 v149, v0, 4, v2
	s_mov_b32 s27, 0x10000
	s_mov_b32 s33, 0
	v_mov_b32_e32 v40, 0
	v_mov_b32_e32 v41, v131
	v_mov_b32_e32 v42, v131
	v_mov_b32_e32 v43, v131
	v_mov_b32_e32 v0, 0
	v_mov_b32_e32 v1, v131
	v_mov_b32_e32 v2, v131
	v_mov_b32_e32 v3, v131
	v_mov_b32_e32 v8, 0
	v_mov_b32_e32 v9, v131
	v_mov_b32_e32 v10, v131
	v_mov_b32_e32 v11, v131
	v_mov_b32_e32 v20, 0
	v_mov_b32_e32 v21, v131
	v_mov_b32_e32 v22, v131
	v_mov_b32_e32 v23, v131
	v_mov_b32_e32 v36, 0
	v_mov_b32_e32 v37, v131
	v_mov_b32_e32 v38, v131
	v_mov_b32_e32 v39, v131
	v_mov_b32_e32 v56, 0
	v_mov_b32_e32 v57, v131
	v_mov_b32_e32 v58, v131
	v_mov_b32_e32 v59, v131
	v_mov_b32_e32 v72, 0
	v_mov_b32_e32 v73, v131
	v_mov_b32_e32 v74, v131
	v_mov_b32_e32 v75, v131
	v_mov_b32_e32 v96, 0
	v_mov_b32_e32 v97, v131
	v_mov_b32_e32 v98, v131
	v_mov_b32_e32 v99, v131
	v_mov_b32_e32 v4, 0
	v_mov_b32_e32 v5, v131
	v_mov_b32_e32 v6, v131
	v_mov_b32_e32 v7, v131
	v_mov_b32_e32 v12, 0
	v_mov_b32_e32 v13, v131
	v_mov_b32_e32 v14, v131
	v_mov_b32_e32 v15, v131
	v_mov_b32_e32 v24, 0
	v_mov_b32_e32 v25, v131
	v_mov_b32_e32 v26, v131
	v_mov_b32_e32 v27, v131
	v_mov_b32_e32 v44, 0
	v_mov_b32_e32 v45, v131
	v_mov_b32_e32 v46, v131
	v_mov_b32_e32 v47, v131
	v_mov_b32_e32 v64, 0
	v_mov_b32_e32 v65, v131
	v_mov_b32_e32 v66, v131
	v_mov_b32_e32 v67, v131
	v_mov_b32_e32 v76, 0
	v_mov_b32_e32 v77, v131
	v_mov_b32_e32 v78, v131
	v_mov_b32_e32 v79, v131
	v_mov_b32_e32 v88, 0
	v_mov_b32_e32 v89, v131
	v_mov_b32_e32 v90, v131
	v_mov_b32_e32 v91, v131
	v_mov_b32_e32 v112, 0
	v_mov_b32_e32 v113, v131
	v_mov_b32_e32 v114, v131
	v_mov_b32_e32 v115, v131
	v_mov_b32_e32 v16, 0
	v_mov_b32_e32 v17, v131
	v_mov_b32_e32 v18, v131
	v_mov_b32_e32 v19, v131
	v_mov_b32_e32 v28, 0
	v_mov_b32_e32 v29, v131
	v_mov_b32_e32 v30, v131
	v_mov_b32_e32 v31, v131
	v_mov_b32_e32 v48, 0
	v_mov_b32_e32 v49, v131
	v_mov_b32_e32 v50, v131
	v_mov_b32_e32 v51, v131
	v_mov_b32_e32 v60, 0
	v_mov_b32_e32 v61, v131
	v_mov_b32_e32 v62, v131
	v_mov_b32_e32 v63, v131
	v_mov_b32_e32 v80, 0
	v_mov_b32_e32 v81, v131
	v_mov_b32_e32 v82, v131
	v_mov_b32_e32 v83, v131
	v_mov_b32_e32 v92, 0
	v_mov_b32_e32 v93, v131
	v_mov_b32_e32 v94, v131
	v_mov_b32_e32 v95, v131
	v_mov_b32_e32 v108, 0
	v_mov_b32_e32 v109, v131
	v_mov_b32_e32 v110, v131
	v_mov_b32_e32 v111, v131
	v_mov_b32_e32 v116, 0
	v_mov_b32_e32 v117, v131
	v_mov_b32_e32 v118, v131
	v_mov_b32_e32 v119, v131
	v_mov_b32_e32 v32, 0
	v_mov_b32_e32 v33, v131
	v_mov_b32_e32 v34, v131
	v_mov_b32_e32 v35, v131
	v_mov_b32_e32 v52, 0
	v_mov_b32_e32 v53, v131
	v_mov_b32_e32 v54, v131
	v_mov_b32_e32 v55, v131
	v_mov_b32_e32 v68, 0
	v_mov_b32_e32 v69, v131
	v_mov_b32_e32 v70, v131
	v_mov_b32_e32 v71, v131
	v_mov_b32_e32 v84, 0
	v_mov_b32_e32 v85, v131
	v_mov_b32_e32 v86, v131
	v_mov_b32_e32 v87, v131
	v_mov_b32_e32 v100, 0
	v_mov_b32_e32 v101, v131
	v_mov_b32_e32 v102, v131
	v_mov_b32_e32 v103, v131
	v_mov_b32_e32 v104, 0
	v_mov_b32_e32 v105, v131
	v_mov_b32_e32 v106, v131
	v_mov_b32_e32 v107, v131
	v_mov_b32_e32 v120, 0
	v_mov_b32_e32 v121, v131
	v_mov_b32_e32 v122, v131
	v_mov_b32_e32 v123, v131
	v_mov_b32_e32 v124, 0
	v_mov_b32_e32 v125, v131
	v_mov_b32_e32 v126, v131
	v_mov_b32_e32 v127, v131
	s_waitcnt vmcnt(0) lgkmcnt(0)
	s_barrier
	s_branch .LBB0_678

; DI u32x2 pack4(float a, float b, float c, float d) { u32x2 r; r.x = pack2(a, b); r.y = pack2(c, d); return r; }
; #define EPI_END if (i == 3 && (j & 3) == 3) __builtin_amdgcn_sched_barrier(0); }
; template <int PIPE>
; DI void gemm_loop_g(const u16* __restrict__ Xp, long ldx_l, long ldx_i, long kxs,
;                     const u16* __restrict__ Yp, long ldy_l, long ldy_i, long kys, int K,
;                     f32x4 (&acc)[4][8], unsigned char* smem) {
;     ...
;   __syncthreads();
;   issue(0, 0);
; template <int MODE>
; DI void gemm_phase(const Params& p, const GP& g, unsigned char* smem) {
;     ...
;     if (MODE == M_PLE) {
;       const u16* pb = (const u16*)g.d1;
;       gemm_loop(g.W2 + (long)n0 * 256, 256, pb + (long)m0 * 256, 256, 256, acc, smem);
;       u16* xb = (u16*)g.d0;
;       EPI_STD_BEGIN
;         *(u32x2*)(xb + (long)m * 1024 + n4) = pack4(v[0], v[1], v[2], v[3]);
;       EPI_END
;       zero_acc(acc);
.LBB0_680:
	v_or_b32_e32 v160, s2, v185
	v_add_u32_e32 v134, s6, v184
	v_ashrrev_i32_e32 v161, 31, v160
	v_lshlrev_b64 v[164:165], 11, v[160:161]
	v_ashrrev_i32_e32 v135, 31, v134
	v_or_b32_e32 v156, 16, v160
	v_lshl_add_u64 v[132:133], s[36:37], 0, v[164:165]
	v_cvt_pk_bf16_f32 v124, v124, v125
	v_cvt_pk_bf16_f32 v125, v126, v127
	v_lshlrev_b64 v[126:127], 1, v[134:135]
	v_ashrrev_i32_e32 v157, 31, v156
	v_lshl_add_u64 v[132:133], v[132:133], 0, v[126:127]
	v_cvt_pk_bf16_f32 v96, v96, v97
	v_cvt_pk_bf16_f32 v97, v98, v99
	v_lshlrev_b64 v[162:163], 11, v[156:157]
	v_or_b32_e32 v152, 32, v160
	global_store_dwordx2 v[132:133], v[96:97], off offset:96
	v_lshl_add_u64 v[96:97], s[36:37], 0, v[162:163]
	v_ashrrev_i32_e32 v153, 31, v152
	v_lshl_add_u64 v[96:97], v[96:97], 0, v[126:127]
	v_cvt_pk_bf16_f32 v72, v72, v73
	v_cvt_pk_bf16_f32 v73, v74, v75
	v_lshlrev_b64 v[158:159], 11, v[152:153]
	v_or_b32_e32 v148, 48, v160
	global_store_dwordx2 v[96:97], v[72:73], off offset:96
	v_lshl_add_u64 v[72:73], s[36:37], 0, v[158:159]
	v_ashrrev_i32_e32 v149, 31, v148
	v_lshl_add_u64 v[72:73], v[72:73], 0, v[126:127]
	v_cvt_pk_bf16_f32 v56, v56, v57
	v_cvt_pk_bf16_f32 v57, v58, v59
	v_lshlrev_b64 v[154:155], 11, v[148:149]
	global_store_dwordx2 v[72:73], v[56:57], off offset:96
	v_lshl_add_u64 v[56:57], s[36:37], 0, v[154:155]
	v_cvt_pk_bf16_f32 v74, v104, v105
	v_cvt_pk_bf16_f32 v75, v106, v107
	v_cvt_pk_bf16_f32 v58, v100, v101
	v_cvt_pk_bf16_f32 v59, v102, v103
	v_lshl_add_u64 v[56:57], v[56:57], 0, v[126:127]
	v_cvt_pk_bf16_f32 v98, v120, v121
	v_cvt_pk_bf16_f32 v99, v122, v123
	global_store_dwordx2 v[72:73], v[74:75], off
	v_cvt_pk_bf16_f32 v74, v92, v93
	v_cvt_pk_bf16_f32 v75, v94, v95
	global_store_dwordx2 v[56:57], v[58:59], off
	v_cvt_pk_bf16_f32 v58, v80, v81
	v_cvt_pk_bf16_f32 v59, v82, v83
	v_cvt_pk_bf16_f32 v116, v116, v117
	v_cvt_pk_bf16_f32 v117, v118, v119
	v_cvt_pk_bf16_f32 v112, v112, v113
	v_cvt_pk_bf16_f32 v113, v114, v115
	global_store_dwordx2 v[96:97], v[98:99], off
	v_cvt_pk_bf16_f32 v98, v108, v109
	v_cvt_pk_bf16_f32 v99, v110, v111
	v_cvt_pk_bf16_f32 v88, v88, v89
	v_cvt_pk_bf16_f32 v89, v90, v91
	global_store_dwordx2 v[72:73], v[74:75], off offset:32
	v_cvt_pk_bf16_f32 v74, v76, v77
	v_cvt_pk_bf16_f32 v75, v78, v79
	global_store_dwordx2 v[56:57], v[58:59], off offset:32
	v_cvt_pk_bf16_f32 v58, v64, v65
	v_cvt_pk_bf16_f32 v59, v66, v67
	v_cvt_pk_bf16_f32 v36, v36, v37
	v_cvt_pk_bf16_f32 v37, v38, v39
	global_store_dwordx2 v[132:133], v[124:125], off
	global_store_dwordx2 v[132:133], v[116:117], off offset:32
	global_store_dwordx2 v[132:133], v[112:113], off offset:64
	global_store_dwordx2 v[96:97], v[98:99], off offset:32
	global_store_dwordx2 v[96:97], v[88:89], off offset:64
	global_store_dwordx2 v[72:73], v[74:75], off offset:64
	global_store_dwordx2 v[56:57], v[58:59], off offset:64
	global_store_dwordx2 v[56:57], v[36:37], off offset:96
	v_or_b32_e32 v144, 64, v160
	v_ashrrev_i32_e32 v145, 31, v144
	v_lshlrev_b64 v[150:151], 11, v[144:145]
	v_or_b32_e32 v140, 0x50, v160
	v_lshl_add_u64 v[36:37], s[36:37], 0, v[150:151]
	v_ashrrev_i32_e32 v141, 31, v140
	v_lshl_add_u64 v[36:37], v[36:37], 0, v[126:127]
	v_cvt_pk_bf16_f32 v20, v20, v21
	v_cvt_pk_bf16_f32 v21, v22, v23
	v_lshlrev_b64 v[146:147], 11, v[140:141]
	v_or_b32_e32 v136, 0x60, v160
	global_store_dwordx2 v[36:37], v[20:21], off offset:96
	v_lshl_add_u64 v[20:21], s[36:37], 0, v[146:147]
	v_ashrrev_i32_e32 v137, 31, v136
	v_lshl_add_u64 v[20:21], v[20:21], 0, v[126:127]
	v_cvt_pk_bf16_f32 v8, v8, v9
	v_cvt_pk_bf16_f32 v9, v10, v11
	v_lshlrev_b64 v[142:143], 11, v[136:137]
	v_or_b32_e32 v132, 0x70, v160
	global_store_dwordx2 v[20:21], v[8:9], off offset:96
	v_lshl_add_u64 v[8:9], s[36:37], 0, v[142:143]
	v_ashrrev_i32_e32 v133, 31, v132
	v_lshl_add_u64 v[8:9], v[8:9], 0, v[126:127]
	v_cvt_pk_bf16_f32 v0, v0, v1
	v_cvt_pk_bf16_f32 v1, v2, v3
	v_lshlrev_b64 v[138:139], 11, v[132:133]
	global_store_dwordx2 v[8:9], v[0:1], off offset:96
	v_lshl_add_u64 v[0:1], s[36:37], 0, v[138:139]
	v_cvt_pk_bf16_f32 v2, v32, v33
	v_cvt_pk_bf16_f32 v3, v34, v35
	v_lshl_add_u64 v[0:1], v[0:1], 0, v[126:127]
	v_cvt_pk_bf16_f32 v38, v84, v85
	v_cvt_pk_bf16_f32 v39, v86, v87
	v_cvt_pk_bf16_f32 v22, v68, v69
	v_cvt_pk_bf16_f32 v23, v70, v71
	v_cvt_pk_bf16_f32 v10, v52, v53
	v_cvt_pk_bf16_f32 v11, v54, v55
	global_store_dwordx2 v[0:1], v[2:3], off
	v_cvt_pk_bf16_f32 v2, v16, v17
	v_cvt_pk_bf16_f32 v3, v18, v19
	global_store_dwordx2 v[36:37], v[38:39], off
	v_cvt_pk_bf16_f32 v38, v60, v61
	v_cvt_pk_bf16_f32 v39, v62, v63
	global_store_dwordx2 v[20:21], v[22:23], off
	v_cvt_pk_bf16_f32 v22, v48, v49
	v_cvt_pk_bf16_f32 v23, v50, v51
	global_store_dwordx2 v[8:9], v[10:11], off
	v_cvt_pk_bf16_f32 v10, v28, v29
	v_cvt_pk_bf16_f32 v11, v30, v31
	global_store_dwordx2 v[0:1], v[2:3], off offset:32
	v_cvt_pk_bf16_f32 v2, v4, v5
	v_cvt_pk_bf16_f32 v3, v6, v7
	global_store_dwordx2 v[36:37], v[38:39], off offset:32
	v_cvt_pk_bf16_f32 v38, v44, v45
	v_cvt_pk_bf16_f32 v39, v46, v47
	global_store_dwordx2 v[20:21], v[22:23], off offset:32
	v_cvt_pk_bf16_f32 v22, v24, v25
	v_cvt_pk_bf16_f32 v23, v26, v27
	global_store_dwordx2 v[8:9], v[10:11], off offset:32
	v_cvt_pk_bf16_f32 v10, v12, v13
	v_cvt_pk_bf16_f32 v11, v14, v15
	global_store_dwordx2 v[0:1], v[2:3], off offset:64
	v_cvt_pk_bf16_f32 v2, v40, v41
	v_cvt_pk_bf16_f32 v3, v42, v43
	global_store_dwordx2 v[36:37], v[38:39], off offset:64
	global_store_dwordx2 v[20:21], v[22:23], off offset:64
	global_store_dwordx2 v[8:9], v[10:11], off offset:64
	global_store_dwordx2 v[0:1], v[2:3], off offset:96
	s_lshl_b32 s6, s6, 11
	s_add_u32 s6, s28, s6
	v_mov_b32_e32 v4, v182
	s_addc_u32 s7, s29, 0
	s_lshl_b64 s[2:3], s[2:3], 11
	s_add_u32 s2, s38, s2
	v_ashrrev_i32_e32 v0, 3, v4
	v_lshrrev_b32_e32 v5, 4, v4
	v_xor_b32_e32 v6, v5, v4
	v_ashrrev_i32_e32 v1, 31, v0
	s_addc_u32 s3, s39, s3
	v_lshlrev_b64 v[0:1], 11, v[0:1]
	v_lshlrev_b32_e32 v6, 4, v6
	v_lshl_add_u64 v[2:3], s[6:7], 0, v[0:1]
	v_and_b32_e32 v130, 0x70, v6
	v_lshl_add_u64 v[0:1], s[2:3], 0, v[0:1]
	v_lshl_add_u64 v[166:167], v[2:3], 0, v[130:131]
	v_lshl_add_u64 v[168:169], v[0:1], 0, v[130:131]
	v_lshlrev_b32_e32 v130, 4, v4
	v_add_u32_e32 v2, 0x2000, v130
	v_readfirstlane_b32 s2, v130
	v_lshl_add_u64 v[0:1], v[166:167], 0, s[18:19]
	s_mov_b32 m0, s2
	v_lshl_add_u64 v[170:171], v[166:167], 0, s[20:21]
	v_readfirstlane_b32 s2, v2
	v_add_u32_e32 v2, 0x4000, v130
	s_barrier
; template <int PIPE>
; DI void gemm_loop_g(const u16* __restrict__ Xp, long ldx_l, long ldx_i, long kxs,
;                     const u16* __restrict__ Yp, long ldy_l, long ldy_i, long kys, int K,
;                     f32x4 (&acc)[4][8], unsigned char* smem) {
;     ...
;   __syncthreads();
;   issue(0, 0);
;   asm volatile("s_waitcnt vmcnt(0)" ::: "memory");
;   __syncthreads();
; DI void zero_acc(f32x4 (&acc)[4][8]) {
; #pragma unroll
;   for (int i = 0; i < 4; ++i)
; #pragma unroll
;     for (int j = 0; j < 8; ++j) acc[i][j] = f32x4{0.f, 0.f, 0.f, 0.f};
; }
	global_load_lds_dwordx4 v[0:1], off
	v_lshl_add_u64 v[0:1], v[170:171], 0, s[18:19]
	s_mov_b32 m0, s2
	v_lshl_add_u64 v[172:173], v[166:167], 0, s[22:23]
	v_readfirstlane_b32 s2, v2
	v_add_u32_e32 v2, 0x6000, v130
	global_load_lds_dwordx4 v[0:1], off
	v_lshl_add_u64 v[0:1], v[172:173], 0, s[18:19]
	s_mov_b32 m0, s2
	v_lshl_add_u64 v[174:175], v[166:167], 0, s[24:25]
	v_readfirstlane_b32 s2, v2
	v_add_u32_e32 v2, 0x8000, v130
	global_load_lds_dwordx4 v[0:1], off
	v_lshl_add_u64 v[0:1], v[174:175], 0, s[18:19]
	s_mov_b32 m0, s2
	v_readfirstlane_b32 s2, v2
	v_add_u32_e32 v2, 0xa000, v130
	global_load_lds_dwordx4 v[0:1], off
	v_lshl_add_u64 v[0:1], v[168:169], 0, s[18:19]
	s_mov_b32 m0, s2
	v_lshl_add_u64 v[176:177], v[168:169], 0, s[20:21]
	v_readfirstlane_b32 s2, v2
	v_add_u32_e32 v2, 0xc000, v130
	global_load_lds_dwordx4 v[0:1], off
	v_lshl_add_u64 v[0:1], v[176:177], 0, s[18:19]
	s_mov_b32 m0, s2
	v_lshl_add_u64 v[178:179], v[168:169], 0, s[22:23]
	v_readfirstlane_b32 s2, v2
	v_add_u32_e32 v2, 0xe000, v130
	global_load_lds_dwordx4 v[0:1], off
	v_lshl_add_u64 v[0:1], v[178:179], 0, s[18:19]
	s_mov_b32 m0, s2
	v_lshl_add_u64 v[180:181], v[168:169], 0, s[24:25]
	v_readfirstlane_b32 s2, v2
	global_load_lds_dwordx4 v[0:1], off
	v_lshl_add_u64 v[0:1], v[180:181], 0, s[18:19]
	s_mov_b32 m0, s2
	v_lshlrev_b32_e32 v2, 7, v4
	global_load_lds_dwordx4 v[0:1], off
	v_bfe_u32 v0, v4, 4, 2
	v_bfe_u32 v1, v4, 1, 3
	v_readfirstlane_b32 s26, v4
	s_nop 0
	v_bitop3_b32 v0, v0, v1, 4 bitop3:0x36
	v_and_b32_e32 v2, 0x780, v2
	s_lshl_b32 s2, s26, 8
	s_lshl_b32 s3, s26, 6
	v_lshl_or_b32 v187, v0, 4, v2
	v_bitop3_b32 v0, v5, v1, 3 bitop3:0x6c
	v_mov_b32_e32 v4, 0
	s_and_b32 s2, s2, 0x4000
	s_and_b32 s3, s3, 0xffffe000
	v_lshl_or_b32 v188, v0, 4, v2
	s_mov_b32 s6, 0
	s_mov_b32 s7, 0x10000
	v_mov_b32_e32 v5, v4
	v_mov_b32_e32 v6, v4
	v_mov_b32_e32 v7, v4
	v_mov_b32_e32 v16, v4
	v_mov_b32_e32 v17, v4
	v_mov_b32_e32 v18, v4
	v_mov_b32_e32 v19, v4
	v_mov_b32_e32 v32, v4
	v_mov_b32_e32 v33, v4
	v_mov_b32_e32 v34, v4
	v_mov_b32_e32 v35, v4
	v_mov_b32_e32 v48, v4
	v_mov_b32_e32 v49, v4
	v_mov_b32_e32 v50, v4
	v_mov_b32_e32 v51, v4
	v_mov_b32_e32 v64, v4
	v_mov_b32_e32 v65, v4
	v_mov_b32_e32 v66, v4
	v_mov_b32_e32 v67, v4
	v_mov_b32_e32 v80, v4
	v_mov_b32_e32 v81, v4
	v_mov_b32_e32 v82, v4
	v_mov_b32_e32 v83, v4
	v_mov_b32_e32 v96, v4
	v_mov_b32_e32 v97, v4
	v_mov_b32_e32 v98, v4
	v_mov_b32_e32 v99, v4
	v_mov_b32_e32 v112, v4
	v_mov_b32_e32 v113, v4
	v_mov_b32_e32 v114, v4
	v_mov_b32_e32 v115, v4
	v_mov_b32_e32 v0, v4
	v_mov_b32_e32 v1, v4
	v_mov_b32_e32 v2, v4
	v_mov_b32_e32 v3, v4
	v_mov_b32_e32 v20, v4
	v_mov_b32_e32 v21, v4
	v_mov_b32_e32 v22, v4
	v_mov_b32_e32 v23, v4
	v_mov_b32_e32 v36, v4
	v_mov_b32_e32 v37, v4
	v_mov_b32_e32 v38, v4
	v_mov_b32_e32 v39, v4
	v_mov_b32_e32 v52, v4
	v_mov_b32_e32 v53, v4
	v_mov_b32_e32 v54, v4
	v_mov_b32_e32 v55, v4
	v_mov_b32_e32 v68, v4
	v_mov_b32_e32 v69, v4
	v_mov_b32_e32 v70, v4
	v_mov_b32_e32 v71, v4
	v_mov_b32_e32 v84, v4
	v_mov_b32_e32 v85, v4
	v_mov_b32_e32 v86, v4
	v_mov_b32_e32 v87, v4
	v_mov_b32_e32 v100, v4
	v_mov_b32_e32 v101, v4
	v_mov_b32_e32 v102, v4
	v_mov_b32_e32 v103, v4
	v_mov_b32_e32 v116, v4
	v_mov_b32_e32 v117, v4
	v_mov_b32_e32 v118, v4
	v_mov_b32_e32 v119, v4
	v_mov_b32_e32 v8, v4
	v_mov_b32_e32 v9, v4
	v_mov_b32_e32 v10, v4
	v_mov_b32_e32 v11, v4
	v_mov_b32_e32 v24, v4
	v_mov_b32_e32 v25, v4
	v_mov_b32_e32 v26, v4
	v_mov_b32_e32 v27, v4
	v_mov_b32_e32 v40, v4
	v_mov_b32_e32 v41, v4
	v_mov_b32_e32 v42, v4
	v_mov_b32_e32 v43, v4
	v_mov_b32_e32 v56, v4
	v_mov_b32_e32 v57, v4
	v_mov_b32_e32 v58, v4
	v_mov_b32_e32 v59, v4
	v_mov_b32_e32 v72, v4
	v_mov_b32_e32 v73, v4
	v_mov_b32_e32 v74, v4
	v_mov_b32_e32 v75, v4
	v_mov_b32_e32 v88, v4
	v_mov_b32_e32 v89, v4
	v_mov_b32_e32 v90, v4
	v_mov_b32_e32 v91, v4
	v_mov_b32_e32 v104, v4
	v_mov_b32_e32 v105, v4
	v_mov_b32_e32 v106, v4
	v_mov_b32_e32 v107, v4
	v_mov_b32_e32 v120, v4
	v_mov_b32_e32 v121, v4
	v_mov_b32_e32 v122, v4
	v_mov_b32_e32 v123, v4
	v_mov_b32_e32 v12, v4
	v_mov_b32_e32 v13, v4
	v_mov_b32_e32 v14, v4
	v_mov_b32_e32 v15, v4
	v_mov_b32_e32 v28, v4
	v_mov_b32_e32 v29, v4
	v_mov_b32_e32 v30, v4
	v_mov_b32_e32 v31, v4
	v_mov_b32_e32 v44, v4
	v_mov_b32_e32 v45, v4
	v_mov_b32_e32 v46, v4
	v_mov_b32_e32 v47, v4
	v_mov_b32_e32 v60, v4
	v_mov_b32_e32 v61, v4
	v_mov_b32_e32 v62, v4
	v_mov_b32_e32 v63, v4
	v_mov_b32_e32 v76, v4
	v_mov_b32_e32 v77, v4
	v_mov_b32_e32 v78, v4
	v_mov_b32_e32 v79, v4
	v_mov_b32_e32 v92, v4
	v_mov_b32_e32 v93, v4
	v_mov_b32_e32 v94, v4
	v_mov_b32_e32 v95, v4
	v_mov_b32_e32 v108, v4
	v_mov_b32_e32 v109, v4
	v_mov_b32_e32 v110, v4
	v_mov_b32_e32 v111, v4
	v_mov_b32_e32 v124, v4
	v_mov_b32_e32 v125, v4
	v_mov_b32_e32 v126, v4
	v_mov_b32_e32 v127, v4
	s_waitcnt vmcnt(0) lgkmcnt(0)
	s_barrier
	s_branch .LBB0_682
